# speedup vs baseline: 1.1258x; 1.0535x over previous
.LBB0_611:
	s_andn2_saveexec_b64 s[76:77], s[76:77]
	s_cbranch_execz .LBB0_651
	ds_read_b128 v[214:217], v150
	ds_read_b128 v[218:221], v170
	ds_read_b128 v[222:225], v150 offset:32
	ds_read_b128 v[226:229], v170 offset:32
	ds_read_b128 v[230:233], v150 offset:64
	ds_read_b128 v[234:237], v170 offset:64
	ds_read_b128 v[238:241], v150 offset:96
	ds_read_b128 v[242:245], v170 offset:96
	s_waitcnt lgkmcnt(6)
	v_mfma_f32_32x32x16_bf16 v[34:49], v[214:217], v[218:221], 0
	ds_read_b128 v[214:217], v150 offset:128
	ds_read_b128 v[218:221], v170 offset:128
	s_waitcnt lgkmcnt(6)
	v_mfma_f32_32x32x16_bf16 v[34:49], v[222:225], v[226:229], v[34:49]
	ds_read_b128 v[222:225], v150 offset:160
	ds_read_b128 v[226:229], v170 offset:160
	s_waitcnt lgkmcnt(6)
	v_mfma_f32_32x32x16_bf16 v[34:49], v[230:233], v[234:237], v[34:49]
	ds_read_b128 v[230:233], v150 offset:192
	ds_read_b128 v[234:237], v170 offset:192
	s_waitcnt lgkmcnt(6)
	v_mfma_f32_32x32x16_bf16 v[34:49], v[238:241], v[242:245], v[34:49]
	ds_read_b128 v[238:241], v150 offset:224
	ds_read_b128 v[242:245], v170 offset:224
	s_waitcnt lgkmcnt(6)
	v_mfma_f32_32x32x16_bf16 v[34:49], v[214:217], v[218:221], v[34:49]
	ds_read_b128 v[214:217], v150 offset:256
	ds_read_b128 v[218:221], v170 offset:256
	s_waitcnt lgkmcnt(6)
	v_mfma_f32_32x32x16_bf16 v[34:49], v[222:225], v[226:229], v[34:49]
	ds_read_b128 v[222:225], v150 offset:288
	ds_read_b128 v[226:229], v170 offset:288
	s_waitcnt lgkmcnt(6)
	v_mfma_f32_32x32x16_bf16 v[34:49], v[230:233], v[234:237], v[34:49]
	ds_read_b128 v[230:233], v150 offset:320
	ds_read_b128 v[234:237], v170 offset:320
	s_waitcnt lgkmcnt(6)
	v_mfma_f32_32x32x16_bf16 v[34:49], v[238:241], v[242:245], v[34:49]
	ds_read_b128 v[238:241], v150 offset:352
	ds_read_b128 v[242:245], v170 offset:352
	s_waitcnt lgkmcnt(6)
	v_mfma_f32_32x32x16_bf16 v[34:49], v[214:217], v[218:221], v[34:49]
	ds_read_b128 v[214:217], v150 offset:384
	ds_read_b128 v[218:221], v170 offset:384
	s_waitcnt lgkmcnt(6)
	v_mfma_f32_32x32x16_bf16 v[34:49], v[222:225], v[226:229], v[34:49]
	ds_read_b128 v[222:225], v150 offset:416
	ds_read_b128 v[226:229], v170 offset:416
	s_waitcnt lgkmcnt(6)
	v_mfma_f32_32x32x16_bf16 v[34:49], v[230:233], v[234:237], v[34:49]
	ds_read_b128 v[230:233], v150 offset:448
	ds_read_b128 v[234:237], v170 offset:448
	s_waitcnt lgkmcnt(6)
	v_mfma_f32_32x32x16_bf16 v[34:49], v[238:241], v[242:245], v[34:49]
	ds_read_b128 v[238:241], v150 offset:480
	ds_read_b128 v[242:245], v170 offset:480
	s_waitcnt lgkmcnt(6)
	v_mfma_f32_32x32x16_bf16 v[34:49], v[214:217], v[218:221], v[34:49]
	s_waitcnt lgkmcnt(4)
	v_mfma_f32_32x32x16_bf16 v[34:49], v[222:225], v[226:229], v[34:49]
	s_waitcnt lgkmcnt(2)
	v_mfma_f32_32x32x16_bf16 v[34:49], v[230:233], v[234:237], v[34:49]
	s_waitcnt lgkmcnt(0)
	v_mfma_f32_32x32x16_bf16 v[34:49], v[238:241], v[242:245], v[34:49]
	v_lshl_add_u32 v122, v151, 2, s69
	v_lshl_add_u32 v193, v152, 2, s69
	ds_read_b32 v122, v122
	ds_read_b128 v[214:217], v193 offset:256
	ds_read_b128 v[218:221], v193 offset:288
	ds_read_b128 v[222:225], v193 offset:320
	ds_read_b128 v[226:229], v193 offset:352
	s_waitcnt lgkmcnt(0)
	v_sub_f32_e32 v214, v122, v214
	v_sub_f32_e32 v215, v122, v215
	v_sub_f32_e32 v216, v122, v216
	v_sub_f32_e32 v217, v122, v217
	v_sub_f32_e32 v218, v122, v218
	v_sub_f32_e32 v219, v122, v219
	v_sub_f32_e32 v220, v122, v220
	v_sub_f32_e32 v221, v122, v221
	v_sub_f32_e32 v222, v122, v222
	v_sub_f32_e32 v223, v122, v223
	v_sub_f32_e32 v224, v122, v224
	v_sub_f32_e32 v225, v122, v225
	v_sub_f32_e32 v226, v122, v226
	v_sub_f32_e32 v227, v122, v227
	v_sub_f32_e32 v228, v122, v228
	v_sub_f32_e32 v229, v122, v229
	v_mul_f32_e32 v214, 0x3fb8aa3b, v214
	v_mul_f32_e32 v215, 0x3fb8aa3b, v215
	v_mul_f32_e32 v216, 0x3fb8aa3b, v216
	v_mul_f32_e32 v217, 0x3fb8aa3b, v217
	v_mul_f32_e32 v218, 0x3fb8aa3b, v218
	v_mul_f32_e32 v219, 0x3fb8aa3b, v219
	v_mul_f32_e32 v220, 0x3fb8aa3b, v220
	v_mul_f32_e32 v221, 0x3fb8aa3b, v221
	v_mul_f32_e32 v222, 0x3fb8aa3b, v222
	v_mul_f32_e32 v223, 0x3fb8aa3b, v223
	v_mul_f32_e32 v224, 0x3fb8aa3b, v224
	v_mul_f32_e32 v225, 0x3fb8aa3b, v225
	v_mul_f32_e32 v226, 0x3fb8aa3b, v226
	v_mul_f32_e32 v227, 0x3fb8aa3b, v227
	v_mul_f32_e32 v228, 0x3fb8aa3b, v228
	v_mul_f32_e32 v229, 0x3fb8aa3b, v229
	v_exp_f32_e32 v214, v214
	v_exp_f32_e32 v215, v215
	v_exp_f32_e32 v216, v216
	v_exp_f32_e32 v217, v217
	v_exp_f32_e32 v218, v218
	v_exp_f32_e32 v219, v219
	v_exp_f32_e32 v220, v220
	v_exp_f32_e32 v221, v221
	v_exp_f32_e32 v222, v222
	v_exp_f32_e32 v223, v223
	v_exp_f32_e32 v224, v224
	v_exp_f32_e32 v225, v225
	v_exp_f32_e32 v226, v226
	v_exp_f32_e32 v227, v227
	v_exp_f32_e32 v228, v228
	v_exp_f32_e32 v229, v229
	v_mul_f32_e32 v214, v34, v214
	v_mul_f32_e32 v215, v35, v215
	v_mul_f32_e32 v216, v36, v216
	v_mul_f32_e32 v217, v37, v217
	v_mul_f32_e32 v218, v38, v218
	v_mul_f32_e32 v219, v39, v219
	v_mul_f32_e32 v220, v40, v220
	v_mul_f32_e32 v221, v41, v221
	v_mul_f32_e32 v222, v42, v222
	v_mul_f32_e32 v223, v43, v223
	v_mul_f32_e32 v224, v44, v224
	v_mul_f32_e32 v225, v45, v225
	v_mul_f32_e32 v226, v46, v226
	v_mul_f32_e32 v227, v47, v227
	v_mul_f32_e32 v228, v48, v228
	v_mul_f32_e32 v229, v49, v229
	v_cndmask_b32_e64 v214, 0, v214, s[18:19]
	v_cndmask_b32_e64 v215, 0, v215, s[20:21]
	v_cndmask_b32_e64 v216, 0, v216, s[22:23]
	v_cndmask_b32_e64 v217, 0, v217, s[24:25]
	v_cndmask_b32_e64 v218, 0, v218, s[26:27]
	v_cndmask_b32_e64 v219, 0, v219, s[28:29]
	v_cndmask_b32_e64 v220, 0, v220, s[30:31]
	v_cndmask_b32_e64 v221, 0, v221, s[34:35]
	v_cndmask_b32_e64 v222, 0, v222, s[36:37]
	v_cndmask_b32_e64 v223, 0, v223, s[38:39]
	v_cndmask_b32_e64 v224, 0, v224, s[40:41]
	v_cndmask_b32_e64 v225, 0, v225, s[42:43]
	v_cndmask_b32_e64 v226, 0, v226, s[44:45]
	v_cndmask_b32_e64 v227, 0, v227, s[46:47]
	v_cndmask_b32_e64 v228, 0, v228, s[48:49]
	v_cndmask_b32_e64 v229, 0, v229, s[50:51]
	v_cvt_pk_bf16_f32 v214, v214, s0
	v_cvt_pk_bf16_f32 v215, v215, s0
	v_cvt_pk_bf16_f32 v216, v216, s0
	v_cvt_pk_bf16_f32 v217, v217, s0
	v_cvt_pk_bf16_f32 v218, v218, s0
	v_cvt_pk_bf16_f32 v219, v219, s0
	v_cvt_pk_bf16_f32 v220, v220, s0
	v_cvt_pk_bf16_f32 v221, v221, s0
	v_cvt_pk_bf16_f32 v222, v222, s0
	v_cvt_pk_bf16_f32 v223, v223, s0
	v_cvt_pk_bf16_f32 v224, v224, s0
	v_cvt_pk_bf16_f32 v225, v225, s0
	v_cvt_pk_bf16_f32 v226, v226, s0
	v_cvt_pk_bf16_f32 v227, v227, s0
	v_cvt_pk_bf16_f32 v228, v228, s0
	v_cvt_pk_bf16_f32 v229, v229, s0
	ds_write_b16 v192, v214
	ds_write_b16 v192, v215 offset:144
	ds_write_b16 v192, v216 offset:288
	ds_write_b16 v192, v217 offset:432
	ds_write_b16 v192, v218 offset:1152
	ds_write_b16 v192, v219 offset:1296
	ds_write_b16 v192, v220 offset:1440
	ds_write_b16 v192, v221 offset:1584
	ds_write_b16 v192, v222 offset:2304
	ds_write_b16 v192, v223 offset:2448
	ds_write_b16 v192, v224 offset:2592
	ds_write_b16 v192, v225 offset:2736
	ds_write_b16 v192, v226 offset:3456
	ds_write_b16 v192, v227 offset:3600
	ds_write_b16 v192, v228 offset:3744
	ds_write_b16 v192, v229 offset:3888
	v_mov_b32_e32 v193, 0
	s_mov_b32 s70, 0
	v_mov_b32_e32 v122, v154
	v_add_u32_e32 v212, 0x26b20, v171
	v_mov_b32_e32 v246, 0
	v_mov_b32_e32 v247, 0
	v_mov_b32_e32 v248, 0
	v_mov_b32_e32 v249, 0
	ds_read_b128 v[214:217], v154
	ds_read_b128 v[218:221], v154 offset:16
	ds_read_b128 v[222:225], v212
	ds_read_b128 v[226:229], v212 offset:16
	ds_read_b128 v[230:233], v212 offset:32
	ds_read_b128 v[234:237], v212 offset:48
	ds_read_b128 v[238:241], v154 offset:32
	ds_read_b128 v[242:245], v154 offset:48
	ds_read_b128 v[194:197], v212 offset:64
	ds_read_b128 v[198:201], v212 offset:80
	ds_read_b128 v[202:205], v212 offset:96
	ds_read_b128 v[206:209], v212 offset:112
	s_waitcnt lgkmcnt(6)
	v_lshlrev_b32_e32 v250, 16, v214
	v_and_b32_e32 v251, 0xffff0000, v214
	v_pk_fma_f32 v[246:247], v[250:251], v[222:223], v[246:247]
	v_lshlrev_b32_e32 v252, 16, v215
	v_and_b32_e32 v253, 0xffff0000, v215
	v_pk_fma_f32 v[248:249], v[252:253], v[224:225], v[248:249]
	v_lshlrev_b32_e32 v250, 16, v216
	v_and_b32_e32 v251, 0xffff0000, v216
	v_pk_fma_f32 v[246:247], v[250:251], v[226:227], v[246:247]
	v_lshlrev_b32_e32 v252, 16, v217
	v_and_b32_e32 v253, 0xffff0000, v217
	v_pk_fma_f32 v[248:249], v[252:253], v[228:229], v[248:249]
	v_lshlrev_b32_e32 v250, 16, v218
	v_and_b32_e32 v251, 0xffff0000, v218
	v_pk_fma_f32 v[246:247], v[250:251], v[230:231], v[246:247]
	v_lshlrev_b32_e32 v252, 16, v219
	v_and_b32_e32 v253, 0xffff0000, v219
	v_pk_fma_f32 v[248:249], v[252:253], v[232:233], v[248:249]
	v_lshlrev_b32_e32 v250, 16, v220
	v_and_b32_e32 v251, 0xffff0000, v220
	v_pk_fma_f32 v[246:247], v[250:251], v[234:235], v[246:247]
	v_lshlrev_b32_e32 v252, 16, v221
	v_and_b32_e32 v253, 0xffff0000, v221
	v_pk_fma_f32 v[248:249], v[252:253], v[236:237], v[248:249]
	ds_read_b128 v[214:217], v154 offset:64
	ds_read_b128 v[218:221], v154 offset:80
	ds_read_b128 v[222:225], v212 offset:128
	ds_read_b128 v[226:229], v212 offset:144
	ds_read_b128 v[230:233], v212 offset:160
	ds_read_b128 v[234:237], v212 offset:176
	s_waitcnt lgkmcnt(6)
	v_lshlrev_b32_e32 v250, 16, v238
	v_and_b32_e32 v251, 0xffff0000, v238
	v_pk_fma_f32 v[246:247], v[250:251], v[194:195], v[246:247]
	v_lshlrev_b32_e32 v252, 16, v239
	v_and_b32_e32 v253, 0xffff0000, v239
	v_pk_fma_f32 v[248:249], v[252:253], v[196:197], v[248:249]
	v_lshlrev_b32_e32 v250, 16, v240
	v_and_b32_e32 v251, 0xffff0000, v240
	v_pk_fma_f32 v[246:247], v[250:251], v[198:199], v[246:247]
	v_lshlrev_b32_e32 v252, 16, v241
	v_and_b32_e32 v253, 0xffff0000, v241
	v_pk_fma_f32 v[248:249], v[252:253], v[200:201], v[248:249]
	v_lshlrev_b32_e32 v250, 16, v242
	v_and_b32_e32 v251, 0xffff0000, v242
	v_pk_fma_f32 v[246:247], v[250:251], v[202:203], v[246:247]
	v_lshlrev_b32_e32 v252, 16, v243
	v_and_b32_e32 v253, 0xffff0000, v243
	v_pk_fma_f32 v[248:249], v[252:253], v[204:205], v[248:249]
	v_lshlrev_b32_e32 v250, 16, v244
	v_and_b32_e32 v251, 0xffff0000, v244
	v_pk_fma_f32 v[246:247], v[250:251], v[206:207], v[246:247]
	v_lshlrev_b32_e32 v252, 16, v245
	v_and_b32_e32 v253, 0xffff0000, v245
	v_pk_fma_f32 v[248:249], v[252:253], v[208:209], v[248:249]
	ds_read_b128 v[238:241], v154 offset:96
	ds_read_b128 v[242:245], v154 offset:112
	ds_read_b128 v[194:197], v212 offset:192
	ds_read_b128 v[198:201], v212 offset:208
	ds_read_b128 v[202:205], v212 offset:224
	ds_read_b128 v[206:209], v212 offset:240
	s_waitcnt lgkmcnt(6)
	v_lshlrev_b32_e32 v250, 16, v214
	v_and_b32_e32 v251, 0xffff0000, v214
	v_pk_fma_f32 v[246:247], v[250:251], v[222:223], v[246:247]
	v_lshlrev_b32_e32 v252, 16, v215
	v_and_b32_e32 v253, 0xffff0000, v215
	v_pk_fma_f32 v[248:249], v[252:253], v[224:225], v[248:249]
	v_lshlrev_b32_e32 v250, 16, v216
	v_and_b32_e32 v251, 0xffff0000, v216
	v_pk_fma_f32 v[246:247], v[250:251], v[226:227], v[246:247]
	v_lshlrev_b32_e32 v252, 16, v217
	v_and_b32_e32 v253, 0xffff0000, v217
	v_pk_fma_f32 v[248:249], v[252:253], v[228:229], v[248:249]
	v_lshlrev_b32_e32 v250, 16, v218
	v_and_b32_e32 v251, 0xffff0000, v218
	v_pk_fma_f32 v[246:247], v[250:251], v[230:231], v[246:247]
	v_lshlrev_b32_e32 v252, 16, v219
	v_and_b32_e32 v253, 0xffff0000, v219
	v_pk_fma_f32 v[248:249], v[252:253], v[232:233], v[248:249]
	v_lshlrev_b32_e32 v250, 16, v220
	v_and_b32_e32 v251, 0xffff0000, v220
	v_pk_fma_f32 v[246:247], v[250:251], v[234:235], v[246:247]
	v_lshlrev_b32_e32 v252, 16, v221
	v_and_b32_e32 v253, 0xffff0000, v221
	v_pk_fma_f32 v[248:249], v[252:253], v[236:237], v[248:249]
	s_waitcnt lgkmcnt(0)
	v_lshlrev_b32_e32 v250, 16, v238
	v_and_b32_e32 v251, 0xffff0000, v238
	v_pk_fma_f32 v[246:247], v[250:251], v[194:195], v[246:247]
	v_lshlrev_b32_e32 v252, 16, v239
	v_and_b32_e32 v253, 0xffff0000, v239
	v_pk_fma_f32 v[248:249], v[252:253], v[196:197], v[248:249]
	v_lshlrev_b32_e32 v250, 16, v240
	v_and_b32_e32 v251, 0xffff0000, v240
	v_pk_fma_f32 v[246:247], v[250:251], v[198:199], v[246:247]
	v_lshlrev_b32_e32 v252, 16, v241
	v_and_b32_e32 v253, 0xffff0000, v241
	v_pk_fma_f32 v[248:249], v[252:253], v[200:201], v[248:249]
	v_lshlrev_b32_e32 v250, 16, v242
	v_and_b32_e32 v251, 0xffff0000, v242
	v_pk_fma_f32 v[246:247], v[250:251], v[202:203], v[246:247]
	v_lshlrev_b32_e32 v252, 16, v243
	v_and_b32_e32 v253, 0xffff0000, v243
	v_pk_fma_f32 v[248:249], v[252:253], v[204:205], v[248:249]
	v_lshlrev_b32_e32 v250, 16, v244
	v_and_b32_e32 v251, 0xffff0000, v244
	v_pk_fma_f32 v[246:247], v[250:251], v[206:207], v[246:247]
	v_lshlrev_b32_e32 v252, 16, v245
	v_and_b32_e32 v253, 0xffff0000, v245
	v_pk_fma_f32 v[248:249], v[252:253], v[208:209], v[248:249]
	v_pk_add_f32 v[246:247], v[246:247], v[248:249]
	v_add_f32_e32 v193, v246, v247
	v_xor_b32_e32 v122, 1, v129
	v_add_u32_e32 v194, 64, v130
	v_cmp_lt_i32_e32 vcc, v122, v194
	s_nop 1
	v_cndmask_b32_e32 v122, v129, v122, vcc
	v_lshlrev_b32_e32 v122, 2, v122
	ds_bpermute_b32 v122, v122, v193
	s_waitcnt lgkmcnt(0)
	v_add_f32_e32 v122, v193, v122
	v_xor_b32_e32 v193, 2, v129
	v_cmp_lt_i32_e32 vcc, v193, v194
	s_nop 1
	v_cndmask_b32_e32 v193, v129, v193, vcc
	v_lshlrev_b32_e32 v193, 2, v193
	ds_bpermute_b32 v193, v193, v122
	s_and_saveexec_b64 s[78:79], s[12:13]
	s_cbranch_execz .LBB0_650
	s_waitcnt lgkmcnt(0)
	v_add_f32_e32 v122, v122, v193
	ds_write_b32 v155, v122

.LBB0_1334:
	v_add_u32_e32 v0, 0x10000, v148
	s_waitcnt vmcnt(0)
	ds_read_b128 v[142:145], v0
	ds_read_b128 v[150:153], v0 offset:1024
	ds_read_b128 v[154:157], v0 offset:2048
	ds_read_b128 v[158:161], v0 offset:3072
	s_add_u32 s26, s24, 0xfffc0080
	s_addc_u32 s27, s25, -1
	s_cmp_eq_u32 vcc_lo, 12
	s_cselect_b32 s29, s2, s27
	s_cselect_b32 s28, s15, s26
	s_cselect_b32 s27, s13, s94
	s_cselect_b32 s26, s89, s90
	v_lshl_add_u64 v[178:179], s[24:25], 0, v[138:139]
	s_add_i32 m0, s36, 0xc000
	ds_read_b128 v[162:165], v147
	ds_read_b128 v[166:169], v147 offset:1024
	ds_read_b128 v[170:173], v147 offset:2048
	ds_read_b128 v[174:177], v147 offset:3072
	ds_read_b128 v[182:185], v147 offset:4096
	ds_read_b128 v[186:189], v147 offset:5120
	ds_read_b128 v[190:193], v147 offset:6144
	ds_read_b128 v[194:197], v147 offset:7168
	global_load_lds_dwordx4 v[178:179], off
	v_lshl_add_u64 v[178:179], s[24:25], 0, v[140:141]
	s_add_i32 m0, s36, 0xe000
	s_nop 0
	global_load_lds_dwordx4 v[178:179], off
	s_waitcnt lgkmcnt(8)
	s_barrier
	s_waitcnt lgkmcnt(0)
	s_setprio 1
	s_waitcnt lgkmcnt(0)
	v_mfma_f32_16x16x32_bf16 v[126:129], v[142:145], v[162:165], v[126:129]
	v_mfma_f32_16x16x32_bf16 v[122:125], v[154:157], v[162:165], v[122:125]
	v_mfma_f32_16x16x32_bf16 v[110:113], v[142:145], v[170:173], v[110:113]
	v_mfma_f32_16x16x32_bf16 v[106:109], v[154:157], v[170:173], v[106:109]
	v_mfma_f32_16x16x32_bf16 v[94:97], v[142:145], v[182:185], v[94:97]
	v_mfma_f32_16x16x32_bf16 v[90:93], v[154:157], v[182:185], v[90:93]
	v_mfma_f32_16x16x32_bf16 v[78:81], v[142:145], v[190:193], v[78:81]
	v_mfma_f32_16x16x32_bf16 v[74:77], v[154:157], v[190:193], v[74:77]
	v_mfma_f32_16x16x32_bf16 v[126:129], v[150:153], v[166:169], v[126:129]
	v_mfma_f32_16x16x32_bf16 v[122:125], v[158:161], v[166:169], v[122:125]
	v_mfma_f32_16x16x32_bf16 v[110:113], v[150:153], v[174:177], v[110:113]
	v_mfma_f32_16x16x32_bf16 v[106:109], v[158:161], v[174:177], v[106:109]
	v_mfma_f32_16x16x32_bf16 v[94:97], v[150:153], v[186:189], v[94:97]
	v_mfma_f32_16x16x32_bf16 v[90:93], v[158:161], v[186:189], v[90:93]
	v_mfma_f32_16x16x32_bf16 v[78:81], v[150:153], v[194:197], v[78:81]
	v_mfma_f32_16x16x32_bf16 v[74:77], v[158:161], v[194:197], v[74:77]
	s_setprio 0
	s_barrier
	s_mov_b32 m0, s21
	v_add_u32_e32 v0, 0x14000, v148
	v_lshl_add_u64 v[178:179], s[26:27], 0, v[134:135]
	s_waitcnt vmcnt(0)
	ds_read_b128 v[198:201], v0
	ds_read_b128 v[202:205], v0 offset:1024
	ds_read_b128 v[206:209], v0 offset:2048
	ds_read_b128 v[210:213], v0 offset:3072
	global_load_lds_dwordx4 v[178:179], off
	v_lshl_add_u64 v[214:215], s[26:27], 0, v[130:131]
	s_mov_b32 m0, s23
	s_nop 0
	global_load_lds_dwordx4 v[214:215], off
	s_barrier
	s_waitcnt lgkmcnt(0)
	s_setprio 1
	s_waitcnt lgkmcnt(0)
	v_mfma_f32_16x16x32_bf16 v[118:121], v[198:201], v[162:165], v[118:121]
	v_mfma_f32_16x16x32_bf16 v[114:117], v[206:209], v[162:165], v[114:117]
	v_mfma_f32_16x16x32_bf16 v[102:105], v[198:201], v[170:173], v[102:105]
	v_mfma_f32_16x16x32_bf16 v[98:101], v[206:209], v[170:173], v[98:101]
	v_mfma_f32_16x16x32_bf16 v[86:89], v[198:201], v[182:185], v[86:89]
	v_mfma_f32_16x16x32_bf16 v[82:85], v[206:209], v[182:185], v[82:85]
	v_mfma_f32_16x16x32_bf16 v[70:73], v[198:201], v[190:193], v[70:73]
	v_mfma_f32_16x16x32_bf16 v[66:69], v[206:209], v[190:193], v[66:69]
	v_mfma_f32_16x16x32_bf16 v[118:121], v[202:205], v[166:169], v[118:121]
	v_mfma_f32_16x16x32_bf16 v[114:117], v[210:213], v[166:169], v[114:117]
	v_mfma_f32_16x16x32_bf16 v[102:105], v[202:205], v[174:177], v[102:105]
	v_mfma_f32_16x16x32_bf16 v[98:101], v[210:213], v[174:177], v[98:101]
	v_mfma_f32_16x16x32_bf16 v[86:89], v[202:205], v[186:189], v[86:89]
	v_mfma_f32_16x16x32_bf16 v[82:85], v[210:213], v[186:189], v[82:85]
	v_mfma_f32_16x16x32_bf16 v[70:73], v[202:205], v[194:197], v[70:73]
	v_mfma_f32_16x16x32_bf16 v[66:69], v[210:213], v[194:197], v[66:69]
	s_setprio 0
	s_mov_b32 m0, s36
	v_lshl_add_u64 v[216:217], s[28:29], 0, v[136:137]
	s_barrier
	s_waitcnt vmcnt(0)
	ds_read_b128 v[162:165], v147 offset:16384
	ds_read_b128 v[166:169], v147 offset:17408
	ds_read_b128 v[170:173], v147 offset:18432
	ds_read_b128 v[174:177], v147 offset:19456
	ds_read_b128 v[182:185], v147 offset:20480
	ds_read_b128 v[186:189], v147 offset:21504
	ds_read_b128 v[190:193], v147 offset:22528
	ds_read_b128 v[194:197], v147 offset:23552
	global_load_lds_dwordx4 v[216:217], off
	v_lshl_add_u64 v[222:223], s[28:29], 0, v[132:133]
	s_mov_b32 m0, s37
	s_nop 0
	global_load_lds_dwordx4 v[222:223], off
	s_barrier
	s_waitcnt lgkmcnt(0)
	s_setprio 1
	s_waitcnt lgkmcnt(0)
	v_mfma_f32_16x16x32_bf16 v[62:65], v[142:145], v[162:165], v[62:65]
	v_mfma_f32_16x16x32_bf16 v[58:61], v[154:157], v[162:165], v[58:61]
	v_mfma_f32_16x16x32_bf16 v[46:49], v[142:145], v[170:173], v[46:49]
	v_mfma_f32_16x16x32_bf16 v[42:45], v[154:157], v[170:173], v[42:45]
	v_mfma_f32_16x16x32_bf16 v[30:33], v[142:145], v[182:185], v[30:33]
	v_mfma_f32_16x16x32_bf16 v[26:29], v[154:157], v[182:185], v[26:29]
	v_mfma_f32_16x16x32_bf16 v[14:17], v[142:145], v[190:193], v[14:17]
	v_mfma_f32_16x16x32_bf16 v[10:13], v[154:157], v[190:193], v[10:13]
	v_mfma_f32_16x16x32_bf16 v[62:65], v[150:153], v[166:169], v[62:65]
	v_mfma_f32_16x16x32_bf16 v[58:61], v[158:161], v[166:169], v[58:61]
	v_mfma_f32_16x16x32_bf16 v[46:49], v[150:153], v[174:177], v[46:49]
	v_mfma_f32_16x16x32_bf16 v[42:45], v[158:161], v[174:177], v[42:45]
	v_mfma_f32_16x16x32_bf16 v[30:33], v[150:153], v[186:189], v[30:33]
	v_mfma_f32_16x16x32_bf16 v[26:29], v[158:161], v[186:189], v[26:29]
	v_mfma_f32_16x16x32_bf16 v[14:17], v[150:153], v[194:197], v[14:17]
	v_mfma_f32_16x16x32_bf16 v[10:13], v[158:161], v[194:197], v[10:13]
	s_setprio 0
	s_barrier
	s_add_u32 s76, s26, 0x40000
	s_addc_u32 s77, s27, 0
	s_mov_b32 m0, s38
	v_lshl_add_u64 v[142:143], s[76:77], 0, v[134:135]
	global_load_lds_dwordx4 v[142:143], off
	v_lshl_add_u64 v[142:143], s[76:77], 0, v[130:131]
	s_mov_b32 m0, s39
	s_nop 0
	global_load_lds_dwordx4 v[142:143], off
	s_waitcnt vmcnt(6)
	s_barrier
	s_setprio 1
	v_mfma_f32_16x16x32_bf16 v[54:57], v[198:201], v[162:165], v[54:57]
	v_mfma_f32_16x16x32_bf16 v[50:53], v[206:209], v[162:165], v[50:53]
	v_mfma_f32_16x16x32_bf16 v[38:41], v[198:201], v[170:173], v[38:41]
	v_mfma_f32_16x16x32_bf16 v[34:37], v[206:209], v[170:173], v[34:37]
	v_mfma_f32_16x16x32_bf16 v[22:25], v[198:201], v[182:185], v[22:25]
	v_mfma_f32_16x16x32_bf16 v[18:21], v[206:209], v[182:185], v[18:21]
	v_mfma_f32_16x16x32_bf16 v[6:9], v[198:201], v[190:193], v[6:9]
	v_mfma_f32_16x16x32_bf16 v[2:5], v[206:209], v[190:193], v[2:5]
	v_mfma_f32_16x16x32_bf16 v[54:57], v[202:205], v[166:169], v[54:57]
	v_mfma_f32_16x16x32_bf16 v[50:53], v[210:213], v[166:169], v[50:53]
	v_mfma_f32_16x16x32_bf16 v[38:41], v[202:205], v[174:177], v[38:41]
	v_mfma_f32_16x16x32_bf16 v[34:37], v[210:213], v[174:177], v[34:37]
	v_mfma_f32_16x16x32_bf16 v[22:25], v[202:205], v[186:189], v[22:25]
	v_mfma_f32_16x16x32_bf16 v[18:21], v[210:213], v[186:189], v[18:21]
	v_mfma_f32_16x16x32_bf16 v[6:9], v[202:205], v[194:197], v[6:9]
	v_mfma_f32_16x16x32_bf16 v[2:5], v[210:213], v[194:197], v[2:5]
	s_setprio 0
	v_add_u32_e32 v0, 0x18000, v148
	s_barrier
	s_waitcnt vmcnt(0)
	ds_read_b128 v[142:145], v0
	ds_read_b128 v[150:153], v0 offset:1024
	ds_read_b128 v[154:157], v0 offset:2048
	ds_read_b128 v[158:161], v0 offset:3072
	s_add_u32 s28, s28, 0x40000
	s_addc_u32 s29, s29, 0
	s_mov_b32 m0, s60
	v_lshl_add_u64 v[198:199], s[28:29], 0, v[136:137]
	ds_read_b128 v[162:165], v147 offset:32768
	ds_read_b128 v[166:169], v147 offset:33792
	ds_read_b128 v[170:173], v147 offset:34816
	ds_read_b128 v[174:177], v147 offset:35840
	ds_read_b128 v[182:185], v147 offset:36864
	ds_read_b128 v[186:189], v147 offset:37888
	ds_read_b128 v[190:193], v147 offset:38912
	ds_read_b128 v[194:197], v147 offset:39936
	global_load_lds_dwordx4 v[198:199], off
	v_lshl_add_u64 v[198:199], s[28:29], 0, v[132:133]
	s_mov_b32 m0, s68
	s_nop 0
	global_load_lds_dwordx4 v[198:199], off
	s_waitcnt lgkmcnt(8)
	s_barrier
	s_waitcnt lgkmcnt(0)
	s_setprio 1
	s_waitcnt lgkmcnt(0)
	v_mfma_f32_16x16x32_bf16 v[126:129], v[142:145], v[162:165], v[126:129]
	v_mfma_f32_16x16x32_bf16 v[122:125], v[154:157], v[162:165], v[122:125]
	v_mfma_f32_16x16x32_bf16 v[110:113], v[142:145], v[170:173], v[110:113]
	v_mfma_f32_16x16x32_bf16 v[106:109], v[154:157], v[170:173], v[106:109]
	v_mfma_f32_16x16x32_bf16 v[94:97], v[142:145], v[182:185], v[94:97]
	v_mfma_f32_16x16x32_bf16 v[90:93], v[154:157], v[182:185], v[90:93]
	v_mfma_f32_16x16x32_bf16 v[78:81], v[142:145], v[190:193], v[78:81]
	v_mfma_f32_16x16x32_bf16 v[74:77], v[154:157], v[190:193], v[74:77]
	v_mfma_f32_16x16x32_bf16 v[126:129], v[150:153], v[166:169], v[126:129]
	v_mfma_f32_16x16x32_bf16 v[122:125], v[158:161], v[166:169], v[122:125]
	v_mfma_f32_16x16x32_bf16 v[110:113], v[150:153], v[174:177], v[110:113]
	v_mfma_f32_16x16x32_bf16 v[106:109], v[158:161], v[174:177], v[106:109]
	v_mfma_f32_16x16x32_bf16 v[94:97], v[150:153], v[186:189], v[94:97]
	v_mfma_f32_16x16x32_bf16 v[90:93], v[158:161], v[186:189], v[90:93]
	v_mfma_f32_16x16x32_bf16 v[78:81], v[150:153], v[194:197], v[78:81]
	v_mfma_f32_16x16x32_bf16 v[74:77], v[158:161], v[194:197], v[74:77]
	s_setprio 0
	s_barrier
	s_mov_b32 m0, s69
	v_add_u32_e32 v0, 0x1c000, v148
	v_lshl_add_u64 v[178:179], v[178:179], 0, s[84:85]
	s_waitcnt vmcnt(0)
	ds_read_b128 v[198:201], v0
	ds_read_b128 v[202:205], v0 offset:1024
	ds_read_b128 v[206:209], v0 offset:2048
	ds_read_b128 v[210:213], v0 offset:3072
	global_load_lds_dwordx4 v[178:179], off
	v_lshl_add_u64 v[178:179], v[214:215], 0, s[84:85]
	s_mov_b32 m0, s75
	s_nop 0
	global_load_lds_dwordx4 v[178:179], off
	s_barrier
	s_waitcnt lgkmcnt(0)
	s_setprio 1
	s_waitcnt lgkmcnt(0)
	v_mfma_f32_16x16x32_bf16 v[118:121], v[198:201], v[162:165], v[118:121]
	v_mfma_f32_16x16x32_bf16 v[114:117], v[206:209], v[162:165], v[114:117]
	v_mfma_f32_16x16x32_bf16 v[102:105], v[198:201], v[170:173], v[102:105]
	v_mfma_f32_16x16x32_bf16 v[98:101], v[206:209], v[170:173], v[98:101]
	v_mfma_f32_16x16x32_bf16 v[86:89], v[198:201], v[182:185], v[86:89]
	v_mfma_f32_16x16x32_bf16 v[82:85], v[206:209], v[182:185], v[82:85]
	v_mfma_f32_16x16x32_bf16 v[70:73], v[198:201], v[190:193], v[70:73]
	v_mfma_f32_16x16x32_bf16 v[66:69], v[206:209], v[190:193], v[66:69]
	v_mfma_f32_16x16x32_bf16 v[118:121], v[202:205], v[166:169], v[118:121]
	v_mfma_f32_16x16x32_bf16 v[114:117], v[210:213], v[166:169], v[114:117]
	v_mfma_f32_16x16x32_bf16 v[102:105], v[202:205], v[174:177], v[102:105]
	v_mfma_f32_16x16x32_bf16 v[98:101], v[210:213], v[174:177], v[98:101]
	v_mfma_f32_16x16x32_bf16 v[86:89], v[202:205], v[186:189], v[86:89]
	v_mfma_f32_16x16x32_bf16 v[82:85], v[210:213], v[186:189], v[82:85]
	v_mfma_f32_16x16x32_bf16 v[70:73], v[202:205], v[194:197], v[70:73]
	v_mfma_f32_16x16x32_bf16 v[66:69], v[210:213], v[194:197], v[66:69]
	s_setprio 0
	s_mov_b32 m0, s82
	v_lshl_add_u64 v[178:179], v[216:217], 0, s[84:85]
	s_barrier
	s_waitcnt vmcnt(0)
	ds_read_b128 v[162:165], v147 offset:49152
	ds_read_b128 v[166:169], v147 offset:50176
	ds_read_b128 v[170:173], v147 offset:51200
	ds_read_b128 v[174:177], v147 offset:52224
	ds_read_b128 v[182:185], v147 offset:53248
	ds_read_b128 v[186:189], v147 offset:54272
	ds_read_b128 v[190:193], v147 offset:55296
	ds_read_b128 v[194:197], v147 offset:56320
	global_load_lds_dwordx4 v[178:179], off
	v_lshl_add_u64 v[178:179], v[222:223], 0, s[84:85]
	s_mov_b32 m0, s92
	s_nop 0
	global_load_lds_dwordx4 v[178:179], off
	s_barrier
	s_waitcnt lgkmcnt(0)
	s_setprio 1
	s_waitcnt lgkmcnt(0)
	v_mfma_f32_16x16x32_bf16 v[62:65], v[142:145], v[162:165], v[62:65]
	v_mfma_f32_16x16x32_bf16 v[58:61], v[154:157], v[162:165], v[58:61]
	v_mfma_f32_16x16x32_bf16 v[46:49], v[142:145], v[170:173], v[46:49]
	v_mfma_f32_16x16x32_bf16 v[42:45], v[154:157], v[170:173], v[42:45]
	v_mfma_f32_16x16x32_bf16 v[30:33], v[142:145], v[182:185], v[30:33]
	v_mfma_f32_16x16x32_bf16 v[26:29], v[154:157], v[182:185], v[26:29]
	v_mfma_f32_16x16x32_bf16 v[14:17], v[142:145], v[190:193], v[14:17]
	v_mfma_f32_16x16x32_bf16 v[10:13], v[154:157], v[190:193], v[10:13]
	v_mfma_f32_16x16x32_bf16 v[62:65], v[150:153], v[166:169], v[62:65]
	v_mfma_f32_16x16x32_bf16 v[58:61], v[158:161], v[166:169], v[58:61]
	v_mfma_f32_16x16x32_bf16 v[46:49], v[150:153], v[174:177], v[46:49]
	v_mfma_f32_16x16x32_bf16 v[42:45], v[158:161], v[174:177], v[42:45]
	v_mfma_f32_16x16x32_bf16 v[30:33], v[150:153], v[186:189], v[30:33]
	v_mfma_f32_16x16x32_bf16 v[26:29], v[158:161], v[186:189], v[26:29]
	v_mfma_f32_16x16x32_bf16 v[14:17], v[150:153], v[194:197], v[14:17]
	v_mfma_f32_16x16x32_bf16 v[10:13], v[158:161], v[194:197], v[10:13]
	s_setprio 0
	s_barrier
	s_add_u32 s26, s26, 0x40080
	s_addc_u32 s27, s27, 0
	s_mov_b32 m0, s93
	v_lshl_add_u64 v[142:143], s[26:27], 0, v[134:135]
	global_load_lds_dwordx4 v[142:143], off
	v_lshl_add_u64 v[142:143], s[26:27], 0, v[130:131]
	s_mov_b32 m0, s96
	s_nop 0
	global_load_lds_dwordx4 v[142:143], off
	s_waitcnt vmcnt(6)
	s_barrier
	s_setprio 1
	v_mfma_f32_16x16x32_bf16 v[54:57], v[198:201], v[162:165], v[54:57]
	v_mfma_f32_16x16x32_bf16 v[50:53], v[206:209], v[162:165], v[50:53]
	v_mfma_f32_16x16x32_bf16 v[38:41], v[198:201], v[170:173], v[38:41]
	v_mfma_f32_16x16x32_bf16 v[34:37], v[206:209], v[170:173], v[34:37]
	v_mfma_f32_16x16x32_bf16 v[22:25], v[198:201], v[182:185], v[22:25]
	v_mfma_f32_16x16x32_bf16 v[18:21], v[206:209], v[182:185], v[18:21]
	v_mfma_f32_16x16x32_bf16 v[6:9], v[198:201], v[190:193], v[6:9]
	v_mfma_f32_16x16x32_bf16 v[2:5], v[206:209], v[190:193], v[2:5]
	v_mfma_f32_16x16x32_bf16 v[54:57], v[202:205], v[166:169], v[54:57]
	v_mfma_f32_16x16x32_bf16 v[50:53], v[210:213], v[166:169], v[50:53]
	v_mfma_f32_16x16x32_bf16 v[38:41], v[202:205], v[174:177], v[38:41]
	v_mfma_f32_16x16x32_bf16 v[34:37], v[210:213], v[174:177], v[34:37]
	v_mfma_f32_16x16x32_bf16 v[22:25], v[202:205], v[186:189], v[22:25]
	v_mfma_f32_16x16x32_bf16 v[18:21], v[210:213], v[186:189], v[18:21]
	v_mfma_f32_16x16x32_bf16 v[6:9], v[202:205], v[194:197], v[6:9]
	v_mfma_f32_16x16x32_bf16 v[2:5], v[210:213], v[194:197], v[2:5]
	s_setprio 0
	s_add_i32 vcc_lo, vcc_lo, 2
	s_add_u32 s24, s24, 0x100
	s_addc_u32 s25, s25, 0
	s_add_u32 s90, s90, 0x100
	s_addc_u32 s94, s94, 0
	s_cmp_gt_u32 vcc_lo, 13
	s_barrier
	s_cbranch_scc0 .LBB0_1334
	v_lshl_add_u32 v152, s22, 8, v146
	v_lshl_add_u32 v150, s20, 8, v149
	v_mul_lo_u32 v151, v152, s71
	v_add_u32_e32 v0, v151, v150
	v_lshl_add_u64 v[142:143], v[0:1], 1, s[8:9]
	global_load_dwordx4 v[142:145], v[142:143], off
	v_mov_b32_e32 v178, v0
	v_mov_b32_e32 v161, 0
	v_add_u32_e32 v160, 0x80, v178
	v_lshl_add_u64 v[162:163], v[160:161], 1, s[8:9]
	global_load_dwordx4 v[162:165], v[162:163], off
	v_add_u32_e32 v160, 0x16c00, v178
	v_lshl_add_u64 v[166:167], v[160:161], 1, s[8:9]
	global_load_dwordx4 v[166:169], v[166:167], off
	v_add_u32_e32 v160, 0x16c80, v178
	v_lshl_add_u64 v[170:171], v[160:161], 1, s[8:9]
	global_load_dwordx4 v[170:173], v[170:171], off
	v_add_u32_e32 v160, 0x2d800, v178
	v_lshl_add_u64 v[174:175], v[160:161], 1, s[8:9]
	global_load_dwordx4 v[174:177], v[174:175], off
	v_add_u32_e32 v160, 0x2d880, v178
	v_lshl_add_u64 v[182:183], v[160:161], 1, s[8:9]
	global_load_dwordx4 v[182:185], v[182:183], off
	v_add_u32_e32 v160, 0x44400, v178
	v_lshl_add_u64 v[186:187], v[160:161], 1, s[8:9]
	global_load_dwordx4 v[186:189], v[186:187], off
	v_add_u32_e32 v160, 0x44480, v178
	v_lshl_add_u64 v[190:191], v[160:161], 1, s[8:9]
	global_load_dwordx4 v[190:193], v[190:191], off
	v_add_u32_e32 v160, 0xb6000, v178
	v_lshl_add_u64 v[194:195], v[160:161], 1, s[8:9]
	global_load_dwordx4 v[194:197], v[194:195], off
	v_add_u32_e32 v160, 0xb6080, v178
	v_lshl_add_u64 v[198:199], v[160:161], 1, s[8:9]
	global_load_dwordx4 v[198:201], v[198:199], off
	v_add_u32_e32 v160, 0xccc00, v178
	v_lshl_add_u64 v[202:203], v[160:161], 1, s[8:9]
	global_load_dwordx4 v[202:205], v[202:203], off
	v_add_u32_e32 v160, 0xccc80, v178
	v_lshl_add_u64 v[206:207], v[160:161], 1, s[8:9]
	global_load_dwordx4 v[206:209], v[206:207], off
	v_add_u32_e32 v160, 0xe3800, v178
	v_lshl_add_u64 v[210:211], v[160:161], 1, s[8:9]
	global_load_dwordx4 v[210:213], v[210:211], off
	s_mov_b32 s20, s12
	s_mov_b32 s22, s14
	s_mov_b64 s[26:27], s[18:19]
	s_waitcnt vmcnt(12)
	v_lshlrev_b32_e32 v153, 16, v142
	v_lshlrev_b32_e32 v155, 16, v143
	v_lshlrev_b32_e32 v156, 16, v144
	v_and_b32_e32 v157, 0xffff0000, v144
	v_lshlrev_b32_e32 v158, 16, v145
	v_and_b32_e32 v159, 0xffff0000, v145
	v_mul_f32_e32 v144, 0xbfb8aa3b, v153
	v_mul_f32_e32 v145, 0xbfb8aa3b, v155
	v_exp_f32_e32 v154, v144
	v_exp_f32_e32 v155, v145
	v_mul_f32_e32 v145, 0xbfb8aa3b, v158
	v_and_b32_e32 v142, 0xffff0000, v142
	v_and_b32_e32 v143, 0xffff0000, v143
	v_pk_add_f32 v[154:155], v[154:155], 1.0 op_sel_hi:[1,0]
	v_mul_f32_e32 v142, 0xbfb8aa3b, v142
	v_mul_f32_e32 v143, 0xbfb8aa3b, v143
	v_mul_f32_e32 v144, 0xbfb8aa3b, v156
	v_exp_f32_e32 v156, v142
	v_mul_f32_e32 v142, 0xbfb8aa3b, v157
	v_exp_f32_e32 v157, v143
	v_mul_f32_e32 v143, 0xbfb8aa3b, v159
	v_rcp_f32_e32 v155, v155
	s_nop 0
	v_pk_add_f32 v[156:157], v[156:157], 1.0 op_sel_hi:[1,0]
	v_exp_f32_e32 v144, v144
	v_exp_f32_e32 v145, v145
	v_mov_b32_e32 v158, v126
	v_mov_b32_e32 v159, v128
	v_rcp_f32_e32 v154, v154
	s_nop 0
	v_pk_mul_f32 v[154:155], v[158:159], v[154:155]
	v_exp_f32_e32 v142, v142
	v_rcp_f32_e32 v157, v157
	s_nop 0
	v_exp_f32_e32 v143, v143
	v_rcp_f32_e32 v156, v156
	s_nop 0
	v_mov_b32_e32 v128, v127
	v_pk_mul_f32 v[126:127], v[128:129], v[156:157]
	v_cvt_pk_bf16_f32 v128, v154, v155
	v_cvt_pk_bf16_f32 v126, v126, v127
	v_and_b32_e32 v127, 0xffff0000, v126
	v_lshlrev_b32_e32 v126, 16, v126
	v_or_b32_sdwa v127, v127, v128 dst_sel:DWORD dst_unused:UNUSED_PAD src0_sel:DWORD src1_sel:WORD_1
	v_or_b32_sdwa v126, v126, v128 dst_sel:DWORD dst_unused:UNUSED_PAD src0_sel:DWORD src1_sel:WORD_0
	v_pk_add_f32 v[128:129], v[144:145], 1.0 op_sel_hi:[1,0]
	v_pk_add_f32 v[142:143], v[142:143], 1.0 op_sel_hi:[1,0]
	s_nop 0
	v_rcp_f32_e32 v129, v129
	s_nop 0
	s_nop 0
	v_rcp_f32_e32 v128, v128
	s_nop 0
	v_mov_b32_e32 v144, v122
	v_mov_b32_e32 v145, v124
	v_pk_mul_f32 v[128:129], v[144:145], v[128:129]
	v_rcp_f32_e32 v143, v143
	s_nop 0
	s_nop 0
	v_rcp_f32_e32 v142, v142
	s_nop 0
	v_mov_b32_e32 v124, v123
	v_pk_mul_f32 v[122:123], v[124:125], v[142:143]
	v_cvt_pk_bf16_f32 v124, v128, v129
	v_cvt_pk_bf16_f32 v122, v122, v123
	v_and_b32_e32 v123, 0xffff0000, v122
	v_lshlrev_b32_e32 v122, 16, v122
	v_or_b32_sdwa v129, v123, v124 dst_sel:DWORD dst_unused:UNUSED_PAD src0_sel:DWORD src1_sel:WORD_1
	v_or_b32_sdwa v128, v122, v124 dst_sel:DWORD dst_unused:UNUSED_PAD src0_sel:DWORD src1_sel:WORD_0
	v_mul_lo_u32 v124, v152, s61
	v_add_u32_e32 v0, v0, v124
	v_add_u32_e32 v125, 0x80, v150
	v_lshl_add_u64 v[122:123], v[0:1], 1, s[6:7]
	v_add_u32_e32 v0, v151, v125
	global_store_dwordx4 v[122:123], v[126:129], off
	v_add_u32_e32 v0, v0, v124
	s_waitcnt vmcnt(12)
	v_lshlrev_b32_e32 v122, 16, v162
	v_lshlrev_b32_e32 v143, 16, v163
	v_and_b32_e32 v144, 0xffff0000, v163
	v_lshlrev_b32_e32 v127, 16, v164
	v_mul_f32_e32 v122, 0xbfb8aa3b, v122
	v_and_b32_e32 v123, 0xffff0000, v162
	v_exp_f32_e32 v126, v122
	v_mul_f32_e32 v122, 0xbfb8aa3b, v127
	v_and_b32_e32 v145, 0xffff0000, v164
	v_exp_f32_e32 v128, v122
	v_mul_f32_e32 v122, 0xbfb8aa3b, v123
	v_mul_f32_e32 v123, 0xbfb8aa3b, v143
	v_exp_f32_e32 v127, v123
	v_lshlrev_b32_e32 v153, 16, v165
	v_mul_f32_e32 v123, 0xbfb8aa3b, v153
	v_and_b32_e32 v154, 0xffff0000, v165
	v_pk_add_f32 v[126:127], v[126:127], 1.0 op_sel_hi:[1,0]
	v_exp_f32_e32 v129, v123
	v_mul_f32_e32 v123, 0xbfb8aa3b, v144
	v_exp_f32_e32 v142, v122
	v_mul_f32_e32 v122, 0xbfb8aa3b, v145
	v_exp_f32_e32 v143, v123
	v_mul_f32_e32 v123, 0xbfb8aa3b, v154
	v_exp_f32_e32 v122, v122
	v_rcp_f32_e32 v127, v127
	s_nop 0
	v_pk_add_f32 v[142:143], v[142:143], 1.0 op_sel_hi:[1,0]
	v_exp_f32_e32 v123, v123
	v_rcp_f32_e32 v126, v126
	s_nop 0
	v_mov_b32_e32 v144, v118
	v_mov_b32_e32 v145, v120
	v_pk_mul_f32 v[126:127], v[144:145], v[126:127]
	v_pk_add_f32 v[122:123], v[122:123], 1.0 op_sel_hi:[1,0]
	v_rcp_f32_e32 v143, v143
	s_nop 0
	s_nop 0
	v_rcp_f32_e32 v142, v142
	s_nop 0
	v_mov_b32_e32 v120, v119
	v_pk_mul_f32 v[118:119], v[120:121], v[142:143]
	v_cvt_pk_bf16_f32 v120, v126, v127
	v_cvt_pk_bf16_f32 v118, v118, v119
	v_and_b32_e32 v119, 0xffff0000, v118
	v_lshlrev_b32_e32 v118, 16, v118
	v_or_b32_sdwa v119, v119, v120 dst_sel:DWORD dst_unused:UNUSED_PAD src0_sel:DWORD src1_sel:WORD_1
	v_or_b32_sdwa v118, v118, v120 dst_sel:DWORD dst_unused:UNUSED_PAD src0_sel:DWORD src1_sel:WORD_0
	v_pk_add_f32 v[120:121], v[128:129], 1.0 op_sel_hi:[1,0]
	s_nop 0
	s_nop 0
	v_rcp_f32_e32 v121, v121
	s_nop 0
	s_nop 0
	v_rcp_f32_e32 v120, v120
	s_nop 0
	v_mov_b32_e32 v126, v114
	v_mov_b32_e32 v127, v116
	v_pk_mul_f32 v[120:121], v[126:127], v[120:121]
	v_rcp_f32_e32 v123, v123
	s_nop 0
	s_nop 0
	v_rcp_f32_e32 v122, v122
	s_nop 0
	v_mov_b32_e32 v116, v115
	v_pk_mul_f32 v[114:115], v[116:117], v[122:123]
	v_cvt_pk_bf16_f32 v116, v120, v121
	v_cvt_pk_bf16_f32 v114, v114, v115
	v_and_b32_e32 v115, 0xffff0000, v114
	v_lshlrev_b32_e32 v114, 16, v114
	v_add_u32_e32 v127, 0x16c00, v151
	v_or_b32_sdwa v121, v115, v116 dst_sel:DWORD dst_unused:UNUSED_PAD src0_sel:DWORD src1_sel:WORD_1
	v_or_b32_sdwa v120, v114, v116 dst_sel:DWORD dst_unused:UNUSED_PAD src0_sel:DWORD src1_sel:WORD_0
	v_lshl_add_u64 v[114:115], v[0:1], 1, s[6:7]
	v_add_u32_e32 v0, v127, v150
	v_add_u32_e32 v160, 0xe3880, v178
	v_lshl_add_u64 v[162:163], v[160:161], 1, s[8:9]
	global_load_dwordx4 v[162:165], v[162:163], off
	global_store_dwordx4 v[114:115], v[118:121], off
	v_or_b32_e32 v126, 16, v152
	s_waitcnt vmcnt(13)
	v_lshlrev_b32_e32 v121, 16, v167
	v_and_b32_e32 v122, 0xffff0000, v167
	v_lshlrev_b32_e32 v115, 16, v168
	v_and_b32_e32 v119, 0xffff0000, v166
	v_mul_f32_e32 v115, 0xbfb8aa3b, v115
	v_lshlrev_b32_e32 v118, 16, v166
	v_and_b32_e32 v120, 0xffff0000, v168
	v_exp_f32_e32 v116, v115
	v_mul_f32_e32 v115, 0xbfb8aa3b, v119
	v_mul_f32_e32 v114, 0xbfb8aa3b, v118
	v_exp_f32_e32 v118, v115
	v_mul_f32_e32 v115, 0xbfb8aa3b, v120
	v_exp_f32_e32 v120, v115
	v_mul_f32_e32 v115, 0xbfb8aa3b, v121
	v_exp_f32_e32 v114, v114
	v_exp_f32_e32 v115, v115
	v_lshlrev_b32_e32 v123, 16, v169
	v_mul_f32_e32 v119, 0xbfb8aa3b, v122
	v_and_b32_e32 v128, 0xffff0000, v169
	v_pk_add_f32 v[114:115], v[114:115], 1.0 op_sel_hi:[1,0]
	v_mul_f32_e32 v117, 0xbfb8aa3b, v123
	v_mul_f32_e32 v121, 0xbfb8aa3b, v128
	v_exp_f32_e32 v119, v119
	v_exp_f32_e32 v117, v117
	v_rcp_f32_e32 v115, v115
	s_nop 0
	v_pk_add_f32 v[118:119], v[118:119], 1.0 op_sel_hi:[1,0]
	v_exp_f32_e32 v121, v121
	v_rcp_f32_e32 v114, v114
	s_nop 0
	v_mov_b32_e32 v122, v110
	v_mov_b32_e32 v123, v112
	v_pk_mul_f32 v[114:115], v[122:123], v[114:115]
	v_rcp_f32_e32 v119, v119
	s_nop 0
	s_nop 0
	v_rcp_f32_e32 v118, v118
	s_nop 0
	v_mov_b32_e32 v112, v111
	v_pk_mul_f32 v[110:111], v[112:113], v[118:119]
	v_cvt_pk_bf16_f32 v112, v114, v115
	v_cvt_pk_bf16_f32 v110, v110, v111
	v_and_b32_e32 v111, 0xffff0000, v110
	v_lshlrev_b32_e32 v110, 16, v110
	v_or_b32_sdwa v111, v111, v112 dst_sel:DWORD dst_unused:UNUSED_PAD src0_sel:DWORD src1_sel:WORD_1
	v_or_b32_sdwa v110, v110, v112 dst_sel:DWORD dst_unused:UNUSED_PAD src0_sel:DWORD src1_sel:WORD_0
	v_pk_add_f32 v[112:113], v[116:117], 1.0 op_sel_hi:[1,0]
	s_nop 0
	s_nop 0
	v_rcp_f32_e32 v113, v113
	s_nop 0
	s_nop 0
	v_rcp_f32_e32 v112, v112
	s_nop 0
	v_mov_b32_e32 v114, v106
	v_mov_b32_e32 v115, v108
	v_pk_mul_f32 v[112:113], v[114:115], v[112:113]
	v_pk_add_f32 v[114:115], v[120:121], 1.0 op_sel_hi:[1,0]
	s_nop 0
	s_nop 0
	v_rcp_f32_e32 v115, v115
	s_nop 0
	s_nop 0
	v_rcp_f32_e32 v114, v114
	s_nop 0
	v_mov_b32_e32 v108, v107
	v_pk_mul_f32 v[106:107], v[108:109], v[114:115]
	v_mul_lo_u32 v116, v126, s61
	v_cvt_pk_bf16_f32 v106, v106, v107
	v_cvt_pk_bf16_f32 v108, v112, v113
	v_and_b32_e32 v107, 0xffff0000, v106
	v_lshlrev_b32_e32 v106, 16, v106
	v_add_u32_e32 v0, v0, v116
	v_or_b32_sdwa v113, v107, v108 dst_sel:DWORD dst_unused:UNUSED_PAD src0_sel:DWORD src1_sel:WORD_1
	v_or_b32_sdwa v112, v106, v108 dst_sel:DWORD dst_unused:UNUSED_PAD src0_sel:DWORD src1_sel:WORD_0
	v_lshl_add_u64 v[106:107], v[0:1], 1, s[6:7]
	v_add_u32_e32 v0, v127, v125
	v_add_u32_e32 v160, 0xfa400, v178
	v_lshl_add_u64 v[166:167], v[160:161], 1, s[8:9]
	global_load_dwordx4 v[166:169], v[166:167], off
	global_store_dwordx4 v[106:107], v[110:113], off
	v_add_u32_e32 v0, v0, v116
	s_waitcnt vmcnt(14)
	v_lshlrev_b32_e32 v113, 16, v171
	v_and_b32_e32 v114, 0xffff0000, v171
	v_lshlrev_b32_e32 v107, 16, v172
	v_and_b32_e32 v111, 0xffff0000, v170
	v_mul_f32_e32 v107, 0xbfb8aa3b, v107
	v_lshlrev_b32_e32 v110, 16, v170
	v_and_b32_e32 v112, 0xffff0000, v172
	v_exp_f32_e32 v108, v107
	v_mul_f32_e32 v107, 0xbfb8aa3b, v111
	v_mul_f32_e32 v106, 0xbfb8aa3b, v110
	v_exp_f32_e32 v110, v107
	v_mul_f32_e32 v107, 0xbfb8aa3b, v112
	v_exp_f32_e32 v112, v107
	v_mul_f32_e32 v107, 0xbfb8aa3b, v113
	v_exp_f32_e32 v106, v106
	v_exp_f32_e32 v107, v107
	v_lshlrev_b32_e32 v115, 16, v173
	v_mul_f32_e32 v111, 0xbfb8aa3b, v114
	v_and_b32_e32 v117, 0xffff0000, v173
	v_pk_add_f32 v[106:107], v[106:107], 1.0 op_sel_hi:[1,0]
	v_mul_f32_e32 v109, 0xbfb8aa3b, v115
	v_mul_f32_e32 v113, 0xbfb8aa3b, v117
	v_exp_f32_e32 v111, v111
	v_exp_f32_e32 v109, v109
	v_rcp_f32_e32 v107, v107
	s_nop 0
	v_pk_add_f32 v[110:111], v[110:111], 1.0 op_sel_hi:[1,0]
	v_exp_f32_e32 v113, v113
	v_rcp_f32_e32 v106, v106
	s_nop 0
	v_mov_b32_e32 v114, v102
	v_mov_b32_e32 v115, v104
	v_pk_mul_f32 v[106:107], v[114:115], v[106:107]
	v_rcp_f32_e32 v111, v111
	s_nop 0
	s_nop 0
	v_rcp_f32_e32 v110, v110
	s_nop 0
	v_mov_b32_e32 v104, v103
	v_pk_mul_f32 v[102:103], v[104:105], v[110:111]
	v_cvt_pk_bf16_f32 v104, v106, v107
	v_cvt_pk_bf16_f32 v102, v102, v103
	v_and_b32_e32 v103, 0xffff0000, v102
	v_lshlrev_b32_e32 v102, 16, v102
	v_or_b32_sdwa v103, v103, v104 dst_sel:DWORD dst_unused:UNUSED_PAD src0_sel:DWORD src1_sel:WORD_1
	v_or_b32_sdwa v102, v102, v104 dst_sel:DWORD dst_unused:UNUSED_PAD src0_sel:DWORD src1_sel:WORD_0
	v_pk_add_f32 v[104:105], v[108:109], 1.0 op_sel_hi:[1,0]
	s_nop 0
	s_nop 0
	v_rcp_f32_e32 v105, v105
	s_nop 0
	s_nop 0
	v_rcp_f32_e32 v104, v104
	s_nop 0
	v_mov_b32_e32 v106, v98
	v_mov_b32_e32 v107, v100
	v_pk_mul_f32 v[104:105], v[106:107], v[104:105]
	v_pk_add_f32 v[106:107], v[112:113], 1.0 op_sel_hi:[1,0]
	s_nop 0
	s_nop 0
	v_rcp_f32_e32 v107, v107
	s_nop 0
	s_nop 0
	v_rcp_f32_e32 v106, v106
	s_nop 0
	v_mov_b32_e32 v100, v99
	v_pk_mul_f32 v[98:99], v[100:101], v[106:107]
	v_cvt_pk_bf16_f32 v100, v104, v105
	v_cvt_pk_bf16_f32 v98, v98, v99
	v_and_b32_e32 v99, 0xffff0000, v98
	v_lshlrev_b32_e32 v98, 16, v98
	v_add_u32_e32 v109, 0x2d800, v151
	v_or_b32_sdwa v105, v99, v100 dst_sel:DWORD dst_unused:UNUSED_PAD src0_sel:DWORD src1_sel:WORD_1
	v_or_b32_sdwa v104, v98, v100 dst_sel:DWORD dst_unused:UNUSED_PAD src0_sel:DWORD src1_sel:WORD_0
	v_lshl_add_u64 v[98:99], v[0:1], 1, s[6:7]
	v_add_u32_e32 v0, v109, v150
	v_add_u32_e32 v160, 0xfa480, v178
	v_lshl_add_u64 v[170:171], v[160:161], 1, s[8:9]
	global_load_dwordx4 v[170:173], v[170:171], off
	global_store_dwordx4 v[98:99], v[102:105], off
	v_or_b32_e32 v108, 32, v152
	s_waitcnt vmcnt(15)
	v_lshlrev_b32_e32 v105, 16, v175
	v_and_b32_e32 v106, 0xffff0000, v175
	v_lshlrev_b32_e32 v99, 16, v176
	v_and_b32_e32 v103, 0xffff0000, v174
	v_mul_f32_e32 v99, 0xbfb8aa3b, v99
	v_lshlrev_b32_e32 v102, 16, v174
	v_and_b32_e32 v104, 0xffff0000, v176
	v_exp_f32_e32 v100, v99
	v_mul_f32_e32 v99, 0xbfb8aa3b, v103
	v_mul_f32_e32 v98, 0xbfb8aa3b, v102
	v_exp_f32_e32 v102, v99
	v_mul_f32_e32 v99, 0xbfb8aa3b, v104
	v_exp_f32_e32 v104, v99
	v_mul_f32_e32 v99, 0xbfb8aa3b, v105
	v_exp_f32_e32 v98, v98
	v_exp_f32_e32 v99, v99
	v_lshlrev_b32_e32 v107, 16, v177
	v_mul_f32_e32 v103, 0xbfb8aa3b, v106
	v_and_b32_e32 v110, 0xffff0000, v177
	v_pk_add_f32 v[98:99], v[98:99], 1.0 op_sel_hi:[1,0]
	v_mul_f32_e32 v101, 0xbfb8aa3b, v107
	v_mul_f32_e32 v105, 0xbfb8aa3b, v110
	v_exp_f32_e32 v103, v103
	v_exp_f32_e32 v101, v101
	v_rcp_f32_e32 v99, v99
	s_nop 0
	v_pk_add_f32 v[102:103], v[102:103], 1.0 op_sel_hi:[1,0]
	v_exp_f32_e32 v105, v105
	v_rcp_f32_e32 v98, v98
	s_nop 0
	v_mov_b32_e32 v106, v94
	v_mov_b32_e32 v107, v96
	v_pk_mul_f32 v[98:99], v[106:107], v[98:99]
	v_rcp_f32_e32 v103, v103
	s_nop 0
	s_nop 0
	v_rcp_f32_e32 v102, v102
	s_nop 0
	v_mov_b32_e32 v96, v95
	v_pk_mul_f32 v[94:95], v[96:97], v[102:103]
	v_cvt_pk_bf16_f32 v96, v98, v99
	v_cvt_pk_bf16_f32 v94, v94, v95
	v_and_b32_e32 v95, 0xffff0000, v94
	v_lshlrev_b32_e32 v94, 16, v94
	v_or_b32_sdwa v95, v95, v96 dst_sel:DWORD dst_unused:UNUSED_PAD src0_sel:DWORD src1_sel:WORD_1
	v_or_b32_sdwa v94, v94, v96 dst_sel:DWORD dst_unused:UNUSED_PAD src0_sel:DWORD src1_sel:WORD_0
	v_pk_add_f32 v[96:97], v[100:101], 1.0 op_sel_hi:[1,0]
	s_nop 0
	s_nop 0
	v_rcp_f32_e32 v97, v97
	s_nop 0
	s_nop 0
	v_rcp_f32_e32 v96, v96
	s_nop 0
	v_mov_b32_e32 v98, v90
	v_mov_b32_e32 v99, v92
	v_pk_mul_f32 v[96:97], v[98:99], v[96:97]
	v_pk_add_f32 v[98:99], v[104:105], 1.0 op_sel_hi:[1,0]
	s_nop 0
	s_nop 0
	v_rcp_f32_e32 v99, v99
	s_nop 0
	s_nop 0
	v_rcp_f32_e32 v98, v98
	s_nop 0
	v_mov_b32_e32 v92, v91
	v_pk_mul_f32 v[90:91], v[92:93], v[98:99]
	v_mul_lo_u32 v100, v108, s61
	v_cvt_pk_bf16_f32 v90, v90, v91
	v_cvt_pk_bf16_f32 v92, v96, v97
	v_and_b32_e32 v91, 0xffff0000, v90
	v_lshlrev_b32_e32 v90, 16, v90
	v_add_u32_e32 v0, v0, v100
	v_or_b32_sdwa v97, v91, v92 dst_sel:DWORD dst_unused:UNUSED_PAD src0_sel:DWORD src1_sel:WORD_1
	v_or_b32_sdwa v96, v90, v92 dst_sel:DWORD dst_unused:UNUSED_PAD src0_sel:DWORD src1_sel:WORD_0
	v_lshl_add_u64 v[90:91], v[0:1], 1, s[6:7]
	v_add_u32_e32 v0, v109, v125
	global_store_dwordx4 v[90:91], v[94:97], off
	v_add_u32_e32 v0, v0, v100
	s_waitcnt vmcnt(15)
	v_lshlrev_b32_e32 v97, 16, v183
	v_and_b32_e32 v98, 0xffff0000, v183
	v_lshlrev_b32_e32 v91, 16, v184
	v_and_b32_e32 v95, 0xffff0000, v182
	v_mul_f32_e32 v91, 0xbfb8aa3b, v91
	v_lshlrev_b32_e32 v94, 16, v182
	v_and_b32_e32 v96, 0xffff0000, v184
	v_exp_f32_e32 v92, v91
	v_mul_f32_e32 v91, 0xbfb8aa3b, v95
	v_mul_f32_e32 v90, 0xbfb8aa3b, v94
	v_exp_f32_e32 v94, v91
	v_mul_f32_e32 v91, 0xbfb8aa3b, v96
	v_exp_f32_e32 v96, v91
	v_mul_f32_e32 v91, 0xbfb8aa3b, v97
	v_exp_f32_e32 v90, v90
	v_exp_f32_e32 v91, v91
	v_lshlrev_b32_e32 v99, 16, v185
	v_mul_f32_e32 v95, 0xbfb8aa3b, v98
	v_and_b32_e32 v101, 0xffff0000, v185
	v_pk_add_f32 v[90:91], v[90:91], 1.0 op_sel_hi:[1,0]
	v_mul_f32_e32 v93, 0xbfb8aa3b, v99
	v_mul_f32_e32 v97, 0xbfb8aa3b, v101
	v_exp_f32_e32 v95, v95
	v_exp_f32_e32 v93, v93
	v_rcp_f32_e32 v91, v91
	s_nop 0
	v_pk_add_f32 v[94:95], v[94:95], 1.0 op_sel_hi:[1,0]
	v_exp_f32_e32 v97, v97
	v_rcp_f32_e32 v90, v90
	s_nop 0
	v_mov_b32_e32 v98, v86
	v_mov_b32_e32 v99, v88
	v_pk_mul_f32 v[90:91], v[98:99], v[90:91]
	v_rcp_f32_e32 v95, v95
	s_nop 0
	s_nop 0
	v_rcp_f32_e32 v94, v94
	s_nop 0
	v_mov_b32_e32 v88, v87
	v_pk_mul_f32 v[86:87], v[88:89], v[94:95]
	v_cvt_pk_bf16_f32 v88, v90, v91
	v_cvt_pk_bf16_f32 v86, v86, v87
	v_and_b32_e32 v87, 0xffff0000, v86
	v_lshlrev_b32_e32 v86, 16, v86
	v_or_b32_sdwa v87, v87, v88 dst_sel:DWORD dst_unused:UNUSED_PAD src0_sel:DWORD src1_sel:WORD_1
	v_or_b32_sdwa v86, v86, v88 dst_sel:DWORD dst_unused:UNUSED_PAD src0_sel:DWORD src1_sel:WORD_0
	v_pk_add_f32 v[88:89], v[92:93], 1.0 op_sel_hi:[1,0]
	s_nop 0
	s_nop 0
	v_rcp_f32_e32 v89, v89
	s_nop 0
	s_nop 0
	v_rcp_f32_e32 v88, v88
	s_nop 0
	v_mov_b32_e32 v90, v82
	v_mov_b32_e32 v91, v84
	v_pk_mul_f32 v[88:89], v[90:91], v[88:89]
	v_pk_add_f32 v[90:91], v[96:97], 1.0 op_sel_hi:[1,0]
	s_nop 0
	s_nop 0
	v_rcp_f32_e32 v91, v91
	s_nop 0
	s_nop 0
	v_rcp_f32_e32 v90, v90
	s_nop 0
	v_mov_b32_e32 v84, v83
	v_pk_mul_f32 v[82:83], v[84:85], v[90:91]
	v_cvt_pk_bf16_f32 v84, v88, v89
	v_cvt_pk_bf16_f32 v82, v82, v83
	v_and_b32_e32 v83, 0xffff0000, v82
	v_lshlrev_b32_e32 v82, 16, v82
	v_add_u32_e32 v93, 0x44400, v151
	v_or_b32_sdwa v89, v83, v84 dst_sel:DWORD dst_unused:UNUSED_PAD src0_sel:DWORD src1_sel:WORD_1
	v_or_b32_sdwa v88, v82, v84 dst_sel:DWORD dst_unused:UNUSED_PAD src0_sel:DWORD src1_sel:WORD_0
	v_lshl_add_u64 v[82:83], v[0:1], 1, s[6:7]
	v_add_u32_e32 v0, v93, v150
	global_store_dwordx4 v[82:83], v[86:89], off
	v_or_b32_e32 v92, 48, v152
	s_waitcnt vmcnt(15)
	v_lshlrev_b32_e32 v89, 16, v187
	v_and_b32_e32 v90, 0xffff0000, v187
	v_lshlrev_b32_e32 v83, 16, v188
	v_and_b32_e32 v87, 0xffff0000, v186
	v_mul_f32_e32 v83, 0xbfb8aa3b, v83
	v_lshlrev_b32_e32 v86, 16, v186
	v_and_b32_e32 v88, 0xffff0000, v188
	v_exp_f32_e32 v84, v83
	v_mul_f32_e32 v83, 0xbfb8aa3b, v87
	v_mul_f32_e32 v82, 0xbfb8aa3b, v86
	v_exp_f32_e32 v86, v83
	v_mul_f32_e32 v83, 0xbfb8aa3b, v88
	v_exp_f32_e32 v88, v83
	v_mul_f32_e32 v83, 0xbfb8aa3b, v89
	v_exp_f32_e32 v82, v82
	v_exp_f32_e32 v83, v83
	v_lshlrev_b32_e32 v91, 16, v189
	v_mul_f32_e32 v87, 0xbfb8aa3b, v90
	v_and_b32_e32 v94, 0xffff0000, v189
	v_pk_add_f32 v[82:83], v[82:83], 1.0 op_sel_hi:[1,0]
	v_mul_f32_e32 v85, 0xbfb8aa3b, v91
	v_mul_f32_e32 v89, 0xbfb8aa3b, v94
	v_exp_f32_e32 v87, v87
	v_exp_f32_e32 v85, v85
	v_rcp_f32_e32 v83, v83
	s_nop 0
	v_pk_add_f32 v[86:87], v[86:87], 1.0 op_sel_hi:[1,0]
	v_exp_f32_e32 v89, v89
	v_rcp_f32_e32 v82, v82
	s_nop 0
	v_mov_b32_e32 v90, v78
	v_mov_b32_e32 v91, v80
	v_pk_mul_f32 v[82:83], v[90:91], v[82:83]
	v_rcp_f32_e32 v87, v87
	s_nop 0
	s_nop 0
	v_rcp_f32_e32 v86, v86
	s_nop 0
	v_mov_b32_e32 v80, v79
	v_pk_mul_f32 v[78:79], v[80:81], v[86:87]
	v_cvt_pk_bf16_f32 v80, v82, v83
	v_cvt_pk_bf16_f32 v78, v78, v79
	v_and_b32_e32 v79, 0xffff0000, v78
	v_lshlrev_b32_e32 v78, 16, v78
	v_or_b32_sdwa v79, v79, v80 dst_sel:DWORD dst_unused:UNUSED_PAD src0_sel:DWORD src1_sel:WORD_1
	v_or_b32_sdwa v78, v78, v80 dst_sel:DWORD dst_unused:UNUSED_PAD src0_sel:DWORD src1_sel:WORD_0
	v_pk_add_f32 v[80:81], v[84:85], 1.0 op_sel_hi:[1,0]
	s_nop 0
	s_nop 0
	v_rcp_f32_e32 v81, v81
	s_nop 0
	s_nop 0
	v_rcp_f32_e32 v80, v80
	s_nop 0
	v_mov_b32_e32 v82, v74
	v_mov_b32_e32 v83, v76
	v_pk_mul_f32 v[80:81], v[82:83], v[80:81]
	v_pk_add_f32 v[82:83], v[88:89], 1.0 op_sel_hi:[1,0]
	s_nop 0
	s_nop 0
	v_rcp_f32_e32 v83, v83
	s_nop 0
	s_nop 0
	v_rcp_f32_e32 v82, v82
	s_nop 0
	v_mov_b32_e32 v76, v75
	v_pk_mul_f32 v[74:75], v[76:77], v[82:83]
	v_mul_lo_u32 v84, v92, s61
	v_cvt_pk_bf16_f32 v74, v74, v75
	v_cvt_pk_bf16_f32 v76, v80, v81
	v_and_b32_e32 v75, 0xffff0000, v74
	v_lshlrev_b32_e32 v74, 16, v74
	v_add_u32_e32 v0, v0, v84
	v_or_b32_sdwa v81, v75, v76 dst_sel:DWORD dst_unused:UNUSED_PAD src0_sel:DWORD src1_sel:WORD_1
	v_or_b32_sdwa v80, v74, v76 dst_sel:DWORD dst_unused:UNUSED_PAD src0_sel:DWORD src1_sel:WORD_0
	v_lshl_add_u64 v[74:75], v[0:1], 1, s[6:7]
	v_add_u32_e32 v0, v93, v125
	global_store_dwordx4 v[74:75], v[78:81], off
	v_add_u32_e32 v0, v0, v84
	s_waitcnt vmcnt(15)
	v_lshlrev_b32_e32 v81, 16, v191
	v_and_b32_e32 v82, 0xffff0000, v191
	v_lshlrev_b32_e32 v75, 16, v192
	v_and_b32_e32 v79, 0xffff0000, v190
	v_mul_f32_e32 v75, 0xbfb8aa3b, v75
	v_lshlrev_b32_e32 v78, 16, v190
	v_and_b32_e32 v80, 0xffff0000, v192
	v_exp_f32_e32 v76, v75
	v_mul_f32_e32 v75, 0xbfb8aa3b, v79
	v_mul_f32_e32 v74, 0xbfb8aa3b, v78
	v_exp_f32_e32 v78, v75
	v_mul_f32_e32 v75, 0xbfb8aa3b, v80
	v_exp_f32_e32 v80, v75
	v_mul_f32_e32 v75, 0xbfb8aa3b, v81
	v_exp_f32_e32 v74, v74
	v_exp_f32_e32 v75, v75
	v_lshlrev_b32_e32 v83, 16, v193
	v_mul_f32_e32 v79, 0xbfb8aa3b, v82
	v_and_b32_e32 v85, 0xffff0000, v193
	v_pk_add_f32 v[74:75], v[74:75], 1.0 op_sel_hi:[1,0]
	v_mul_f32_e32 v77, 0xbfb8aa3b, v83
	v_mul_f32_e32 v81, 0xbfb8aa3b, v85
	v_exp_f32_e32 v79, v79
	v_exp_f32_e32 v77, v77
	v_rcp_f32_e32 v75, v75
	s_nop 0
	v_pk_add_f32 v[78:79], v[78:79], 1.0 op_sel_hi:[1,0]
	v_exp_f32_e32 v81, v81
	v_rcp_f32_e32 v74, v74
	s_nop 0
	v_mov_b32_e32 v82, v70
	v_mov_b32_e32 v83, v72
	v_pk_mul_f32 v[74:75], v[82:83], v[74:75]
	v_rcp_f32_e32 v79, v79
	s_nop 0
	s_nop 0
	v_rcp_f32_e32 v78, v78
	s_nop 0
	v_mov_b32_e32 v72, v71
	v_pk_mul_f32 v[70:71], v[72:73], v[78:79]
	v_cvt_pk_bf16_f32 v72, v74, v75
	v_cvt_pk_bf16_f32 v70, v70, v71
	v_and_b32_e32 v71, 0xffff0000, v70
	v_lshlrev_b32_e32 v70, 16, v70
	v_or_b32_sdwa v71, v71, v72 dst_sel:DWORD dst_unused:UNUSED_PAD src0_sel:DWORD src1_sel:WORD_1
	v_or_b32_sdwa v70, v70, v72 dst_sel:DWORD dst_unused:UNUSED_PAD src0_sel:DWORD src1_sel:WORD_0
	v_pk_add_f32 v[72:73], v[76:77], 1.0 op_sel_hi:[1,0]
	s_nop 0
	s_nop 0
	v_rcp_f32_e32 v73, v73
	s_nop 0
	s_nop 0
	v_rcp_f32_e32 v72, v72
	s_nop 0
	v_mov_b32_e32 v74, v66
	v_mov_b32_e32 v75, v68
	v_pk_mul_f32 v[72:73], v[74:75], v[72:73]
	v_pk_add_f32 v[74:75], v[80:81], 1.0 op_sel_hi:[1,0]
	s_nop 0
	s_nop 0
	v_rcp_f32_e32 v75, v75
	s_nop 0
	s_nop 0
	v_rcp_f32_e32 v74, v74
	s_nop 0
	v_mov_b32_e32 v68, v67
	v_pk_mul_f32 v[66:67], v[68:69], v[74:75]
	v_cvt_pk_bf16_f32 v68, v72, v73
	v_cvt_pk_bf16_f32 v66, v66, v67
	v_and_b32_e32 v67, 0xffff0000, v66
	v_lshlrev_b32_e32 v66, 16, v66
	v_add_u32_e32 v76, 0xb6000, v151
	v_or_b32_sdwa v73, v67, v68 dst_sel:DWORD dst_unused:UNUSED_PAD src0_sel:DWORD src1_sel:WORD_1
	v_or_b32_sdwa v72, v66, v68 dst_sel:DWORD dst_unused:UNUSED_PAD src0_sel:DWORD src1_sel:WORD_0
	v_lshl_add_u64 v[66:67], v[0:1], 1, s[6:7]
	v_add_u32_e32 v0, v76, v150
	global_store_dwordx4 v[66:67], v[70:73], off
	s_nop 1
	s_waitcnt vmcnt(15)
	v_lshlrev_b32_e32 v73, 16, v195
	v_and_b32_e32 v74, 0xffff0000, v195
	v_lshlrev_b32_e32 v67, 16, v196
	v_and_b32_e32 v71, 0xffff0000, v194
	v_mul_f32_e32 v67, 0xbfb8aa3b, v67
	v_lshlrev_b32_e32 v70, 16, v194
	v_and_b32_e32 v72, 0xffff0000, v196
	v_exp_f32_e32 v68, v67
	v_mul_f32_e32 v67, 0xbfb8aa3b, v71
	v_mul_f32_e32 v66, 0xbfb8aa3b, v70
	v_exp_f32_e32 v70, v67
	v_mul_f32_e32 v67, 0xbfb8aa3b, v72
	v_exp_f32_e32 v72, v67
	v_mul_f32_e32 v67, 0xbfb8aa3b, v73
	v_exp_f32_e32 v66, v66
	v_exp_f32_e32 v67, v67
	v_lshlrev_b32_e32 v75, 16, v197
	v_mul_f32_e32 v71, 0xbfb8aa3b, v74
	v_and_b32_e32 v77, 0xffff0000, v197
	v_pk_add_f32 v[66:67], v[66:67], 1.0 op_sel_hi:[1,0]
	v_mul_f32_e32 v69, 0xbfb8aa3b, v75
	v_mul_f32_e32 v73, 0xbfb8aa3b, v77
	v_exp_f32_e32 v71, v71
	v_exp_f32_e32 v69, v69
	v_rcp_f32_e32 v67, v67
	s_nop 0
	v_pk_add_f32 v[70:71], v[70:71], 1.0 op_sel_hi:[1,0]
	v_exp_f32_e32 v73, v73
	v_rcp_f32_e32 v66, v66
	s_nop 0
	v_mov_b32_e32 v74, v62
	v_mov_b32_e32 v75, v64
	v_pk_mul_f32 v[66:67], v[74:75], v[66:67]
	v_rcp_f32_e32 v71, v71
	s_nop 0
	s_nop 0
	v_rcp_f32_e32 v70, v70
	s_nop 0
	v_mov_b32_e32 v64, v63
	v_pk_mul_f32 v[62:63], v[64:65], v[70:71]
	v_cvt_pk_bf16_f32 v64, v66, v67
	v_cvt_pk_bf16_f32 v62, v62, v63
	v_and_b32_e32 v63, 0xffff0000, v62
	v_lshlrev_b32_e32 v62, 16, v62
	v_or_b32_sdwa v63, v63, v64 dst_sel:DWORD dst_unused:UNUSED_PAD src0_sel:DWORD src1_sel:WORD_1
	v_or_b32_sdwa v62, v62, v64 dst_sel:DWORD dst_unused:UNUSED_PAD src0_sel:DWORD src1_sel:WORD_0
	v_pk_add_f32 v[64:65], v[68:69], 1.0 op_sel_hi:[1,0]
	s_nop 0
	s_nop 0
	v_rcp_f32_e32 v65, v65
	s_nop 0
	s_nop 0
	v_rcp_f32_e32 v64, v64
	s_nop 0
	v_mov_b32_e32 v66, v58
	v_mov_b32_e32 v67, v60
	v_pk_mul_f32 v[64:65], v[66:67], v[64:65]
	v_pk_add_f32 v[66:67], v[72:73], 1.0 op_sel_hi:[1,0]
	s_nop 0
	s_nop 0
	v_rcp_f32_e32 v67, v67
	s_nop 0
	s_nop 0
	v_rcp_f32_e32 v66, v66
	s_nop 0
	v_mov_b32_e32 v60, v59
	v_pk_mul_f32 v[58:59], v[60:61], v[66:67]
	v_add_u32_e32 v68, 0xfff6a000, v124
	v_cvt_pk_bf16_f32 v58, v58, v59
	v_cvt_pk_bf16_f32 v60, v64, v65
	v_and_b32_e32 v59, 0xffff0000, v58
	v_lshlrev_b32_e32 v58, 16, v58
	v_add_u32_e32 v0, v0, v68
	v_or_b32_sdwa v65, v59, v60 dst_sel:DWORD dst_unused:UNUSED_PAD src0_sel:DWORD src1_sel:WORD_1
	v_or_b32_sdwa v64, v58, v60 dst_sel:DWORD dst_unused:UNUSED_PAD src0_sel:DWORD src1_sel:WORD_0
	v_lshl_add_u64 v[58:59], v[0:1], 1, s[6:7]
	v_add_u32_e32 v0, v76, v125
	global_store_dwordx4 v[58:59], v[62:65], off
	v_add_u32_e32 v0, v0, v68
	s_waitcnt vmcnt(15)
	v_lshlrev_b32_e32 v65, 16, v199
	v_and_b32_e32 v66, 0xffff0000, v199
	v_lshlrev_b32_e32 v59, 16, v200
	v_and_b32_e32 v63, 0xffff0000, v198
	v_mul_f32_e32 v59, 0xbfb8aa3b, v59
	v_lshlrev_b32_e32 v62, 16, v198
	v_and_b32_e32 v64, 0xffff0000, v200
	v_exp_f32_e32 v60, v59
	v_mul_f32_e32 v59, 0xbfb8aa3b, v63
	v_mul_f32_e32 v58, 0xbfb8aa3b, v62
	v_exp_f32_e32 v62, v59
	v_mul_f32_e32 v59, 0xbfb8aa3b, v64
	v_exp_f32_e32 v64, v59
	v_mul_f32_e32 v59, 0xbfb8aa3b, v65
	v_exp_f32_e32 v58, v58
	v_exp_f32_e32 v59, v59
	v_lshlrev_b32_e32 v67, 16, v201
	v_mul_f32_e32 v63, 0xbfb8aa3b, v66
	v_and_b32_e32 v69, 0xffff0000, v201
	v_pk_add_f32 v[58:59], v[58:59], 1.0 op_sel_hi:[1,0]
	v_mul_f32_e32 v61, 0xbfb8aa3b, v67
	v_mul_f32_e32 v65, 0xbfb8aa3b, v69
	v_exp_f32_e32 v63, v63
	v_exp_f32_e32 v61, v61
	v_rcp_f32_e32 v59, v59
	s_nop 0
	v_pk_add_f32 v[62:63], v[62:63], 1.0 op_sel_hi:[1,0]
	v_exp_f32_e32 v65, v65
	v_rcp_f32_e32 v58, v58
	s_nop 0
	v_mov_b32_e32 v66, v54
	v_mov_b32_e32 v67, v56
	v_pk_mul_f32 v[58:59], v[66:67], v[58:59]
	v_rcp_f32_e32 v63, v63
	s_nop 0
	s_nop 0
	v_rcp_f32_e32 v62, v62
	s_nop 0
	v_mov_b32_e32 v56, v55
	v_pk_mul_f32 v[54:55], v[56:57], v[62:63]
	v_cvt_pk_bf16_f32 v56, v58, v59
	v_cvt_pk_bf16_f32 v54, v54, v55
	v_and_b32_e32 v55, 0xffff0000, v54
	v_lshlrev_b32_e32 v54, 16, v54
	v_or_b32_sdwa v55, v55, v56 dst_sel:DWORD dst_unused:UNUSED_PAD src0_sel:DWORD src1_sel:WORD_1
	v_or_b32_sdwa v54, v54, v56 dst_sel:DWORD dst_unused:UNUSED_PAD src0_sel:DWORD src1_sel:WORD_0
	v_pk_add_f32 v[56:57], v[60:61], 1.0 op_sel_hi:[1,0]
	s_nop 0
	s_nop 0
	v_rcp_f32_e32 v57, v57
	s_nop 0
	s_nop 0
	v_rcp_f32_e32 v56, v56
	s_nop 0
	v_mov_b32_e32 v58, v50
	v_mov_b32_e32 v59, v52
	v_pk_mul_f32 v[56:57], v[58:59], v[56:57]
	v_pk_add_f32 v[58:59], v[64:65], 1.0 op_sel_hi:[1,0]
	s_nop 0
	s_nop 0
	v_rcp_f32_e32 v59, v59
	s_nop 0
	s_nop 0
	v_rcp_f32_e32 v58, v58
	s_nop 0
	v_mov_b32_e32 v52, v51
	v_pk_mul_f32 v[50:51], v[52:53], v[58:59]
	v_cvt_pk_bf16_f32 v52, v56, v57
	v_cvt_pk_bf16_f32 v50, v50, v51
	v_and_b32_e32 v51, 0xffff0000, v50
	v_lshlrev_b32_e32 v50, 16, v50
	v_add_u32_e32 v60, 0xccc00, v151
	v_or_b32_sdwa v57, v51, v52 dst_sel:DWORD dst_unused:UNUSED_PAD src0_sel:DWORD src1_sel:WORD_1
	v_or_b32_sdwa v56, v50, v52 dst_sel:DWORD dst_unused:UNUSED_PAD src0_sel:DWORD src1_sel:WORD_0
	v_lshl_add_u64 v[50:51], v[0:1], 1, s[6:7]
	v_add_u32_e32 v0, v60, v150
	global_store_dwordx4 v[50:51], v[54:57], off
	s_nop 1
	s_waitcnt vmcnt(15)
	v_lshlrev_b32_e32 v57, 16, v203
	v_and_b32_e32 v58, 0xffff0000, v203
	v_lshlrev_b32_e32 v51, 16, v204
	v_and_b32_e32 v55, 0xffff0000, v202
	v_mul_f32_e32 v51, 0xbfb8aa3b, v51
	v_lshlrev_b32_e32 v54, 16, v202
	v_and_b32_e32 v56, 0xffff0000, v204
	v_exp_f32_e32 v52, v51
	v_mul_f32_e32 v51, 0xbfb8aa3b, v55
	v_mul_f32_e32 v50, 0xbfb8aa3b, v54
	v_exp_f32_e32 v54, v51
	v_mul_f32_e32 v51, 0xbfb8aa3b, v56
	v_exp_f32_e32 v56, v51
	v_mul_f32_e32 v51, 0xbfb8aa3b, v57
	v_exp_f32_e32 v50, v50
	v_exp_f32_e32 v51, v51
	v_lshlrev_b32_e32 v59, 16, v205
	v_mul_f32_e32 v55, 0xbfb8aa3b, v58
	v_and_b32_e32 v61, 0xffff0000, v205
	v_pk_add_f32 v[50:51], v[50:51], 1.0 op_sel_hi:[1,0]
	v_mul_f32_e32 v53, 0xbfb8aa3b, v59
	v_mul_f32_e32 v57, 0xbfb8aa3b, v61
	v_exp_f32_e32 v55, v55
	v_exp_f32_e32 v53, v53
	v_rcp_f32_e32 v51, v51
	s_nop 0
	v_pk_add_f32 v[54:55], v[54:55], 1.0 op_sel_hi:[1,0]
	v_exp_f32_e32 v57, v57
	v_rcp_f32_e32 v50, v50
	s_nop 0
	v_mov_b32_e32 v58, v46
	v_mov_b32_e32 v59, v48
	v_pk_mul_f32 v[50:51], v[58:59], v[50:51]
	v_rcp_f32_e32 v55, v55
	s_nop 0
	s_nop 0
	v_rcp_f32_e32 v54, v54
	s_nop 0
	v_mov_b32_e32 v48, v47
	v_pk_mul_f32 v[46:47], v[48:49], v[54:55]
	v_cvt_pk_bf16_f32 v48, v50, v51
	v_cvt_pk_bf16_f32 v46, v46, v47
	v_and_b32_e32 v47, 0xffff0000, v46
	v_lshlrev_b32_e32 v46, 16, v46
	v_or_b32_sdwa v47, v47, v48 dst_sel:DWORD dst_unused:UNUSED_PAD src0_sel:DWORD src1_sel:WORD_1
	v_or_b32_sdwa v46, v46, v48 dst_sel:DWORD dst_unused:UNUSED_PAD src0_sel:DWORD src1_sel:WORD_0
	v_pk_add_f32 v[48:49], v[52:53], 1.0 op_sel_hi:[1,0]
	s_nop 0
	s_nop 0
	v_rcp_f32_e32 v49, v49
	s_nop 0
	s_nop 0
	v_rcp_f32_e32 v48, v48
	s_nop 0
	v_mov_b32_e32 v50, v42
	v_mov_b32_e32 v51, v44
	v_pk_mul_f32 v[48:49], v[50:51], v[48:49]
	v_pk_add_f32 v[50:51], v[56:57], 1.0 op_sel_hi:[1,0]
	s_nop 0
	s_nop 0
	v_rcp_f32_e32 v51, v51
	s_nop 0
	s_nop 0
	v_rcp_f32_e32 v50, v50
	s_nop 0
	v_mov_b32_e32 v44, v43
	v_pk_mul_f32 v[42:43], v[44:45], v[50:51]
	v_add_u32_e32 v52, 0xfff57400, v124
	v_cvt_pk_bf16_f32 v42, v42, v43
	v_cvt_pk_bf16_f32 v44, v48, v49
	v_and_b32_e32 v43, 0xffff0000, v42
	v_lshlrev_b32_e32 v42, 16, v42
	v_add_u32_e32 v0, v0, v52
	v_or_b32_sdwa v49, v43, v44 dst_sel:DWORD dst_unused:UNUSED_PAD src0_sel:DWORD src1_sel:WORD_1
	v_or_b32_sdwa v48, v42, v44 dst_sel:DWORD dst_unused:UNUSED_PAD src0_sel:DWORD src1_sel:WORD_0
	v_lshl_add_u64 v[42:43], v[0:1], 1, s[6:7]
	v_add_u32_e32 v0, v60, v125
	global_store_dwordx4 v[42:43], v[46:49], off
	v_add_u32_e32 v0, v0, v52
	s_waitcnt vmcnt(15)
	v_lshlrev_b32_e32 v49, 16, v207
	v_and_b32_e32 v50, 0xffff0000, v207
	v_lshlrev_b32_e32 v43, 16, v208
	v_and_b32_e32 v47, 0xffff0000, v206
	v_mul_f32_e32 v43, 0xbfb8aa3b, v43
	v_lshlrev_b32_e32 v46, 16, v206
	v_and_b32_e32 v48, 0xffff0000, v208
	v_exp_f32_e32 v44, v43
	v_mul_f32_e32 v43, 0xbfb8aa3b, v47
	v_mul_f32_e32 v42, 0xbfb8aa3b, v46
	v_exp_f32_e32 v46, v43
	v_mul_f32_e32 v43, 0xbfb8aa3b, v48
	v_exp_f32_e32 v48, v43
	v_mul_f32_e32 v43, 0xbfb8aa3b, v49
	v_exp_f32_e32 v42, v42
	v_exp_f32_e32 v43, v43
	v_lshlrev_b32_e32 v51, 16, v209
	v_mul_f32_e32 v47, 0xbfb8aa3b, v50
	v_and_b32_e32 v53, 0xffff0000, v209
	v_pk_add_f32 v[42:43], v[42:43], 1.0 op_sel_hi:[1,0]
	v_mul_f32_e32 v45, 0xbfb8aa3b, v51
	v_mul_f32_e32 v49, 0xbfb8aa3b, v53
	v_exp_f32_e32 v47, v47
	v_exp_f32_e32 v45, v45
	v_rcp_f32_e32 v43, v43
	s_nop 0
	v_pk_add_f32 v[46:47], v[46:47], 1.0 op_sel_hi:[1,0]
	v_exp_f32_e32 v49, v49
	v_rcp_f32_e32 v42, v42
	s_nop 0
	v_mov_b32_e32 v50, v38
	v_mov_b32_e32 v51, v40
	v_pk_mul_f32 v[42:43], v[50:51], v[42:43]
	v_rcp_f32_e32 v47, v47
	s_nop 0
	s_nop 0
	v_rcp_f32_e32 v46, v46
	s_nop 0
	v_mov_b32_e32 v40, v39
	v_pk_mul_f32 v[38:39], v[40:41], v[46:47]
	v_cvt_pk_bf16_f32 v40, v42, v43
	v_cvt_pk_bf16_f32 v38, v38, v39
	v_and_b32_e32 v39, 0xffff0000, v38
	v_lshlrev_b32_e32 v38, 16, v38
	v_or_b32_sdwa v39, v39, v40 dst_sel:DWORD dst_unused:UNUSED_PAD src0_sel:DWORD src1_sel:WORD_1
	v_or_b32_sdwa v38, v38, v40 dst_sel:DWORD dst_unused:UNUSED_PAD src0_sel:DWORD src1_sel:WORD_0
	v_pk_add_f32 v[40:41], v[44:45], 1.0 op_sel_hi:[1,0]
	s_nop 0
	s_nop 0
	v_rcp_f32_e32 v41, v41
	s_nop 0
	s_nop 0
	v_rcp_f32_e32 v40, v40
	s_nop 0
	v_mov_b32_e32 v42, v34
	v_mov_b32_e32 v43, v36
	v_pk_mul_f32 v[40:41], v[42:43], v[40:41]
	v_pk_add_f32 v[42:43], v[48:49], 1.0 op_sel_hi:[1,0]
	s_nop 0
	s_nop 0
	v_rcp_f32_e32 v43, v43
	s_nop 0
	s_nop 0
	v_rcp_f32_e32 v42, v42
	s_nop 0
	v_mov_b32_e32 v36, v35
	v_pk_mul_f32 v[34:35], v[36:37], v[42:43]
	v_cvt_pk_bf16_f32 v36, v40, v41
	v_cvt_pk_bf16_f32 v34, v34, v35
	v_and_b32_e32 v35, 0xffff0000, v34
	v_lshlrev_b32_e32 v34, 16, v34
	v_add_u32_e32 v44, 0xe3800, v151
	v_or_b32_sdwa v41, v35, v36 dst_sel:DWORD dst_unused:UNUSED_PAD src0_sel:DWORD src1_sel:WORD_1
	v_or_b32_sdwa v40, v34, v36 dst_sel:DWORD dst_unused:UNUSED_PAD src0_sel:DWORD src1_sel:WORD_0
	v_lshl_add_u64 v[34:35], v[0:1], 1, s[6:7]
	v_add_u32_e32 v0, v44, v150
	global_store_dwordx4 v[34:35], v[38:41], off
	s_nop 1
	s_waitcnt vmcnt(15)
	v_lshlrev_b32_e32 v41, 16, v211
	v_and_b32_e32 v42, 0xffff0000, v211
	v_lshlrev_b32_e32 v35, 16, v212
	v_and_b32_e32 v39, 0xffff0000, v210
	v_mul_f32_e32 v35, 0xbfb8aa3b, v35
	v_lshlrev_b32_e32 v38, 16, v210
	v_and_b32_e32 v40, 0xffff0000, v212
	v_exp_f32_e32 v36, v35
	v_mul_f32_e32 v35, 0xbfb8aa3b, v39
	v_mul_f32_e32 v34, 0xbfb8aa3b, v38
	v_exp_f32_e32 v38, v35
	v_mul_f32_e32 v35, 0xbfb8aa3b, v40
	v_exp_f32_e32 v40, v35
	v_mul_f32_e32 v35, 0xbfb8aa3b, v41
	v_exp_f32_e32 v34, v34
	v_exp_f32_e32 v35, v35
	v_lshlrev_b32_e32 v43, 16, v213
	v_mul_f32_e32 v39, 0xbfb8aa3b, v42
	v_and_b32_e32 v45, 0xffff0000, v213
	v_pk_add_f32 v[34:35], v[34:35], 1.0 op_sel_hi:[1,0]
	v_mul_f32_e32 v37, 0xbfb8aa3b, v43
	v_mul_f32_e32 v41, 0xbfb8aa3b, v45
	v_exp_f32_e32 v39, v39
	v_exp_f32_e32 v37, v37
	v_rcp_f32_e32 v35, v35
	s_nop 0
	v_pk_add_f32 v[38:39], v[38:39], 1.0 op_sel_hi:[1,0]
	v_exp_f32_e32 v41, v41
	v_rcp_f32_e32 v34, v34
	s_nop 0
	v_mov_b32_e32 v42, v30
	v_mov_b32_e32 v43, v32
	v_pk_mul_f32 v[34:35], v[42:43], v[34:35]
	v_rcp_f32_e32 v39, v39
	s_nop 0
	s_nop 0
	v_rcp_f32_e32 v38, v38
	s_nop 0
	v_mov_b32_e32 v32, v31
	v_pk_mul_f32 v[30:31], v[32:33], v[38:39]
	v_cvt_pk_bf16_f32 v32, v34, v35
	v_cvt_pk_bf16_f32 v30, v30, v31
	v_and_b32_e32 v31, 0xffff0000, v30
	v_lshlrev_b32_e32 v30, 16, v30
	v_or_b32_sdwa v31, v31, v32 dst_sel:DWORD dst_unused:UNUSED_PAD src0_sel:DWORD src1_sel:WORD_1
	v_or_b32_sdwa v30, v30, v32 dst_sel:DWORD dst_unused:UNUSED_PAD src0_sel:DWORD src1_sel:WORD_0
	v_pk_add_f32 v[32:33], v[36:37], 1.0 op_sel_hi:[1,0]
	s_nop 0
	s_nop 0
	v_rcp_f32_e32 v33, v33
	s_nop 0
	s_nop 0
	v_rcp_f32_e32 v32, v32
	s_nop 0
	v_mov_b32_e32 v34, v26
	v_mov_b32_e32 v35, v28
	v_pk_mul_f32 v[32:33], v[34:35], v[32:33]
	v_pk_add_f32 v[34:35], v[40:41], 1.0 op_sel_hi:[1,0]
	s_nop 0
	s_nop 0
	v_rcp_f32_e32 v35, v35
	s_nop 0
	s_nop 0
	v_rcp_f32_e32 v34, v34
	s_nop 0
	v_mov_b32_e32 v28, v27
	v_pk_mul_f32 v[26:27], v[28:29], v[34:35]
	v_add_u32_e32 v36, 0xfff44800, v124
	v_cvt_pk_bf16_f32 v26, v26, v27
	v_cvt_pk_bf16_f32 v28, v32, v33
	v_and_b32_e32 v27, 0xffff0000, v26
	v_lshlrev_b32_e32 v26, 16, v26
	v_add_u32_e32 v0, v0, v36
	v_or_b32_sdwa v33, v27, v28 dst_sel:DWORD dst_unused:UNUSED_PAD src0_sel:DWORD src1_sel:WORD_1
	v_or_b32_sdwa v32, v26, v28 dst_sel:DWORD dst_unused:UNUSED_PAD src0_sel:DWORD src1_sel:WORD_0
	v_lshl_add_u64 v[26:27], v[0:1], 1, s[6:7]
	v_add_u32_e32 v0, v44, v125
	global_store_dwordx4 v[26:27], v[30:33], off
	v_add_u32_e32 v0, v0, v36
	s_waitcnt vmcnt(14)
	v_lshlrev_b32_e32 v33, 16, v163
	v_and_b32_e32 v34, 0xffff0000, v163
	v_lshlrev_b32_e32 v27, 16, v164
	v_and_b32_e32 v31, 0xffff0000, v162
	v_mul_f32_e32 v27, 0xbfb8aa3b, v27
	v_lshlrev_b32_e32 v30, 16, v162
	v_and_b32_e32 v32, 0xffff0000, v164
	v_exp_f32_e32 v28, v27
	v_mul_f32_e32 v27, 0xbfb8aa3b, v31
	v_mul_f32_e32 v26, 0xbfb8aa3b, v30
	v_exp_f32_e32 v30, v27
	v_mul_f32_e32 v27, 0xbfb8aa3b, v32
	v_exp_f32_e32 v32, v27
	v_mul_f32_e32 v27, 0xbfb8aa3b, v33
	v_exp_f32_e32 v26, v26
	v_exp_f32_e32 v27, v27
	v_lshlrev_b32_e32 v35, 16, v165
	v_mul_f32_e32 v31, 0xbfb8aa3b, v34
	v_and_b32_e32 v37, 0xffff0000, v165
	v_pk_add_f32 v[26:27], v[26:27], 1.0 op_sel_hi:[1,0]
	v_mul_f32_e32 v29, 0xbfb8aa3b, v35
	v_mul_f32_e32 v33, 0xbfb8aa3b, v37
	v_exp_f32_e32 v31, v31
	v_exp_f32_e32 v29, v29
	v_rcp_f32_e32 v27, v27
	s_nop 0
	v_pk_add_f32 v[30:31], v[30:31], 1.0 op_sel_hi:[1,0]
	v_exp_f32_e32 v33, v33
	v_rcp_f32_e32 v26, v26
	s_nop 0
	v_mov_b32_e32 v34, v22
	v_mov_b32_e32 v35, v24
	v_pk_mul_f32 v[26:27], v[34:35], v[26:27]
	v_rcp_f32_e32 v31, v31
	s_nop 0
	s_nop 0
	v_rcp_f32_e32 v30, v30
	s_nop 0
	v_mov_b32_e32 v24, v23
	v_pk_mul_f32 v[22:23], v[24:25], v[30:31]
	v_cvt_pk_bf16_f32 v24, v26, v27
	v_cvt_pk_bf16_f32 v22, v22, v23
	v_and_b32_e32 v23, 0xffff0000, v22
	v_lshlrev_b32_e32 v22, 16, v22
	v_or_b32_sdwa v23, v23, v24 dst_sel:DWORD dst_unused:UNUSED_PAD src0_sel:DWORD src1_sel:WORD_1
	v_or_b32_sdwa v22, v22, v24 dst_sel:DWORD dst_unused:UNUSED_PAD src0_sel:DWORD src1_sel:WORD_0
	v_pk_add_f32 v[24:25], v[28:29], 1.0 op_sel_hi:[1,0]
	s_nop 0
	s_nop 0
	v_rcp_f32_e32 v25, v25
	s_nop 0
	s_nop 0
	v_rcp_f32_e32 v24, v24
	s_nop 0
	v_mov_b32_e32 v26, v18
	v_mov_b32_e32 v27, v20
	v_pk_mul_f32 v[24:25], v[26:27], v[24:25]
	v_pk_add_f32 v[26:27], v[32:33], 1.0 op_sel_hi:[1,0]
	s_nop 0
	s_nop 0
	v_rcp_f32_e32 v27, v27
	s_nop 0
	s_nop 0
	v_rcp_f32_e32 v26, v26
	s_nop 0
	v_mov_b32_e32 v20, v19
	v_pk_mul_f32 v[18:19], v[20:21], v[26:27]
	v_cvt_pk_bf16_f32 v20, v24, v25
	v_cvt_pk_bf16_f32 v18, v18, v19
	v_and_b32_e32 v19, 0xffff0000, v18
	v_lshlrev_b32_e32 v18, 16, v18
	v_add_u32_e32 v28, 0xfa400, v151
	v_or_b32_sdwa v25, v19, v20 dst_sel:DWORD dst_unused:UNUSED_PAD src0_sel:DWORD src1_sel:WORD_1
	v_or_b32_sdwa v24, v18, v20 dst_sel:DWORD dst_unused:UNUSED_PAD src0_sel:DWORD src1_sel:WORD_0
	v_lshl_add_u64 v[18:19], v[0:1], 1, s[6:7]
	v_add_u32_e32 v0, v28, v150
	global_store_dwordx4 v[18:19], v[22:25], off
	s_nop 1
	s_waitcnt vmcnt(13)
	v_lshlrev_b32_e32 v25, 16, v167
	v_and_b32_e32 v26, 0xffff0000, v167
	v_lshlrev_b32_e32 v19, 16, v168
	v_and_b32_e32 v23, 0xffff0000, v166
	v_mul_f32_e32 v19, 0xbfb8aa3b, v19
	v_lshlrev_b32_e32 v22, 16, v166
	v_and_b32_e32 v24, 0xffff0000, v168
	v_exp_f32_e32 v20, v19
	v_mul_f32_e32 v19, 0xbfb8aa3b, v23
	v_mul_f32_e32 v18, 0xbfb8aa3b, v22
	v_exp_f32_e32 v22, v19
	v_mul_f32_e32 v19, 0xbfb8aa3b, v24
	v_exp_f32_e32 v24, v19
	v_mul_f32_e32 v19, 0xbfb8aa3b, v25
	v_exp_f32_e32 v18, v18
	v_exp_f32_e32 v19, v19
	v_lshlrev_b32_e32 v27, 16, v169
	v_mul_f32_e32 v23, 0xbfb8aa3b, v26
	v_and_b32_e32 v29, 0xffff0000, v169
	v_pk_add_f32 v[18:19], v[18:19], 1.0 op_sel_hi:[1,0]
	v_mul_f32_e32 v21, 0xbfb8aa3b, v27
	v_mul_f32_e32 v25, 0xbfb8aa3b, v29
	v_exp_f32_e32 v23, v23
	v_exp_f32_e32 v21, v21
	v_rcp_f32_e32 v19, v19
	s_nop 0
	v_pk_add_f32 v[22:23], v[22:23], 1.0 op_sel_hi:[1,0]
	v_exp_f32_e32 v25, v25
	v_rcp_f32_e32 v18, v18
	s_nop 0
	v_mov_b32_e32 v26, v14
	v_mov_b32_e32 v27, v16
	v_pk_mul_f32 v[18:19], v[26:27], v[18:19]
	v_rcp_f32_e32 v23, v23
	s_nop 0
	s_nop 0
	v_rcp_f32_e32 v22, v22
	s_nop 0
	v_mov_b32_e32 v16, v15
	v_pk_mul_f32 v[14:15], v[16:17], v[22:23]
	v_cvt_pk_bf16_f32 v16, v18, v19
	v_cvt_pk_bf16_f32 v14, v14, v15
	v_and_b32_e32 v15, 0xffff0000, v14
	v_lshlrev_b32_e32 v14, 16, v14
	v_or_b32_sdwa v15, v15, v16 dst_sel:DWORD dst_unused:UNUSED_PAD src0_sel:DWORD src1_sel:WORD_1
	v_or_b32_sdwa v14, v14, v16 dst_sel:DWORD dst_unused:UNUSED_PAD src0_sel:DWORD src1_sel:WORD_0
	v_pk_add_f32 v[16:17], v[20:21], 1.0 op_sel_hi:[1,0]
	s_nop 0
	s_nop 0
	v_rcp_f32_e32 v17, v17
	s_nop 0
	s_nop 0
	v_rcp_f32_e32 v16, v16
	s_nop 0
	v_mov_b32_e32 v18, v10
	v_mov_b32_e32 v19, v12
	v_pk_mul_f32 v[16:17], v[18:19], v[16:17]
	v_pk_add_f32 v[18:19], v[24:25], 1.0 op_sel_hi:[1,0]
	s_nop 0
	s_nop 0
	v_rcp_f32_e32 v19, v19
	s_nop 0
	s_nop 0
	v_rcp_f32_e32 v18, v18
	s_nop 0
	v_mov_b32_e32 v12, v11
	v_pk_mul_f32 v[10:11], v[12:13], v[18:19]
	v_add_u32_e32 v20, 0xfff31c00, v124
	v_cvt_pk_bf16_f32 v10, v10, v11
	v_cvt_pk_bf16_f32 v12, v16, v17
	v_and_b32_e32 v11, 0xffff0000, v10
	v_lshlrev_b32_e32 v10, 16, v10
	v_add_u32_e32 v0, v0, v20
	v_or_b32_sdwa v17, v11, v12 dst_sel:DWORD dst_unused:UNUSED_PAD src0_sel:DWORD src1_sel:WORD_1
	v_or_b32_sdwa v16, v10, v12 dst_sel:DWORD dst_unused:UNUSED_PAD src0_sel:DWORD src1_sel:WORD_0
	v_lshl_add_u64 v[10:11], v[0:1], 1, s[6:7]
	v_add_u32_e32 v0, v28, v125
	global_store_dwordx4 v[10:11], v[14:17], off
	v_add_u32_e32 v0, v0, v20
	s_waitcnt vmcnt(12)
	v_lshlrev_b32_e32 v17, 16, v171
	v_and_b32_e32 v18, 0xffff0000, v171
	v_lshlrev_b32_e32 v11, 16, v172
	v_and_b32_e32 v15, 0xffff0000, v170
	v_mul_f32_e32 v11, 0xbfb8aa3b, v11
	v_lshlrev_b32_e32 v14, 16, v170
	v_and_b32_e32 v16, 0xffff0000, v172
	v_exp_f32_e32 v12, v11
	v_mul_f32_e32 v11, 0xbfb8aa3b, v15
	v_mul_f32_e32 v10, 0xbfb8aa3b, v14
	v_exp_f32_e32 v14, v11
	v_mul_f32_e32 v11, 0xbfb8aa3b, v16
	v_exp_f32_e32 v16, v11
	v_mul_f32_e32 v11, 0xbfb8aa3b, v17
	v_exp_f32_e32 v10, v10
	v_exp_f32_e32 v11, v11
	v_lshlrev_b32_e32 v19, 16, v173
	v_mul_f32_e32 v15, 0xbfb8aa3b, v18
	v_and_b32_e32 v21, 0xffff0000, v173
	v_pk_add_f32 v[10:11], v[10:11], 1.0 op_sel_hi:[1,0]
	v_mul_f32_e32 v13, 0xbfb8aa3b, v19
	v_mul_f32_e32 v17, 0xbfb8aa3b, v21
	v_exp_f32_e32 v15, v15
	v_exp_f32_e32 v13, v13
	v_rcp_f32_e32 v11, v11
	s_nop 0
	v_pk_add_f32 v[14:15], v[14:15], 1.0 op_sel_hi:[1,0]
	v_exp_f32_e32 v17, v17
	v_rcp_f32_e32 v10, v10
	s_nop 0
	v_mov_b32_e32 v18, v6
	v_mov_b32_e32 v19, v8
	v_pk_mul_f32 v[10:11], v[18:19], v[10:11]
	v_rcp_f32_e32 v15, v15
	s_nop 0
	s_nop 0
	v_rcp_f32_e32 v14, v14
	s_nop 0
	v_mov_b32_e32 v8, v7
	v_pk_mul_f32 v[6:7], v[8:9], v[14:15]
	v_cvt_pk_bf16_f32 v8, v10, v11
	v_cvt_pk_bf16_f32 v6, v6, v7
	v_and_b32_e32 v7, 0xffff0000, v6
	v_lshlrev_b32_e32 v6, 16, v6
	v_or_b32_sdwa v7, v7, v8 dst_sel:DWORD dst_unused:UNUSED_PAD src0_sel:DWORD src1_sel:WORD_1
	v_or_b32_sdwa v6, v6, v8 dst_sel:DWORD dst_unused:UNUSED_PAD src0_sel:DWORD src1_sel:WORD_0
	v_pk_add_f32 v[8:9], v[12:13], 1.0 op_sel_hi:[1,0]
	s_nop 0
	s_nop 0
	v_rcp_f32_e32 v9, v9
	s_nop 0
	s_nop 0
	v_rcp_f32_e32 v8, v8
	s_nop 0
	v_mov_b32_e32 v10, v2
	v_mov_b32_e32 v11, v4
	v_pk_mul_f32 v[8:9], v[10:11], v[8:9]
	v_pk_add_f32 v[10:11], v[16:17], 1.0 op_sel_hi:[1,0]
	s_nop 0
	s_nop 0
	v_rcp_f32_e32 v11, v11
	s_nop 0
	s_mov_b64 s[24:25], s[16:17]
	v_rcp_f32_e32 v10, v10
	s_nop 0
	v_mov_b32_e32 v4, v3
	v_pk_mul_f32 v[2:3], v[4:5], v[10:11]
	v_cvt_pk_bf16_f32 v4, v8, v9
	v_cvt_pk_bf16_f32 v2, v2, v3
	v_and_b32_e32 v3, 0xffff0000, v2
	v_lshlrev_b32_e32 v2, 16, v2
	v_or_b32_sdwa v9, v3, v4 dst_sel:DWORD dst_unused:UNUSED_PAD src0_sel:DWORD src1_sel:WORD_1
	v_or_b32_sdwa v8, v2, v4 dst_sel:DWORD dst_unused:UNUSED_PAD src0_sel:DWORD src1_sel:WORD_0
	v_lshl_add_u64 v[2:3], v[0:1], 1, s[6:7]
	s_and_b64 vcc, exec, s[10:11]
	global_store_dwordx4 v[2:3], v[6:9], off
	s_cbranch_vccz .LBB0_1331
	s_waitcnt vmcnt(0)
	v_readlane_b32 s76, v255, 8
	s_mov_b32 s92, 0x3b2aaaab
	s_cmp_gt_u32 s5, 3
	v_readlane_b32 s77, v255, 9
	s_mul_i32 s60, s33, 0x1800
	s_mul_hi_i32 s62, s64, 0x300
	s_mul_i32 s75, s33, 0x16c00
	s_mov_b32 s93, 0x3c800000
	s_mov_b32 s82, s70
	s_cbranch_scc1 .LBB0_1338
	s_barrier

.LBB0_1347:
	v_add_u32_e32 v0, 0x10000, v148
	s_waitcnt vmcnt(0)
	ds_read_b128 v[142:145], v0
	ds_read_b128 v[150:153], v0 offset:1024
	ds_read_b128 v[154:157], v0 offset:2048
	ds_read_b128 v[158:161], v0 offset:3072
	s_add_u32 s26, s24, 0xfffc0080
	s_addc_u32 s27, s25, -1
	s_cmp_eq_u32 s97, 12
	s_cselect_b32 s29, s2, s27
	s_cselect_b32 s28, s15, s26
	s_cselect_b32 s27, s13, s94
	s_cselect_b32 s26, s89, s90
	v_lshl_add_u64 v[178:179], s[24:25], 0, v[138:139]
	s_add_i32 m0, s35, 0xc000
	ds_read_b128 v[162:165], v147
	ds_read_b128 v[166:169], v147 offset:1024
	ds_read_b128 v[170:173], v147 offset:2048
	ds_read_b128 v[174:177], v147 offset:3072
	ds_read_b128 v[182:185], v147 offset:4096
	ds_read_b128 v[186:189], v147 offset:5120
	ds_read_b128 v[190:193], v147 offset:6144
	ds_read_b128 v[194:197], v147 offset:7168
	global_load_lds_dwordx4 v[178:179], off
	v_lshl_add_u64 v[178:179], s[24:25], 0, v[140:141]
	s_add_i32 m0, s35, 0xe000
	s_nop 0
	global_load_lds_dwordx4 v[178:179], off
	s_waitcnt lgkmcnt(8)
	s_barrier
	s_waitcnt lgkmcnt(0)
	s_setprio 1
	s_waitcnt lgkmcnt(0)
	v_mfma_f32_16x16x32_bf16 v[126:129], v[142:145], v[162:165], v[126:129]
	v_mfma_f32_16x16x32_bf16 v[122:125], v[154:157], v[162:165], v[122:125]
	v_mfma_f32_16x16x32_bf16 v[110:113], v[142:145], v[170:173], v[110:113]
	v_mfma_f32_16x16x32_bf16 v[106:109], v[154:157], v[170:173], v[106:109]
	v_mfma_f32_16x16x32_bf16 v[94:97], v[142:145], v[182:185], v[94:97]
	v_mfma_f32_16x16x32_bf16 v[90:93], v[154:157], v[182:185], v[90:93]
	v_mfma_f32_16x16x32_bf16 v[78:81], v[142:145], v[190:193], v[78:81]
	v_mfma_f32_16x16x32_bf16 v[74:77], v[154:157], v[190:193], v[74:77]
	v_mfma_f32_16x16x32_bf16 v[126:129], v[150:153], v[166:169], v[126:129]
	v_mfma_f32_16x16x32_bf16 v[122:125], v[158:161], v[166:169], v[122:125]
	v_mfma_f32_16x16x32_bf16 v[110:113], v[150:153], v[174:177], v[110:113]
	v_mfma_f32_16x16x32_bf16 v[106:109], v[158:161], v[174:177], v[106:109]
	v_mfma_f32_16x16x32_bf16 v[94:97], v[150:153], v[186:189], v[94:97]
	v_mfma_f32_16x16x32_bf16 v[90:93], v[158:161], v[186:189], v[90:93]
	v_mfma_f32_16x16x32_bf16 v[78:81], v[150:153], v[194:197], v[78:81]
	v_mfma_f32_16x16x32_bf16 v[74:77], v[158:161], v[194:197], v[74:77]
	s_setprio 0
	s_barrier
	s_mov_b32 m0, s21
	v_add_u32_e32 v0, 0x14000, v148
	v_lshl_add_u64 v[178:179], s[26:27], 0, v[134:135]
	s_waitcnt vmcnt(0)
	ds_read_b128 v[198:201], v0
	ds_read_b128 v[202:205], v0 offset:1024
	ds_read_b128 v[206:209], v0 offset:2048
	ds_read_b128 v[210:213], v0 offset:3072
	global_load_lds_dwordx4 v[178:179], off
	v_lshl_add_u64 v[214:215], s[26:27], 0, v[130:131]
	s_mov_b32 m0, s23
	s_nop 0
	global_load_lds_dwordx4 v[214:215], off
	s_barrier
	s_waitcnt lgkmcnt(0)
	s_setprio 1
	s_waitcnt lgkmcnt(0)
	v_mfma_f32_16x16x32_bf16 v[118:121], v[198:201], v[162:165], v[118:121]
	v_mfma_f32_16x16x32_bf16 v[114:117], v[206:209], v[162:165], v[114:117]
	v_mfma_f32_16x16x32_bf16 v[102:105], v[198:201], v[170:173], v[102:105]
	v_mfma_f32_16x16x32_bf16 v[98:101], v[206:209], v[170:173], v[98:101]
	v_mfma_f32_16x16x32_bf16 v[86:89], v[198:201], v[182:185], v[86:89]
	v_mfma_f32_16x16x32_bf16 v[82:85], v[206:209], v[182:185], v[82:85]
	v_mfma_f32_16x16x32_bf16 v[70:73], v[198:201], v[190:193], v[70:73]
	v_mfma_f32_16x16x32_bf16 v[66:69], v[206:209], v[190:193], v[66:69]
	v_mfma_f32_16x16x32_bf16 v[118:121], v[202:205], v[166:169], v[118:121]
	v_mfma_f32_16x16x32_bf16 v[114:117], v[210:213], v[166:169], v[114:117]
	v_mfma_f32_16x16x32_bf16 v[102:105], v[202:205], v[174:177], v[102:105]
	v_mfma_f32_16x16x32_bf16 v[98:101], v[210:213], v[174:177], v[98:101]
	v_mfma_f32_16x16x32_bf16 v[86:89], v[202:205], v[186:189], v[86:89]
	v_mfma_f32_16x16x32_bf16 v[82:85], v[210:213], v[186:189], v[82:85]
	v_mfma_f32_16x16x32_bf16 v[70:73], v[202:205], v[194:197], v[70:73]
	v_mfma_f32_16x16x32_bf16 v[66:69], v[210:213], v[194:197], v[66:69]
	s_setprio 0
	s_mov_b32 m0, s35
	v_lshl_add_u64 v[216:217], s[28:29], 0, v[136:137]
	s_barrier
	s_waitcnt vmcnt(0)
	ds_read_b128 v[162:165], v147 offset:16384
	ds_read_b128 v[166:169], v147 offset:17408
	ds_read_b128 v[170:173], v147 offset:18432
	ds_read_b128 v[174:177], v147 offset:19456
	ds_read_b128 v[182:185], v147 offset:20480
	ds_read_b128 v[186:189], v147 offset:21504
	ds_read_b128 v[190:193], v147 offset:22528
	ds_read_b128 v[194:197], v147 offset:23552
	global_load_lds_dwordx4 v[216:217], off
	v_lshl_add_u64 v[222:223], s[28:29], 0, v[132:133]
	s_mov_b32 m0, s36
	s_nop 0
	global_load_lds_dwordx4 v[222:223], off
	s_barrier
	s_waitcnt lgkmcnt(0)
	s_setprio 1
	s_waitcnt lgkmcnt(0)
	v_mfma_f32_16x16x32_bf16 v[62:65], v[142:145], v[162:165], v[62:65]
	v_mfma_f32_16x16x32_bf16 v[58:61], v[154:157], v[162:165], v[58:61]
	v_mfma_f32_16x16x32_bf16 v[46:49], v[142:145], v[170:173], v[46:49]
	v_mfma_f32_16x16x32_bf16 v[42:45], v[154:157], v[170:173], v[42:45]
	v_mfma_f32_16x16x32_bf16 v[30:33], v[142:145], v[182:185], v[30:33]
	v_mfma_f32_16x16x32_bf16 v[26:29], v[154:157], v[182:185], v[26:29]
	v_mfma_f32_16x16x32_bf16 v[14:17], v[142:145], v[190:193], v[14:17]
	v_mfma_f32_16x16x32_bf16 v[10:13], v[154:157], v[190:193], v[10:13]
	v_mfma_f32_16x16x32_bf16 v[62:65], v[150:153], v[166:169], v[62:65]
	v_mfma_f32_16x16x32_bf16 v[58:61], v[158:161], v[166:169], v[58:61]
	v_mfma_f32_16x16x32_bf16 v[46:49], v[150:153], v[174:177], v[46:49]
	v_mfma_f32_16x16x32_bf16 v[42:45], v[158:161], v[174:177], v[42:45]
	v_mfma_f32_16x16x32_bf16 v[30:33], v[150:153], v[186:189], v[30:33]
	v_mfma_f32_16x16x32_bf16 v[26:29], v[158:161], v[186:189], v[26:29]
	v_mfma_f32_16x16x32_bf16 v[14:17], v[150:153], v[194:197], v[14:17]
	v_mfma_f32_16x16x32_bf16 v[10:13], v[158:161], v[194:197], v[10:13]
	s_setprio 0
	s_barrier
	s_add_u32 s76, s26, 0x40000
	s_addc_u32 s77, s27, 0
	s_mov_b32 m0, s37
	v_lshl_add_u64 v[142:143], s[76:77], 0, v[134:135]
	global_load_lds_dwordx4 v[142:143], off
	v_lshl_add_u64 v[142:143], s[76:77], 0, v[130:131]
	s_mov_b32 m0, s38
	s_nop 0
	global_load_lds_dwordx4 v[142:143], off
	s_waitcnt vmcnt(6)
	s_barrier
	s_setprio 1
	v_mfma_f32_16x16x32_bf16 v[54:57], v[198:201], v[162:165], v[54:57]
	v_mfma_f32_16x16x32_bf16 v[50:53], v[206:209], v[162:165], v[50:53]
	v_mfma_f32_16x16x32_bf16 v[38:41], v[198:201], v[170:173], v[38:41]
	v_mfma_f32_16x16x32_bf16 v[34:37], v[206:209], v[170:173], v[34:37]
	v_mfma_f32_16x16x32_bf16 v[22:25], v[198:201], v[182:185], v[22:25]
	v_mfma_f32_16x16x32_bf16 v[18:21], v[206:209], v[182:185], v[18:21]
	v_mfma_f32_16x16x32_bf16 v[6:9], v[198:201], v[190:193], v[6:9]
	v_mfma_f32_16x16x32_bf16 v[2:5], v[206:209], v[190:193], v[2:5]
	v_mfma_f32_16x16x32_bf16 v[54:57], v[202:205], v[166:169], v[54:57]
	v_mfma_f32_16x16x32_bf16 v[50:53], v[210:213], v[166:169], v[50:53]
	v_mfma_f32_16x16x32_bf16 v[38:41], v[202:205], v[174:177], v[38:41]
	v_mfma_f32_16x16x32_bf16 v[34:37], v[210:213], v[174:177], v[34:37]
	v_mfma_f32_16x16x32_bf16 v[22:25], v[202:205], v[186:189], v[22:25]
	v_mfma_f32_16x16x32_bf16 v[18:21], v[210:213], v[186:189], v[18:21]
	v_mfma_f32_16x16x32_bf16 v[6:9], v[202:205], v[194:197], v[6:9]
	v_mfma_f32_16x16x32_bf16 v[2:5], v[210:213], v[194:197], v[2:5]
	s_setprio 0
	v_add_u32_e32 v0, 0x18000, v148
	s_barrier
	s_waitcnt vmcnt(0)
	ds_read_b128 v[142:145], v0
	ds_read_b128 v[150:153], v0 offset:1024
	ds_read_b128 v[154:157], v0 offset:2048
	ds_read_b128 v[158:161], v0 offset:3072
	s_add_u32 s28, s28, 0x40000
	s_addc_u32 s29, s29, 0
	s_mov_b32 m0, s39
	v_lshl_add_u64 v[198:199], s[28:29], 0, v[136:137]
	ds_read_b128 v[162:165], v147 offset:32768
	ds_read_b128 v[166:169], v147 offset:33792
	ds_read_b128 v[170:173], v147 offset:34816
	ds_read_b128 v[174:177], v147 offset:35840
	ds_read_b128 v[182:185], v147 offset:36864
	ds_read_b128 v[186:189], v147 offset:37888
	ds_read_b128 v[190:193], v147 offset:38912
	ds_read_b128 v[194:197], v147 offset:39936
	global_load_lds_dwordx4 v[198:199], off
	v_lshl_add_u64 v[198:199], s[28:29], 0, v[132:133]
	s_mov_b32 m0, s60
	s_nop 0
	global_load_lds_dwordx4 v[198:199], off
	s_waitcnt lgkmcnt(8)
	s_barrier
	s_waitcnt lgkmcnt(0)
	s_setprio 1
	s_waitcnt lgkmcnt(0)
	v_mfma_f32_16x16x32_bf16 v[126:129], v[142:145], v[162:165], v[126:129]
	v_mfma_f32_16x16x32_bf16 v[122:125], v[154:157], v[162:165], v[122:125]
	v_mfma_f32_16x16x32_bf16 v[110:113], v[142:145], v[170:173], v[110:113]
	v_mfma_f32_16x16x32_bf16 v[106:109], v[154:157], v[170:173], v[106:109]
	v_mfma_f32_16x16x32_bf16 v[94:97], v[142:145], v[182:185], v[94:97]
	v_mfma_f32_16x16x32_bf16 v[90:93], v[154:157], v[182:185], v[90:93]
	v_mfma_f32_16x16x32_bf16 v[78:81], v[142:145], v[190:193], v[78:81]
	v_mfma_f32_16x16x32_bf16 v[74:77], v[154:157], v[190:193], v[74:77]
	v_mfma_f32_16x16x32_bf16 v[126:129], v[150:153], v[166:169], v[126:129]
	v_mfma_f32_16x16x32_bf16 v[122:125], v[158:161], v[166:169], v[122:125]
	v_mfma_f32_16x16x32_bf16 v[110:113], v[150:153], v[174:177], v[110:113]
	v_mfma_f32_16x16x32_bf16 v[106:109], v[158:161], v[174:177], v[106:109]
	v_mfma_f32_16x16x32_bf16 v[94:97], v[150:153], v[186:189], v[94:97]
	v_mfma_f32_16x16x32_bf16 v[90:93], v[158:161], v[186:189], v[90:93]
	v_mfma_f32_16x16x32_bf16 v[78:81], v[150:153], v[194:197], v[78:81]
	v_mfma_f32_16x16x32_bf16 v[74:77], v[158:161], v[194:197], v[74:77]
	s_setprio 0
	s_barrier
	s_mov_b32 m0, s68
	v_add_u32_e32 v0, 0x1c000, v148
	v_lshl_add_u64 v[178:179], v[178:179], 0, s[84:85]
	s_waitcnt vmcnt(0)
	ds_read_b128 v[198:201], v0
	ds_read_b128 v[202:205], v0 offset:1024
	ds_read_b128 v[206:209], v0 offset:2048
	ds_read_b128 v[210:213], v0 offset:3072
	global_load_lds_dwordx4 v[178:179], off
	v_lshl_add_u64 v[178:179], v[214:215], 0, s[84:85]
	s_mov_b32 m0, s69
	s_nop 0
	global_load_lds_dwordx4 v[178:179], off
	s_barrier
	s_waitcnt lgkmcnt(0)
	s_setprio 1
	s_waitcnt lgkmcnt(0)
	v_mfma_f32_16x16x32_bf16 v[118:121], v[198:201], v[162:165], v[118:121]
	v_mfma_f32_16x16x32_bf16 v[114:117], v[206:209], v[162:165], v[114:117]
	v_mfma_f32_16x16x32_bf16 v[102:105], v[198:201], v[170:173], v[102:105]
	v_mfma_f32_16x16x32_bf16 v[98:101], v[206:209], v[170:173], v[98:101]
	v_mfma_f32_16x16x32_bf16 v[86:89], v[198:201], v[182:185], v[86:89]
	v_mfma_f32_16x16x32_bf16 v[82:85], v[206:209], v[182:185], v[82:85]
	v_mfma_f32_16x16x32_bf16 v[70:73], v[198:201], v[190:193], v[70:73]
	v_mfma_f32_16x16x32_bf16 v[66:69], v[206:209], v[190:193], v[66:69]
	v_mfma_f32_16x16x32_bf16 v[118:121], v[202:205], v[166:169], v[118:121]
	v_mfma_f32_16x16x32_bf16 v[114:117], v[210:213], v[166:169], v[114:117]
	v_mfma_f32_16x16x32_bf16 v[102:105], v[202:205], v[174:177], v[102:105]
	v_mfma_f32_16x16x32_bf16 v[98:101], v[210:213], v[174:177], v[98:101]
	v_mfma_f32_16x16x32_bf16 v[86:89], v[202:205], v[186:189], v[86:89]
	v_mfma_f32_16x16x32_bf16 v[82:85], v[210:213], v[186:189], v[82:85]
	v_mfma_f32_16x16x32_bf16 v[70:73], v[202:205], v[194:197], v[70:73]
	v_mfma_f32_16x16x32_bf16 v[66:69], v[210:213], v[194:197], v[66:69]
	s_setprio 0
	s_mov_b32 m0, s75
	v_lshl_add_u64 v[178:179], v[216:217], 0, s[84:85]
	s_barrier
	s_waitcnt vmcnt(0)
	ds_read_b128 v[162:165], v147 offset:49152
	ds_read_b128 v[166:169], v147 offset:50176
	ds_read_b128 v[170:173], v147 offset:51200
	ds_read_b128 v[174:177], v147 offset:52224
	ds_read_b128 v[182:185], v147 offset:53248
	ds_read_b128 v[186:189], v147 offset:54272
	ds_read_b128 v[190:193], v147 offset:55296
	ds_read_b128 v[194:197], v147 offset:56320
	global_load_lds_dwordx4 v[178:179], off
	v_lshl_add_u64 v[178:179], v[222:223], 0, s[84:85]
	s_mov_b32 m0, s82
	s_nop 0
	global_load_lds_dwordx4 v[178:179], off
	s_barrier
	s_waitcnt lgkmcnt(0)
	s_setprio 1
	s_waitcnt lgkmcnt(0)
	v_mfma_f32_16x16x32_bf16 v[62:65], v[142:145], v[162:165], v[62:65]
	v_mfma_f32_16x16x32_bf16 v[58:61], v[154:157], v[162:165], v[58:61]
	v_mfma_f32_16x16x32_bf16 v[46:49], v[142:145], v[170:173], v[46:49]
	v_mfma_f32_16x16x32_bf16 v[42:45], v[154:157], v[170:173], v[42:45]
	v_mfma_f32_16x16x32_bf16 v[30:33], v[142:145], v[182:185], v[30:33]
	v_mfma_f32_16x16x32_bf16 v[26:29], v[154:157], v[182:185], v[26:29]
	v_mfma_f32_16x16x32_bf16 v[14:17], v[142:145], v[190:193], v[14:17]
	v_mfma_f32_16x16x32_bf16 v[10:13], v[154:157], v[190:193], v[10:13]
	v_mfma_f32_16x16x32_bf16 v[62:65], v[150:153], v[166:169], v[62:65]
	v_mfma_f32_16x16x32_bf16 v[58:61], v[158:161], v[166:169], v[58:61]
	v_mfma_f32_16x16x32_bf16 v[46:49], v[150:153], v[174:177], v[46:49]
	v_mfma_f32_16x16x32_bf16 v[42:45], v[158:161], v[174:177], v[42:45]
	v_mfma_f32_16x16x32_bf16 v[30:33], v[150:153], v[186:189], v[30:33]
	v_mfma_f32_16x16x32_bf16 v[26:29], v[158:161], v[186:189], v[26:29]
	v_mfma_f32_16x16x32_bf16 v[14:17], v[150:153], v[194:197], v[14:17]
	v_mfma_f32_16x16x32_bf16 v[10:13], v[158:161], v[194:197], v[10:13]
	s_setprio 0
	s_barrier
	s_add_u32 s26, s26, 0x40080
	s_addc_u32 s27, s27, 0
	s_mov_b32 m0, s92
	v_lshl_add_u64 v[142:143], s[26:27], 0, v[134:135]
	global_load_lds_dwordx4 v[142:143], off
	v_lshl_add_u64 v[142:143], s[26:27], 0, v[130:131]
	s_mov_b32 m0, s93
	s_nop 0
	global_load_lds_dwordx4 v[142:143], off
	s_waitcnt vmcnt(6)
	s_barrier
	s_setprio 1
	v_mfma_f32_16x16x32_bf16 v[54:57], v[198:201], v[162:165], v[54:57]
	v_mfma_f32_16x16x32_bf16 v[50:53], v[206:209], v[162:165], v[50:53]
	v_mfma_f32_16x16x32_bf16 v[38:41], v[198:201], v[170:173], v[38:41]
	v_mfma_f32_16x16x32_bf16 v[34:37], v[206:209], v[170:173], v[34:37]
	v_mfma_f32_16x16x32_bf16 v[22:25], v[198:201], v[182:185], v[22:25]
	v_mfma_f32_16x16x32_bf16 v[18:21], v[206:209], v[182:185], v[18:21]
	v_mfma_f32_16x16x32_bf16 v[6:9], v[198:201], v[190:193], v[6:9]
	v_mfma_f32_16x16x32_bf16 v[2:5], v[206:209], v[190:193], v[2:5]
	v_mfma_f32_16x16x32_bf16 v[54:57], v[202:205], v[166:169], v[54:57]
	v_mfma_f32_16x16x32_bf16 v[50:53], v[210:213], v[166:169], v[50:53]
	v_mfma_f32_16x16x32_bf16 v[38:41], v[202:205], v[174:177], v[38:41]
	v_mfma_f32_16x16x32_bf16 v[34:37], v[210:213], v[174:177], v[34:37]
	v_mfma_f32_16x16x32_bf16 v[22:25], v[202:205], v[186:189], v[22:25]
	v_mfma_f32_16x16x32_bf16 v[18:21], v[210:213], v[186:189], v[18:21]
	v_mfma_f32_16x16x32_bf16 v[6:9], v[202:205], v[194:197], v[6:9]
	v_mfma_f32_16x16x32_bf16 v[2:5], v[210:213], v[194:197], v[2:5]
	s_setprio 0
	s_add_i32 s97, s97, 2
	s_add_u32 s24, s24, 0x100
	s_addc_u32 s25, s25, 0
	s_add_u32 s90, s90, 0x100
	s_addc_u32 s94, s94, 0
	s_cmp_gt_u32 s97, 13
	s_barrier
	s_cbranch_scc0 .LBB0_1347
	v_lshl_add_u32 v152, s22, 8, v146
	v_lshl_add_u32 v150, s20, 8, v149
	v_mul_lo_u32 v151, v152, s71
	v_add_u32_e32 v0, v151, v150
	v_lshl_add_u64 v[142:143], v[0:1], 1, s[8:9]
	global_load_dwordx4 v[142:145], v[142:143], off
	v_mov_b32_e32 v178, v0
	v_mov_b32_e32 v161, 0
	v_add_u32_e32 v160, 0x80, v178
	v_lshl_add_u64 v[162:163], v[160:161], 1, s[8:9]
	global_load_dwordx4 v[162:165], v[162:163], off
	v_add_u32_e32 v160, 0x16c00, v178
	v_lshl_add_u64 v[166:167], v[160:161], 1, s[8:9]
	global_load_dwordx4 v[166:169], v[166:167], off
	v_add_u32_e32 v160, 0x16c80, v178
	v_lshl_add_u64 v[170:171], v[160:161], 1, s[8:9]
	global_load_dwordx4 v[170:173], v[170:171], off
	v_add_u32_e32 v160, 0x2d800, v178
	v_lshl_add_u64 v[174:175], v[160:161], 1, s[8:9]
	global_load_dwordx4 v[174:177], v[174:175], off
	v_add_u32_e32 v160, 0x2d880, v178
	v_lshl_add_u64 v[182:183], v[160:161], 1, s[8:9]
	global_load_dwordx4 v[182:185], v[182:183], off
	v_add_u32_e32 v160, 0x44400, v178
	v_lshl_add_u64 v[186:187], v[160:161], 1, s[8:9]
	global_load_dwordx4 v[186:189], v[186:187], off
	v_add_u32_e32 v160, 0x44480, v178
	v_lshl_add_u64 v[190:191], v[160:161], 1, s[8:9]
	global_load_dwordx4 v[190:193], v[190:191], off
	v_add_u32_e32 v160, 0xb6000, v178
	v_lshl_add_u64 v[194:195], v[160:161], 1, s[8:9]
	global_load_dwordx4 v[194:197], v[194:195], off
	v_add_u32_e32 v160, 0xb6080, v178
	v_lshl_add_u64 v[198:199], v[160:161], 1, s[8:9]
	global_load_dwordx4 v[198:201], v[198:199], off
	v_add_u32_e32 v160, 0xccc00, v178
	v_lshl_add_u64 v[202:203], v[160:161], 1, s[8:9]
	global_load_dwordx4 v[202:205], v[202:203], off
	v_add_u32_e32 v160, 0xccc80, v178
	v_lshl_add_u64 v[206:207], v[160:161], 1, s[8:9]
	global_load_dwordx4 v[206:209], v[206:207], off
	v_add_u32_e32 v160, 0xe3800, v178
	v_lshl_add_u64 v[210:211], v[160:161], 1, s[8:9]
	global_load_dwordx4 v[210:213], v[210:211], off
	s_mov_b32 s20, s12
	s_mov_b32 s22, s14
	s_mov_b64 s[26:27], s[18:19]
	s_waitcnt vmcnt(12)
	v_lshlrev_b32_e32 v153, 16, v142
	v_lshlrev_b32_e32 v155, 16, v143
	v_lshlrev_b32_e32 v156, 16, v144
	v_and_b32_e32 v157, 0xffff0000, v144
	v_lshlrev_b32_e32 v158, 16, v145
	v_and_b32_e32 v159, 0xffff0000, v145
	v_mul_f32_e32 v144, 0xbfb8aa3b, v153
	v_mul_f32_e32 v145, 0xbfb8aa3b, v155
	v_exp_f32_e32 v154, v144
	v_exp_f32_e32 v155, v145
	v_mul_f32_e32 v145, 0xbfb8aa3b, v158
	v_and_b32_e32 v142, 0xffff0000, v142
	v_and_b32_e32 v143, 0xffff0000, v143
	v_pk_add_f32 v[154:155], v[154:155], 1.0 op_sel_hi:[1,0]
	v_mul_f32_e32 v142, 0xbfb8aa3b, v142
	v_mul_f32_e32 v143, 0xbfb8aa3b, v143
	v_mul_f32_e32 v144, 0xbfb8aa3b, v156
	v_exp_f32_e32 v156, v142
	v_mul_f32_e32 v142, 0xbfb8aa3b, v157
	v_exp_f32_e32 v157, v143
	v_mul_f32_e32 v143, 0xbfb8aa3b, v159
	v_rcp_f32_e32 v155, v155
	s_nop 0
	v_pk_add_f32 v[156:157], v[156:157], 1.0 op_sel_hi:[1,0]
	v_exp_f32_e32 v144, v144
	v_exp_f32_e32 v145, v145
	v_mov_b32_e32 v158, v126
	v_mov_b32_e32 v159, v128
	v_rcp_f32_e32 v154, v154
	s_nop 0
	v_pk_mul_f32 v[154:155], v[158:159], v[154:155]
	v_exp_f32_e32 v142, v142
	v_rcp_f32_e32 v157, v157
	s_nop 0
	v_exp_f32_e32 v143, v143
	v_rcp_f32_e32 v156, v156
	s_nop 0
	v_mov_b32_e32 v128, v127
	v_pk_mul_f32 v[126:127], v[128:129], v[156:157]
	v_cvt_pk_bf16_f32 v128, v154, v155
	v_cvt_pk_bf16_f32 v126, v126, v127
	v_and_b32_e32 v127, 0xffff0000, v126
	v_lshlrev_b32_e32 v126, 16, v126
	v_or_b32_sdwa v127, v127, v128 dst_sel:DWORD dst_unused:UNUSED_PAD src0_sel:DWORD src1_sel:WORD_1
	v_or_b32_sdwa v126, v126, v128 dst_sel:DWORD dst_unused:UNUSED_PAD src0_sel:DWORD src1_sel:WORD_0
	v_pk_add_f32 v[128:129], v[144:145], 1.0 op_sel_hi:[1,0]
	v_pk_add_f32 v[142:143], v[142:143], 1.0 op_sel_hi:[1,0]
	s_nop 0
	v_rcp_f32_e32 v129, v129
	s_nop 0
	s_nop 0
	v_rcp_f32_e32 v128, v128
	s_nop 0
	v_mov_b32_e32 v144, v122
	v_mov_b32_e32 v145, v124
	v_pk_mul_f32 v[128:129], v[144:145], v[128:129]
	v_rcp_f32_e32 v143, v143
	s_nop 0
	s_nop 0
	v_rcp_f32_e32 v142, v142
	s_nop 0
	v_mov_b32_e32 v124, v123
	v_pk_mul_f32 v[122:123], v[124:125], v[142:143]
	v_cvt_pk_bf16_f32 v124, v128, v129
	v_cvt_pk_bf16_f32 v122, v122, v123
	v_and_b32_e32 v123, 0xffff0000, v122
	v_lshlrev_b32_e32 v122, 16, v122
	v_or_b32_sdwa v129, v123, v124 dst_sel:DWORD dst_unused:UNUSED_PAD src0_sel:DWORD src1_sel:WORD_1
	v_or_b32_sdwa v128, v122, v124 dst_sel:DWORD dst_unused:UNUSED_PAD src0_sel:DWORD src1_sel:WORD_0
	v_mul_lo_u32 v124, v152, s61
	v_add_u32_e32 v0, v0, v124
	v_add_u32_e32 v125, 0x80, v150
	v_lshl_add_u64 v[122:123], v[0:1], 1, s[6:7]
	v_add_u32_e32 v0, v151, v125
	global_store_dwordx4 v[122:123], v[126:129], off
	v_add_u32_e32 v0, v0, v124
	s_waitcnt vmcnt(12)
	v_lshlrev_b32_e32 v122, 16, v162
	v_lshlrev_b32_e32 v143, 16, v163
	v_and_b32_e32 v144, 0xffff0000, v163
	v_lshlrev_b32_e32 v127, 16, v164
	v_mul_f32_e32 v122, 0xbfb8aa3b, v122
	v_and_b32_e32 v123, 0xffff0000, v162
	v_exp_f32_e32 v126, v122
	v_mul_f32_e32 v122, 0xbfb8aa3b, v127
	v_and_b32_e32 v145, 0xffff0000, v164
	v_exp_f32_e32 v128, v122
	v_mul_f32_e32 v122, 0xbfb8aa3b, v123
	v_mul_f32_e32 v123, 0xbfb8aa3b, v143
	v_exp_f32_e32 v127, v123
	v_lshlrev_b32_e32 v153, 16, v165
	v_mul_f32_e32 v123, 0xbfb8aa3b, v153
	v_and_b32_e32 v154, 0xffff0000, v165
	v_pk_add_f32 v[126:127], v[126:127], 1.0 op_sel_hi:[1,0]
	v_exp_f32_e32 v129, v123
	v_mul_f32_e32 v123, 0xbfb8aa3b, v144
	v_exp_f32_e32 v142, v122
	v_mul_f32_e32 v122, 0xbfb8aa3b, v145
	v_exp_f32_e32 v143, v123
	v_mul_f32_e32 v123, 0xbfb8aa3b, v154
	v_exp_f32_e32 v122, v122
	v_rcp_f32_e32 v127, v127
	s_nop 0
	v_pk_add_f32 v[142:143], v[142:143], 1.0 op_sel_hi:[1,0]
	v_exp_f32_e32 v123, v123
	v_rcp_f32_e32 v126, v126
	s_nop 0
	v_mov_b32_e32 v144, v118
	v_mov_b32_e32 v145, v120
	v_pk_mul_f32 v[126:127], v[144:145], v[126:127]
	v_pk_add_f32 v[122:123], v[122:123], 1.0 op_sel_hi:[1,0]
	v_rcp_f32_e32 v143, v143
	s_nop 0
	s_nop 0
	v_rcp_f32_e32 v142, v142
	s_nop 0
	v_mov_b32_e32 v120, v119
	v_pk_mul_f32 v[118:119], v[120:121], v[142:143]
	v_cvt_pk_bf16_f32 v120, v126, v127
	v_cvt_pk_bf16_f32 v118, v118, v119
	v_and_b32_e32 v119, 0xffff0000, v118
	v_lshlrev_b32_e32 v118, 16, v118
	v_or_b32_sdwa v119, v119, v120 dst_sel:DWORD dst_unused:UNUSED_PAD src0_sel:DWORD src1_sel:WORD_1
	v_or_b32_sdwa v118, v118, v120 dst_sel:DWORD dst_unused:UNUSED_PAD src0_sel:DWORD src1_sel:WORD_0
	v_pk_add_f32 v[120:121], v[128:129], 1.0 op_sel_hi:[1,0]
	s_nop 0
	s_nop 0
	v_rcp_f32_e32 v121, v121
	s_nop 0
	s_nop 0
	v_rcp_f32_e32 v120, v120
	s_nop 0
	v_mov_b32_e32 v126, v114
	v_mov_b32_e32 v127, v116
	v_pk_mul_f32 v[120:121], v[126:127], v[120:121]
	v_rcp_f32_e32 v123, v123
	s_nop 0
	s_nop 0
	v_rcp_f32_e32 v122, v122
	s_nop 0
	v_mov_b32_e32 v116, v115
	v_pk_mul_f32 v[114:115], v[116:117], v[122:123]
	v_cvt_pk_bf16_f32 v116, v120, v121
	v_cvt_pk_bf16_f32 v114, v114, v115
	v_and_b32_e32 v115, 0xffff0000, v114
	v_lshlrev_b32_e32 v114, 16, v114
	v_add_u32_e32 v127, 0x16c00, v151
	v_or_b32_sdwa v121, v115, v116 dst_sel:DWORD dst_unused:UNUSED_PAD src0_sel:DWORD src1_sel:WORD_1
	v_or_b32_sdwa v120, v114, v116 dst_sel:DWORD dst_unused:UNUSED_PAD src0_sel:DWORD src1_sel:WORD_0
	v_lshl_add_u64 v[114:115], v[0:1], 1, s[6:7]
	v_add_u32_e32 v0, v127, v150
	v_add_u32_e32 v160, 0xe3880, v178
	v_lshl_add_u64 v[162:163], v[160:161], 1, s[8:9]
	global_load_dwordx4 v[162:165], v[162:163], off
	global_store_dwordx4 v[114:115], v[118:121], off
	v_or_b32_e32 v126, 16, v152
	s_waitcnt vmcnt(13)
	v_lshlrev_b32_e32 v121, 16, v167
	v_and_b32_e32 v122, 0xffff0000, v167
	v_lshlrev_b32_e32 v115, 16, v168
	v_and_b32_e32 v119, 0xffff0000, v166
	v_mul_f32_e32 v115, 0xbfb8aa3b, v115
	v_lshlrev_b32_e32 v118, 16, v166
	v_and_b32_e32 v120, 0xffff0000, v168
	v_exp_f32_e32 v116, v115
	v_mul_f32_e32 v115, 0xbfb8aa3b, v119
	v_mul_f32_e32 v114, 0xbfb8aa3b, v118
	v_exp_f32_e32 v118, v115
	v_mul_f32_e32 v115, 0xbfb8aa3b, v120
	v_exp_f32_e32 v120, v115
	v_mul_f32_e32 v115, 0xbfb8aa3b, v121
	v_exp_f32_e32 v114, v114
	v_exp_f32_e32 v115, v115
	v_lshlrev_b32_e32 v123, 16, v169
	v_mul_f32_e32 v119, 0xbfb8aa3b, v122
	v_and_b32_e32 v128, 0xffff0000, v169
	v_pk_add_f32 v[114:115], v[114:115], 1.0 op_sel_hi:[1,0]
	v_mul_f32_e32 v117, 0xbfb8aa3b, v123
	v_mul_f32_e32 v121, 0xbfb8aa3b, v128
	v_exp_f32_e32 v119, v119
	v_exp_f32_e32 v117, v117
	v_rcp_f32_e32 v115, v115
	s_nop 0
	v_pk_add_f32 v[118:119], v[118:119], 1.0 op_sel_hi:[1,0]
	v_exp_f32_e32 v121, v121
	v_rcp_f32_e32 v114, v114
	s_nop 0
	v_mov_b32_e32 v122, v110
	v_mov_b32_e32 v123, v112
	v_pk_mul_f32 v[114:115], v[122:123], v[114:115]
	v_rcp_f32_e32 v119, v119
	s_nop 0
	s_nop 0
	v_rcp_f32_e32 v118, v118
	s_nop 0
	v_mov_b32_e32 v112, v111
	v_pk_mul_f32 v[110:111], v[112:113], v[118:119]
	v_cvt_pk_bf16_f32 v112, v114, v115
	v_cvt_pk_bf16_f32 v110, v110, v111
	v_and_b32_e32 v111, 0xffff0000, v110
	v_lshlrev_b32_e32 v110, 16, v110
	v_or_b32_sdwa v111, v111, v112 dst_sel:DWORD dst_unused:UNUSED_PAD src0_sel:DWORD src1_sel:WORD_1
	v_or_b32_sdwa v110, v110, v112 dst_sel:DWORD dst_unused:UNUSED_PAD src0_sel:DWORD src1_sel:WORD_0
	v_pk_add_f32 v[112:113], v[116:117], 1.0 op_sel_hi:[1,0]
	s_nop 0
	s_nop 0
	v_rcp_f32_e32 v113, v113
	s_nop 0
	s_nop 0
	v_rcp_f32_e32 v112, v112
	s_nop 0
	v_mov_b32_e32 v114, v106
	v_mov_b32_e32 v115, v108
	v_pk_mul_f32 v[112:113], v[114:115], v[112:113]
	v_pk_add_f32 v[114:115], v[120:121], 1.0 op_sel_hi:[1,0]
	s_nop 0
	s_nop 0
	v_rcp_f32_e32 v115, v115
	s_nop 0
	s_nop 0
	v_rcp_f32_e32 v114, v114
	s_nop 0
	v_mov_b32_e32 v108, v107
	v_pk_mul_f32 v[106:107], v[108:109], v[114:115]
	v_mul_lo_u32 v116, v126, s61
	v_cvt_pk_bf16_f32 v106, v106, v107
	v_cvt_pk_bf16_f32 v108, v112, v113
	v_and_b32_e32 v107, 0xffff0000, v106
	v_lshlrev_b32_e32 v106, 16, v106
	v_add_u32_e32 v0, v0, v116
	v_or_b32_sdwa v113, v107, v108 dst_sel:DWORD dst_unused:UNUSED_PAD src0_sel:DWORD src1_sel:WORD_1
	v_or_b32_sdwa v112, v106, v108 dst_sel:DWORD dst_unused:UNUSED_PAD src0_sel:DWORD src1_sel:WORD_0
	v_lshl_add_u64 v[106:107], v[0:1], 1, s[6:7]
	v_add_u32_e32 v0, v127, v125
	v_add_u32_e32 v160, 0xfa400, v178
	v_lshl_add_u64 v[166:167], v[160:161], 1, s[8:9]
	global_load_dwordx4 v[166:169], v[166:167], off
	global_store_dwordx4 v[106:107], v[110:113], off
	v_add_u32_e32 v0, v0, v116
	s_waitcnt vmcnt(14)
	v_lshlrev_b32_e32 v113, 16, v171
	v_and_b32_e32 v114, 0xffff0000, v171
	v_lshlrev_b32_e32 v107, 16, v172
	v_and_b32_e32 v111, 0xffff0000, v170
	v_mul_f32_e32 v107, 0xbfb8aa3b, v107
	v_lshlrev_b32_e32 v110, 16, v170
	v_and_b32_e32 v112, 0xffff0000, v172
	v_exp_f32_e32 v108, v107
	v_mul_f32_e32 v107, 0xbfb8aa3b, v111
	v_mul_f32_e32 v106, 0xbfb8aa3b, v110
	v_exp_f32_e32 v110, v107
	v_mul_f32_e32 v107, 0xbfb8aa3b, v112
	v_exp_f32_e32 v112, v107
	v_mul_f32_e32 v107, 0xbfb8aa3b, v113
	v_exp_f32_e32 v106, v106
	v_exp_f32_e32 v107, v107
	v_lshlrev_b32_e32 v115, 16, v173
	v_mul_f32_e32 v111, 0xbfb8aa3b, v114
	v_and_b32_e32 v117, 0xffff0000, v173
	v_pk_add_f32 v[106:107], v[106:107], 1.0 op_sel_hi:[1,0]
	v_mul_f32_e32 v109, 0xbfb8aa3b, v115
	v_mul_f32_e32 v113, 0xbfb8aa3b, v117
	v_exp_f32_e32 v111, v111
	v_exp_f32_e32 v109, v109
	v_rcp_f32_e32 v107, v107
	s_nop 0
	v_pk_add_f32 v[110:111], v[110:111], 1.0 op_sel_hi:[1,0]
	v_exp_f32_e32 v113, v113
	v_rcp_f32_e32 v106, v106
	s_nop 0
	v_mov_b32_e32 v114, v102
	v_mov_b32_e32 v115, v104
	v_pk_mul_f32 v[106:107], v[114:115], v[106:107]
	v_rcp_f32_e32 v111, v111
	s_nop 0
	s_nop 0
	v_rcp_f32_e32 v110, v110
	s_nop 0
	v_mov_b32_e32 v104, v103
	v_pk_mul_f32 v[102:103], v[104:105], v[110:111]
	v_cvt_pk_bf16_f32 v104, v106, v107
	v_cvt_pk_bf16_f32 v102, v102, v103
	v_and_b32_e32 v103, 0xffff0000, v102
	v_lshlrev_b32_e32 v102, 16, v102
	v_or_b32_sdwa v103, v103, v104 dst_sel:DWORD dst_unused:UNUSED_PAD src0_sel:DWORD src1_sel:WORD_1
	v_or_b32_sdwa v102, v102, v104 dst_sel:DWORD dst_unused:UNUSED_PAD src0_sel:DWORD src1_sel:WORD_0
	v_pk_add_f32 v[104:105], v[108:109], 1.0 op_sel_hi:[1,0]
	s_nop 0
	s_nop 0
	v_rcp_f32_e32 v105, v105
	s_nop 0
	s_nop 0
	v_rcp_f32_e32 v104, v104
	s_nop 0
	v_mov_b32_e32 v106, v98
	v_mov_b32_e32 v107, v100
	v_pk_mul_f32 v[104:105], v[106:107], v[104:105]
	v_pk_add_f32 v[106:107], v[112:113], 1.0 op_sel_hi:[1,0]
	s_nop 0
	s_nop 0
	v_rcp_f32_e32 v107, v107
	s_nop 0
	s_nop 0
	v_rcp_f32_e32 v106, v106
	s_nop 0
	v_mov_b32_e32 v100, v99
	v_pk_mul_f32 v[98:99], v[100:101], v[106:107]
	v_cvt_pk_bf16_f32 v100, v104, v105
	v_cvt_pk_bf16_f32 v98, v98, v99
	v_and_b32_e32 v99, 0xffff0000, v98
	v_lshlrev_b32_e32 v98, 16, v98
	v_add_u32_e32 v109, 0x2d800, v151
	v_or_b32_sdwa v105, v99, v100 dst_sel:DWORD dst_unused:UNUSED_PAD src0_sel:DWORD src1_sel:WORD_1
	v_or_b32_sdwa v104, v98, v100 dst_sel:DWORD dst_unused:UNUSED_PAD src0_sel:DWORD src1_sel:WORD_0
	v_lshl_add_u64 v[98:99], v[0:1], 1, s[6:7]
	v_add_u32_e32 v0, v109, v150
	v_add_u32_e32 v160, 0xfa480, v178
	v_lshl_add_u64 v[170:171], v[160:161], 1, s[8:9]
	global_load_dwordx4 v[170:173], v[170:171], off
	global_store_dwordx4 v[98:99], v[102:105], off
	v_or_b32_e32 v108, 32, v152
	s_waitcnt vmcnt(15)
	v_lshlrev_b32_e32 v105, 16, v175
	v_and_b32_e32 v106, 0xffff0000, v175
	v_lshlrev_b32_e32 v99, 16, v176
	v_and_b32_e32 v103, 0xffff0000, v174
	v_mul_f32_e32 v99, 0xbfb8aa3b, v99
	v_lshlrev_b32_e32 v102, 16, v174
	v_and_b32_e32 v104, 0xffff0000, v176
	v_exp_f32_e32 v100, v99
	v_mul_f32_e32 v99, 0xbfb8aa3b, v103
	v_mul_f32_e32 v98, 0xbfb8aa3b, v102
	v_exp_f32_e32 v102, v99
	v_mul_f32_e32 v99, 0xbfb8aa3b, v104
	v_exp_f32_e32 v104, v99
	v_mul_f32_e32 v99, 0xbfb8aa3b, v105
	v_exp_f32_e32 v98, v98
	v_exp_f32_e32 v99, v99
	v_lshlrev_b32_e32 v107, 16, v177
	v_mul_f32_e32 v103, 0xbfb8aa3b, v106
	v_and_b32_e32 v110, 0xffff0000, v177
	v_pk_add_f32 v[98:99], v[98:99], 1.0 op_sel_hi:[1,0]
	v_mul_f32_e32 v101, 0xbfb8aa3b, v107
	v_mul_f32_e32 v105, 0xbfb8aa3b, v110
	v_exp_f32_e32 v103, v103
	v_exp_f32_e32 v101, v101
	v_rcp_f32_e32 v99, v99
	s_nop 0
	v_pk_add_f32 v[102:103], v[102:103], 1.0 op_sel_hi:[1,0]
	v_exp_f32_e32 v105, v105
	v_rcp_f32_e32 v98, v98
	s_nop 0
	v_mov_b32_e32 v106, v94
	v_mov_b32_e32 v107, v96
	v_pk_mul_f32 v[98:99], v[106:107], v[98:99]
	v_rcp_f32_e32 v103, v103
	s_nop 0
	s_nop 0
	v_rcp_f32_e32 v102, v102
	s_nop 0
	v_mov_b32_e32 v96, v95
	v_pk_mul_f32 v[94:95], v[96:97], v[102:103]
	v_cvt_pk_bf16_f32 v96, v98, v99
	v_cvt_pk_bf16_f32 v94, v94, v95
	v_and_b32_e32 v95, 0xffff0000, v94
	v_lshlrev_b32_e32 v94, 16, v94
	v_or_b32_sdwa v95, v95, v96 dst_sel:DWORD dst_unused:UNUSED_PAD src0_sel:DWORD src1_sel:WORD_1
	v_or_b32_sdwa v94, v94, v96 dst_sel:DWORD dst_unused:UNUSED_PAD src0_sel:DWORD src1_sel:WORD_0
	v_pk_add_f32 v[96:97], v[100:101], 1.0 op_sel_hi:[1,0]
	s_nop 0
	s_nop 0
	v_rcp_f32_e32 v97, v97
	s_nop 0
	s_nop 0
	v_rcp_f32_e32 v96, v96
	s_nop 0
	v_mov_b32_e32 v98, v90
	v_mov_b32_e32 v99, v92
	v_pk_mul_f32 v[96:97], v[98:99], v[96:97]
	v_pk_add_f32 v[98:99], v[104:105], 1.0 op_sel_hi:[1,0]
	s_nop 0
	s_nop 0
	v_rcp_f32_e32 v99, v99
	s_nop 0
	s_nop 0
	v_rcp_f32_e32 v98, v98
	s_nop 0
	v_mov_b32_e32 v92, v91
	v_pk_mul_f32 v[90:91], v[92:93], v[98:99]
	v_mul_lo_u32 v100, v108, s61
	v_cvt_pk_bf16_f32 v90, v90, v91
	v_cvt_pk_bf16_f32 v92, v96, v97
	v_and_b32_e32 v91, 0xffff0000, v90
	v_lshlrev_b32_e32 v90, 16, v90
	v_add_u32_e32 v0, v0, v100
	v_or_b32_sdwa v97, v91, v92 dst_sel:DWORD dst_unused:UNUSED_PAD src0_sel:DWORD src1_sel:WORD_1
	v_or_b32_sdwa v96, v90, v92 dst_sel:DWORD dst_unused:UNUSED_PAD src0_sel:DWORD src1_sel:WORD_0
	v_lshl_add_u64 v[90:91], v[0:1], 1, s[6:7]
	v_add_u32_e32 v0, v109, v125
	global_store_dwordx4 v[90:91], v[94:97], off
	v_add_u32_e32 v0, v0, v100
	s_waitcnt vmcnt(15)
	v_lshlrev_b32_e32 v97, 16, v183
	v_and_b32_e32 v98, 0xffff0000, v183
	v_lshlrev_b32_e32 v91, 16, v184
	v_and_b32_e32 v95, 0xffff0000, v182
	v_mul_f32_e32 v91, 0xbfb8aa3b, v91
	v_lshlrev_b32_e32 v94, 16, v182
	v_and_b32_e32 v96, 0xffff0000, v184
	v_exp_f32_e32 v92, v91
	v_mul_f32_e32 v91, 0xbfb8aa3b, v95
	v_mul_f32_e32 v90, 0xbfb8aa3b, v94
	v_exp_f32_e32 v94, v91
	v_mul_f32_e32 v91, 0xbfb8aa3b, v96
	v_exp_f32_e32 v96, v91
	v_mul_f32_e32 v91, 0xbfb8aa3b, v97
	v_exp_f32_e32 v90, v90
	v_exp_f32_e32 v91, v91
	v_lshlrev_b32_e32 v99, 16, v185
	v_mul_f32_e32 v95, 0xbfb8aa3b, v98
	v_and_b32_e32 v101, 0xffff0000, v185
	v_pk_add_f32 v[90:91], v[90:91], 1.0 op_sel_hi:[1,0]
	v_mul_f32_e32 v93, 0xbfb8aa3b, v99
	v_mul_f32_e32 v97, 0xbfb8aa3b, v101
	v_exp_f32_e32 v95, v95
	v_exp_f32_e32 v93, v93
	v_rcp_f32_e32 v91, v91
	s_nop 0
	v_pk_add_f32 v[94:95], v[94:95], 1.0 op_sel_hi:[1,0]
	v_exp_f32_e32 v97, v97
	v_rcp_f32_e32 v90, v90
	s_nop 0
	v_mov_b32_e32 v98, v86
	v_mov_b32_e32 v99, v88
	v_pk_mul_f32 v[90:91], v[98:99], v[90:91]
	v_rcp_f32_e32 v95, v95
	s_nop 0
	s_nop 0
	v_rcp_f32_e32 v94, v94
	s_nop 0
	v_mov_b32_e32 v88, v87
	v_pk_mul_f32 v[86:87], v[88:89], v[94:95]
	v_cvt_pk_bf16_f32 v88, v90, v91
	v_cvt_pk_bf16_f32 v86, v86, v87
	v_and_b32_e32 v87, 0xffff0000, v86
	v_lshlrev_b32_e32 v86, 16, v86
	v_or_b32_sdwa v87, v87, v88 dst_sel:DWORD dst_unused:UNUSED_PAD src0_sel:DWORD src1_sel:WORD_1
	v_or_b32_sdwa v86, v86, v88 dst_sel:DWORD dst_unused:UNUSED_PAD src0_sel:DWORD src1_sel:WORD_0
	v_pk_add_f32 v[88:89], v[92:93], 1.0 op_sel_hi:[1,0]
	s_nop 0
	s_nop 0
	v_rcp_f32_e32 v89, v89
	s_nop 0
	s_nop 0
	v_rcp_f32_e32 v88, v88
	s_nop 0
	v_mov_b32_e32 v90, v82
	v_mov_b32_e32 v91, v84
	v_pk_mul_f32 v[88:89], v[90:91], v[88:89]
	v_pk_add_f32 v[90:91], v[96:97], 1.0 op_sel_hi:[1,0]
	s_nop 0
	s_nop 0
	v_rcp_f32_e32 v91, v91
	s_nop 0
	s_nop 0
	v_rcp_f32_e32 v90, v90
	s_nop 0
	v_mov_b32_e32 v84, v83
	v_pk_mul_f32 v[82:83], v[84:85], v[90:91]
	v_cvt_pk_bf16_f32 v84, v88, v89
	v_cvt_pk_bf16_f32 v82, v82, v83
	v_and_b32_e32 v83, 0xffff0000, v82
	v_lshlrev_b32_e32 v82, 16, v82
	v_add_u32_e32 v93, 0x44400, v151
	v_or_b32_sdwa v89, v83, v84 dst_sel:DWORD dst_unused:UNUSED_PAD src0_sel:DWORD src1_sel:WORD_1
	v_or_b32_sdwa v88, v82, v84 dst_sel:DWORD dst_unused:UNUSED_PAD src0_sel:DWORD src1_sel:WORD_0
	v_lshl_add_u64 v[82:83], v[0:1], 1, s[6:7]
	v_add_u32_e32 v0, v93, v150
	global_store_dwordx4 v[82:83], v[86:89], off
	v_or_b32_e32 v92, 48, v152
	s_waitcnt vmcnt(15)
	v_lshlrev_b32_e32 v89, 16, v187
	v_and_b32_e32 v90, 0xffff0000, v187
	v_lshlrev_b32_e32 v83, 16, v188
	v_and_b32_e32 v87, 0xffff0000, v186
	v_mul_f32_e32 v83, 0xbfb8aa3b, v83
	v_lshlrev_b32_e32 v86, 16, v186
	v_and_b32_e32 v88, 0xffff0000, v188
	v_exp_f32_e32 v84, v83
	v_mul_f32_e32 v83, 0xbfb8aa3b, v87
	v_mul_f32_e32 v82, 0xbfb8aa3b, v86
	v_exp_f32_e32 v86, v83
	v_mul_f32_e32 v83, 0xbfb8aa3b, v88
	v_exp_f32_e32 v88, v83
	v_mul_f32_e32 v83, 0xbfb8aa3b, v89
	v_exp_f32_e32 v82, v82
	v_exp_f32_e32 v83, v83
	v_lshlrev_b32_e32 v91, 16, v189
	v_mul_f32_e32 v87, 0xbfb8aa3b, v90
	v_and_b32_e32 v94, 0xffff0000, v189
	v_pk_add_f32 v[82:83], v[82:83], 1.0 op_sel_hi:[1,0]
	v_mul_f32_e32 v85, 0xbfb8aa3b, v91
	v_mul_f32_e32 v89, 0xbfb8aa3b, v94
	v_exp_f32_e32 v87, v87
	v_exp_f32_e32 v85, v85
	v_rcp_f32_e32 v83, v83
	s_nop 0
	v_pk_add_f32 v[86:87], v[86:87], 1.0 op_sel_hi:[1,0]
	v_exp_f32_e32 v89, v89
	v_rcp_f32_e32 v82, v82
	s_nop 0
	v_mov_b32_e32 v90, v78
	v_mov_b32_e32 v91, v80
	v_pk_mul_f32 v[82:83], v[90:91], v[82:83]
	v_rcp_f32_e32 v87, v87
	s_nop 0
	s_nop 0
	v_rcp_f32_e32 v86, v86
	s_nop 0
	v_mov_b32_e32 v80, v79
	v_pk_mul_f32 v[78:79], v[80:81], v[86:87]
	v_cvt_pk_bf16_f32 v80, v82, v83
	v_cvt_pk_bf16_f32 v78, v78, v79
	v_and_b32_e32 v79, 0xffff0000, v78
	v_lshlrev_b32_e32 v78, 16, v78
	v_or_b32_sdwa v79, v79, v80 dst_sel:DWORD dst_unused:UNUSED_PAD src0_sel:DWORD src1_sel:WORD_1
	v_or_b32_sdwa v78, v78, v80 dst_sel:DWORD dst_unused:UNUSED_PAD src0_sel:DWORD src1_sel:WORD_0
	v_pk_add_f32 v[80:81], v[84:85], 1.0 op_sel_hi:[1,0]
	s_nop 0
	s_nop 0
	v_rcp_f32_e32 v81, v81
	s_nop 0
	s_nop 0
	v_rcp_f32_e32 v80, v80
	s_nop 0
	v_mov_b32_e32 v82, v74
	v_mov_b32_e32 v83, v76
	v_pk_mul_f32 v[80:81], v[82:83], v[80:81]
	v_pk_add_f32 v[82:83], v[88:89], 1.0 op_sel_hi:[1,0]
	s_nop 0
	s_nop 0
	v_rcp_f32_e32 v83, v83
	s_nop 0
	s_nop 0
	v_rcp_f32_e32 v82, v82
	s_nop 0
	v_mov_b32_e32 v76, v75
	v_pk_mul_f32 v[74:75], v[76:77], v[82:83]
	v_mul_lo_u32 v84, v92, s61
	v_cvt_pk_bf16_f32 v74, v74, v75
	v_cvt_pk_bf16_f32 v76, v80, v81
	v_and_b32_e32 v75, 0xffff0000, v74
	v_lshlrev_b32_e32 v74, 16, v74
	v_add_u32_e32 v0, v0, v84
	v_or_b32_sdwa v81, v75, v76 dst_sel:DWORD dst_unused:UNUSED_PAD src0_sel:DWORD src1_sel:WORD_1
	v_or_b32_sdwa v80, v74, v76 dst_sel:DWORD dst_unused:UNUSED_PAD src0_sel:DWORD src1_sel:WORD_0
	v_lshl_add_u64 v[74:75], v[0:1], 1, s[6:7]
	v_add_u32_e32 v0, v93, v125
	global_store_dwordx4 v[74:75], v[78:81], off
	v_add_u32_e32 v0, v0, v84
	s_waitcnt vmcnt(15)
	v_lshlrev_b32_e32 v81, 16, v191
	v_and_b32_e32 v82, 0xffff0000, v191
	v_lshlrev_b32_e32 v75, 16, v192
	v_and_b32_e32 v79, 0xffff0000, v190
	v_mul_f32_e32 v75, 0xbfb8aa3b, v75
	v_lshlrev_b32_e32 v78, 16, v190
	v_and_b32_e32 v80, 0xffff0000, v192
	v_exp_f32_e32 v76, v75
	v_mul_f32_e32 v75, 0xbfb8aa3b, v79
	v_mul_f32_e32 v74, 0xbfb8aa3b, v78
	v_exp_f32_e32 v78, v75
	v_mul_f32_e32 v75, 0xbfb8aa3b, v80
	v_exp_f32_e32 v80, v75
	v_mul_f32_e32 v75, 0xbfb8aa3b, v81
	v_exp_f32_e32 v74, v74
	v_exp_f32_e32 v75, v75
	v_lshlrev_b32_e32 v83, 16, v193
	v_mul_f32_e32 v79, 0xbfb8aa3b, v82
	v_and_b32_e32 v85, 0xffff0000, v193
	v_pk_add_f32 v[74:75], v[74:75], 1.0 op_sel_hi:[1,0]
	v_mul_f32_e32 v77, 0xbfb8aa3b, v83
	v_mul_f32_e32 v81, 0xbfb8aa3b, v85
	v_exp_f32_e32 v79, v79
	v_exp_f32_e32 v77, v77
	v_rcp_f32_e32 v75, v75
	s_nop 0
	v_pk_add_f32 v[78:79], v[78:79], 1.0 op_sel_hi:[1,0]
	v_exp_f32_e32 v81, v81
	v_rcp_f32_e32 v74, v74
	s_nop 0
	v_mov_b32_e32 v82, v70
	v_mov_b32_e32 v83, v72
	v_pk_mul_f32 v[74:75], v[82:83], v[74:75]
	v_rcp_f32_e32 v79, v79
	s_nop 0
	s_nop 0
	v_rcp_f32_e32 v78, v78
	s_nop 0
	v_mov_b32_e32 v72, v71
	v_pk_mul_f32 v[70:71], v[72:73], v[78:79]
	v_cvt_pk_bf16_f32 v72, v74, v75
	v_cvt_pk_bf16_f32 v70, v70, v71
	v_and_b32_e32 v71, 0xffff0000, v70
	v_lshlrev_b32_e32 v70, 16, v70
	v_or_b32_sdwa v71, v71, v72 dst_sel:DWORD dst_unused:UNUSED_PAD src0_sel:DWORD src1_sel:WORD_1
	v_or_b32_sdwa v70, v70, v72 dst_sel:DWORD dst_unused:UNUSED_PAD src0_sel:DWORD src1_sel:WORD_0
	v_pk_add_f32 v[72:73], v[76:77], 1.0 op_sel_hi:[1,0]
	s_nop 0
	s_nop 0
	v_rcp_f32_e32 v73, v73
	s_nop 0
	s_nop 0
	v_rcp_f32_e32 v72, v72
	s_nop 0
	v_mov_b32_e32 v74, v66
	v_mov_b32_e32 v75, v68
	v_pk_mul_f32 v[72:73], v[74:75], v[72:73]
	v_pk_add_f32 v[74:75], v[80:81], 1.0 op_sel_hi:[1,0]
	s_nop 0
	s_nop 0
	v_rcp_f32_e32 v75, v75
	s_nop 0
	s_nop 0
	v_rcp_f32_e32 v74, v74
	s_nop 0
	v_mov_b32_e32 v68, v67
	v_pk_mul_f32 v[66:67], v[68:69], v[74:75]
	v_cvt_pk_bf16_f32 v68, v72, v73
	v_cvt_pk_bf16_f32 v66, v66, v67
	v_and_b32_e32 v67, 0xffff0000, v66
	v_lshlrev_b32_e32 v66, 16, v66
	v_add_u32_e32 v76, 0xb6000, v151
	v_or_b32_sdwa v73, v67, v68 dst_sel:DWORD dst_unused:UNUSED_PAD src0_sel:DWORD src1_sel:WORD_1
	v_or_b32_sdwa v72, v66, v68 dst_sel:DWORD dst_unused:UNUSED_PAD src0_sel:DWORD src1_sel:WORD_0
	v_lshl_add_u64 v[66:67], v[0:1], 1, s[6:7]
	v_add_u32_e32 v0, v76, v150
	global_store_dwordx4 v[66:67], v[70:73], off
	s_nop 1
	s_waitcnt vmcnt(15)
	v_lshlrev_b32_e32 v73, 16, v195
	v_and_b32_e32 v74, 0xffff0000, v195
	v_lshlrev_b32_e32 v67, 16, v196
	v_and_b32_e32 v71, 0xffff0000, v194
	v_mul_f32_e32 v67, 0xbfb8aa3b, v67
	v_lshlrev_b32_e32 v70, 16, v194
	v_and_b32_e32 v72, 0xffff0000, v196
	v_exp_f32_e32 v68, v67
	v_mul_f32_e32 v67, 0xbfb8aa3b, v71
	v_mul_f32_e32 v66, 0xbfb8aa3b, v70
	v_exp_f32_e32 v70, v67
	v_mul_f32_e32 v67, 0xbfb8aa3b, v72
	v_exp_f32_e32 v72, v67
	v_mul_f32_e32 v67, 0xbfb8aa3b, v73
	v_exp_f32_e32 v66, v66
	v_exp_f32_e32 v67, v67
	v_lshlrev_b32_e32 v75, 16, v197
	v_mul_f32_e32 v71, 0xbfb8aa3b, v74
	v_and_b32_e32 v77, 0xffff0000, v197
	v_pk_add_f32 v[66:67], v[66:67], 1.0 op_sel_hi:[1,0]
	v_mul_f32_e32 v69, 0xbfb8aa3b, v75
	v_mul_f32_e32 v73, 0xbfb8aa3b, v77
	v_exp_f32_e32 v71, v71
	v_exp_f32_e32 v69, v69
	v_rcp_f32_e32 v67, v67
	s_nop 0
	v_pk_add_f32 v[70:71], v[70:71], 1.0 op_sel_hi:[1,0]
	v_exp_f32_e32 v73, v73
	v_rcp_f32_e32 v66, v66
	s_nop 0
	v_mov_b32_e32 v74, v62
	v_mov_b32_e32 v75, v64
	v_pk_mul_f32 v[66:67], v[74:75], v[66:67]
	v_rcp_f32_e32 v71, v71
	s_nop 0
	s_nop 0
	v_rcp_f32_e32 v70, v70
	s_nop 0
	v_mov_b32_e32 v64, v63
	v_pk_mul_f32 v[62:63], v[64:65], v[70:71]
	v_cvt_pk_bf16_f32 v64, v66, v67
	v_cvt_pk_bf16_f32 v62, v62, v63
	v_and_b32_e32 v63, 0xffff0000, v62
	v_lshlrev_b32_e32 v62, 16, v62
	v_or_b32_sdwa v63, v63, v64 dst_sel:DWORD dst_unused:UNUSED_PAD src0_sel:DWORD src1_sel:WORD_1
	v_or_b32_sdwa v62, v62, v64 dst_sel:DWORD dst_unused:UNUSED_PAD src0_sel:DWORD src1_sel:WORD_0
	v_pk_add_f32 v[64:65], v[68:69], 1.0 op_sel_hi:[1,0]
	s_nop 0
	s_nop 0
	v_rcp_f32_e32 v65, v65
	s_nop 0
	s_nop 0
	v_rcp_f32_e32 v64, v64
	s_nop 0
	v_mov_b32_e32 v66, v58
	v_mov_b32_e32 v67, v60
	v_pk_mul_f32 v[64:65], v[66:67], v[64:65]
	v_pk_add_f32 v[66:67], v[72:73], 1.0 op_sel_hi:[1,0]
	s_nop 0
	s_nop 0
	v_rcp_f32_e32 v67, v67
	s_nop 0
	s_nop 0
	v_rcp_f32_e32 v66, v66
	s_nop 0
	v_mov_b32_e32 v60, v59
	v_pk_mul_f32 v[58:59], v[60:61], v[66:67]
	v_add_u32_e32 v68, 0xfff6a000, v124
	v_cvt_pk_bf16_f32 v58, v58, v59
	v_cvt_pk_bf16_f32 v60, v64, v65
	v_and_b32_e32 v59, 0xffff0000, v58
	v_lshlrev_b32_e32 v58, 16, v58
	v_add_u32_e32 v0, v0, v68
	v_or_b32_sdwa v65, v59, v60 dst_sel:DWORD dst_unused:UNUSED_PAD src0_sel:DWORD src1_sel:WORD_1
	v_or_b32_sdwa v64, v58, v60 dst_sel:DWORD dst_unused:UNUSED_PAD src0_sel:DWORD src1_sel:WORD_0
	v_lshl_add_u64 v[58:59], v[0:1], 1, s[6:7]
	v_add_u32_e32 v0, v76, v125
	global_store_dwordx4 v[58:59], v[62:65], off
	v_add_u32_e32 v0, v0, v68
	s_waitcnt vmcnt(15)
	v_lshlrev_b32_e32 v65, 16, v199
	v_and_b32_e32 v66, 0xffff0000, v199
	v_lshlrev_b32_e32 v59, 16, v200
	v_and_b32_e32 v63, 0xffff0000, v198
	v_mul_f32_e32 v59, 0xbfb8aa3b, v59
	v_lshlrev_b32_e32 v62, 16, v198
	v_and_b32_e32 v64, 0xffff0000, v200
	v_exp_f32_e32 v60, v59
	v_mul_f32_e32 v59, 0xbfb8aa3b, v63
	v_mul_f32_e32 v58, 0xbfb8aa3b, v62
	v_exp_f32_e32 v62, v59
	v_mul_f32_e32 v59, 0xbfb8aa3b, v64
	v_exp_f32_e32 v64, v59
	v_mul_f32_e32 v59, 0xbfb8aa3b, v65
	v_exp_f32_e32 v58, v58
	v_exp_f32_e32 v59, v59
	v_lshlrev_b32_e32 v67, 16, v201
	v_mul_f32_e32 v63, 0xbfb8aa3b, v66
	v_and_b32_e32 v69, 0xffff0000, v201
	v_pk_add_f32 v[58:59], v[58:59], 1.0 op_sel_hi:[1,0]
	v_mul_f32_e32 v61, 0xbfb8aa3b, v67
	v_mul_f32_e32 v65, 0xbfb8aa3b, v69
	v_exp_f32_e32 v63, v63
	v_exp_f32_e32 v61, v61
	v_rcp_f32_e32 v59, v59
	s_nop 0
	v_pk_add_f32 v[62:63], v[62:63], 1.0 op_sel_hi:[1,0]
	v_exp_f32_e32 v65, v65
	v_rcp_f32_e32 v58, v58
	s_nop 0
	v_mov_b32_e32 v66, v54
	v_mov_b32_e32 v67, v56
	v_pk_mul_f32 v[58:59], v[66:67], v[58:59]
	v_rcp_f32_e32 v63, v63
	s_nop 0
	s_nop 0
	v_rcp_f32_e32 v62, v62
	s_nop 0
	v_mov_b32_e32 v56, v55
	v_pk_mul_f32 v[54:55], v[56:57], v[62:63]
	v_cvt_pk_bf16_f32 v56, v58, v59
	v_cvt_pk_bf16_f32 v54, v54, v55
	v_and_b32_e32 v55, 0xffff0000, v54
	v_lshlrev_b32_e32 v54, 16, v54
	v_or_b32_sdwa v55, v55, v56 dst_sel:DWORD dst_unused:UNUSED_PAD src0_sel:DWORD src1_sel:WORD_1
	v_or_b32_sdwa v54, v54, v56 dst_sel:DWORD dst_unused:UNUSED_PAD src0_sel:DWORD src1_sel:WORD_0
	v_pk_add_f32 v[56:57], v[60:61], 1.0 op_sel_hi:[1,0]
	s_nop 0
	s_nop 0
	v_rcp_f32_e32 v57, v57
	s_nop 0
	s_nop 0
	v_rcp_f32_e32 v56, v56
	s_nop 0
	v_mov_b32_e32 v58, v50
	v_mov_b32_e32 v59, v52
	v_pk_mul_f32 v[56:57], v[58:59], v[56:57]
	v_pk_add_f32 v[58:59], v[64:65], 1.0 op_sel_hi:[1,0]
	s_nop 0
	s_nop 0
	v_rcp_f32_e32 v59, v59
	s_nop 0
	s_nop 0
	v_rcp_f32_e32 v58, v58
	s_nop 0
	v_mov_b32_e32 v52, v51
	v_pk_mul_f32 v[50:51], v[52:53], v[58:59]
	v_cvt_pk_bf16_f32 v52, v56, v57
	v_cvt_pk_bf16_f32 v50, v50, v51
	v_and_b32_e32 v51, 0xffff0000, v50
	v_lshlrev_b32_e32 v50, 16, v50
	v_add_u32_e32 v60, 0xccc00, v151
	v_or_b32_sdwa v57, v51, v52 dst_sel:DWORD dst_unused:UNUSED_PAD src0_sel:DWORD src1_sel:WORD_1
	v_or_b32_sdwa v56, v50, v52 dst_sel:DWORD dst_unused:UNUSED_PAD src0_sel:DWORD src1_sel:WORD_0
	v_lshl_add_u64 v[50:51], v[0:1], 1, s[6:7]
	v_add_u32_e32 v0, v60, v150
	global_store_dwordx4 v[50:51], v[54:57], off
	s_nop 1
	s_waitcnt vmcnt(15)
	v_lshlrev_b32_e32 v57, 16, v203
	v_and_b32_e32 v58, 0xffff0000, v203
	v_lshlrev_b32_e32 v51, 16, v204
	v_and_b32_e32 v55, 0xffff0000, v202
	v_mul_f32_e32 v51, 0xbfb8aa3b, v51
	v_lshlrev_b32_e32 v54, 16, v202
	v_and_b32_e32 v56, 0xffff0000, v204
	v_exp_f32_e32 v52, v51
	v_mul_f32_e32 v51, 0xbfb8aa3b, v55
	v_mul_f32_e32 v50, 0xbfb8aa3b, v54
	v_exp_f32_e32 v54, v51
	v_mul_f32_e32 v51, 0xbfb8aa3b, v56
	v_exp_f32_e32 v56, v51
	v_mul_f32_e32 v51, 0xbfb8aa3b, v57
	v_exp_f32_e32 v50, v50
	v_exp_f32_e32 v51, v51
	v_lshlrev_b32_e32 v59, 16, v205
	v_mul_f32_e32 v55, 0xbfb8aa3b, v58
	v_and_b32_e32 v61, 0xffff0000, v205
	v_pk_add_f32 v[50:51], v[50:51], 1.0 op_sel_hi:[1,0]
	v_mul_f32_e32 v53, 0xbfb8aa3b, v59
	v_mul_f32_e32 v57, 0xbfb8aa3b, v61
	v_exp_f32_e32 v55, v55
	v_exp_f32_e32 v53, v53
	v_rcp_f32_e32 v51, v51
	s_nop 0
	v_pk_add_f32 v[54:55], v[54:55], 1.0 op_sel_hi:[1,0]
	v_exp_f32_e32 v57, v57
	v_rcp_f32_e32 v50, v50
	s_nop 0
	v_mov_b32_e32 v58, v46
	v_mov_b32_e32 v59, v48
	v_pk_mul_f32 v[50:51], v[58:59], v[50:51]
	v_rcp_f32_e32 v55, v55
	s_nop 0
	s_nop 0
	v_rcp_f32_e32 v54, v54
	s_nop 0
	v_mov_b32_e32 v48, v47
	v_pk_mul_f32 v[46:47], v[48:49], v[54:55]
	v_cvt_pk_bf16_f32 v48, v50, v51
	v_cvt_pk_bf16_f32 v46, v46, v47
	v_and_b32_e32 v47, 0xffff0000, v46
	v_lshlrev_b32_e32 v46, 16, v46
	v_or_b32_sdwa v47, v47, v48 dst_sel:DWORD dst_unused:UNUSED_PAD src0_sel:DWORD src1_sel:WORD_1
	v_or_b32_sdwa v46, v46, v48 dst_sel:DWORD dst_unused:UNUSED_PAD src0_sel:DWORD src1_sel:WORD_0
	v_pk_add_f32 v[48:49], v[52:53], 1.0 op_sel_hi:[1,0]
	s_nop 0
	s_nop 0
	v_rcp_f32_e32 v49, v49
	s_nop 0
	s_nop 0
	v_rcp_f32_e32 v48, v48
	s_nop 0
	v_mov_b32_e32 v50, v42
	v_mov_b32_e32 v51, v44
	v_pk_mul_f32 v[48:49], v[50:51], v[48:49]
	v_pk_add_f32 v[50:51], v[56:57], 1.0 op_sel_hi:[1,0]
	s_nop 0
	s_nop 0
	v_rcp_f32_e32 v51, v51
	s_nop 0
	s_nop 0
	v_rcp_f32_e32 v50, v50
	s_nop 0
	v_mov_b32_e32 v44, v43
	v_pk_mul_f32 v[42:43], v[44:45], v[50:51]
	v_add_u32_e32 v52, 0xfff57400, v124
	v_cvt_pk_bf16_f32 v42, v42, v43
	v_cvt_pk_bf16_f32 v44, v48, v49
	v_and_b32_e32 v43, 0xffff0000, v42
	v_lshlrev_b32_e32 v42, 16, v42
	v_add_u32_e32 v0, v0, v52
	v_or_b32_sdwa v49, v43, v44 dst_sel:DWORD dst_unused:UNUSED_PAD src0_sel:DWORD src1_sel:WORD_1
	v_or_b32_sdwa v48, v42, v44 dst_sel:DWORD dst_unused:UNUSED_PAD src0_sel:DWORD src1_sel:WORD_0
	v_lshl_add_u64 v[42:43], v[0:1], 1, s[6:7]
	v_add_u32_e32 v0, v60, v125
	global_store_dwordx4 v[42:43], v[46:49], off
	v_add_u32_e32 v0, v0, v52
	s_waitcnt vmcnt(15)
	v_lshlrev_b32_e32 v49, 16, v207
	v_and_b32_e32 v50, 0xffff0000, v207
	v_lshlrev_b32_e32 v43, 16, v208
	v_and_b32_e32 v47, 0xffff0000, v206
	v_mul_f32_e32 v43, 0xbfb8aa3b, v43
	v_lshlrev_b32_e32 v46, 16, v206
	v_and_b32_e32 v48, 0xffff0000, v208
	v_exp_f32_e32 v44, v43
	v_mul_f32_e32 v43, 0xbfb8aa3b, v47
	v_mul_f32_e32 v42, 0xbfb8aa3b, v46
	v_exp_f32_e32 v46, v43
	v_mul_f32_e32 v43, 0xbfb8aa3b, v48
	v_exp_f32_e32 v48, v43
	v_mul_f32_e32 v43, 0xbfb8aa3b, v49
	v_exp_f32_e32 v42, v42
	v_exp_f32_e32 v43, v43
	v_lshlrev_b32_e32 v51, 16, v209
	v_mul_f32_e32 v47, 0xbfb8aa3b, v50
	v_and_b32_e32 v53, 0xffff0000, v209
	v_pk_add_f32 v[42:43], v[42:43], 1.0 op_sel_hi:[1,0]
	v_mul_f32_e32 v45, 0xbfb8aa3b, v51
	v_mul_f32_e32 v49, 0xbfb8aa3b, v53
	v_exp_f32_e32 v47, v47
	v_exp_f32_e32 v45, v45
	v_rcp_f32_e32 v43, v43
	s_nop 0
	v_pk_add_f32 v[46:47], v[46:47], 1.0 op_sel_hi:[1,0]
	v_exp_f32_e32 v49, v49
	v_rcp_f32_e32 v42, v42
	s_nop 0
	v_mov_b32_e32 v50, v38
	v_mov_b32_e32 v51, v40
	v_pk_mul_f32 v[42:43], v[50:51], v[42:43]
	v_rcp_f32_e32 v47, v47
	s_nop 0
	s_nop 0
	v_rcp_f32_e32 v46, v46
	s_nop 0
	v_mov_b32_e32 v40, v39
	v_pk_mul_f32 v[38:39], v[40:41], v[46:47]
	v_cvt_pk_bf16_f32 v40, v42, v43
	v_cvt_pk_bf16_f32 v38, v38, v39
	v_and_b32_e32 v39, 0xffff0000, v38
	v_lshlrev_b32_e32 v38, 16, v38
	v_or_b32_sdwa v39, v39, v40 dst_sel:DWORD dst_unused:UNUSED_PAD src0_sel:DWORD src1_sel:WORD_1
	v_or_b32_sdwa v38, v38, v40 dst_sel:DWORD dst_unused:UNUSED_PAD src0_sel:DWORD src1_sel:WORD_0
	v_pk_add_f32 v[40:41], v[44:45], 1.0 op_sel_hi:[1,0]
	s_nop 0
	s_nop 0
	v_rcp_f32_e32 v41, v41
	s_nop 0
	s_nop 0
	v_rcp_f32_e32 v40, v40
	s_nop 0
	v_mov_b32_e32 v42, v34
	v_mov_b32_e32 v43, v36
	v_pk_mul_f32 v[40:41], v[42:43], v[40:41]
	v_pk_add_f32 v[42:43], v[48:49], 1.0 op_sel_hi:[1,0]
	s_nop 0
	s_nop 0
	v_rcp_f32_e32 v43, v43
	s_nop 0
	s_nop 0
	v_rcp_f32_e32 v42, v42
	s_nop 0
	v_mov_b32_e32 v36, v35
	v_pk_mul_f32 v[34:35], v[36:37], v[42:43]
	v_cvt_pk_bf16_f32 v36, v40, v41
	v_cvt_pk_bf16_f32 v34, v34, v35
	v_and_b32_e32 v35, 0xffff0000, v34
	v_lshlrev_b32_e32 v34, 16, v34
	v_add_u32_e32 v44, 0xe3800, v151
	v_or_b32_sdwa v41, v35, v36 dst_sel:DWORD dst_unused:UNUSED_PAD src0_sel:DWORD src1_sel:WORD_1
	v_or_b32_sdwa v40, v34, v36 dst_sel:DWORD dst_unused:UNUSED_PAD src0_sel:DWORD src1_sel:WORD_0
	v_lshl_add_u64 v[34:35], v[0:1], 1, s[6:7]
	v_add_u32_e32 v0, v44, v150
	global_store_dwordx4 v[34:35], v[38:41], off
	s_nop 1
	s_waitcnt vmcnt(15)
	v_lshlrev_b32_e32 v41, 16, v211
	v_and_b32_e32 v42, 0xffff0000, v211
	v_lshlrev_b32_e32 v35, 16, v212
	v_and_b32_e32 v39, 0xffff0000, v210
	v_mul_f32_e32 v35, 0xbfb8aa3b, v35
	v_lshlrev_b32_e32 v38, 16, v210
	v_and_b32_e32 v40, 0xffff0000, v212
	v_exp_f32_e32 v36, v35
	v_mul_f32_e32 v35, 0xbfb8aa3b, v39
	v_mul_f32_e32 v34, 0xbfb8aa3b, v38
	v_exp_f32_e32 v38, v35
	v_mul_f32_e32 v35, 0xbfb8aa3b, v40
	v_exp_f32_e32 v40, v35
	v_mul_f32_e32 v35, 0xbfb8aa3b, v41
	v_exp_f32_e32 v34, v34
	v_exp_f32_e32 v35, v35
	v_lshlrev_b32_e32 v43, 16, v213
	v_mul_f32_e32 v39, 0xbfb8aa3b, v42
	v_and_b32_e32 v45, 0xffff0000, v213
	v_pk_add_f32 v[34:35], v[34:35], 1.0 op_sel_hi:[1,0]
	v_mul_f32_e32 v37, 0xbfb8aa3b, v43
	v_mul_f32_e32 v41, 0xbfb8aa3b, v45
	v_exp_f32_e32 v39, v39
	v_exp_f32_e32 v37, v37
	v_rcp_f32_e32 v35, v35
	s_nop 0
	v_pk_add_f32 v[38:39], v[38:39], 1.0 op_sel_hi:[1,0]
	v_exp_f32_e32 v41, v41
	v_rcp_f32_e32 v34, v34
	s_nop 0
	v_mov_b32_e32 v42, v30
	v_mov_b32_e32 v43, v32
	v_pk_mul_f32 v[34:35], v[42:43], v[34:35]
	v_rcp_f32_e32 v39, v39
	s_nop 0
	s_nop 0
	v_rcp_f32_e32 v38, v38
	s_nop 0
	v_mov_b32_e32 v32, v31
	v_pk_mul_f32 v[30:31], v[32:33], v[38:39]
	v_cvt_pk_bf16_f32 v32, v34, v35
	v_cvt_pk_bf16_f32 v30, v30, v31
	v_and_b32_e32 v31, 0xffff0000, v30
	v_lshlrev_b32_e32 v30, 16, v30
	v_or_b32_sdwa v31, v31, v32 dst_sel:DWORD dst_unused:UNUSED_PAD src0_sel:DWORD src1_sel:WORD_1
	v_or_b32_sdwa v30, v30, v32 dst_sel:DWORD dst_unused:UNUSED_PAD src0_sel:DWORD src1_sel:WORD_0
	v_pk_add_f32 v[32:33], v[36:37], 1.0 op_sel_hi:[1,0]
	s_nop 0
	s_nop 0
	v_rcp_f32_e32 v33, v33
	s_nop 0
	s_nop 0
	v_rcp_f32_e32 v32, v32
	s_nop 0
	v_mov_b32_e32 v34, v26
	v_mov_b32_e32 v35, v28
	v_pk_mul_f32 v[32:33], v[34:35], v[32:33]
	v_pk_add_f32 v[34:35], v[40:41], 1.0 op_sel_hi:[1,0]
	s_nop 0
	s_nop 0
	v_rcp_f32_e32 v35, v35
	s_nop 0
	s_nop 0
	v_rcp_f32_e32 v34, v34
	s_nop 0
	v_mov_b32_e32 v28, v27
	v_pk_mul_f32 v[26:27], v[28:29], v[34:35]
	v_add_u32_e32 v36, 0xfff44800, v124
	v_cvt_pk_bf16_f32 v26, v26, v27
	v_cvt_pk_bf16_f32 v28, v32, v33
	v_and_b32_e32 v27, 0xffff0000, v26
	v_lshlrev_b32_e32 v26, 16, v26
	v_add_u32_e32 v0, v0, v36
	v_or_b32_sdwa v33, v27, v28 dst_sel:DWORD dst_unused:UNUSED_PAD src0_sel:DWORD src1_sel:WORD_1
	v_or_b32_sdwa v32, v26, v28 dst_sel:DWORD dst_unused:UNUSED_PAD src0_sel:DWORD src1_sel:WORD_0
	v_lshl_add_u64 v[26:27], v[0:1], 1, s[6:7]
	v_add_u32_e32 v0, v44, v125
	global_store_dwordx4 v[26:27], v[30:33], off
	v_add_u32_e32 v0, v0, v36
	s_waitcnt vmcnt(14)
	v_lshlrev_b32_e32 v33, 16, v163
	v_and_b32_e32 v34, 0xffff0000, v163
	v_lshlrev_b32_e32 v27, 16, v164
	v_and_b32_e32 v31, 0xffff0000, v162
	v_mul_f32_e32 v27, 0xbfb8aa3b, v27
	v_lshlrev_b32_e32 v30, 16, v162
	v_and_b32_e32 v32, 0xffff0000, v164
	v_exp_f32_e32 v28, v27
	v_mul_f32_e32 v27, 0xbfb8aa3b, v31
	v_mul_f32_e32 v26, 0xbfb8aa3b, v30
	v_exp_f32_e32 v30, v27
	v_mul_f32_e32 v27, 0xbfb8aa3b, v32
	v_exp_f32_e32 v32, v27
	v_mul_f32_e32 v27, 0xbfb8aa3b, v33
	v_exp_f32_e32 v26, v26
	v_exp_f32_e32 v27, v27
	v_lshlrev_b32_e32 v35, 16, v165
	v_mul_f32_e32 v31, 0xbfb8aa3b, v34
	v_and_b32_e32 v37, 0xffff0000, v165
	v_pk_add_f32 v[26:27], v[26:27], 1.0 op_sel_hi:[1,0]
	v_mul_f32_e32 v29, 0xbfb8aa3b, v35
	v_mul_f32_e32 v33, 0xbfb8aa3b, v37
	v_exp_f32_e32 v31, v31
	v_exp_f32_e32 v29, v29
	v_rcp_f32_e32 v27, v27
	s_nop 0
	v_pk_add_f32 v[30:31], v[30:31], 1.0 op_sel_hi:[1,0]
	v_exp_f32_e32 v33, v33
	v_rcp_f32_e32 v26, v26
	s_nop 0
	v_mov_b32_e32 v34, v22
	v_mov_b32_e32 v35, v24
	v_pk_mul_f32 v[26:27], v[34:35], v[26:27]
	v_rcp_f32_e32 v31, v31
	s_nop 0
	s_nop 0
	v_rcp_f32_e32 v30, v30
	s_nop 0
	v_mov_b32_e32 v24, v23
	v_pk_mul_f32 v[22:23], v[24:25], v[30:31]
	v_cvt_pk_bf16_f32 v24, v26, v27
	v_cvt_pk_bf16_f32 v22, v22, v23
	v_and_b32_e32 v23, 0xffff0000, v22
	v_lshlrev_b32_e32 v22, 16, v22
	v_or_b32_sdwa v23, v23, v24 dst_sel:DWORD dst_unused:UNUSED_PAD src0_sel:DWORD src1_sel:WORD_1
	v_or_b32_sdwa v22, v22, v24 dst_sel:DWORD dst_unused:UNUSED_PAD src0_sel:DWORD src1_sel:WORD_0
	v_pk_add_f32 v[24:25], v[28:29], 1.0 op_sel_hi:[1,0]
	s_nop 0
	s_nop 0
	v_rcp_f32_e32 v25, v25
	s_nop 0
	s_nop 0
	v_rcp_f32_e32 v24, v24
	s_nop 0
	v_mov_b32_e32 v26, v18
	v_mov_b32_e32 v27, v20
	v_pk_mul_f32 v[24:25], v[26:27], v[24:25]
	v_pk_add_f32 v[26:27], v[32:33], 1.0 op_sel_hi:[1,0]
	s_nop 0
	s_nop 0
	v_rcp_f32_e32 v27, v27
	s_nop 0
	s_nop 0
	v_rcp_f32_e32 v26, v26
	s_nop 0
	v_mov_b32_e32 v20, v19
	v_pk_mul_f32 v[18:19], v[20:21], v[26:27]
	v_cvt_pk_bf16_f32 v20, v24, v25
	v_cvt_pk_bf16_f32 v18, v18, v19
	v_and_b32_e32 v19, 0xffff0000, v18
	v_lshlrev_b32_e32 v18, 16, v18
	v_add_u32_e32 v28, 0xfa400, v151
	v_or_b32_sdwa v25, v19, v20 dst_sel:DWORD dst_unused:UNUSED_PAD src0_sel:DWORD src1_sel:WORD_1
	v_or_b32_sdwa v24, v18, v20 dst_sel:DWORD dst_unused:UNUSED_PAD src0_sel:DWORD src1_sel:WORD_0
	v_lshl_add_u64 v[18:19], v[0:1], 1, s[6:7]
	v_add_u32_e32 v0, v28, v150
	global_store_dwordx4 v[18:19], v[22:25], off
	s_nop 1
	s_waitcnt vmcnt(13)
	v_lshlrev_b32_e32 v25, 16, v167
	v_and_b32_e32 v26, 0xffff0000, v167
	v_lshlrev_b32_e32 v19, 16, v168
	v_and_b32_e32 v23, 0xffff0000, v166
	v_mul_f32_e32 v19, 0xbfb8aa3b, v19
	v_lshlrev_b32_e32 v22, 16, v166
	v_and_b32_e32 v24, 0xffff0000, v168
	v_exp_f32_e32 v20, v19
	v_mul_f32_e32 v19, 0xbfb8aa3b, v23
	v_mul_f32_e32 v18, 0xbfb8aa3b, v22
	v_exp_f32_e32 v22, v19
	v_mul_f32_e32 v19, 0xbfb8aa3b, v24
	v_exp_f32_e32 v24, v19
	v_mul_f32_e32 v19, 0xbfb8aa3b, v25
	v_exp_f32_e32 v18, v18
	v_exp_f32_e32 v19, v19
	v_lshlrev_b32_e32 v27, 16, v169
	v_mul_f32_e32 v23, 0xbfb8aa3b, v26
	v_and_b32_e32 v29, 0xffff0000, v169
	v_pk_add_f32 v[18:19], v[18:19], 1.0 op_sel_hi:[1,0]
	v_mul_f32_e32 v21, 0xbfb8aa3b, v27
	v_mul_f32_e32 v25, 0xbfb8aa3b, v29
	v_exp_f32_e32 v23, v23
	v_exp_f32_e32 v21, v21
	v_rcp_f32_e32 v19, v19
	s_nop 0
	v_pk_add_f32 v[22:23], v[22:23], 1.0 op_sel_hi:[1,0]
	v_exp_f32_e32 v25, v25
	v_rcp_f32_e32 v18, v18
	s_nop 0
	v_mov_b32_e32 v26, v14
	v_mov_b32_e32 v27, v16
	v_pk_mul_f32 v[18:19], v[26:27], v[18:19]
	v_rcp_f32_e32 v23, v23
	s_nop 0
	s_nop 0
	v_rcp_f32_e32 v22, v22
	s_nop 0
	v_mov_b32_e32 v16, v15
	v_pk_mul_f32 v[14:15], v[16:17], v[22:23]
	v_cvt_pk_bf16_f32 v16, v18, v19
	v_cvt_pk_bf16_f32 v14, v14, v15
	v_and_b32_e32 v15, 0xffff0000, v14
	v_lshlrev_b32_e32 v14, 16, v14
	v_or_b32_sdwa v15, v15, v16 dst_sel:DWORD dst_unused:UNUSED_PAD src0_sel:DWORD src1_sel:WORD_1
	v_or_b32_sdwa v14, v14, v16 dst_sel:DWORD dst_unused:UNUSED_PAD src0_sel:DWORD src1_sel:WORD_0
	v_pk_add_f32 v[16:17], v[20:21], 1.0 op_sel_hi:[1,0]
	s_nop 0
	s_nop 0
	v_rcp_f32_e32 v17, v17
	s_nop 0
	s_nop 0
	v_rcp_f32_e32 v16, v16
	s_nop 0
	v_mov_b32_e32 v18, v10
	v_mov_b32_e32 v19, v12
	v_pk_mul_f32 v[16:17], v[18:19], v[16:17]
	v_pk_add_f32 v[18:19], v[24:25], 1.0 op_sel_hi:[1,0]
	s_nop 0
	s_nop 0
	v_rcp_f32_e32 v19, v19
	s_nop 0
	s_nop 0
	v_rcp_f32_e32 v18, v18
	s_nop 0
	v_mov_b32_e32 v12, v11
	v_pk_mul_f32 v[10:11], v[12:13], v[18:19]
	v_add_u32_e32 v20, 0xfff31c00, v124
	v_cvt_pk_bf16_f32 v10, v10, v11
	v_cvt_pk_bf16_f32 v12, v16, v17
	v_and_b32_e32 v11, 0xffff0000, v10
	v_lshlrev_b32_e32 v10, 16, v10
	v_add_u32_e32 v0, v0, v20
	v_or_b32_sdwa v17, v11, v12 dst_sel:DWORD dst_unused:UNUSED_PAD src0_sel:DWORD src1_sel:WORD_1
	v_or_b32_sdwa v16, v10, v12 dst_sel:DWORD dst_unused:UNUSED_PAD src0_sel:DWORD src1_sel:WORD_0
	v_lshl_add_u64 v[10:11], v[0:1], 1, s[6:7]
	v_add_u32_e32 v0, v28, v125
	global_store_dwordx4 v[10:11], v[14:17], off
	v_add_u32_e32 v0, v0, v20
	s_waitcnt vmcnt(12)
	v_lshlrev_b32_e32 v17, 16, v171
	v_and_b32_e32 v18, 0xffff0000, v171
	v_lshlrev_b32_e32 v11, 16, v172
	v_and_b32_e32 v15, 0xffff0000, v170
	v_mul_f32_e32 v11, 0xbfb8aa3b, v11
	v_lshlrev_b32_e32 v14, 16, v170
	v_and_b32_e32 v16, 0xffff0000, v172
	v_exp_f32_e32 v12, v11
	v_mul_f32_e32 v11, 0xbfb8aa3b, v15
	v_mul_f32_e32 v10, 0xbfb8aa3b, v14
	v_exp_f32_e32 v14, v11
	v_mul_f32_e32 v11, 0xbfb8aa3b, v16
	v_exp_f32_e32 v16, v11
	v_mul_f32_e32 v11, 0xbfb8aa3b, v17
	v_exp_f32_e32 v10, v10
	v_exp_f32_e32 v11, v11
	v_lshlrev_b32_e32 v19, 16, v173
	v_mul_f32_e32 v15, 0xbfb8aa3b, v18
	v_and_b32_e32 v21, 0xffff0000, v173
	v_pk_add_f32 v[10:11], v[10:11], 1.0 op_sel_hi:[1,0]
	v_mul_f32_e32 v13, 0xbfb8aa3b, v19
	v_mul_f32_e32 v17, 0xbfb8aa3b, v21
	v_exp_f32_e32 v15, v15
	v_exp_f32_e32 v13, v13
	v_rcp_f32_e32 v11, v11
	s_nop 0
	v_pk_add_f32 v[14:15], v[14:15], 1.0 op_sel_hi:[1,0]
	v_exp_f32_e32 v17, v17
	v_rcp_f32_e32 v10, v10
	s_nop 0
	v_mov_b32_e32 v18, v6
	v_mov_b32_e32 v19, v8
	v_pk_mul_f32 v[10:11], v[18:19], v[10:11]
	v_rcp_f32_e32 v15, v15
	s_nop 0
	s_nop 0
	v_rcp_f32_e32 v14, v14
	s_nop 0
	v_mov_b32_e32 v8, v7
	v_pk_mul_f32 v[6:7], v[8:9], v[14:15]
	v_cvt_pk_bf16_f32 v8, v10, v11
	v_cvt_pk_bf16_f32 v6, v6, v7
	v_and_b32_e32 v7, 0xffff0000, v6
	v_lshlrev_b32_e32 v6, 16, v6
	v_or_b32_sdwa v7, v7, v8 dst_sel:DWORD dst_unused:UNUSED_PAD src0_sel:DWORD src1_sel:WORD_1
	v_or_b32_sdwa v6, v6, v8 dst_sel:DWORD dst_unused:UNUSED_PAD src0_sel:DWORD src1_sel:WORD_0
	v_pk_add_f32 v[8:9], v[12:13], 1.0 op_sel_hi:[1,0]
	s_nop 0
	s_nop 0
	v_rcp_f32_e32 v9, v9
	s_nop 0
	s_nop 0
	v_rcp_f32_e32 v8, v8
	s_nop 0
	v_mov_b32_e32 v10, v2
	v_mov_b32_e32 v11, v4
	v_pk_mul_f32 v[8:9], v[10:11], v[8:9]
	v_pk_add_f32 v[10:11], v[16:17], 1.0 op_sel_hi:[1,0]
	s_nop 0
	s_nop 0
	v_rcp_f32_e32 v11, v11
	s_nop 0
	s_mov_b64 s[24:25], s[16:17]
	v_rcp_f32_e32 v10, v10
	s_nop 0
	v_mov_b32_e32 v4, v3
	v_pk_mul_f32 v[2:3], v[4:5], v[10:11]
	v_cvt_pk_bf16_f32 v4, v8, v9
	v_cvt_pk_bf16_f32 v2, v2, v3
	v_and_b32_e32 v3, 0xffff0000, v2
	v_lshlrev_b32_e32 v2, 16, v2
	v_or_b32_sdwa v9, v3, v4 dst_sel:DWORD dst_unused:UNUSED_PAD src0_sel:DWORD src1_sel:WORD_1
	v_or_b32_sdwa v8, v2, v4 dst_sel:DWORD dst_unused:UNUSED_PAD src0_sel:DWORD src1_sel:WORD_0
	v_lshl_add_u64 v[2:3], v[0:1], 1, s[6:7]
	s_and_b64 vcc, exec, s[10:11]
	global_store_dwordx4 v[2:3], v[6:9], off
	s_cbranch_vccz .LBB0_1344
	s_waitcnt vmcnt(0)
	v_readlane_b32 s76, v255, 8
	s_mov_b32 s92, 0x3b2aaaab
	s_cmp_gt_u32 s4, 3
	v_readlane_b32 s77, v255, 9
	s_mul_i32 s60, s33, 0x1800
	s_mul_hi_i32 s62, s64, 0x300
	s_mul_i32 s75, s33, 0x16c00
	s_mov_b32 s93, 0x3c800000
	s_mov_b32 s82, s70
	s_cbranch_scc1 .LBB0_1351
	s_barrier

.LBB0_1359:
	v_add_u32_e32 v0, 0x10000, v154
	s_waitcnt vmcnt(0)
	ds_read_b128 v[130:133], v0
	ds_read_b128 v[146:149], v0 offset:1024
	ds_read_b128 v[156:159], v0 offset:2048
	ds_read_b128 v[160:163], v0 offset:3072
	s_add_u32 s28, s26, 0xfffc0080
	s_addc_u32 s29, s27, -1
	s_cmp_eq_u32 vcc_lo, 12
	s_cselect_b32 s31, s2, s29
	s_cselect_b32 s30, s17, s28
	s_cselect_b32 s29, s15, s94
	s_cselect_b32 s28, s89, s90
	v_lshl_add_u64 v[150:151], s[26:27], 0, v[142:143]
	s_add_i32 m0, s39, 0xc000
	ds_read_b128 v[164:167], v153
	ds_read_b128 v[168:171], v153 offset:1024
	ds_read_b128 v[172:175], v153 offset:2048
	ds_read_b128 v[176:179], v153 offset:3072
	ds_read_b128 v[182:185], v153 offset:4096
	ds_read_b128 v[186:189], v153 offset:5120
	ds_read_b128 v[190:193], v153 offset:6144
	ds_read_b128 v[194:197], v153 offset:7168
	global_load_lds_dwordx4 v[150:151], off
	v_lshl_add_u64 v[150:151], s[26:27], 0, v[144:145]
	s_add_i32 m0, s39, 0xe000
	s_nop 0
	global_load_lds_dwordx4 v[150:151], off
	s_waitcnt lgkmcnt(8)
	s_barrier
	s_waitcnt lgkmcnt(0)
	s_setprio 1
	s_waitcnt lgkmcnt(0)
	v_mfma_f32_16x16x32_bf16 v[126:129], v[130:133], v[164:167], v[126:129]
	v_mfma_f32_16x16x32_bf16 v[122:125], v[156:159], v[164:167], v[122:125]
	v_mfma_f32_16x16x32_bf16 v[110:113], v[130:133], v[172:175], v[110:113]
	v_mfma_f32_16x16x32_bf16 v[106:109], v[156:159], v[172:175], v[106:109]
	v_mfma_f32_16x16x32_bf16 v[94:97], v[130:133], v[182:185], v[94:97]
	v_mfma_f32_16x16x32_bf16 v[90:93], v[156:159], v[182:185], v[90:93]
	v_mfma_f32_16x16x32_bf16 v[78:81], v[130:133], v[190:193], v[78:81]
	v_mfma_f32_16x16x32_bf16 v[74:77], v[156:159], v[190:193], v[74:77]
	v_mfma_f32_16x16x32_bf16 v[126:129], v[146:149], v[168:171], v[126:129]
	v_mfma_f32_16x16x32_bf16 v[122:125], v[160:163], v[168:171], v[122:125]
	v_mfma_f32_16x16x32_bf16 v[110:113], v[146:149], v[176:179], v[110:113]
	v_mfma_f32_16x16x32_bf16 v[106:109], v[160:163], v[176:179], v[106:109]
	v_mfma_f32_16x16x32_bf16 v[94:97], v[146:149], v[186:189], v[94:97]
	v_mfma_f32_16x16x32_bf16 v[90:93], v[160:163], v[186:189], v[90:93]
	v_mfma_f32_16x16x32_bf16 v[78:81], v[146:149], v[194:197], v[78:81]
	v_mfma_f32_16x16x32_bf16 v[74:77], v[160:163], v[194:197], v[74:77]
	s_setprio 0
	s_barrier
	s_mov_b32 m0, s23
	v_add_u32_e32 v0, 0x14000, v154
	v_lshl_add_u64 v[150:151], s[28:29], 0, v[138:139]
	s_waitcnt vmcnt(0)
	ds_read_b128 v[198:201], v0
	ds_read_b128 v[202:205], v0 offset:1024
	ds_read_b128 v[206:209], v0 offset:2048
	ds_read_b128 v[210:213], v0 offset:3072
	global_load_lds_dwordx4 v[150:151], off
	v_lshl_add_u64 v[214:215], s[28:29], 0, v[134:135]
	s_mov_b32 m0, s25
	s_nop 0
	global_load_lds_dwordx4 v[214:215], off
	s_barrier
	s_waitcnt lgkmcnt(0)
	s_setprio 1
	s_waitcnt lgkmcnt(0)
	v_mfma_f32_16x16x32_bf16 v[118:121], v[198:201], v[164:167], v[118:121]
	v_mfma_f32_16x16x32_bf16 v[114:117], v[206:209], v[164:167], v[114:117]
	v_mfma_f32_16x16x32_bf16 v[102:105], v[198:201], v[172:175], v[102:105]
	v_mfma_f32_16x16x32_bf16 v[98:101], v[206:209], v[172:175], v[98:101]
	v_mfma_f32_16x16x32_bf16 v[86:89], v[198:201], v[182:185], v[86:89]
	v_mfma_f32_16x16x32_bf16 v[82:85], v[206:209], v[182:185], v[82:85]
	v_mfma_f32_16x16x32_bf16 v[70:73], v[198:201], v[190:193], v[70:73]
	v_mfma_f32_16x16x32_bf16 v[66:69], v[206:209], v[190:193], v[66:69]
	v_mfma_f32_16x16x32_bf16 v[118:121], v[202:205], v[168:171], v[118:121]
	v_mfma_f32_16x16x32_bf16 v[114:117], v[210:213], v[168:171], v[114:117]
	v_mfma_f32_16x16x32_bf16 v[102:105], v[202:205], v[176:179], v[102:105]
	v_mfma_f32_16x16x32_bf16 v[98:101], v[210:213], v[176:179], v[98:101]
	v_mfma_f32_16x16x32_bf16 v[86:89], v[202:205], v[186:189], v[86:89]
	v_mfma_f32_16x16x32_bf16 v[82:85], v[210:213], v[186:189], v[82:85]
	v_mfma_f32_16x16x32_bf16 v[70:73], v[202:205], v[194:197], v[70:73]
	v_mfma_f32_16x16x32_bf16 v[66:69], v[210:213], v[194:197], v[66:69]
	s_setprio 0
	s_mov_b32 m0, s39
	v_lshl_add_u64 v[216:217], s[30:31], 0, v[140:141]
	s_barrier
	s_waitcnt vmcnt(0)
	ds_read_b128 v[164:167], v153 offset:16384
	ds_read_b128 v[168:171], v153 offset:17408
	ds_read_b128 v[172:175], v153 offset:18432
	ds_read_b128 v[176:179], v153 offset:19456
	ds_read_b128 v[182:185], v153 offset:20480
	ds_read_b128 v[186:189], v153 offset:21504
	ds_read_b128 v[190:193], v153 offset:22528
	ds_read_b128 v[194:197], v153 offset:23552
	global_load_lds_dwordx4 v[216:217], off
	v_lshl_add_u64 v[222:223], s[30:31], 0, v[136:137]
	s_mov_b32 m0, s82
	s_nop 0
	global_load_lds_dwordx4 v[222:223], off
	s_barrier
	s_waitcnt lgkmcnt(0)
	s_setprio 1
	s_waitcnt lgkmcnt(0)
	v_mfma_f32_16x16x32_bf16 v[62:65], v[130:133], v[164:167], v[62:65]
	v_mfma_f32_16x16x32_bf16 v[58:61], v[156:159], v[164:167], v[58:61]
	v_mfma_f32_16x16x32_bf16 v[46:49], v[130:133], v[172:175], v[46:49]
	v_mfma_f32_16x16x32_bf16 v[42:45], v[156:159], v[172:175], v[42:45]
	v_mfma_f32_16x16x32_bf16 v[30:33], v[130:133], v[182:185], v[30:33]
	v_mfma_f32_16x16x32_bf16 v[26:29], v[156:159], v[182:185], v[26:29]
	v_mfma_f32_16x16x32_bf16 v[14:17], v[130:133], v[190:193], v[14:17]
	v_mfma_f32_16x16x32_bf16 v[10:13], v[156:159], v[190:193], v[10:13]
	v_mfma_f32_16x16x32_bf16 v[62:65], v[146:149], v[168:171], v[62:65]
	v_mfma_f32_16x16x32_bf16 v[58:61], v[160:163], v[168:171], v[58:61]
	v_mfma_f32_16x16x32_bf16 v[46:49], v[146:149], v[176:179], v[46:49]
	v_mfma_f32_16x16x32_bf16 v[42:45], v[160:163], v[176:179], v[42:45]
	v_mfma_f32_16x16x32_bf16 v[30:33], v[146:149], v[186:189], v[30:33]
	v_mfma_f32_16x16x32_bf16 v[26:29], v[160:163], v[186:189], v[26:29]
	v_mfma_f32_16x16x32_bf16 v[14:17], v[146:149], v[194:197], v[14:17]
	v_mfma_f32_16x16x32_bf16 v[10:13], v[160:163], v[194:197], v[10:13]
	s_setprio 0
	s_barrier
	s_add_u32 s76, s28, 0x40000
	s_addc_u32 s77, s29, 0
	s_mov_b32 m0, s96
	v_lshl_add_u64 v[130:131], s[76:77], 0, v[138:139]
	global_load_lds_dwordx4 v[130:131], off
	v_lshl_add_u64 v[130:131], s[76:77], 0, v[134:135]
	s_mov_b32 m0, s97
	s_nop 0
	global_load_lds_dwordx4 v[130:131], off
	s_waitcnt vmcnt(6)
	s_barrier
	s_setprio 1
	v_mfma_f32_16x16x32_bf16 v[54:57], v[198:201], v[164:167], v[54:57]
	v_mfma_f32_16x16x32_bf16 v[50:53], v[206:209], v[164:167], v[50:53]
	v_mfma_f32_16x16x32_bf16 v[38:41], v[198:201], v[172:175], v[38:41]
	v_mfma_f32_16x16x32_bf16 v[34:37], v[206:209], v[172:175], v[34:37]
	v_mfma_f32_16x16x32_bf16 v[22:25], v[198:201], v[182:185], v[22:25]
	v_mfma_f32_16x16x32_bf16 v[18:21], v[206:209], v[182:185], v[18:21]
	v_mfma_f32_16x16x32_bf16 v[6:9], v[198:201], v[190:193], v[6:9]
	v_mfma_f32_16x16x32_bf16 v[2:5], v[206:209], v[190:193], v[2:5]
	v_mfma_f32_16x16x32_bf16 v[54:57], v[202:205], v[168:171], v[54:57]
	v_mfma_f32_16x16x32_bf16 v[50:53], v[210:213], v[168:171], v[50:53]
	v_mfma_f32_16x16x32_bf16 v[38:41], v[202:205], v[176:179], v[38:41]
	v_mfma_f32_16x16x32_bf16 v[34:37], v[210:213], v[176:179], v[34:37]
	v_mfma_f32_16x16x32_bf16 v[22:25], v[202:205], v[186:189], v[22:25]
	v_mfma_f32_16x16x32_bf16 v[18:21], v[210:213], v[186:189], v[18:21]
	v_mfma_f32_16x16x32_bf16 v[6:9], v[202:205], v[194:197], v[6:9]
	v_mfma_f32_16x16x32_bf16 v[2:5], v[210:213], v[194:197], v[2:5]
	s_setprio 0
	v_add_u32_e32 v0, 0x18000, v154
	s_barrier
	s_waitcnt vmcnt(0)
	ds_read_b128 v[130:133], v0
	ds_read_b128 v[146:149], v0 offset:1024
	ds_read_b128 v[156:159], v0 offset:2048
	ds_read_b128 v[160:163], v0 offset:3072
	s_add_u32 s30, s30, 0x40000
	s_addc_u32 s31, s31, 0
	s_mov_b32 m0, s68
	v_lshl_add_u64 v[198:199], s[30:31], 0, v[140:141]
	ds_read_b128 v[164:167], v153 offset:32768
	ds_read_b128 v[168:171], v153 offset:33792
	ds_read_b128 v[172:175], v153 offset:34816
	ds_read_b128 v[176:179], v153 offset:35840
	ds_read_b128 v[182:185], v153 offset:36864
	ds_read_b128 v[186:189], v153 offset:37888
	ds_read_b128 v[190:193], v153 offset:38912
	ds_read_b128 v[194:197], v153 offset:39936
	global_load_lds_dwordx4 v[198:199], off
	v_lshl_add_u64 v[198:199], s[30:31], 0, v[136:137]
	s_mov_b32 m0, s69
	s_nop 0
	global_load_lds_dwordx4 v[198:199], off
	s_waitcnt lgkmcnt(8)
	s_barrier
	s_waitcnt lgkmcnt(0)
	s_setprio 1
	s_waitcnt lgkmcnt(0)
	v_mfma_f32_16x16x32_bf16 v[126:129], v[130:133], v[164:167], v[126:129]
	v_mfma_f32_16x16x32_bf16 v[122:125], v[156:159], v[164:167], v[122:125]
	v_mfma_f32_16x16x32_bf16 v[110:113], v[130:133], v[172:175], v[110:113]
	v_mfma_f32_16x16x32_bf16 v[106:109], v[156:159], v[172:175], v[106:109]
	v_mfma_f32_16x16x32_bf16 v[94:97], v[130:133], v[182:185], v[94:97]
	v_mfma_f32_16x16x32_bf16 v[90:93], v[156:159], v[182:185], v[90:93]
	v_mfma_f32_16x16x32_bf16 v[78:81], v[130:133], v[190:193], v[78:81]
	v_mfma_f32_16x16x32_bf16 v[74:77], v[156:159], v[190:193], v[74:77]
	v_mfma_f32_16x16x32_bf16 v[126:129], v[146:149], v[168:171], v[126:129]
	v_mfma_f32_16x16x32_bf16 v[122:125], v[160:163], v[168:171], v[122:125]
	v_mfma_f32_16x16x32_bf16 v[110:113], v[146:149], v[176:179], v[110:113]
	v_mfma_f32_16x16x32_bf16 v[106:109], v[160:163], v[176:179], v[106:109]
	v_mfma_f32_16x16x32_bf16 v[94:97], v[146:149], v[186:189], v[94:97]
	v_mfma_f32_16x16x32_bf16 v[90:93], v[160:163], v[186:189], v[90:93]
	v_mfma_f32_16x16x32_bf16 v[78:81], v[146:149], v[194:197], v[78:81]
	v_mfma_f32_16x16x32_bf16 v[74:77], v[160:163], v[194:197], v[74:77]
	s_setprio 0
	s_barrier
	s_mov_b32 m0, s4
	v_add_u32_e32 v0, 0x1c000, v154
	v_lshl_add_u64 v[150:151], v[150:151], 0, s[84:85]
	s_waitcnt vmcnt(0)
	ds_read_b128 v[198:201], v0
	ds_read_b128 v[202:205], v0 offset:1024
	ds_read_b128 v[206:209], v0 offset:2048
	ds_read_b128 v[210:213], v0 offset:3072
	global_load_lds_dwordx4 v[150:151], off
	v_lshl_add_u64 v[150:151], v[214:215], 0, s[84:85]
	s_mov_b32 m0, s5
	s_nop 0
	global_load_lds_dwordx4 v[150:151], off
	s_barrier
	s_waitcnt lgkmcnt(0)
	s_setprio 1
	s_waitcnt lgkmcnt(0)
	v_mfma_f32_16x16x32_bf16 v[118:121], v[198:201], v[164:167], v[118:121]
	v_mfma_f32_16x16x32_bf16 v[114:117], v[206:209], v[164:167], v[114:117]
	v_mfma_f32_16x16x32_bf16 v[102:105], v[198:201], v[172:175], v[102:105]
	v_mfma_f32_16x16x32_bf16 v[98:101], v[206:209], v[172:175], v[98:101]
	v_mfma_f32_16x16x32_bf16 v[86:89], v[198:201], v[182:185], v[86:89]
	v_mfma_f32_16x16x32_bf16 v[82:85], v[206:209], v[182:185], v[82:85]
	v_mfma_f32_16x16x32_bf16 v[70:73], v[198:201], v[190:193], v[70:73]
	v_mfma_f32_16x16x32_bf16 v[66:69], v[206:209], v[190:193], v[66:69]
	v_mfma_f32_16x16x32_bf16 v[118:121], v[202:205], v[168:171], v[118:121]
	v_mfma_f32_16x16x32_bf16 v[114:117], v[210:213], v[168:171], v[114:117]
	v_mfma_f32_16x16x32_bf16 v[102:105], v[202:205], v[176:179], v[102:105]
	v_mfma_f32_16x16x32_bf16 v[98:101], v[210:213], v[176:179], v[98:101]
	v_mfma_f32_16x16x32_bf16 v[86:89], v[202:205], v[186:189], v[86:89]
	v_mfma_f32_16x16x32_bf16 v[82:85], v[210:213], v[186:189], v[82:85]
	v_mfma_f32_16x16x32_bf16 v[70:73], v[202:205], v[194:197], v[70:73]
	v_mfma_f32_16x16x32_bf16 v[66:69], v[210:213], v[194:197], v[66:69]
	s_setprio 0
	s_mov_b32 m0, s60
	v_lshl_add_u64 v[150:151], v[216:217], 0, s[84:85]
	s_barrier
	s_waitcnt vmcnt(0)
	ds_read_b128 v[164:167], v153 offset:49152
	ds_read_b128 v[168:171], v153 offset:50176
	ds_read_b128 v[172:175], v153 offset:51200
	ds_read_b128 v[176:179], v153 offset:52224
	ds_read_b128 v[182:185], v153 offset:53248
	ds_read_b128 v[186:189], v153 offset:54272
	ds_read_b128 v[190:193], v153 offset:55296
	ds_read_b128 v[194:197], v153 offset:56320
	global_load_lds_dwordx4 v[150:151], off
	v_lshl_add_u64 v[150:151], v[222:223], 0, s[84:85]
	s_mov_b32 m0, s92
	s_nop 0
	global_load_lds_dwordx4 v[150:151], off
	s_barrier
	s_waitcnt lgkmcnt(0)
	s_setprio 1
	s_waitcnt lgkmcnt(0)
	v_mfma_f32_16x16x32_bf16 v[62:65], v[130:133], v[164:167], v[62:65]
	v_mfma_f32_16x16x32_bf16 v[58:61], v[156:159], v[164:167], v[58:61]
	v_mfma_f32_16x16x32_bf16 v[46:49], v[130:133], v[172:175], v[46:49]
	v_mfma_f32_16x16x32_bf16 v[42:45], v[156:159], v[172:175], v[42:45]
	v_mfma_f32_16x16x32_bf16 v[30:33], v[130:133], v[182:185], v[30:33]
	v_mfma_f32_16x16x32_bf16 v[26:29], v[156:159], v[182:185], v[26:29]
	v_mfma_f32_16x16x32_bf16 v[14:17], v[130:133], v[190:193], v[14:17]
	v_mfma_f32_16x16x32_bf16 v[10:13], v[156:159], v[190:193], v[10:13]
	v_mfma_f32_16x16x32_bf16 v[62:65], v[146:149], v[168:171], v[62:65]
	v_mfma_f32_16x16x32_bf16 v[58:61], v[160:163], v[168:171], v[58:61]
	v_mfma_f32_16x16x32_bf16 v[46:49], v[146:149], v[176:179], v[46:49]
	v_mfma_f32_16x16x32_bf16 v[42:45], v[160:163], v[176:179], v[42:45]
	v_mfma_f32_16x16x32_bf16 v[30:33], v[146:149], v[186:189], v[30:33]
	v_mfma_f32_16x16x32_bf16 v[26:29], v[160:163], v[186:189], v[26:29]
	v_mfma_f32_16x16x32_bf16 v[14:17], v[146:149], v[194:197], v[14:17]
	v_mfma_f32_16x16x32_bf16 v[10:13], v[160:163], v[194:197], v[10:13]
	s_setprio 0
	s_barrier
	s_add_u32 s28, s28, 0x40080
	s_addc_u32 s29, s29, 0
	s_mov_b32 m0, s93
	v_lshl_add_u64 v[130:131], s[28:29], 0, v[138:139]
	global_load_lds_dwordx4 v[130:131], off
	v_lshl_add_u64 v[130:131], s[28:29], 0, v[134:135]
	s_mov_b32 m0, s3
	s_nop 0
	global_load_lds_dwordx4 v[130:131], off
	s_waitcnt vmcnt(6)
	s_barrier
	s_setprio 1
	v_mfma_f32_16x16x32_bf16 v[54:57], v[198:201], v[164:167], v[54:57]
	v_mfma_f32_16x16x32_bf16 v[50:53], v[206:209], v[164:167], v[50:53]
	v_mfma_f32_16x16x32_bf16 v[38:41], v[198:201], v[172:175], v[38:41]
	v_mfma_f32_16x16x32_bf16 v[34:37], v[206:209], v[172:175], v[34:37]
	v_mfma_f32_16x16x32_bf16 v[22:25], v[198:201], v[182:185], v[22:25]
	v_mfma_f32_16x16x32_bf16 v[18:21], v[206:209], v[182:185], v[18:21]
	v_mfma_f32_16x16x32_bf16 v[6:9], v[198:201], v[190:193], v[6:9]
	v_mfma_f32_16x16x32_bf16 v[2:5], v[206:209], v[190:193], v[2:5]
	v_mfma_f32_16x16x32_bf16 v[54:57], v[202:205], v[168:171], v[54:57]
	v_mfma_f32_16x16x32_bf16 v[50:53], v[210:213], v[168:171], v[50:53]
	v_mfma_f32_16x16x32_bf16 v[38:41], v[202:205], v[176:179], v[38:41]
	v_mfma_f32_16x16x32_bf16 v[34:37], v[210:213], v[176:179], v[34:37]
	v_mfma_f32_16x16x32_bf16 v[22:25], v[202:205], v[186:189], v[22:25]
	v_mfma_f32_16x16x32_bf16 v[18:21], v[210:213], v[186:189], v[18:21]
	v_mfma_f32_16x16x32_bf16 v[6:9], v[202:205], v[194:197], v[6:9]
	v_mfma_f32_16x16x32_bf16 v[2:5], v[210:213], v[194:197], v[2:5]
	s_setprio 0
	s_add_i32 vcc_lo, vcc_lo, 2
	s_add_u32 s26, s26, 0x100
	s_addc_u32 s27, s27, 0
	s_add_u32 s90, s90, 0x100
	s_addc_u32 s94, s94, 0
	s_cmp_gt_u32 vcc_lo, 13
	s_barrier
	s_cbranch_scc0 .LBB0_1359
	v_lshl_add_u32 v159, s24, 8, v152
	v_lshl_add_u32 v156, s22, 8, v155
	v_mul_lo_u32 v157, v159, s71
	v_add_u32_e32 v0, v157, v156
	v_lshl_add_u64 v[130:131], v[0:1], 1, s[6:7]
	global_load_dwordx4 v[130:133], v[130:131], off
	v_mul_lo_u32 v158, v159, s61
	v_mov_b32_e32 v210, v0
	v_add_u32_e32 v211, v0, v158
	v_mov_b32_e32 v213, 0
	v_add_u32_e32 v212, 0x80, v210
	v_lshl_add_u64 v[168:169], v[212:213], 1, s[6:7]
	global_load_dwordx4 v[168:171], v[168:169], off
	v_add_u32_e32 v212, 0x80, v211
	v_lshl_add_u64 v[172:173], v[212:213], 1, s[10:11]
	global_load_dwordx4 v[172:175], v[172:173], off
	v_add_u32_e32 v212, 0x16c00, v210
	v_lshl_add_u64 v[176:177], v[212:213], 1, s[6:7]
	global_load_dwordx4 v[176:179], v[176:177], off
	v_add_u32_e32 v212, 0x4000, v211
	v_lshl_add_u64 v[182:183], v[212:213], 1, s[10:11]
	global_load_dwordx4 v[182:185], v[182:183], off
	v_add_u32_e32 v212, 0x16c80, v210
	v_lshl_add_u64 v[186:187], v[212:213], 1, s[6:7]
	global_load_dwordx4 v[186:189], v[186:187], off
	v_add_u32_e32 v212, 0x4080, v211
	v_lshl_add_u64 v[190:191], v[212:213], 1, s[10:11]
	global_load_dwordx4 v[190:193], v[190:191], off
	v_add_u32_e32 v212, 0x2d800, v210
	v_lshl_add_u64 v[194:195], v[212:213], 1, s[6:7]
	global_load_dwordx4 v[194:197], v[194:195], off
	v_add_u32_e32 v212, 0x8000, v211
	v_lshl_add_u64 v[198:199], v[212:213], 1, s[10:11]
	global_load_dwordx4 v[198:201], v[198:199], off
	v_add_u32_e32 v212, 0x2d880, v210
	v_lshl_add_u64 v[202:203], v[212:213], 1, s[6:7]
	global_load_dwordx4 v[202:205], v[202:203], off
	v_add_u32_e32 v212, 0x8080, v211
	v_lshl_add_u64 v[206:207], v[212:213], 1, s[10:11]
	global_load_dwordx4 v[206:209], v[206:207], off
	v_add_u32_e32 v0, v0, v158
	v_lshl_add_u64 v[146:147], v[0:1], 1, s[10:11]
	s_mov_b32 s22, s14
	s_mov_b32 s24, s16
	s_mov_b64 s[28:29], s[20:21]
	s_waitcnt vmcnt(10)
	v_lshlrev_b32_e32 v148, 16, v130
	v_and_b32_e32 v149, 0xffff0000, v130
	v_lshlrev_b32_e32 v151, 16, v131
	v_and_b32_e32 v163, 0xffff0000, v131
	v_lshlrev_b32_e32 v150, 16, v132
	v_and_b32_e32 v161, 0xffff0000, v132
	v_lshlrev_b32_e32 v164, 16, v133
	v_and_b32_e32 v165, 0xffff0000, v133
	global_load_dwordx4 v[130:133], v[146:147], off
	v_mul_f32_e32 v0, 0xbfb8aa3b, v148
	v_exp_f32_e32 v160, v0
	v_mul_f32_e32 v0, 0xbfb8aa3b, v150
	v_exp_f32_e32 v150, v0
	v_mul_f32_e32 v0, 0xbfb8aa3b, v149
	v_exp_f32_e32 v162, v0
	v_mul_f32_e32 v0, 0xbfb8aa3b, v161
	v_exp_f32_e32 v148, v0
	v_mul_f32_e32 v0, 0xbfb8aa3b, v151
	v_exp_f32_e32 v161, v0
	v_mul_f32_e32 v0, 0xbfb8aa3b, v164
	v_exp_f32_e32 v151, v0
	v_mul_f32_e32 v0, 0xbfb8aa3b, v163
	v_exp_f32_e32 v163, v0
	v_mul_f32_e32 v0, 0xbfb8aa3b, v165
	v_pk_add_f32 v[160:161], v[160:161], 1.0 op_sel_hi:[1,0]
	v_exp_f32_e32 v149, v0
	v_pk_add_f32 v[162:163], v[162:163], 1.0 op_sel_hi:[1,0]
	v_rcp_f32_e32 v161, v161
	s_nop 0
	s_waitcnt vmcnt(0)
	v_lshlrev_b32_e32 v165, 16, v131
	v_rcp_f32_e32 v160, v160
	s_nop 0
	v_mov_b32_e32 v166, v126
	v_mov_b32_e32 v167, v128
	v_lshlrev_b32_e32 v164, 16, v130
	v_pk_fma_f32 v[160:161], v[166:167], v[160:161], v[164:165]
	v_rcp_f32_e32 v163, v163
	s_nop 0
	v_and_b32_e32 v131, 0xffff0000, v131
	v_and_b32_e32 v130, 0xffff0000, v130
	v_rcp_f32_e32 v162, v162
	s_nop 0
	v_mov_b32_e32 v128, v127
	v_pk_fma_f32 v[126:127], v[128:129], v[162:163], v[130:131]
	v_cvt_pk_bf16_f32 v0, v160, v161
	v_cvt_pk_bf16_f32 v126, v126, v127
	v_and_b32_e32 v127, 0xffff0000, v126
	v_lshlrev_b32_e32 v126, 16, v126
	v_lshlrev_b32_e32 v131, 16, v133
	v_lshlrev_b32_e32 v130, 16, v132
	v_and_b32_e32 v129, 0xffff0000, v133
	v_and_b32_e32 v128, 0xffff0000, v132
	v_pk_add_f32 v[132:133], v[150:151], 1.0 op_sel_hi:[1,0]
	v_or_b32_sdwa v127, v127, v0 dst_sel:DWORD dst_unused:UNUSED_PAD src0_sel:DWORD src1_sel:WORD_1
	v_or_b32_sdwa v126, v126, v0 dst_sel:DWORD dst_unused:UNUSED_PAD src0_sel:DWORD src1_sel:WORD_0
	s_nop 0
	v_rcp_f32_e32 v133, v133
	s_nop 0
	s_nop 0
	v_rcp_f32_e32 v132, v132
	s_nop 0
	v_mov_b32_e32 v150, v122
	v_mov_b32_e32 v151, v124
	v_pk_fma_f32 v[130:131], v[150:151], v[132:133], v[130:131]
	v_pk_add_f32 v[132:133], v[148:149], 1.0 op_sel_hi:[1,0]
	s_nop 0
	s_nop 0
	v_rcp_f32_e32 v133, v133
	s_nop 0
	s_nop 0
	v_rcp_f32_e32 v132, v132
	s_nop 0
	v_mov_b32_e32 v124, v123
	v_pk_fma_f32 v[122:123], v[124:125], v[132:133], v[128:129]
	v_cvt_pk_bf16_f32 v0, v130, v131
	v_cvt_pk_bf16_f32 v122, v122, v123
	v_and_b32_e32 v123, 0xffff0000, v122
	v_lshlrev_b32_e32 v122, 16, v122
	v_or_b32_sdwa v129, v123, v0 dst_sel:DWORD dst_unused:UNUSED_PAD src0_sel:DWORD src1_sel:WORD_1
	v_or_b32_sdwa v128, v122, v0 dst_sel:DWORD dst_unused:UNUSED_PAD src0_sel:DWORD src1_sel:WORD_0
	global_store_dwordx4 v[146:147], v[126:129], off
	s_nop 1
	v_add_u32_e32 v126, 0x80, v156
	v_add_u32_e32 v0, v157, v126
	v_add_u32_e32 v0, v0, v158
	s_waitcnt vmcnt(11)
	v_lshlrev_b32_e32 v127, 16, v168
	v_and_b32_e32 v133, 0xffff0000, v168
	v_lshlrev_b32_e32 v147, 16, v169
	v_and_b32_e32 v149, 0xffff0000, v169
	v_lshl_add_u64 v[122:123], v[0:1], 1, s[10:11]
	v_lshlrev_b32_e32 v146, 16, v170
	v_mul_f32_e32 v0, 0xbfb8aa3b, v127
	v_exp_f32_e32 v132, v0
	v_mul_f32_e32 v0, 0xbfb8aa3b, v146
	v_and_b32_e32 v124, 0xffff0000, v170
	v_exp_f32_e32 v146, v0
	v_mul_f32_e32 v0, 0xbfb8aa3b, v133
	v_exp_f32_e32 v148, v0
	v_mul_f32_e32 v0, 0xbfb8aa3b, v124
	v_exp_f32_e32 v124, v0
	v_mul_f32_e32 v0, 0xbfb8aa3b, v147
	v_exp_f32_e32 v133, v0
	v_lshlrev_b32_e32 v150, 16, v171
	v_mul_f32_e32 v0, 0xbfb8aa3b, v150
	v_and_b32_e32 v125, 0xffff0000, v171
	v_exp_f32_e32 v147, v0
	v_mul_f32_e32 v0, 0xbfb8aa3b, v149
	v_exp_f32_e32 v149, v0
	v_mul_f32_e32 v0, 0xbfb8aa3b, v125
	v_pk_add_f32 v[132:133], v[132:133], 1.0 op_sel_hi:[1,0]
	v_exp_f32_e32 v125, v0
	v_pk_add_f32 v[148:149], v[148:149], 1.0 op_sel_hi:[1,0]
	v_pk_add_f32 v[124:125], v[124:125], 1.0 op_sel_hi:[1,0]
	v_rcp_f32_e32 v133, v133
	s_nop 0
	s_waitcnt vmcnt(10)
	v_lshlrev_b32_e32 v151, 16, v173
	v_rcp_f32_e32 v132, v132
	s_nop 0
	v_mov_b32_e32 v160, v118
	v_mov_b32_e32 v161, v120
	v_lshlrev_b32_e32 v150, 16, v172
	v_pk_fma_f32 v[132:133], v[160:161], v[132:133], v[150:151]
	v_rcp_f32_e32 v149, v149
	s_nop 0
	v_and_b32_e32 v129, 0xffff0000, v173
	v_and_b32_e32 v128, 0xffff0000, v172
	v_rcp_f32_e32 v148, v148
	s_nop 0
	v_mov_b32_e32 v120, v119
	v_pk_fma_f32 v[118:119], v[120:121], v[148:149], v[128:129]
	v_cvt_pk_bf16_f32 v0, v132, v133
	v_cvt_pk_bf16_f32 v118, v118, v119
	v_and_b32_e32 v119, 0xffff0000, v118
	v_lshlrev_b32_e32 v118, 16, v118
	v_lshlrev_b32_e32 v121, 16, v175
	v_lshlrev_b32_e32 v120, 16, v174
	v_and_b32_e32 v129, 0xffff0000, v175
	v_and_b32_e32 v128, 0xffff0000, v174
	v_pk_add_f32 v[130:131], v[146:147], 1.0 op_sel_hi:[1,0]
	v_or_b32_sdwa v119, v119, v0 dst_sel:DWORD dst_unused:UNUSED_PAD src0_sel:DWORD src1_sel:WORD_1
	v_or_b32_sdwa v118, v118, v0 dst_sel:DWORD dst_unused:UNUSED_PAD src0_sel:DWORD src1_sel:WORD_0
	s_nop 0
	v_rcp_f32_e32 v131, v131
	s_nop 0
	s_nop 0
	v_rcp_f32_e32 v130, v130
	s_nop 0
	v_mov_b32_e32 v132, v114
	v_mov_b32_e32 v133, v116
	v_pk_fma_f32 v[120:121], v[132:133], v[130:131], v[120:121]
	v_rcp_f32_e32 v125, v125
	s_nop 0
	s_nop 0
	v_rcp_f32_e32 v124, v124
	s_nop 0
	v_mov_b32_e32 v116, v115
	v_pk_fma_f32 v[114:115], v[116:117], v[124:125], v[128:129]
	v_cvt_pk_bf16_f32 v0, v120, v121
	v_cvt_pk_bf16_f32 v114, v114, v115
	v_and_b32_e32 v115, 0xffff0000, v114
	v_lshlrev_b32_e32 v114, 16, v114
	v_add_u32_e32 v127, 0x16c00, v157
	v_or_b32_sdwa v121, v115, v0 dst_sel:DWORD dst_unused:UNUSED_PAD src0_sel:DWORD src1_sel:WORD_1
	v_or_b32_sdwa v120, v114, v0 dst_sel:DWORD dst_unused:UNUSED_PAD src0_sel:DWORD src1_sel:WORD_0
	v_add_u32_e32 v0, v127, v156
	v_add_u32_e32 v212, 0x44400, v210
	v_lshl_add_u64 v[168:169], v[212:213], 1, s[6:7]
	global_load_dwordx4 v[168:171], v[168:169], off
	v_add_u32_e32 v212, 0xc000, v211
	v_lshl_add_u64 v[172:173], v[212:213], 1, s[10:11]
	global_load_dwordx4 v[172:175], v[172:173], off
	global_store_dwordx4 v[122:123], v[118:121], off
	s_nop 1
	v_or_b32_e32 v118, 16, v159
	v_mul_lo_u32 v146, v118, s61
	v_add_u32_e32 v0, v0, v146
	s_waitcnt vmcnt(12)
	v_lshlrev_b32_e32 v122, 16, v176
	v_and_b32_e32 v123, 0xffff0000, v176
	v_lshlrev_b32_e32 v125, 16, v177
	v_and_b32_e32 v129, 0xffff0000, v177
	v_lshl_add_u64 v[114:115], v[0:1], 1, s[10:11]
	v_lshlrev_b32_e32 v124, 16, v178
	v_mul_f32_e32 v0, 0xbfb8aa3b, v122
	v_exp_f32_e32 v122, v0
	v_mul_f32_e32 v0, 0xbfb8aa3b, v124
	v_and_b32_e32 v116, 0xffff0000, v178
	v_exp_f32_e32 v124, v0
	v_mul_f32_e32 v0, 0xbfb8aa3b, v123
	v_exp_f32_e32 v128, v0
	v_mul_f32_e32 v0, 0xbfb8aa3b, v116
	v_exp_f32_e32 v116, v0
	v_mul_f32_e32 v0, 0xbfb8aa3b, v125
	v_exp_f32_e32 v123, v0
	v_lshlrev_b32_e32 v130, 16, v179
	v_mul_f32_e32 v0, 0xbfb8aa3b, v130
	v_and_b32_e32 v117, 0xffff0000, v179
	v_exp_f32_e32 v125, v0
	v_mul_f32_e32 v0, 0xbfb8aa3b, v129
	v_exp_f32_e32 v129, v0
	v_mul_f32_e32 v0, 0xbfb8aa3b, v117
	v_pk_add_f32 v[122:123], v[122:123], 1.0 op_sel_hi:[1,0]
	v_exp_f32_e32 v117, v0
	v_pk_add_f32 v[128:129], v[128:129], 1.0 op_sel_hi:[1,0]
	v_pk_add_f32 v[116:117], v[116:117], 1.0 op_sel_hi:[1,0]
	v_rcp_f32_e32 v123, v123
	s_nop 0
	s_waitcnt vmcnt(11)
	v_lshlrev_b32_e32 v131, 16, v183
	v_rcp_f32_e32 v122, v122
	s_nop 0
	v_mov_b32_e32 v132, v110
	v_mov_b32_e32 v133, v112
	v_lshlrev_b32_e32 v130, 16, v182
	v_pk_fma_f32 v[122:123], v[132:133], v[122:123], v[130:131]
	v_rcp_f32_e32 v129, v129
	s_nop 0
	v_and_b32_e32 v119, 0xffff0000, v183
	v_and_b32_e32 v118, 0xffff0000, v182
	v_rcp_f32_e32 v128, v128
	s_nop 0
	v_mov_b32_e32 v112, v111
	v_pk_fma_f32 v[110:111], v[112:113], v[128:129], v[118:119]
	v_cvt_pk_bf16_f32 v0, v122, v123
	v_cvt_pk_bf16_f32 v110, v110, v111
	v_and_b32_e32 v111, 0xffff0000, v110
	v_lshlrev_b32_e32 v110, 16, v110
	v_lshlrev_b32_e32 v113, 16, v185
	v_lshlrev_b32_e32 v112, 16, v184
	v_and_b32_e32 v119, 0xffff0000, v185
	v_and_b32_e32 v118, 0xffff0000, v184
	v_pk_add_f32 v[120:121], v[124:125], 1.0 op_sel_hi:[1,0]
	v_or_b32_sdwa v111, v111, v0 dst_sel:DWORD dst_unused:UNUSED_PAD src0_sel:DWORD src1_sel:WORD_1
	v_or_b32_sdwa v110, v110, v0 dst_sel:DWORD dst_unused:UNUSED_PAD src0_sel:DWORD src1_sel:WORD_0
	s_nop 0
	v_rcp_f32_e32 v121, v121
	s_nop 0
	s_nop 0
	v_rcp_f32_e32 v120, v120
	s_nop 0
	v_mov_b32_e32 v122, v106
	v_mov_b32_e32 v123, v108
	v_pk_fma_f32 v[112:113], v[122:123], v[120:121], v[112:113]
	v_rcp_f32_e32 v117, v117
	s_nop 0
	s_nop 0
	v_rcp_f32_e32 v116, v116
	s_nop 0
	v_mov_b32_e32 v108, v107
	v_pk_fma_f32 v[106:107], v[108:109], v[116:117], v[118:119]
	v_cvt_pk_bf16_f32 v0, v112, v113
	v_cvt_pk_bf16_f32 v106, v106, v107
	v_and_b32_e32 v107, 0xffff0000, v106
	v_lshlrev_b32_e32 v106, 16, v106
	v_or_b32_sdwa v113, v107, v0 dst_sel:DWORD dst_unused:UNUSED_PAD src0_sel:DWORD src1_sel:WORD_1
	v_or_b32_sdwa v112, v106, v0 dst_sel:DWORD dst_unused:UNUSED_PAD src0_sel:DWORD src1_sel:WORD_0
	v_add_u32_e32 v0, v127, v126
	v_add_u32_e32 v212, 0x44480, v210
	v_lshl_add_u64 v[176:177], v[212:213], 1, s[6:7]
	global_load_dwordx4 v[176:179], v[176:177], off
	v_add_u32_e32 v212, 0xc080, v211
	v_lshl_add_u64 v[182:183], v[212:213], 1, s[10:11]
	global_load_dwordx4 v[182:185], v[182:183], off
	global_store_dwordx4 v[114:115], v[110:113], off
	v_add_u32_e32 v0, v0, v146
	s_waitcnt vmcnt(13)
	v_lshlrev_b32_e32 v114, 16, v186
	v_and_b32_e32 v115, 0xffff0000, v186
	v_lshlrev_b32_e32 v117, 16, v187
	v_and_b32_e32 v119, 0xffff0000, v187
	v_lshl_add_u64 v[106:107], v[0:1], 1, s[10:11]
	v_lshlrev_b32_e32 v116, 16, v188
	v_mul_f32_e32 v0, 0xbfb8aa3b, v114
	v_exp_f32_e32 v114, v0
	v_mul_f32_e32 v0, 0xbfb8aa3b, v116
	v_and_b32_e32 v108, 0xffff0000, v188
	v_exp_f32_e32 v116, v0
	v_mul_f32_e32 v0, 0xbfb8aa3b, v115
	v_exp_f32_e32 v118, v0
	v_mul_f32_e32 v0, 0xbfb8aa3b, v108
	v_exp_f32_e32 v108, v0
	v_mul_f32_e32 v0, 0xbfb8aa3b, v117
	v_exp_f32_e32 v115, v0
	v_lshlrev_b32_e32 v120, 16, v189
	v_mul_f32_e32 v0, 0xbfb8aa3b, v120
	v_and_b32_e32 v109, 0xffff0000, v189
	v_exp_f32_e32 v117, v0
	v_mul_f32_e32 v0, 0xbfb8aa3b, v119
	v_exp_f32_e32 v119, v0
	v_mul_f32_e32 v0, 0xbfb8aa3b, v109
	v_pk_add_f32 v[114:115], v[114:115], 1.0 op_sel_hi:[1,0]
	v_exp_f32_e32 v109, v0
	v_pk_add_f32 v[118:119], v[118:119], 1.0 op_sel_hi:[1,0]
	v_pk_add_f32 v[108:109], v[108:109], 1.0 op_sel_hi:[1,0]
	v_rcp_f32_e32 v115, v115
	s_nop 0
	s_waitcnt vmcnt(12)
	v_lshlrev_b32_e32 v121, 16, v191
	v_rcp_f32_e32 v114, v114
	s_nop 0
	v_mov_b32_e32 v122, v102
	v_mov_b32_e32 v123, v104
	v_lshlrev_b32_e32 v120, 16, v190
	v_pk_fma_f32 v[114:115], v[122:123], v[114:115], v[120:121]
	v_rcp_f32_e32 v119, v119
	s_nop 0
	v_and_b32_e32 v111, 0xffff0000, v191
	v_and_b32_e32 v110, 0xffff0000, v190
	v_rcp_f32_e32 v118, v118
	s_nop 0
	v_mov_b32_e32 v104, v103
	v_pk_fma_f32 v[102:103], v[104:105], v[118:119], v[110:111]
	v_cvt_pk_bf16_f32 v0, v114, v115
	v_cvt_pk_bf16_f32 v102, v102, v103
	v_and_b32_e32 v103, 0xffff0000, v102
	v_lshlrev_b32_e32 v102, 16, v102
	v_lshlrev_b32_e32 v105, 16, v193
	v_lshlrev_b32_e32 v104, 16, v192
	v_and_b32_e32 v111, 0xffff0000, v193
	v_and_b32_e32 v110, 0xffff0000, v192
	v_pk_add_f32 v[112:113], v[116:117], 1.0 op_sel_hi:[1,0]
	v_or_b32_sdwa v103, v103, v0 dst_sel:DWORD dst_unused:UNUSED_PAD src0_sel:DWORD src1_sel:WORD_1
	v_or_b32_sdwa v102, v102, v0 dst_sel:DWORD dst_unused:UNUSED_PAD src0_sel:DWORD src1_sel:WORD_0
	s_nop 0
	v_rcp_f32_e32 v113, v113
	s_nop 0
	s_nop 0
	v_rcp_f32_e32 v112, v112
	s_nop 0
	v_mov_b32_e32 v114, v98
	v_mov_b32_e32 v115, v100
	v_pk_fma_f32 v[104:105], v[114:115], v[112:113], v[104:105]
	v_add_u32_e32 v116, 0x2d800, v157
	v_rcp_f32_e32 v109, v109
	s_nop 0
	s_nop 0
	v_rcp_f32_e32 v108, v108
	s_nop 0
	v_mov_b32_e32 v100, v99
	v_pk_fma_f32 v[98:99], v[100:101], v[108:109], v[110:111]
	v_cvt_pk_bf16_f32 v0, v104, v105
	v_cvt_pk_bf16_f32 v98, v98, v99
	v_and_b32_e32 v99, 0xffff0000, v98
	v_lshlrev_b32_e32 v98, 16, v98
	v_or_b32_sdwa v105, v99, v0 dst_sel:DWORD dst_unused:UNUSED_PAD src0_sel:DWORD src1_sel:WORD_1
	v_or_b32_sdwa v104, v98, v0 dst_sel:DWORD dst_unused:UNUSED_PAD src0_sel:DWORD src1_sel:WORD_0
	v_add_u32_e32 v0, v116, v156
	v_add_u32_e32 v212, 0xb6000, v210
	v_lshl_add_u64 v[186:187], v[212:213], 1, s[6:7]
	global_load_dwordx4 v[186:189], v[186:187], off
	v_add_u32_e32 v212, 0x20000, v211
	v_lshl_add_u64 v[190:191], v[212:213], 1, s[10:11]
	global_load_dwordx4 v[190:193], v[190:191], off
	global_store_dwordx4 v[106:107], v[102:105], off
	s_nop 1
	v_or_b32_e32 v102, 32, v159
	v_mul_lo_u32 v117, v102, s61
	v_add_u32_e32 v0, v0, v117
	s_waitcnt vmcnt(14)
	v_lshlrev_b32_e32 v106, 16, v194
	v_and_b32_e32 v107, 0xffff0000, v194
	v_lshlrev_b32_e32 v109, 16, v195
	v_and_b32_e32 v111, 0xffff0000, v195
	v_lshl_add_u64 v[98:99], v[0:1], 1, s[10:11]
	v_lshlrev_b32_e32 v108, 16, v196
	v_mul_f32_e32 v0, 0xbfb8aa3b, v106
	v_exp_f32_e32 v106, v0
	v_mul_f32_e32 v0, 0xbfb8aa3b, v108
	v_and_b32_e32 v100, 0xffff0000, v196
	v_exp_f32_e32 v108, v0
	v_mul_f32_e32 v0, 0xbfb8aa3b, v107
	v_exp_f32_e32 v110, v0
	v_mul_f32_e32 v0, 0xbfb8aa3b, v100
	v_exp_f32_e32 v100, v0
	v_mul_f32_e32 v0, 0xbfb8aa3b, v109
	v_exp_f32_e32 v107, v0
	v_lshlrev_b32_e32 v112, 16, v197
	v_mul_f32_e32 v0, 0xbfb8aa3b, v112
	v_and_b32_e32 v101, 0xffff0000, v197
	v_exp_f32_e32 v109, v0
	v_mul_f32_e32 v0, 0xbfb8aa3b, v111
	v_exp_f32_e32 v111, v0
	v_mul_f32_e32 v0, 0xbfb8aa3b, v101
	v_pk_add_f32 v[106:107], v[106:107], 1.0 op_sel_hi:[1,0]
	v_exp_f32_e32 v101, v0
	v_pk_add_f32 v[110:111], v[110:111], 1.0 op_sel_hi:[1,0]
	v_pk_add_f32 v[100:101], v[100:101], 1.0 op_sel_hi:[1,0]
	v_rcp_f32_e32 v107, v107
	s_nop 0
	s_waitcnt vmcnt(13)
	v_lshlrev_b32_e32 v113, 16, v199
	v_rcp_f32_e32 v106, v106
	s_nop 0
	v_mov_b32_e32 v114, v94
	v_mov_b32_e32 v115, v96
	v_lshlrev_b32_e32 v112, 16, v198
	v_pk_fma_f32 v[106:107], v[114:115], v[106:107], v[112:113]
	v_rcp_f32_e32 v111, v111
	s_nop 0
	v_and_b32_e32 v103, 0xffff0000, v199
	v_and_b32_e32 v102, 0xffff0000, v198
	v_rcp_f32_e32 v110, v110
	s_nop 0
	v_mov_b32_e32 v96, v95
	v_pk_fma_f32 v[94:95], v[96:97], v[110:111], v[102:103]
	v_cvt_pk_bf16_f32 v0, v106, v107
	v_cvt_pk_bf16_f32 v94, v94, v95
	v_and_b32_e32 v95, 0xffff0000, v94
	v_lshlrev_b32_e32 v94, 16, v94
	v_lshlrev_b32_e32 v97, 16, v201
	v_lshlrev_b32_e32 v96, 16, v200
	v_and_b32_e32 v103, 0xffff0000, v201
	v_and_b32_e32 v102, 0xffff0000, v200
	v_pk_add_f32 v[104:105], v[108:109], 1.0 op_sel_hi:[1,0]
	v_or_b32_sdwa v95, v95, v0 dst_sel:DWORD dst_unused:UNUSED_PAD src0_sel:DWORD src1_sel:WORD_1
	v_or_b32_sdwa v94, v94, v0 dst_sel:DWORD dst_unused:UNUSED_PAD src0_sel:DWORD src1_sel:WORD_0
	s_nop 0
	v_rcp_f32_e32 v105, v105
	s_nop 0
	s_nop 0
	v_rcp_f32_e32 v104, v104
	s_nop 0
	v_mov_b32_e32 v106, v90
	v_mov_b32_e32 v107, v92
	v_pk_fma_f32 v[96:97], v[106:107], v[104:105], v[96:97]
	v_rcp_f32_e32 v101, v101
	s_nop 0
	s_nop 0
	v_rcp_f32_e32 v100, v100
	s_nop 0
	v_mov_b32_e32 v92, v91
	v_pk_fma_f32 v[90:91], v[92:93], v[100:101], v[102:103]
	v_cvt_pk_bf16_f32 v0, v96, v97
	v_cvt_pk_bf16_f32 v90, v90, v91
	v_and_b32_e32 v91, 0xffff0000, v90
	v_lshlrev_b32_e32 v90, 16, v90
	v_or_b32_sdwa v97, v91, v0 dst_sel:DWORD dst_unused:UNUSED_PAD src0_sel:DWORD src1_sel:WORD_1
	v_or_b32_sdwa v96, v90, v0 dst_sel:DWORD dst_unused:UNUSED_PAD src0_sel:DWORD src1_sel:WORD_0
	v_add_u32_e32 v0, v116, v126
	v_add_u32_e32 v212, 0xb6080, v210
	v_lshl_add_u64 v[194:195], v[212:213], 1, s[6:7]
	global_load_dwordx4 v[194:197], v[194:195], off
	v_add_u32_e32 v212, 0x20080, v211
	v_lshl_add_u64 v[198:199], v[212:213], 1, s[10:11]
	global_load_dwordx4 v[198:201], v[198:199], off
	global_store_dwordx4 v[98:99], v[94:97], off
	v_add_u32_e32 v0, v0, v117
	s_waitcnt vmcnt(15)
	v_lshlrev_b32_e32 v98, 16, v202
	v_and_b32_e32 v99, 0xffff0000, v202
	v_lshlrev_b32_e32 v101, 16, v203
	v_and_b32_e32 v103, 0xffff0000, v203
	v_lshl_add_u64 v[90:91], v[0:1], 1, s[10:11]
	v_lshlrev_b32_e32 v100, 16, v204
	v_mul_f32_e32 v0, 0xbfb8aa3b, v98
	v_exp_f32_e32 v98, v0
	v_mul_f32_e32 v0, 0xbfb8aa3b, v100
	v_and_b32_e32 v92, 0xffff0000, v204
	v_exp_f32_e32 v100, v0
	v_mul_f32_e32 v0, 0xbfb8aa3b, v99
	v_exp_f32_e32 v102, v0
	v_mul_f32_e32 v0, 0xbfb8aa3b, v92
	v_exp_f32_e32 v92, v0
	v_mul_f32_e32 v0, 0xbfb8aa3b, v101
	v_exp_f32_e32 v99, v0
	v_lshlrev_b32_e32 v104, 16, v205
	v_mul_f32_e32 v0, 0xbfb8aa3b, v104
	v_and_b32_e32 v93, 0xffff0000, v205
	v_exp_f32_e32 v101, v0
	v_mul_f32_e32 v0, 0xbfb8aa3b, v103
	v_exp_f32_e32 v103, v0
	v_mul_f32_e32 v0, 0xbfb8aa3b, v93
	v_pk_add_f32 v[98:99], v[98:99], 1.0 op_sel_hi:[1,0]
	v_exp_f32_e32 v93, v0
	v_pk_add_f32 v[102:103], v[102:103], 1.0 op_sel_hi:[1,0]
	v_pk_add_f32 v[92:93], v[92:93], 1.0 op_sel_hi:[1,0]
	v_rcp_f32_e32 v99, v99
	s_nop 0
	s_waitcnt vmcnt(14)
	v_lshlrev_b32_e32 v105, 16, v207
	v_rcp_f32_e32 v98, v98
	s_nop 0
	v_mov_b32_e32 v106, v86
	v_mov_b32_e32 v107, v88
	v_lshlrev_b32_e32 v104, 16, v206
	v_pk_fma_f32 v[98:99], v[106:107], v[98:99], v[104:105]
	v_rcp_f32_e32 v103, v103
	s_nop 0
	v_and_b32_e32 v95, 0xffff0000, v207
	v_and_b32_e32 v94, 0xffff0000, v206
	v_rcp_f32_e32 v102, v102
	s_nop 0
	v_mov_b32_e32 v88, v87
	v_pk_fma_f32 v[86:87], v[88:89], v[102:103], v[94:95]
	v_cvt_pk_bf16_f32 v0, v98, v99
	v_cvt_pk_bf16_f32 v86, v86, v87
	v_and_b32_e32 v87, 0xffff0000, v86
	v_lshlrev_b32_e32 v86, 16, v86
	v_lshlrev_b32_e32 v89, 16, v209
	v_lshlrev_b32_e32 v88, 16, v208
	v_and_b32_e32 v95, 0xffff0000, v209
	v_and_b32_e32 v94, 0xffff0000, v208
	v_pk_add_f32 v[96:97], v[100:101], 1.0 op_sel_hi:[1,0]
	v_or_b32_sdwa v87, v87, v0 dst_sel:DWORD dst_unused:UNUSED_PAD src0_sel:DWORD src1_sel:WORD_1
	v_or_b32_sdwa v86, v86, v0 dst_sel:DWORD dst_unused:UNUSED_PAD src0_sel:DWORD src1_sel:WORD_0
	s_nop 0
	v_rcp_f32_e32 v97, v97
	s_nop 0
	s_nop 0
	v_rcp_f32_e32 v96, v96
	s_nop 0
	v_mov_b32_e32 v98, v82
	v_mov_b32_e32 v99, v84
	v_pk_fma_f32 v[88:89], v[98:99], v[96:97], v[88:89]
	v_add_u32_e32 v100, 0x44400, v157
	v_rcp_f32_e32 v93, v93
	s_nop 0
	s_nop 0
	v_rcp_f32_e32 v92, v92
	s_nop 0
	v_mov_b32_e32 v84, v83
	v_pk_fma_f32 v[82:83], v[84:85], v[92:93], v[94:95]
	v_cvt_pk_bf16_f32 v0, v88, v89
	v_cvt_pk_bf16_f32 v82, v82, v83
	v_and_b32_e32 v83, 0xffff0000, v82
	v_lshlrev_b32_e32 v82, 16, v82
	v_or_b32_sdwa v89, v83, v0 dst_sel:DWORD dst_unused:UNUSED_PAD src0_sel:DWORD src1_sel:WORD_1
	v_or_b32_sdwa v88, v82, v0 dst_sel:DWORD dst_unused:UNUSED_PAD src0_sel:DWORD src1_sel:WORD_0
	v_add_u32_e32 v0, v100, v156
	v_add_u32_e32 v212, 0xccc00, v210
	v_lshl_add_u64 v[202:203], v[212:213], 1, s[6:7]
	global_load_dwordx4 v[202:205], v[202:203], off
	v_add_u32_e32 v212, 0x24000, v211
	v_lshl_add_u64 v[206:207], v[212:213], 1, s[10:11]
	global_load_dwordx4 v[206:209], v[206:207], off
	global_store_dwordx4 v[90:91], v[86:89], off
	s_nop 1
	v_or_b32_e32 v86, 48, v159
	v_mul_lo_u32 v101, v86, s61
	v_add_u32_e32 v0, v0, v101
	s_waitcnt vmcnt(14)
	v_lshlrev_b32_e32 v90, 16, v168
	v_and_b32_e32 v91, 0xffff0000, v168
	v_lshlrev_b32_e32 v93, 16, v169
	v_and_b32_e32 v95, 0xffff0000, v169
	v_lshl_add_u64 v[82:83], v[0:1], 1, s[10:11]
	v_lshlrev_b32_e32 v92, 16, v170
	v_mul_f32_e32 v0, 0xbfb8aa3b, v90
	v_exp_f32_e32 v90, v0
	v_mul_f32_e32 v0, 0xbfb8aa3b, v92
	v_and_b32_e32 v84, 0xffff0000, v170
	v_exp_f32_e32 v92, v0
	v_mul_f32_e32 v0, 0xbfb8aa3b, v91
	v_exp_f32_e32 v94, v0
	v_mul_f32_e32 v0, 0xbfb8aa3b, v84
	v_exp_f32_e32 v84, v0
	v_mul_f32_e32 v0, 0xbfb8aa3b, v93
	v_exp_f32_e32 v91, v0
	v_lshlrev_b32_e32 v96, 16, v171
	v_mul_f32_e32 v0, 0xbfb8aa3b, v96
	v_and_b32_e32 v85, 0xffff0000, v171
	v_exp_f32_e32 v93, v0
	v_mul_f32_e32 v0, 0xbfb8aa3b, v95
	v_exp_f32_e32 v95, v0
	v_mul_f32_e32 v0, 0xbfb8aa3b, v85
	v_pk_add_f32 v[90:91], v[90:91], 1.0 op_sel_hi:[1,0]
	v_exp_f32_e32 v85, v0
	v_pk_add_f32 v[94:95], v[94:95], 1.0 op_sel_hi:[1,0]
	v_pk_add_f32 v[84:85], v[84:85], 1.0 op_sel_hi:[1,0]
	v_rcp_f32_e32 v91, v91
	s_nop 0
	s_waitcnt vmcnt(13)
	v_lshlrev_b32_e32 v97, 16, v173
	v_rcp_f32_e32 v90, v90
	s_nop 0
	v_mov_b32_e32 v98, v78
	v_mov_b32_e32 v99, v80
	v_lshlrev_b32_e32 v96, 16, v172
	v_pk_fma_f32 v[90:91], v[98:99], v[90:91], v[96:97]
	v_rcp_f32_e32 v95, v95
	s_nop 0
	v_and_b32_e32 v87, 0xffff0000, v173
	v_and_b32_e32 v86, 0xffff0000, v172
	v_rcp_f32_e32 v94, v94
	s_nop 0
	v_mov_b32_e32 v80, v79
	v_pk_fma_f32 v[78:79], v[80:81], v[94:95], v[86:87]
	v_cvt_pk_bf16_f32 v0, v90, v91
	v_cvt_pk_bf16_f32 v78, v78, v79
	v_and_b32_e32 v79, 0xffff0000, v78
	v_lshlrev_b32_e32 v78, 16, v78
	v_lshlrev_b32_e32 v81, 16, v175
	v_lshlrev_b32_e32 v80, 16, v174
	v_and_b32_e32 v87, 0xffff0000, v175
	v_and_b32_e32 v86, 0xffff0000, v174
	v_pk_add_f32 v[88:89], v[92:93], 1.0 op_sel_hi:[1,0]
	v_or_b32_sdwa v79, v79, v0 dst_sel:DWORD dst_unused:UNUSED_PAD src0_sel:DWORD src1_sel:WORD_1
	v_or_b32_sdwa v78, v78, v0 dst_sel:DWORD dst_unused:UNUSED_PAD src0_sel:DWORD src1_sel:WORD_0
	s_nop 0
	v_rcp_f32_e32 v89, v89
	s_nop 0
	s_nop 0
	v_rcp_f32_e32 v88, v88
	s_nop 0
	v_mov_b32_e32 v90, v74
	v_mov_b32_e32 v91, v76
	v_pk_fma_f32 v[80:81], v[90:91], v[88:89], v[80:81]
	v_rcp_f32_e32 v85, v85
	s_nop 0
	s_nop 0
	v_rcp_f32_e32 v84, v84
	s_nop 0
	v_mov_b32_e32 v76, v75
	v_pk_fma_f32 v[74:75], v[76:77], v[84:85], v[86:87]
	v_cvt_pk_bf16_f32 v0, v80, v81
	v_cvt_pk_bf16_f32 v74, v74, v75
	v_and_b32_e32 v75, 0xffff0000, v74
	v_lshlrev_b32_e32 v74, 16, v74
	v_or_b32_sdwa v81, v75, v0 dst_sel:DWORD dst_unused:UNUSED_PAD src0_sel:DWORD src1_sel:WORD_1
	v_or_b32_sdwa v80, v74, v0 dst_sel:DWORD dst_unused:UNUSED_PAD src0_sel:DWORD src1_sel:WORD_0
	v_add_u32_e32 v0, v100, v126
	v_add_u32_e32 v212, 0xccc80, v210
	v_lshl_add_u64 v[168:169], v[212:213], 1, s[6:7]
	global_load_dwordx4 v[168:171], v[168:169], off
	v_add_u32_e32 v212, 0x24080, v211
	v_lshl_add_u64 v[172:173], v[212:213], 1, s[10:11]
	global_load_dwordx4 v[172:175], v[172:173], off
	global_store_dwordx4 v[82:83], v[78:81], off
	v_add_u32_e32 v0, v0, v101
	s_waitcnt vmcnt(14)
	v_lshlrev_b32_e32 v82, 16, v176
	v_and_b32_e32 v83, 0xffff0000, v176
	v_lshlrev_b32_e32 v85, 16, v177
	v_and_b32_e32 v87, 0xffff0000, v177
	v_lshl_add_u64 v[74:75], v[0:1], 1, s[10:11]
	v_lshlrev_b32_e32 v84, 16, v178
	v_mul_f32_e32 v0, 0xbfb8aa3b, v82
	v_exp_f32_e32 v82, v0
	v_mul_f32_e32 v0, 0xbfb8aa3b, v84
	v_and_b32_e32 v76, 0xffff0000, v178
	v_exp_f32_e32 v84, v0
	v_mul_f32_e32 v0, 0xbfb8aa3b, v83
	v_exp_f32_e32 v86, v0
	v_mul_f32_e32 v0, 0xbfb8aa3b, v76
	v_exp_f32_e32 v76, v0
	v_mul_f32_e32 v0, 0xbfb8aa3b, v85
	v_exp_f32_e32 v83, v0
	v_lshlrev_b32_e32 v88, 16, v179
	v_mul_f32_e32 v0, 0xbfb8aa3b, v88
	v_and_b32_e32 v77, 0xffff0000, v179
	v_exp_f32_e32 v85, v0
	v_mul_f32_e32 v0, 0xbfb8aa3b, v87
	v_exp_f32_e32 v87, v0
	v_mul_f32_e32 v0, 0xbfb8aa3b, v77
	v_pk_add_f32 v[82:83], v[82:83], 1.0 op_sel_hi:[1,0]
	v_exp_f32_e32 v77, v0
	v_pk_add_f32 v[86:87], v[86:87], 1.0 op_sel_hi:[1,0]
	v_pk_add_f32 v[76:77], v[76:77], 1.0 op_sel_hi:[1,0]
	v_rcp_f32_e32 v83, v83
	s_nop 0
	s_waitcnt vmcnt(13)
	v_lshlrev_b32_e32 v89, 16, v183
	v_rcp_f32_e32 v82, v82
	s_nop 0
	v_mov_b32_e32 v90, v70
	v_mov_b32_e32 v91, v72
	v_lshlrev_b32_e32 v88, 16, v182
	v_pk_fma_f32 v[82:83], v[90:91], v[82:83], v[88:89]
	v_rcp_f32_e32 v87, v87
	s_nop 0
	v_and_b32_e32 v79, 0xffff0000, v183
	v_and_b32_e32 v78, 0xffff0000, v182
	v_rcp_f32_e32 v86, v86
	s_nop 0
	v_mov_b32_e32 v72, v71
	v_pk_fma_f32 v[70:71], v[72:73], v[86:87], v[78:79]
	v_cvt_pk_bf16_f32 v0, v82, v83
	v_cvt_pk_bf16_f32 v70, v70, v71
	v_and_b32_e32 v71, 0xffff0000, v70
	v_lshlrev_b32_e32 v70, 16, v70
	v_lshlrev_b32_e32 v73, 16, v185
	v_lshlrev_b32_e32 v72, 16, v184
	v_and_b32_e32 v79, 0xffff0000, v185
	v_and_b32_e32 v78, 0xffff0000, v184
	v_pk_add_f32 v[80:81], v[84:85], 1.0 op_sel_hi:[1,0]
	v_or_b32_sdwa v71, v71, v0 dst_sel:DWORD dst_unused:UNUSED_PAD src0_sel:DWORD src1_sel:WORD_1
	v_or_b32_sdwa v70, v70, v0 dst_sel:DWORD dst_unused:UNUSED_PAD src0_sel:DWORD src1_sel:WORD_0
	s_nop 0
	v_rcp_f32_e32 v81, v81
	s_nop 0
	s_nop 0
	v_rcp_f32_e32 v80, v80
	s_nop 0
	v_mov_b32_e32 v82, v66
	v_mov_b32_e32 v83, v68
	v_pk_fma_f32 v[72:73], v[82:83], v[80:81], v[72:73]
	v_add_u32_e32 v84, 0xb6000, v157
	v_rcp_f32_e32 v77, v77
	s_nop 0
	v_add_u32_e32 v85, 0xfff6a000, v158
	v_rcp_f32_e32 v76, v76
	s_nop 0
	v_mov_b32_e32 v68, v67
	v_pk_fma_f32 v[66:67], v[68:69], v[76:77], v[78:79]
	v_cvt_pk_bf16_f32 v0, v72, v73
	v_cvt_pk_bf16_f32 v66, v66, v67
	v_and_b32_e32 v67, 0xffff0000, v66
	v_lshlrev_b32_e32 v66, 16, v66
	v_or_b32_sdwa v73, v67, v0 dst_sel:DWORD dst_unused:UNUSED_PAD src0_sel:DWORD src1_sel:WORD_1
	v_or_b32_sdwa v72, v66, v0 dst_sel:DWORD dst_unused:UNUSED_PAD src0_sel:DWORD src1_sel:WORD_0
	v_add_u32_e32 v0, v84, v156
	v_add_u32_e32 v212, 0xe3800, v210
	v_lshl_add_u64 v[176:177], v[212:213], 1, s[6:7]
	global_load_dwordx4 v[176:179], v[176:177], off
	v_add_u32_e32 v212, 0x28000, v211
	v_lshl_add_u64 v[182:183], v[212:213], 1, s[10:11]
	global_load_dwordx4 v[182:185], v[182:183], off
	global_store_dwordx4 v[74:75], v[70:73], off
	v_add_u32_e32 v0, v0, v85
	s_waitcnt vmcnt(14)
	v_lshlrev_b32_e32 v74, 16, v186
	v_and_b32_e32 v75, 0xffff0000, v186
	v_lshlrev_b32_e32 v77, 16, v187
	v_and_b32_e32 v79, 0xffff0000, v187
	v_lshl_add_u64 v[66:67], v[0:1], 1, s[10:11]
	v_lshlrev_b32_e32 v76, 16, v188
	v_mul_f32_e32 v0, 0xbfb8aa3b, v74
	v_exp_f32_e32 v74, v0
	v_mul_f32_e32 v0, 0xbfb8aa3b, v76
	v_and_b32_e32 v68, 0xffff0000, v188
	v_exp_f32_e32 v76, v0
	v_mul_f32_e32 v0, 0xbfb8aa3b, v75
	v_exp_f32_e32 v78, v0
	v_mul_f32_e32 v0, 0xbfb8aa3b, v68
	v_exp_f32_e32 v68, v0
	v_mul_f32_e32 v0, 0xbfb8aa3b, v77
	v_exp_f32_e32 v75, v0
	v_lshlrev_b32_e32 v80, 16, v189
	v_mul_f32_e32 v0, 0xbfb8aa3b, v80
	v_and_b32_e32 v69, 0xffff0000, v189
	v_exp_f32_e32 v77, v0
	v_mul_f32_e32 v0, 0xbfb8aa3b, v79
	v_exp_f32_e32 v79, v0
	v_mul_f32_e32 v0, 0xbfb8aa3b, v69
	v_pk_add_f32 v[74:75], v[74:75], 1.0 op_sel_hi:[1,0]
	v_exp_f32_e32 v69, v0
	v_pk_add_f32 v[78:79], v[78:79], 1.0 op_sel_hi:[1,0]
	v_pk_add_f32 v[68:69], v[68:69], 1.0 op_sel_hi:[1,0]
	v_rcp_f32_e32 v75, v75
	s_nop 0
	s_waitcnt vmcnt(13)
	v_lshlrev_b32_e32 v81, 16, v191
	v_rcp_f32_e32 v74, v74
	s_nop 0
	v_mov_b32_e32 v82, v62
	v_mov_b32_e32 v83, v64
	v_lshlrev_b32_e32 v80, 16, v190
	v_pk_fma_f32 v[74:75], v[82:83], v[74:75], v[80:81]
	v_rcp_f32_e32 v79, v79
	s_nop 0
	v_and_b32_e32 v71, 0xffff0000, v191
	v_and_b32_e32 v70, 0xffff0000, v190
	v_rcp_f32_e32 v78, v78
	s_nop 0
	v_mov_b32_e32 v64, v63
	v_pk_fma_f32 v[62:63], v[64:65], v[78:79], v[70:71]
	v_cvt_pk_bf16_f32 v0, v74, v75
	v_cvt_pk_bf16_f32 v62, v62, v63
	v_and_b32_e32 v63, 0xffff0000, v62
	v_lshlrev_b32_e32 v62, 16, v62
	v_lshlrev_b32_e32 v65, 16, v193
	v_lshlrev_b32_e32 v64, 16, v192
	v_and_b32_e32 v71, 0xffff0000, v193
	v_and_b32_e32 v70, 0xffff0000, v192
	v_pk_add_f32 v[72:73], v[76:77], 1.0 op_sel_hi:[1,0]
	v_or_b32_sdwa v63, v63, v0 dst_sel:DWORD dst_unused:UNUSED_PAD src0_sel:DWORD src1_sel:WORD_1
	v_or_b32_sdwa v62, v62, v0 dst_sel:DWORD dst_unused:UNUSED_PAD src0_sel:DWORD src1_sel:WORD_0
	s_nop 0
	v_rcp_f32_e32 v73, v73
	s_nop 0
	s_nop 0
	v_rcp_f32_e32 v72, v72
	s_nop 0
	v_mov_b32_e32 v74, v58
	v_mov_b32_e32 v75, v60
	v_pk_fma_f32 v[64:65], v[74:75], v[72:73], v[64:65]
	v_rcp_f32_e32 v69, v69
	s_nop 0
	s_nop 0
	v_rcp_f32_e32 v68, v68
	s_nop 0
	v_mov_b32_e32 v60, v59
	v_pk_fma_f32 v[58:59], v[60:61], v[68:69], v[70:71]
	v_cvt_pk_bf16_f32 v0, v64, v65
	v_cvt_pk_bf16_f32 v58, v58, v59
	v_and_b32_e32 v59, 0xffff0000, v58
	v_lshlrev_b32_e32 v58, 16, v58
	v_or_b32_sdwa v65, v59, v0 dst_sel:DWORD dst_unused:UNUSED_PAD src0_sel:DWORD src1_sel:WORD_1
	v_or_b32_sdwa v64, v58, v0 dst_sel:DWORD dst_unused:UNUSED_PAD src0_sel:DWORD src1_sel:WORD_0
	v_add_u32_e32 v0, v84, v126
	v_add_u32_e32 v212, 0xe3880, v210
	v_lshl_add_u64 v[186:187], v[212:213], 1, s[6:7]
	global_load_dwordx4 v[186:189], v[186:187], off
	v_add_u32_e32 v212, 0x28080, v211
	v_lshl_add_u64 v[190:191], v[212:213], 1, s[10:11]
	global_load_dwordx4 v[190:193], v[190:191], off
	global_store_dwordx4 v[66:67], v[62:65], off
	v_add_u32_e32 v0, v0, v85
	s_waitcnt vmcnt(14)
	v_lshlrev_b32_e32 v66, 16, v194
	v_and_b32_e32 v67, 0xffff0000, v194
	v_lshlrev_b32_e32 v69, 16, v195
	v_and_b32_e32 v71, 0xffff0000, v195
	v_lshl_add_u64 v[58:59], v[0:1], 1, s[10:11]
	v_lshlrev_b32_e32 v68, 16, v196
	v_mul_f32_e32 v0, 0xbfb8aa3b, v66
	v_exp_f32_e32 v66, v0
	v_mul_f32_e32 v0, 0xbfb8aa3b, v68
	v_and_b32_e32 v60, 0xffff0000, v196
	v_exp_f32_e32 v68, v0
	v_mul_f32_e32 v0, 0xbfb8aa3b, v67
	v_exp_f32_e32 v70, v0
	v_mul_f32_e32 v0, 0xbfb8aa3b, v60
	v_exp_f32_e32 v60, v0
	v_mul_f32_e32 v0, 0xbfb8aa3b, v69
	v_exp_f32_e32 v67, v0
	v_lshlrev_b32_e32 v72, 16, v197
	v_mul_f32_e32 v0, 0xbfb8aa3b, v72
	v_and_b32_e32 v61, 0xffff0000, v197
	v_exp_f32_e32 v69, v0
	v_mul_f32_e32 v0, 0xbfb8aa3b, v71
	v_exp_f32_e32 v71, v0
	v_mul_f32_e32 v0, 0xbfb8aa3b, v61
	v_pk_add_f32 v[66:67], v[66:67], 1.0 op_sel_hi:[1,0]
	v_exp_f32_e32 v61, v0
	v_pk_add_f32 v[70:71], v[70:71], 1.0 op_sel_hi:[1,0]
	v_pk_add_f32 v[60:61], v[60:61], 1.0 op_sel_hi:[1,0]
	v_rcp_f32_e32 v67, v67
	s_nop 0
	s_waitcnt vmcnt(13)
	v_lshlrev_b32_e32 v73, 16, v199
	v_rcp_f32_e32 v66, v66
	s_nop 0
	v_mov_b32_e32 v74, v54
	v_mov_b32_e32 v75, v56
	v_lshlrev_b32_e32 v72, 16, v198
	v_pk_fma_f32 v[66:67], v[74:75], v[66:67], v[72:73]
	v_rcp_f32_e32 v71, v71
	s_nop 0
	v_and_b32_e32 v63, 0xffff0000, v199
	v_and_b32_e32 v62, 0xffff0000, v198
	v_rcp_f32_e32 v70, v70
	s_nop 0
	v_mov_b32_e32 v56, v55
	v_pk_fma_f32 v[54:55], v[56:57], v[70:71], v[62:63]
	v_cvt_pk_bf16_f32 v0, v66, v67
	v_cvt_pk_bf16_f32 v54, v54, v55
	v_and_b32_e32 v55, 0xffff0000, v54
	v_lshlrev_b32_e32 v54, 16, v54
	v_lshlrev_b32_e32 v57, 16, v201
	v_lshlrev_b32_e32 v56, 16, v200
	v_and_b32_e32 v63, 0xffff0000, v201
	v_and_b32_e32 v62, 0xffff0000, v200
	v_pk_add_f32 v[64:65], v[68:69], 1.0 op_sel_hi:[1,0]
	v_or_b32_sdwa v55, v55, v0 dst_sel:DWORD dst_unused:UNUSED_PAD src0_sel:DWORD src1_sel:WORD_1
	v_or_b32_sdwa v54, v54, v0 dst_sel:DWORD dst_unused:UNUSED_PAD src0_sel:DWORD src1_sel:WORD_0
	s_nop 0
	v_rcp_f32_e32 v65, v65
	s_nop 0
	s_nop 0
	v_rcp_f32_e32 v64, v64
	s_nop 0
	v_mov_b32_e32 v66, v50
	v_mov_b32_e32 v67, v52
	v_pk_fma_f32 v[56:57], v[66:67], v[64:65], v[56:57]
	v_add_u32_e32 v68, 0xccc00, v157
	v_rcp_f32_e32 v61, v61
	s_nop 0
	v_add_u32_e32 v69, 0xfff57400, v158
	v_rcp_f32_e32 v60, v60
	s_nop 0
	v_mov_b32_e32 v52, v51
	v_pk_fma_f32 v[50:51], v[52:53], v[60:61], v[62:63]
	v_cvt_pk_bf16_f32 v0, v56, v57
	v_cvt_pk_bf16_f32 v50, v50, v51
	v_and_b32_e32 v51, 0xffff0000, v50
	v_lshlrev_b32_e32 v50, 16, v50
	v_or_b32_sdwa v57, v51, v0 dst_sel:DWORD dst_unused:UNUSED_PAD src0_sel:DWORD src1_sel:WORD_1
	v_or_b32_sdwa v56, v50, v0 dst_sel:DWORD dst_unused:UNUSED_PAD src0_sel:DWORD src1_sel:WORD_0
	v_add_u32_e32 v0, v68, v156
	v_add_u32_e32 v212, 0xfa400, v210
	v_lshl_add_u64 v[194:195], v[212:213], 1, s[6:7]
	global_load_dwordx4 v[194:197], v[194:195], off
	v_add_u32_e32 v212, 0x2c000, v211
	v_lshl_add_u64 v[198:199], v[212:213], 1, s[10:11]
	global_load_dwordx4 v[198:201], v[198:199], off
	global_store_dwordx4 v[58:59], v[54:57], off
	v_add_u32_e32 v0, v0, v69
	s_waitcnt vmcnt(14)
	v_lshlrev_b32_e32 v58, 16, v202
	v_and_b32_e32 v59, 0xffff0000, v202
	v_lshlrev_b32_e32 v61, 16, v203
	v_and_b32_e32 v63, 0xffff0000, v203
	v_lshl_add_u64 v[50:51], v[0:1], 1, s[10:11]
	v_lshlrev_b32_e32 v60, 16, v204
	v_mul_f32_e32 v0, 0xbfb8aa3b, v58
	v_exp_f32_e32 v58, v0
	v_mul_f32_e32 v0, 0xbfb8aa3b, v60
	v_and_b32_e32 v52, 0xffff0000, v204
	v_exp_f32_e32 v60, v0
	v_mul_f32_e32 v0, 0xbfb8aa3b, v59
	v_exp_f32_e32 v62, v0
	v_mul_f32_e32 v0, 0xbfb8aa3b, v52
	v_exp_f32_e32 v52, v0
	v_mul_f32_e32 v0, 0xbfb8aa3b, v61
	v_exp_f32_e32 v59, v0
	v_lshlrev_b32_e32 v64, 16, v205
	v_mul_f32_e32 v0, 0xbfb8aa3b, v64
	v_and_b32_e32 v53, 0xffff0000, v205
	v_exp_f32_e32 v61, v0
	v_mul_f32_e32 v0, 0xbfb8aa3b, v63
	v_exp_f32_e32 v63, v0
	v_mul_f32_e32 v0, 0xbfb8aa3b, v53
	v_pk_add_f32 v[58:59], v[58:59], 1.0 op_sel_hi:[1,0]
	v_exp_f32_e32 v53, v0
	v_pk_add_f32 v[62:63], v[62:63], 1.0 op_sel_hi:[1,0]
	v_pk_add_f32 v[52:53], v[52:53], 1.0 op_sel_hi:[1,0]
	v_rcp_f32_e32 v59, v59
	s_nop 0
	s_waitcnt vmcnt(13)
	v_lshlrev_b32_e32 v65, 16, v207
	v_rcp_f32_e32 v58, v58
	s_nop 0
	v_mov_b32_e32 v66, v46
	v_mov_b32_e32 v67, v48
	v_lshlrev_b32_e32 v64, 16, v206
	v_pk_fma_f32 v[58:59], v[66:67], v[58:59], v[64:65]
	v_rcp_f32_e32 v63, v63
	s_nop 0
	v_and_b32_e32 v55, 0xffff0000, v207
	v_and_b32_e32 v54, 0xffff0000, v206
	v_rcp_f32_e32 v62, v62
	s_nop 0
	v_mov_b32_e32 v48, v47
	v_pk_fma_f32 v[46:47], v[48:49], v[62:63], v[54:55]
	v_cvt_pk_bf16_f32 v0, v58, v59
	v_cvt_pk_bf16_f32 v46, v46, v47
	v_and_b32_e32 v47, 0xffff0000, v46
	v_lshlrev_b32_e32 v46, 16, v46
	v_lshlrev_b32_e32 v49, 16, v209
	v_lshlrev_b32_e32 v48, 16, v208
	v_and_b32_e32 v55, 0xffff0000, v209
	v_and_b32_e32 v54, 0xffff0000, v208
	v_pk_add_f32 v[56:57], v[60:61], 1.0 op_sel_hi:[1,0]
	v_or_b32_sdwa v47, v47, v0 dst_sel:DWORD dst_unused:UNUSED_PAD src0_sel:DWORD src1_sel:WORD_1
	v_or_b32_sdwa v46, v46, v0 dst_sel:DWORD dst_unused:UNUSED_PAD src0_sel:DWORD src1_sel:WORD_0
	s_nop 0
	v_rcp_f32_e32 v57, v57
	s_nop 0
	s_nop 0
	v_rcp_f32_e32 v56, v56
	s_nop 0
	v_mov_b32_e32 v58, v42
	v_mov_b32_e32 v59, v44
	v_pk_fma_f32 v[48:49], v[58:59], v[56:57], v[48:49]
	v_rcp_f32_e32 v53, v53
	s_nop 0
	s_nop 0
	v_rcp_f32_e32 v52, v52
	s_nop 0
	v_mov_b32_e32 v44, v43
	v_pk_fma_f32 v[42:43], v[44:45], v[52:53], v[54:55]
	v_cvt_pk_bf16_f32 v0, v48, v49
	v_cvt_pk_bf16_f32 v42, v42, v43
	v_and_b32_e32 v43, 0xffff0000, v42
	v_lshlrev_b32_e32 v42, 16, v42
	v_or_b32_sdwa v49, v43, v0 dst_sel:DWORD dst_unused:UNUSED_PAD src0_sel:DWORD src1_sel:WORD_1
	v_or_b32_sdwa v48, v42, v0 dst_sel:DWORD dst_unused:UNUSED_PAD src0_sel:DWORD src1_sel:WORD_0
	v_add_u32_e32 v0, v68, v126
	v_add_u32_e32 v212, 0xfa480, v210
	v_lshl_add_u64 v[202:203], v[212:213], 1, s[6:7]
	global_load_dwordx4 v[202:205], v[202:203], off
	v_add_u32_e32 v212, 0x2c080, v211
	v_lshl_add_u64 v[206:207], v[212:213], 1, s[10:11]
	global_load_dwordx4 v[206:209], v[206:207], off
	global_store_dwordx4 v[50:51], v[46:49], off
	v_add_u32_e32 v0, v0, v69
	s_waitcnt vmcnt(14)
	v_lshlrev_b32_e32 v50, 16, v168
	v_and_b32_e32 v51, 0xffff0000, v168
	v_lshlrev_b32_e32 v53, 16, v169
	v_and_b32_e32 v55, 0xffff0000, v169
	v_lshl_add_u64 v[42:43], v[0:1], 1, s[10:11]
	v_lshlrev_b32_e32 v52, 16, v170
	v_mul_f32_e32 v0, 0xbfb8aa3b, v50
	v_exp_f32_e32 v50, v0
	v_mul_f32_e32 v0, 0xbfb8aa3b, v52
	v_and_b32_e32 v44, 0xffff0000, v170
	v_exp_f32_e32 v52, v0
	v_mul_f32_e32 v0, 0xbfb8aa3b, v51
	v_exp_f32_e32 v54, v0
	v_mul_f32_e32 v0, 0xbfb8aa3b, v44
	v_exp_f32_e32 v44, v0
	v_mul_f32_e32 v0, 0xbfb8aa3b, v53
	v_exp_f32_e32 v51, v0
	v_lshlrev_b32_e32 v56, 16, v171
	v_mul_f32_e32 v0, 0xbfb8aa3b, v56
	v_and_b32_e32 v45, 0xffff0000, v171
	v_exp_f32_e32 v53, v0
	v_mul_f32_e32 v0, 0xbfb8aa3b, v55
	v_exp_f32_e32 v55, v0
	v_mul_f32_e32 v0, 0xbfb8aa3b, v45
	v_pk_add_f32 v[50:51], v[50:51], 1.0 op_sel_hi:[1,0]
	v_exp_f32_e32 v45, v0
	v_pk_add_f32 v[54:55], v[54:55], 1.0 op_sel_hi:[1,0]
	v_pk_add_f32 v[44:45], v[44:45], 1.0 op_sel_hi:[1,0]
	v_rcp_f32_e32 v51, v51
	s_nop 0
	s_waitcnt vmcnt(13)
	v_lshlrev_b32_e32 v57, 16, v173
	v_rcp_f32_e32 v50, v50
	s_nop 0
	v_mov_b32_e32 v58, v38
	v_mov_b32_e32 v59, v40
	v_lshlrev_b32_e32 v56, 16, v172
	v_pk_fma_f32 v[50:51], v[58:59], v[50:51], v[56:57]
	v_rcp_f32_e32 v55, v55
	s_nop 0
	v_and_b32_e32 v47, 0xffff0000, v173
	v_and_b32_e32 v46, 0xffff0000, v172
	v_rcp_f32_e32 v54, v54
	s_nop 0
	v_mov_b32_e32 v40, v39
	v_pk_fma_f32 v[38:39], v[40:41], v[54:55], v[46:47]
	v_cvt_pk_bf16_f32 v0, v50, v51
	v_cvt_pk_bf16_f32 v38, v38, v39
	v_and_b32_e32 v39, 0xffff0000, v38
	v_lshlrev_b32_e32 v38, 16, v38
	v_lshlrev_b32_e32 v41, 16, v175
	v_lshlrev_b32_e32 v40, 16, v174
	v_and_b32_e32 v47, 0xffff0000, v175
	v_and_b32_e32 v46, 0xffff0000, v174
	v_pk_add_f32 v[48:49], v[52:53], 1.0 op_sel_hi:[1,0]
	v_or_b32_sdwa v39, v39, v0 dst_sel:DWORD dst_unused:UNUSED_PAD src0_sel:DWORD src1_sel:WORD_1
	v_or_b32_sdwa v38, v38, v0 dst_sel:DWORD dst_unused:UNUSED_PAD src0_sel:DWORD src1_sel:WORD_0
	s_nop 0
	v_rcp_f32_e32 v49, v49
	s_nop 0
	s_nop 0
	v_rcp_f32_e32 v48, v48
	s_nop 0
	v_mov_b32_e32 v50, v34
	v_mov_b32_e32 v51, v36
	v_pk_fma_f32 v[40:41], v[50:51], v[48:49], v[40:41]
	v_add_u32_e32 v52, 0xe3800, v157
	v_rcp_f32_e32 v45, v45
	s_nop 0
	v_add_u32_e32 v53, 0xfff44800, v158
	v_rcp_f32_e32 v44, v44
	s_nop 0
	v_mov_b32_e32 v36, v35
	v_pk_fma_f32 v[34:35], v[36:37], v[44:45], v[46:47]
	v_cvt_pk_bf16_f32 v0, v40, v41
	v_cvt_pk_bf16_f32 v34, v34, v35
	v_and_b32_e32 v35, 0xffff0000, v34
	v_lshlrev_b32_e32 v34, 16, v34
	v_or_b32_sdwa v41, v35, v0 dst_sel:DWORD dst_unused:UNUSED_PAD src0_sel:DWORD src1_sel:WORD_1
	v_or_b32_sdwa v40, v34, v0 dst_sel:DWORD dst_unused:UNUSED_PAD src0_sel:DWORD src1_sel:WORD_0
	v_add_u32_e32 v0, v52, v156
	global_store_dwordx4 v[42:43], v[38:41], off
	v_add_u32_e32 v0, v0, v53
	s_waitcnt vmcnt(12)
	v_lshlrev_b32_e32 v42, 16, v176
	v_and_b32_e32 v43, 0xffff0000, v176
	v_lshlrev_b32_e32 v45, 16, v177
	v_and_b32_e32 v47, 0xffff0000, v177
	v_lshl_add_u64 v[34:35], v[0:1], 1, s[10:11]
	v_lshlrev_b32_e32 v44, 16, v178
	v_mul_f32_e32 v0, 0xbfb8aa3b, v42
	v_exp_f32_e32 v42, v0
	v_mul_f32_e32 v0, 0xbfb8aa3b, v44
	v_and_b32_e32 v36, 0xffff0000, v178
	v_exp_f32_e32 v44, v0
	v_mul_f32_e32 v0, 0xbfb8aa3b, v43
	v_exp_f32_e32 v46, v0
	v_mul_f32_e32 v0, 0xbfb8aa3b, v36
	v_exp_f32_e32 v36, v0
	v_mul_f32_e32 v0, 0xbfb8aa3b, v45
	v_exp_f32_e32 v43, v0
	v_lshlrev_b32_e32 v48, 16, v179
	v_mul_f32_e32 v0, 0xbfb8aa3b, v48
	v_and_b32_e32 v37, 0xffff0000, v179
	v_exp_f32_e32 v45, v0
	v_mul_f32_e32 v0, 0xbfb8aa3b, v47
	v_exp_f32_e32 v47, v0
	v_mul_f32_e32 v0, 0xbfb8aa3b, v37
	v_pk_add_f32 v[42:43], v[42:43], 1.0 op_sel_hi:[1,0]
	v_exp_f32_e32 v37, v0
	v_pk_add_f32 v[46:47], v[46:47], 1.0 op_sel_hi:[1,0]
	v_pk_add_f32 v[36:37], v[36:37], 1.0 op_sel_hi:[1,0]
	v_rcp_f32_e32 v43, v43
	s_nop 0
	s_waitcnt vmcnt(11)
	v_lshlrev_b32_e32 v49, 16, v183
	v_rcp_f32_e32 v42, v42
	s_nop 0
	v_mov_b32_e32 v50, v30
	v_mov_b32_e32 v51, v32
	v_lshlrev_b32_e32 v48, 16, v182
	v_pk_fma_f32 v[42:43], v[50:51], v[42:43], v[48:49]
	v_rcp_f32_e32 v47, v47
	s_nop 0
	v_and_b32_e32 v39, 0xffff0000, v183
	v_and_b32_e32 v38, 0xffff0000, v182
	v_rcp_f32_e32 v46, v46
	s_nop 0
	v_mov_b32_e32 v32, v31
	v_pk_fma_f32 v[30:31], v[32:33], v[46:47], v[38:39]
	v_cvt_pk_bf16_f32 v0, v42, v43
	v_cvt_pk_bf16_f32 v30, v30, v31
	v_and_b32_e32 v31, 0xffff0000, v30
	v_lshlrev_b32_e32 v30, 16, v30
	v_lshlrev_b32_e32 v33, 16, v185
	v_lshlrev_b32_e32 v32, 16, v184
	v_and_b32_e32 v39, 0xffff0000, v185
	v_and_b32_e32 v38, 0xffff0000, v184
	v_pk_add_f32 v[40:41], v[44:45], 1.0 op_sel_hi:[1,0]
	v_or_b32_sdwa v31, v31, v0 dst_sel:DWORD dst_unused:UNUSED_PAD src0_sel:DWORD src1_sel:WORD_1
	v_or_b32_sdwa v30, v30, v0 dst_sel:DWORD dst_unused:UNUSED_PAD src0_sel:DWORD src1_sel:WORD_0
	s_nop 0
	v_rcp_f32_e32 v41, v41
	s_nop 0
	s_nop 0
	v_rcp_f32_e32 v40, v40
	s_nop 0
	v_mov_b32_e32 v42, v26
	v_mov_b32_e32 v43, v28
	v_pk_fma_f32 v[32:33], v[42:43], v[40:41], v[32:33]
	v_rcp_f32_e32 v37, v37
	s_nop 0
	s_nop 0
	v_rcp_f32_e32 v36, v36
	s_nop 0
	v_mov_b32_e32 v28, v27
	v_pk_fma_f32 v[26:27], v[28:29], v[36:37], v[38:39]
	v_cvt_pk_bf16_f32 v0, v32, v33
	v_cvt_pk_bf16_f32 v26, v26, v27
	v_and_b32_e32 v27, 0xffff0000, v26
	v_lshlrev_b32_e32 v26, 16, v26
	v_or_b32_sdwa v33, v27, v0 dst_sel:DWORD dst_unused:UNUSED_PAD src0_sel:DWORD src1_sel:WORD_1
	v_or_b32_sdwa v32, v26, v0 dst_sel:DWORD dst_unused:UNUSED_PAD src0_sel:DWORD src1_sel:WORD_0
	v_add_u32_e32 v0, v52, v126
	global_store_dwordx4 v[34:35], v[30:33], off
	v_add_u32_e32 v0, v0, v53
	s_waitcnt vmcnt(10)
	v_lshlrev_b32_e32 v34, 16, v186
	v_and_b32_e32 v35, 0xffff0000, v186
	v_lshlrev_b32_e32 v37, 16, v187
	v_and_b32_e32 v39, 0xffff0000, v187
	v_lshl_add_u64 v[26:27], v[0:1], 1, s[10:11]
	v_lshlrev_b32_e32 v36, 16, v188
	v_mul_f32_e32 v0, 0xbfb8aa3b, v34
	v_exp_f32_e32 v34, v0
	v_mul_f32_e32 v0, 0xbfb8aa3b, v36
	v_and_b32_e32 v28, 0xffff0000, v188
	v_exp_f32_e32 v36, v0
	v_mul_f32_e32 v0, 0xbfb8aa3b, v35
	v_exp_f32_e32 v38, v0
	v_mul_f32_e32 v0, 0xbfb8aa3b, v28
	v_exp_f32_e32 v28, v0
	v_mul_f32_e32 v0, 0xbfb8aa3b, v37
	v_exp_f32_e32 v35, v0
	v_lshlrev_b32_e32 v40, 16, v189
	v_mul_f32_e32 v0, 0xbfb8aa3b, v40
	v_and_b32_e32 v29, 0xffff0000, v189
	v_exp_f32_e32 v37, v0
	v_mul_f32_e32 v0, 0xbfb8aa3b, v39
	v_exp_f32_e32 v39, v0
	v_mul_f32_e32 v0, 0xbfb8aa3b, v29
	v_pk_add_f32 v[34:35], v[34:35], 1.0 op_sel_hi:[1,0]
	v_exp_f32_e32 v29, v0
	v_pk_add_f32 v[38:39], v[38:39], 1.0 op_sel_hi:[1,0]
	v_pk_add_f32 v[28:29], v[28:29], 1.0 op_sel_hi:[1,0]
	v_rcp_f32_e32 v35, v35
	s_nop 0
	s_waitcnt vmcnt(9)
	v_lshlrev_b32_e32 v41, 16, v191
	v_rcp_f32_e32 v34, v34
	s_nop 0
	v_mov_b32_e32 v42, v22
	v_mov_b32_e32 v43, v24
	v_lshlrev_b32_e32 v40, 16, v190
	v_pk_fma_f32 v[34:35], v[42:43], v[34:35], v[40:41]
	v_rcp_f32_e32 v39, v39
	s_nop 0
	v_and_b32_e32 v31, 0xffff0000, v191
	v_and_b32_e32 v30, 0xffff0000, v190
	v_rcp_f32_e32 v38, v38
	s_nop 0
	v_mov_b32_e32 v24, v23
	v_pk_fma_f32 v[22:23], v[24:25], v[38:39], v[30:31]
	v_cvt_pk_bf16_f32 v0, v34, v35
	v_cvt_pk_bf16_f32 v22, v22, v23
	v_and_b32_e32 v23, 0xffff0000, v22
	v_lshlrev_b32_e32 v22, 16, v22
	v_lshlrev_b32_e32 v25, 16, v193
	v_lshlrev_b32_e32 v24, 16, v192
	v_and_b32_e32 v31, 0xffff0000, v193
	v_and_b32_e32 v30, 0xffff0000, v192
	v_pk_add_f32 v[32:33], v[36:37], 1.0 op_sel_hi:[1,0]
	v_or_b32_sdwa v23, v23, v0 dst_sel:DWORD dst_unused:UNUSED_PAD src0_sel:DWORD src1_sel:WORD_1
	v_or_b32_sdwa v22, v22, v0 dst_sel:DWORD dst_unused:UNUSED_PAD src0_sel:DWORD src1_sel:WORD_0
	s_nop 0
	v_rcp_f32_e32 v33, v33
	s_nop 0
	s_nop 0
	v_rcp_f32_e32 v32, v32
	s_nop 0
	v_mov_b32_e32 v34, v18
	v_mov_b32_e32 v35, v20
	v_pk_fma_f32 v[24:25], v[34:35], v[32:33], v[24:25]
	v_add_u32_e32 v36, 0xfa400, v157
	v_rcp_f32_e32 v29, v29
	s_nop 0
	v_add_u32_e32 v37, 0xfff31c00, v158
	v_rcp_f32_e32 v28, v28
	s_nop 0
	v_mov_b32_e32 v20, v19
	v_pk_fma_f32 v[18:19], v[20:21], v[28:29], v[30:31]
	v_cvt_pk_bf16_f32 v0, v24, v25
	v_cvt_pk_bf16_f32 v18, v18, v19
	v_and_b32_e32 v19, 0xffff0000, v18
	v_lshlrev_b32_e32 v18, 16, v18
	v_or_b32_sdwa v25, v19, v0 dst_sel:DWORD dst_unused:UNUSED_PAD src0_sel:DWORD src1_sel:WORD_1
	v_or_b32_sdwa v24, v18, v0 dst_sel:DWORD dst_unused:UNUSED_PAD src0_sel:DWORD src1_sel:WORD_0
	v_add_u32_e32 v0, v36, v156
	global_store_dwordx4 v[26:27], v[22:25], off
	v_add_u32_e32 v0, v0, v37
	s_waitcnt vmcnt(8)
	v_lshlrev_b32_e32 v26, 16, v194
	v_and_b32_e32 v27, 0xffff0000, v194
	v_lshlrev_b32_e32 v29, 16, v195
	v_and_b32_e32 v31, 0xffff0000, v195
	v_lshl_add_u64 v[18:19], v[0:1], 1, s[10:11]
	v_lshlrev_b32_e32 v28, 16, v196
	v_mul_f32_e32 v0, 0xbfb8aa3b, v26
	v_exp_f32_e32 v26, v0
	v_mul_f32_e32 v0, 0xbfb8aa3b, v28
	v_and_b32_e32 v20, 0xffff0000, v196
	v_exp_f32_e32 v28, v0
	v_mul_f32_e32 v0, 0xbfb8aa3b, v27
	v_exp_f32_e32 v30, v0
	v_mul_f32_e32 v0, 0xbfb8aa3b, v20
	v_exp_f32_e32 v20, v0
	v_mul_f32_e32 v0, 0xbfb8aa3b, v29
	v_exp_f32_e32 v27, v0
	v_lshlrev_b32_e32 v32, 16, v197
	v_mul_f32_e32 v0, 0xbfb8aa3b, v32
	v_and_b32_e32 v21, 0xffff0000, v197
	v_exp_f32_e32 v29, v0
	v_mul_f32_e32 v0, 0xbfb8aa3b, v31
	v_exp_f32_e32 v31, v0
	v_mul_f32_e32 v0, 0xbfb8aa3b, v21
	v_pk_add_f32 v[26:27], v[26:27], 1.0 op_sel_hi:[1,0]
	v_exp_f32_e32 v21, v0
	v_pk_add_f32 v[30:31], v[30:31], 1.0 op_sel_hi:[1,0]
	v_pk_add_f32 v[20:21], v[20:21], 1.0 op_sel_hi:[1,0]
	v_rcp_f32_e32 v27, v27
	s_nop 0
	s_waitcnt vmcnt(7)
	v_lshlrev_b32_e32 v33, 16, v199
	v_rcp_f32_e32 v26, v26
	s_nop 0
	v_mov_b32_e32 v34, v14
	v_mov_b32_e32 v35, v16
	v_lshlrev_b32_e32 v32, 16, v198
	v_pk_fma_f32 v[26:27], v[34:35], v[26:27], v[32:33]
	v_rcp_f32_e32 v31, v31
	s_nop 0
	v_and_b32_e32 v23, 0xffff0000, v199
	v_and_b32_e32 v22, 0xffff0000, v198
	v_rcp_f32_e32 v30, v30
	s_nop 0
	v_mov_b32_e32 v16, v15
	v_pk_fma_f32 v[14:15], v[16:17], v[30:31], v[22:23]
	v_cvt_pk_bf16_f32 v0, v26, v27
	v_cvt_pk_bf16_f32 v14, v14, v15
	v_and_b32_e32 v15, 0xffff0000, v14
	v_lshlrev_b32_e32 v14, 16, v14
	v_lshlrev_b32_e32 v17, 16, v201
	v_lshlrev_b32_e32 v16, 16, v200
	v_and_b32_e32 v23, 0xffff0000, v201
	v_and_b32_e32 v22, 0xffff0000, v200
	v_pk_add_f32 v[24:25], v[28:29], 1.0 op_sel_hi:[1,0]
	v_or_b32_sdwa v15, v15, v0 dst_sel:DWORD dst_unused:UNUSED_PAD src0_sel:DWORD src1_sel:WORD_1
	v_or_b32_sdwa v14, v14, v0 dst_sel:DWORD dst_unused:UNUSED_PAD src0_sel:DWORD src1_sel:WORD_0
	s_nop 0
	v_rcp_f32_e32 v25, v25
	s_nop 0
	s_nop 0
	v_rcp_f32_e32 v24, v24
	s_nop 0
	v_mov_b32_e32 v26, v10
	v_mov_b32_e32 v27, v12
	v_pk_fma_f32 v[16:17], v[26:27], v[24:25], v[16:17]
	v_rcp_f32_e32 v21, v21
	s_nop 0
	s_nop 0
	v_rcp_f32_e32 v20, v20
	s_nop 0
	v_mov_b32_e32 v12, v11
	v_pk_fma_f32 v[10:11], v[12:13], v[20:21], v[22:23]
	v_cvt_pk_bf16_f32 v0, v16, v17
	v_cvt_pk_bf16_f32 v10, v10, v11
	v_and_b32_e32 v11, 0xffff0000, v10
	v_lshlrev_b32_e32 v10, 16, v10
	v_or_b32_sdwa v17, v11, v0 dst_sel:DWORD dst_unused:UNUSED_PAD src0_sel:DWORD src1_sel:WORD_1
	v_or_b32_sdwa v16, v10, v0 dst_sel:DWORD dst_unused:UNUSED_PAD src0_sel:DWORD src1_sel:WORD_0
	v_add_u32_e32 v0, v36, v126
	global_store_dwordx4 v[18:19], v[14:17], off
	v_add_u32_e32 v0, v0, v37
	s_waitcnt vmcnt(6)
	v_lshlrev_b32_e32 v18, 16, v202
	v_and_b32_e32 v19, 0xffff0000, v202
	v_lshlrev_b32_e32 v21, 16, v203
	v_and_b32_e32 v23, 0xffff0000, v203
	v_lshl_add_u64 v[10:11], v[0:1], 1, s[10:11]
	v_lshlrev_b32_e32 v20, 16, v204
	v_mul_f32_e32 v0, 0xbfb8aa3b, v18
	v_exp_f32_e32 v18, v0
	v_mul_f32_e32 v0, 0xbfb8aa3b, v20
	v_and_b32_e32 v12, 0xffff0000, v204
	v_exp_f32_e32 v20, v0
	v_mul_f32_e32 v0, 0xbfb8aa3b, v19
	v_exp_f32_e32 v22, v0
	v_mul_f32_e32 v0, 0xbfb8aa3b, v12
	v_exp_f32_e32 v12, v0
	v_mul_f32_e32 v0, 0xbfb8aa3b, v21
	v_exp_f32_e32 v19, v0
	v_lshlrev_b32_e32 v24, 16, v205
	v_mul_f32_e32 v0, 0xbfb8aa3b, v24
	v_and_b32_e32 v13, 0xffff0000, v205
	v_exp_f32_e32 v21, v0
	v_mul_f32_e32 v0, 0xbfb8aa3b, v23
	v_exp_f32_e32 v23, v0
	v_mul_f32_e32 v0, 0xbfb8aa3b, v13
	v_pk_add_f32 v[18:19], v[18:19], 1.0 op_sel_hi:[1,0]
	v_exp_f32_e32 v13, v0
	v_pk_add_f32 v[22:23], v[22:23], 1.0 op_sel_hi:[1,0]
	v_pk_add_f32 v[12:13], v[12:13], 1.0 op_sel_hi:[1,0]
	v_rcp_f32_e32 v19, v19
	s_nop 0
	s_waitcnt vmcnt(5)
	v_lshlrev_b32_e32 v25, 16, v207
	v_rcp_f32_e32 v18, v18
	s_nop 0
	v_mov_b32_e32 v26, v6
	v_mov_b32_e32 v27, v8
	v_lshlrev_b32_e32 v24, 16, v206
	v_pk_fma_f32 v[18:19], v[26:27], v[18:19], v[24:25]
	v_rcp_f32_e32 v23, v23
	s_nop 0
	v_and_b32_e32 v15, 0xffff0000, v207
	v_and_b32_e32 v14, 0xffff0000, v206
	v_rcp_f32_e32 v22, v22
	s_nop 0
	v_mov_b32_e32 v8, v7
	v_pk_fma_f32 v[6:7], v[8:9], v[22:23], v[14:15]
	v_cvt_pk_bf16_f32 v0, v18, v19
	v_cvt_pk_bf16_f32 v6, v6, v7
	v_and_b32_e32 v7, 0xffff0000, v6
	v_lshlrev_b32_e32 v6, 16, v6
	v_lshlrev_b32_e32 v9, 16, v209
	v_lshlrev_b32_e32 v8, 16, v208
	v_and_b32_e32 v15, 0xffff0000, v209
	v_and_b32_e32 v14, 0xffff0000, v208
	v_pk_add_f32 v[16:17], v[20:21], 1.0 op_sel_hi:[1,0]
	v_or_b32_sdwa v7, v7, v0 dst_sel:DWORD dst_unused:UNUSED_PAD src0_sel:DWORD src1_sel:WORD_1
	v_or_b32_sdwa v6, v6, v0 dst_sel:DWORD dst_unused:UNUSED_PAD src0_sel:DWORD src1_sel:WORD_0
	s_nop 0
	v_rcp_f32_e32 v17, v17
	s_nop 0
	s_nop 0
	v_rcp_f32_e32 v16, v16
	s_nop 0
	v_mov_b32_e32 v18, v2
	v_mov_b32_e32 v19, v4
	v_pk_fma_f32 v[8:9], v[18:19], v[16:17], v[8:9]
	v_rcp_f32_e32 v13, v13
	s_nop 0
	s_mov_b64 s[26:27], s[18:19]
	v_rcp_f32_e32 v12, v12
	s_nop 0
	v_mov_b32_e32 v4, v3
	v_pk_fma_f32 v[2:3], v[4:5], v[12:13], v[14:15]
	v_cvt_pk_bf16_f32 v0, v8, v9
	v_cvt_pk_bf16_f32 v2, v2, v3
	v_and_b32_e32 v3, 0xffff0000, v2
	v_lshlrev_b32_e32 v2, 16, v2
	v_or_b32_sdwa v9, v3, v0 dst_sel:DWORD dst_unused:UNUSED_PAD src0_sel:DWORD src1_sel:WORD_1
	v_or_b32_sdwa v8, v2, v0 dst_sel:DWORD dst_unused:UNUSED_PAD src0_sel:DWORD src1_sel:WORD_0
	s_and_b64 vcc, exec, s[12:13]
	global_store_dwordx4 v[10:11], v[6:9], off
	s_cbranch_vccz .LBB0_1356
	s_waitcnt vmcnt(0)
	v_readlane_b32 s76, v255, 8
	s_mov_b32 s92, 0x3b2aaaab
	s_cmp_gt_u32 s36, 3
	v_readlane_b32 s77, v255, 9
	s_mul_i32 s60, s33, 0x1800
	s_mul_hi_i32 s62, s64, 0x300
	s_mul_i32 s75, s33, 0x16c00
	s_mov_b32 s93, 0x3c800000
	s_cbranch_scc1 .LBB0_1363
	s_barrier

.LBB0_1372:
	v_add_u32_e32 v0, 0x10000, v154
	s_waitcnt vmcnt(0)
	ds_read_b128 v[130:133], v0
	ds_read_b128 v[146:149], v0 offset:1024
	ds_read_b128 v[156:159], v0 offset:2048
	ds_read_b128 v[160:163], v0 offset:3072
	s_add_u32 s28, s26, 0xfffc0080
	s_addc_u32 s29, s27, -1
	s_cmp_eq_u32 s97, 12
	s_cselect_b32 s31, s2, s29
	s_cselect_b32 s30, s17, s28
	s_cselect_b32 s29, s15, s94
	s_cselect_b32 s28, s89, s90
	v_lshl_add_u64 v[150:151], s[26:27], 0, v[142:143]
	s_add_i32 m0, s38, 0xc000
	ds_read_b128 v[164:167], v153
	ds_read_b128 v[168:171], v153 offset:1024
	ds_read_b128 v[172:175], v153 offset:2048
	ds_read_b128 v[176:179], v153 offset:3072
	ds_read_b128 v[182:185], v153 offset:4096
	ds_read_b128 v[186:189], v153 offset:5120
	ds_read_b128 v[190:193], v153 offset:6144
	ds_read_b128 v[194:197], v153 offset:7168
	global_load_lds_dwordx4 v[150:151], off
	v_lshl_add_u64 v[150:151], s[26:27], 0, v[144:145]
	s_add_i32 m0, s38, 0xe000
	s_nop 0
	global_load_lds_dwordx4 v[150:151], off
	s_waitcnt lgkmcnt(8)
	s_barrier
	s_waitcnt lgkmcnt(0)
	s_setprio 1
	s_waitcnt lgkmcnt(0)
	v_mfma_f32_16x16x32_bf16 v[126:129], v[130:133], v[164:167], v[126:129]
	v_mfma_f32_16x16x32_bf16 v[122:125], v[156:159], v[164:167], v[122:125]
	v_mfma_f32_16x16x32_bf16 v[110:113], v[130:133], v[172:175], v[110:113]
	v_mfma_f32_16x16x32_bf16 v[106:109], v[156:159], v[172:175], v[106:109]
	v_mfma_f32_16x16x32_bf16 v[94:97], v[130:133], v[182:185], v[94:97]
	v_mfma_f32_16x16x32_bf16 v[90:93], v[156:159], v[182:185], v[90:93]
	v_mfma_f32_16x16x32_bf16 v[78:81], v[130:133], v[190:193], v[78:81]
	v_mfma_f32_16x16x32_bf16 v[74:77], v[156:159], v[190:193], v[74:77]
	v_mfma_f32_16x16x32_bf16 v[126:129], v[146:149], v[168:171], v[126:129]
	v_mfma_f32_16x16x32_bf16 v[122:125], v[160:163], v[168:171], v[122:125]
	v_mfma_f32_16x16x32_bf16 v[110:113], v[146:149], v[176:179], v[110:113]
	v_mfma_f32_16x16x32_bf16 v[106:109], v[160:163], v[176:179], v[106:109]
	v_mfma_f32_16x16x32_bf16 v[94:97], v[146:149], v[186:189], v[94:97]
	v_mfma_f32_16x16x32_bf16 v[90:93], v[160:163], v[186:189], v[90:93]
	v_mfma_f32_16x16x32_bf16 v[78:81], v[146:149], v[194:197], v[78:81]
	v_mfma_f32_16x16x32_bf16 v[74:77], v[160:163], v[194:197], v[74:77]
	s_setprio 0
	s_barrier
	s_mov_b32 m0, s23
	v_add_u32_e32 v0, 0x14000, v154
	v_lshl_add_u64 v[150:151], s[28:29], 0, v[138:139]
	s_waitcnt vmcnt(0)
	ds_read_b128 v[198:201], v0
	ds_read_b128 v[202:205], v0 offset:1024
	ds_read_b128 v[206:209], v0 offset:2048
	ds_read_b128 v[210:213], v0 offset:3072
	global_load_lds_dwordx4 v[150:151], off
	v_lshl_add_u64 v[214:215], s[28:29], 0, v[134:135]
	s_mov_b32 m0, s25
	s_nop 0
	global_load_lds_dwordx4 v[214:215], off
	s_barrier
	s_waitcnt lgkmcnt(0)
	s_setprio 1
	s_waitcnt lgkmcnt(0)
	v_mfma_f32_16x16x32_bf16 v[118:121], v[198:201], v[164:167], v[118:121]
	v_mfma_f32_16x16x32_bf16 v[114:117], v[206:209], v[164:167], v[114:117]
	v_mfma_f32_16x16x32_bf16 v[102:105], v[198:201], v[172:175], v[102:105]
	v_mfma_f32_16x16x32_bf16 v[98:101], v[206:209], v[172:175], v[98:101]
	v_mfma_f32_16x16x32_bf16 v[86:89], v[198:201], v[182:185], v[86:89]
	v_mfma_f32_16x16x32_bf16 v[82:85], v[206:209], v[182:185], v[82:85]
	v_mfma_f32_16x16x32_bf16 v[70:73], v[198:201], v[190:193], v[70:73]
	v_mfma_f32_16x16x32_bf16 v[66:69], v[206:209], v[190:193], v[66:69]
	v_mfma_f32_16x16x32_bf16 v[118:121], v[202:205], v[168:171], v[118:121]
	v_mfma_f32_16x16x32_bf16 v[114:117], v[210:213], v[168:171], v[114:117]
	v_mfma_f32_16x16x32_bf16 v[102:105], v[202:205], v[176:179], v[102:105]
	v_mfma_f32_16x16x32_bf16 v[98:101], v[210:213], v[176:179], v[98:101]
	v_mfma_f32_16x16x32_bf16 v[86:89], v[202:205], v[186:189], v[86:89]
	v_mfma_f32_16x16x32_bf16 v[82:85], v[210:213], v[186:189], v[82:85]
	v_mfma_f32_16x16x32_bf16 v[70:73], v[202:205], v[194:197], v[70:73]
	v_mfma_f32_16x16x32_bf16 v[66:69], v[210:213], v[194:197], v[66:69]
	s_setprio 0
	s_mov_b32 m0, s38
	v_lshl_add_u64 v[216:217], s[30:31], 0, v[140:141]
	s_barrier
	s_waitcnt vmcnt(0)
	ds_read_b128 v[164:167], v153 offset:16384
	ds_read_b128 v[168:171], v153 offset:17408
	ds_read_b128 v[172:175], v153 offset:18432
	ds_read_b128 v[176:179], v153 offset:19456
	ds_read_b128 v[182:185], v153 offset:20480
	ds_read_b128 v[186:189], v153 offset:21504
	ds_read_b128 v[190:193], v153 offset:22528
	ds_read_b128 v[194:197], v153 offset:23552
	global_load_lds_dwordx4 v[216:217], off
	v_lshl_add_u64 v[222:223], s[30:31], 0, v[136:137]
	s_mov_b32 m0, s39
	s_nop 0
	global_load_lds_dwordx4 v[222:223], off
	s_barrier
	s_waitcnt lgkmcnt(0)
	s_setprio 1
	s_waitcnt lgkmcnt(0)
	v_mfma_f32_16x16x32_bf16 v[62:65], v[130:133], v[164:167], v[62:65]
	v_mfma_f32_16x16x32_bf16 v[58:61], v[156:159], v[164:167], v[58:61]
	v_mfma_f32_16x16x32_bf16 v[46:49], v[130:133], v[172:175], v[46:49]
	v_mfma_f32_16x16x32_bf16 v[42:45], v[156:159], v[172:175], v[42:45]
	v_mfma_f32_16x16x32_bf16 v[30:33], v[130:133], v[182:185], v[30:33]
	v_mfma_f32_16x16x32_bf16 v[26:29], v[156:159], v[182:185], v[26:29]
	v_mfma_f32_16x16x32_bf16 v[14:17], v[130:133], v[190:193], v[14:17]
	v_mfma_f32_16x16x32_bf16 v[10:13], v[156:159], v[190:193], v[10:13]
	v_mfma_f32_16x16x32_bf16 v[62:65], v[146:149], v[168:171], v[62:65]
	v_mfma_f32_16x16x32_bf16 v[58:61], v[160:163], v[168:171], v[58:61]
	v_mfma_f32_16x16x32_bf16 v[46:49], v[146:149], v[176:179], v[46:49]
	v_mfma_f32_16x16x32_bf16 v[42:45], v[160:163], v[176:179], v[42:45]
	v_mfma_f32_16x16x32_bf16 v[30:33], v[146:149], v[186:189], v[30:33]
	v_mfma_f32_16x16x32_bf16 v[26:29], v[160:163], v[186:189], v[26:29]
	v_mfma_f32_16x16x32_bf16 v[14:17], v[146:149], v[194:197], v[14:17]
	v_mfma_f32_16x16x32_bf16 v[10:13], v[160:163], v[194:197], v[10:13]
	s_setprio 0
	s_barrier
	s_add_u32 s76, s28, 0x40000
	s_addc_u32 s77, s29, 0
	s_mov_b32 m0, s68
	v_lshl_add_u64 v[130:131], s[76:77], 0, v[138:139]
	global_load_lds_dwordx4 v[130:131], off
	v_lshl_add_u64 v[130:131], s[76:77], 0, v[134:135]
	s_mov_b32 m0, s69
	s_nop 0
	global_load_lds_dwordx4 v[130:131], off
	s_waitcnt vmcnt(6)
	s_barrier
	s_setprio 1
	v_mfma_f32_16x16x32_bf16 v[54:57], v[198:201], v[164:167], v[54:57]
	v_mfma_f32_16x16x32_bf16 v[50:53], v[206:209], v[164:167], v[50:53]
	v_mfma_f32_16x16x32_bf16 v[38:41], v[198:201], v[172:175], v[38:41]
	v_mfma_f32_16x16x32_bf16 v[34:37], v[206:209], v[172:175], v[34:37]
	v_mfma_f32_16x16x32_bf16 v[22:25], v[198:201], v[182:185], v[22:25]
	v_mfma_f32_16x16x32_bf16 v[18:21], v[206:209], v[182:185], v[18:21]
	v_mfma_f32_16x16x32_bf16 v[6:9], v[198:201], v[190:193], v[6:9]
	v_mfma_f32_16x16x32_bf16 v[2:5], v[206:209], v[190:193], v[2:5]
	v_mfma_f32_16x16x32_bf16 v[54:57], v[202:205], v[168:171], v[54:57]
	v_mfma_f32_16x16x32_bf16 v[50:53], v[210:213], v[168:171], v[50:53]
	v_mfma_f32_16x16x32_bf16 v[38:41], v[202:205], v[176:179], v[38:41]
	v_mfma_f32_16x16x32_bf16 v[34:37], v[210:213], v[176:179], v[34:37]
	v_mfma_f32_16x16x32_bf16 v[22:25], v[202:205], v[186:189], v[22:25]
	v_mfma_f32_16x16x32_bf16 v[18:21], v[210:213], v[186:189], v[18:21]
	v_mfma_f32_16x16x32_bf16 v[6:9], v[202:205], v[194:197], v[6:9]
	v_mfma_f32_16x16x32_bf16 v[2:5], v[210:213], v[194:197], v[2:5]
	s_setprio 0
	v_add_u32_e32 v0, 0x18000, v154
	s_barrier
	s_waitcnt vmcnt(0)
	ds_read_b128 v[130:133], v0
	ds_read_b128 v[146:149], v0 offset:1024
	ds_read_b128 v[156:159], v0 offset:2048
	ds_read_b128 v[160:163], v0 offset:3072
	s_add_u32 s30, s30, 0x40000
	s_addc_u32 s31, s31, 0
	s_mov_b32 m0, s82
	v_lshl_add_u64 v[198:199], s[30:31], 0, v[140:141]
	ds_read_b128 v[164:167], v153 offset:32768
	ds_read_b128 v[168:171], v153 offset:33792
	ds_read_b128 v[172:175], v153 offset:34816
	ds_read_b128 v[176:179], v153 offset:35840
	ds_read_b128 v[182:185], v153 offset:36864
	ds_read_b128 v[186:189], v153 offset:37888
	ds_read_b128 v[190:193], v153 offset:38912
	ds_read_b128 v[194:197], v153 offset:39936
	global_load_lds_dwordx4 v[198:199], off
	v_lshl_add_u64 v[198:199], s[30:31], 0, v[136:137]
	s_mov_b32 m0, s96
	s_nop 0
	global_load_lds_dwordx4 v[198:199], off
	s_waitcnt lgkmcnt(8)
	s_barrier
	s_waitcnt lgkmcnt(0)
	s_setprio 1
	s_waitcnt lgkmcnt(0)
	v_mfma_f32_16x16x32_bf16 v[126:129], v[130:133], v[164:167], v[126:129]
	v_mfma_f32_16x16x32_bf16 v[122:125], v[156:159], v[164:167], v[122:125]
	v_mfma_f32_16x16x32_bf16 v[110:113], v[130:133], v[172:175], v[110:113]
	v_mfma_f32_16x16x32_bf16 v[106:109], v[156:159], v[172:175], v[106:109]
	v_mfma_f32_16x16x32_bf16 v[94:97], v[130:133], v[182:185], v[94:97]
	v_mfma_f32_16x16x32_bf16 v[90:93], v[156:159], v[182:185], v[90:93]
	v_mfma_f32_16x16x32_bf16 v[78:81], v[130:133], v[190:193], v[78:81]
	v_mfma_f32_16x16x32_bf16 v[74:77], v[156:159], v[190:193], v[74:77]
	v_mfma_f32_16x16x32_bf16 v[126:129], v[146:149], v[168:171], v[126:129]
	v_mfma_f32_16x16x32_bf16 v[122:125], v[160:163], v[168:171], v[122:125]
	v_mfma_f32_16x16x32_bf16 v[110:113], v[146:149], v[176:179], v[110:113]
	v_mfma_f32_16x16x32_bf16 v[106:109], v[160:163], v[176:179], v[106:109]
	v_mfma_f32_16x16x32_bf16 v[94:97], v[146:149], v[186:189], v[94:97]
	v_mfma_f32_16x16x32_bf16 v[90:93], v[160:163], v[186:189], v[90:93]
	v_mfma_f32_16x16x32_bf16 v[78:81], v[146:149], v[194:197], v[78:81]
	v_mfma_f32_16x16x32_bf16 v[74:77], v[160:163], v[194:197], v[74:77]
	s_setprio 0
	s_barrier
	s_mov_b32 m0, s4
	v_add_u32_e32 v0, 0x1c000, v154
	v_lshl_add_u64 v[150:151], v[150:151], 0, s[84:85]
	s_waitcnt vmcnt(0)
	ds_read_b128 v[198:201], v0
	ds_read_b128 v[202:205], v0 offset:1024
	ds_read_b128 v[206:209], v0 offset:2048
	ds_read_b128 v[210:213], v0 offset:3072
	global_load_lds_dwordx4 v[150:151], off
	v_lshl_add_u64 v[150:151], v[214:215], 0, s[84:85]
	s_mov_b32 m0, s5
	s_nop 0
	global_load_lds_dwordx4 v[150:151], off
	s_barrier
	s_waitcnt lgkmcnt(0)
	s_setprio 1
	s_waitcnt lgkmcnt(0)
	v_mfma_f32_16x16x32_bf16 v[118:121], v[198:201], v[164:167], v[118:121]
	v_mfma_f32_16x16x32_bf16 v[114:117], v[206:209], v[164:167], v[114:117]
	v_mfma_f32_16x16x32_bf16 v[102:105], v[198:201], v[172:175], v[102:105]
	v_mfma_f32_16x16x32_bf16 v[98:101], v[206:209], v[172:175], v[98:101]
	v_mfma_f32_16x16x32_bf16 v[86:89], v[198:201], v[182:185], v[86:89]
	v_mfma_f32_16x16x32_bf16 v[82:85], v[206:209], v[182:185], v[82:85]
	v_mfma_f32_16x16x32_bf16 v[70:73], v[198:201], v[190:193], v[70:73]
	v_mfma_f32_16x16x32_bf16 v[66:69], v[206:209], v[190:193], v[66:69]
	v_mfma_f32_16x16x32_bf16 v[118:121], v[202:205], v[168:171], v[118:121]
	v_mfma_f32_16x16x32_bf16 v[114:117], v[210:213], v[168:171], v[114:117]
	v_mfma_f32_16x16x32_bf16 v[102:105], v[202:205], v[176:179], v[102:105]
	v_mfma_f32_16x16x32_bf16 v[98:101], v[210:213], v[176:179], v[98:101]
	v_mfma_f32_16x16x32_bf16 v[86:89], v[202:205], v[186:189], v[86:89]
	v_mfma_f32_16x16x32_bf16 v[82:85], v[210:213], v[186:189], v[82:85]
	v_mfma_f32_16x16x32_bf16 v[70:73], v[202:205], v[194:197], v[70:73]
	v_mfma_f32_16x16x32_bf16 v[66:69], v[210:213], v[194:197], v[66:69]
	s_setprio 0
	s_mov_b32 m0, s60
	v_lshl_add_u64 v[150:151], v[216:217], 0, s[84:85]
	s_barrier
	s_waitcnt vmcnt(0)
	ds_read_b128 v[164:167], v153 offset:49152
	ds_read_b128 v[168:171], v153 offset:50176
	ds_read_b128 v[172:175], v153 offset:51200
	ds_read_b128 v[176:179], v153 offset:52224
	ds_read_b128 v[182:185], v153 offset:53248
	ds_read_b128 v[186:189], v153 offset:54272
	ds_read_b128 v[190:193], v153 offset:55296
	ds_read_b128 v[194:197], v153 offset:56320
	global_load_lds_dwordx4 v[150:151], off
	v_lshl_add_u64 v[150:151], v[222:223], 0, s[84:85]
	s_mov_b32 m0, s92
	s_nop 0
	global_load_lds_dwordx4 v[150:151], off
	s_barrier
	s_waitcnt lgkmcnt(0)
	s_setprio 1
	s_waitcnt lgkmcnt(0)
	v_mfma_f32_16x16x32_bf16 v[62:65], v[130:133], v[164:167], v[62:65]
	v_mfma_f32_16x16x32_bf16 v[58:61], v[156:159], v[164:167], v[58:61]
	v_mfma_f32_16x16x32_bf16 v[46:49], v[130:133], v[172:175], v[46:49]
	v_mfma_f32_16x16x32_bf16 v[42:45], v[156:159], v[172:175], v[42:45]
	v_mfma_f32_16x16x32_bf16 v[30:33], v[130:133], v[182:185], v[30:33]
	v_mfma_f32_16x16x32_bf16 v[26:29], v[156:159], v[182:185], v[26:29]
	v_mfma_f32_16x16x32_bf16 v[14:17], v[130:133], v[190:193], v[14:17]
	v_mfma_f32_16x16x32_bf16 v[10:13], v[156:159], v[190:193], v[10:13]
	v_mfma_f32_16x16x32_bf16 v[62:65], v[146:149], v[168:171], v[62:65]
	v_mfma_f32_16x16x32_bf16 v[58:61], v[160:163], v[168:171], v[58:61]
	v_mfma_f32_16x16x32_bf16 v[46:49], v[146:149], v[176:179], v[46:49]
	v_mfma_f32_16x16x32_bf16 v[42:45], v[160:163], v[176:179], v[42:45]
	v_mfma_f32_16x16x32_bf16 v[30:33], v[146:149], v[186:189], v[30:33]
	v_mfma_f32_16x16x32_bf16 v[26:29], v[160:163], v[186:189], v[26:29]
	v_mfma_f32_16x16x32_bf16 v[14:17], v[146:149], v[194:197], v[14:17]
	v_mfma_f32_16x16x32_bf16 v[10:13], v[160:163], v[194:197], v[10:13]
	s_setprio 0
	s_barrier
	s_add_u32 s28, s28, 0x40080
	s_addc_u32 s29, s29, 0
	s_mov_b32 m0, s93
	v_lshl_add_u64 v[130:131], s[28:29], 0, v[138:139]
	global_load_lds_dwordx4 v[130:131], off
	v_lshl_add_u64 v[130:131], s[28:29], 0, v[134:135]
	s_mov_b32 m0, s3
	s_nop 0
	global_load_lds_dwordx4 v[130:131], off
	s_waitcnt vmcnt(6)
	s_barrier
	s_setprio 1
	v_mfma_f32_16x16x32_bf16 v[54:57], v[198:201], v[164:167], v[54:57]
	v_mfma_f32_16x16x32_bf16 v[50:53], v[206:209], v[164:167], v[50:53]
	v_mfma_f32_16x16x32_bf16 v[38:41], v[198:201], v[172:175], v[38:41]
	v_mfma_f32_16x16x32_bf16 v[34:37], v[206:209], v[172:175], v[34:37]
	v_mfma_f32_16x16x32_bf16 v[22:25], v[198:201], v[182:185], v[22:25]
	v_mfma_f32_16x16x32_bf16 v[18:21], v[206:209], v[182:185], v[18:21]
	v_mfma_f32_16x16x32_bf16 v[6:9], v[198:201], v[190:193], v[6:9]
	v_mfma_f32_16x16x32_bf16 v[2:5], v[206:209], v[190:193], v[2:5]
	v_mfma_f32_16x16x32_bf16 v[54:57], v[202:205], v[168:171], v[54:57]
	v_mfma_f32_16x16x32_bf16 v[50:53], v[210:213], v[168:171], v[50:53]
	v_mfma_f32_16x16x32_bf16 v[38:41], v[202:205], v[176:179], v[38:41]
	v_mfma_f32_16x16x32_bf16 v[34:37], v[210:213], v[176:179], v[34:37]
	v_mfma_f32_16x16x32_bf16 v[22:25], v[202:205], v[186:189], v[22:25]
	v_mfma_f32_16x16x32_bf16 v[18:21], v[210:213], v[186:189], v[18:21]
	v_mfma_f32_16x16x32_bf16 v[6:9], v[202:205], v[194:197], v[6:9]
	v_mfma_f32_16x16x32_bf16 v[2:5], v[210:213], v[194:197], v[2:5]
	s_setprio 0
	s_add_i32 s97, s97, 2
	s_add_u32 s26, s26, 0x100
	s_addc_u32 s27, s27, 0
	s_add_u32 s90, s90, 0x100
	s_addc_u32 s94, s94, 0
	s_cmp_gt_u32 s97, 13
	s_barrier
	s_cbranch_scc0 .LBB0_1372
	v_lshl_add_u32 v159, s24, 8, v152
	v_lshl_add_u32 v156, s22, 8, v155
	v_mul_lo_u32 v157, v159, s71
	v_add_u32_e32 v0, v157, v156
	v_lshl_add_u64 v[130:131], v[0:1], 1, s[6:7]
	global_load_dwordx4 v[130:133], v[130:131], off
	v_mul_lo_u32 v158, v159, s61
	v_mov_b32_e32 v210, v0
	v_add_u32_e32 v211, v0, v158
	v_mov_b32_e32 v213, 0
	v_add_u32_e32 v212, 0x80, v210
	v_lshl_add_u64 v[168:169], v[212:213], 1, s[6:7]
	global_load_dwordx4 v[168:171], v[168:169], off
	v_add_u32_e32 v212, 0x80, v211
	v_lshl_add_u64 v[172:173], v[212:213], 1, s[10:11]
	global_load_dwordx4 v[172:175], v[172:173], off
	v_add_u32_e32 v212, 0x16c00, v210
	v_lshl_add_u64 v[176:177], v[212:213], 1, s[6:7]
	global_load_dwordx4 v[176:179], v[176:177], off
	v_add_u32_e32 v212, 0x4000, v211
	v_lshl_add_u64 v[182:183], v[212:213], 1, s[10:11]
	global_load_dwordx4 v[182:185], v[182:183], off
	v_add_u32_e32 v212, 0x16c80, v210
	v_lshl_add_u64 v[186:187], v[212:213], 1, s[6:7]
	global_load_dwordx4 v[186:189], v[186:187], off
	v_add_u32_e32 v212, 0x4080, v211
	v_lshl_add_u64 v[190:191], v[212:213], 1, s[10:11]
	global_load_dwordx4 v[190:193], v[190:191], off
	v_add_u32_e32 v212, 0x2d800, v210
	v_lshl_add_u64 v[194:195], v[212:213], 1, s[6:7]
	global_load_dwordx4 v[194:197], v[194:195], off
	v_add_u32_e32 v212, 0x8000, v211
	v_lshl_add_u64 v[198:199], v[212:213], 1, s[10:11]
	global_load_dwordx4 v[198:201], v[198:199], off
	v_add_u32_e32 v212, 0x2d880, v210
	v_lshl_add_u64 v[202:203], v[212:213], 1, s[6:7]
	global_load_dwordx4 v[202:205], v[202:203], off
	v_add_u32_e32 v212, 0x8080, v211
	v_lshl_add_u64 v[206:207], v[212:213], 1, s[10:11]
	global_load_dwordx4 v[206:209], v[206:207], off
	v_add_u32_e32 v0, v0, v158
	v_lshl_add_u64 v[146:147], v[0:1], 1, s[10:11]
	s_mov_b32 s22, s14
	s_mov_b32 s24, s16
	s_mov_b64 s[28:29], s[20:21]
	s_waitcnt vmcnt(10)
	v_lshlrev_b32_e32 v148, 16, v130
	v_and_b32_e32 v149, 0xffff0000, v130
	v_lshlrev_b32_e32 v151, 16, v131
	v_and_b32_e32 v163, 0xffff0000, v131
	v_lshlrev_b32_e32 v150, 16, v132
	v_and_b32_e32 v161, 0xffff0000, v132
	v_lshlrev_b32_e32 v164, 16, v133
	v_and_b32_e32 v165, 0xffff0000, v133
	global_load_dwordx4 v[130:133], v[146:147], off
	v_mul_f32_e32 v0, 0xbfb8aa3b, v148
	v_exp_f32_e32 v160, v0
	v_mul_f32_e32 v0, 0xbfb8aa3b, v150
	v_exp_f32_e32 v150, v0
	v_mul_f32_e32 v0, 0xbfb8aa3b, v149
	v_exp_f32_e32 v162, v0
	v_mul_f32_e32 v0, 0xbfb8aa3b, v161
	v_exp_f32_e32 v148, v0
	v_mul_f32_e32 v0, 0xbfb8aa3b, v151
	v_exp_f32_e32 v161, v0
	v_mul_f32_e32 v0, 0xbfb8aa3b, v164
	v_exp_f32_e32 v151, v0
	v_mul_f32_e32 v0, 0xbfb8aa3b, v163
	v_exp_f32_e32 v163, v0
	v_mul_f32_e32 v0, 0xbfb8aa3b, v165
	v_pk_add_f32 v[160:161], v[160:161], 1.0 op_sel_hi:[1,0]
	v_exp_f32_e32 v149, v0
	v_pk_add_f32 v[162:163], v[162:163], 1.0 op_sel_hi:[1,0]
	v_rcp_f32_e32 v161, v161
	s_nop 0
	s_waitcnt vmcnt(0)
	v_lshlrev_b32_e32 v165, 16, v131
	v_rcp_f32_e32 v160, v160
	s_nop 0
	v_mov_b32_e32 v166, v126
	v_mov_b32_e32 v167, v128
	v_lshlrev_b32_e32 v164, 16, v130
	v_pk_fma_f32 v[160:161], v[166:167], v[160:161], v[164:165]
	v_rcp_f32_e32 v163, v163
	s_nop 0
	v_and_b32_e32 v131, 0xffff0000, v131
	v_and_b32_e32 v130, 0xffff0000, v130
	v_rcp_f32_e32 v162, v162
	s_nop 0
	v_mov_b32_e32 v128, v127
	v_pk_fma_f32 v[126:127], v[128:129], v[162:163], v[130:131]
	v_cvt_pk_bf16_f32 v0, v160, v161
	v_cvt_pk_bf16_f32 v126, v126, v127
	v_and_b32_e32 v127, 0xffff0000, v126
	v_lshlrev_b32_e32 v126, 16, v126
	v_lshlrev_b32_e32 v131, 16, v133
	v_lshlrev_b32_e32 v130, 16, v132
	v_and_b32_e32 v129, 0xffff0000, v133
	v_and_b32_e32 v128, 0xffff0000, v132
	v_pk_add_f32 v[132:133], v[150:151], 1.0 op_sel_hi:[1,0]
	v_or_b32_sdwa v127, v127, v0 dst_sel:DWORD dst_unused:UNUSED_PAD src0_sel:DWORD src1_sel:WORD_1
	v_or_b32_sdwa v126, v126, v0 dst_sel:DWORD dst_unused:UNUSED_PAD src0_sel:DWORD src1_sel:WORD_0
	s_nop 0
	v_rcp_f32_e32 v133, v133
	s_nop 0
	s_nop 0
	v_rcp_f32_e32 v132, v132
	s_nop 0
	v_mov_b32_e32 v150, v122
	v_mov_b32_e32 v151, v124
	v_pk_fma_f32 v[130:131], v[150:151], v[132:133], v[130:131]
	v_pk_add_f32 v[132:133], v[148:149], 1.0 op_sel_hi:[1,0]
	s_nop 0
	s_nop 0
	v_rcp_f32_e32 v133, v133
	s_nop 0
	s_nop 0
	v_rcp_f32_e32 v132, v132
	s_nop 0
	v_mov_b32_e32 v124, v123
	v_pk_fma_f32 v[122:123], v[124:125], v[132:133], v[128:129]
	v_cvt_pk_bf16_f32 v0, v130, v131
	v_cvt_pk_bf16_f32 v122, v122, v123
	v_and_b32_e32 v123, 0xffff0000, v122
	v_lshlrev_b32_e32 v122, 16, v122
	v_or_b32_sdwa v129, v123, v0 dst_sel:DWORD dst_unused:UNUSED_PAD src0_sel:DWORD src1_sel:WORD_1
	v_or_b32_sdwa v128, v122, v0 dst_sel:DWORD dst_unused:UNUSED_PAD src0_sel:DWORD src1_sel:WORD_0
	global_store_dwordx4 v[146:147], v[126:129], off
	s_nop 1
	v_add_u32_e32 v126, 0x80, v156
	v_add_u32_e32 v0, v157, v126
	v_add_u32_e32 v0, v0, v158
	s_waitcnt vmcnt(11)
	v_lshlrev_b32_e32 v127, 16, v168
	v_and_b32_e32 v133, 0xffff0000, v168
	v_lshlrev_b32_e32 v147, 16, v169
	v_and_b32_e32 v149, 0xffff0000, v169
	v_lshl_add_u64 v[122:123], v[0:1], 1, s[10:11]
	v_lshlrev_b32_e32 v146, 16, v170
	v_mul_f32_e32 v0, 0xbfb8aa3b, v127
	v_exp_f32_e32 v132, v0
	v_mul_f32_e32 v0, 0xbfb8aa3b, v146
	v_and_b32_e32 v124, 0xffff0000, v170
	v_exp_f32_e32 v146, v0
	v_mul_f32_e32 v0, 0xbfb8aa3b, v133
	v_exp_f32_e32 v148, v0
	v_mul_f32_e32 v0, 0xbfb8aa3b, v124
	v_exp_f32_e32 v124, v0
	v_mul_f32_e32 v0, 0xbfb8aa3b, v147
	v_exp_f32_e32 v133, v0
	v_lshlrev_b32_e32 v150, 16, v171
	v_mul_f32_e32 v0, 0xbfb8aa3b, v150
	v_and_b32_e32 v125, 0xffff0000, v171
	v_exp_f32_e32 v147, v0
	v_mul_f32_e32 v0, 0xbfb8aa3b, v149
	v_exp_f32_e32 v149, v0
	v_mul_f32_e32 v0, 0xbfb8aa3b, v125
	v_pk_add_f32 v[132:133], v[132:133], 1.0 op_sel_hi:[1,0]
	v_exp_f32_e32 v125, v0
	v_pk_add_f32 v[148:149], v[148:149], 1.0 op_sel_hi:[1,0]
	v_pk_add_f32 v[124:125], v[124:125], 1.0 op_sel_hi:[1,0]
	v_rcp_f32_e32 v133, v133
	s_nop 0
	s_waitcnt vmcnt(10)
	v_lshlrev_b32_e32 v151, 16, v173
	v_rcp_f32_e32 v132, v132
	s_nop 0
	v_mov_b32_e32 v160, v118
	v_mov_b32_e32 v161, v120
	v_lshlrev_b32_e32 v150, 16, v172
	v_pk_fma_f32 v[132:133], v[160:161], v[132:133], v[150:151]
	v_rcp_f32_e32 v149, v149
	s_nop 0
	v_and_b32_e32 v129, 0xffff0000, v173
	v_and_b32_e32 v128, 0xffff0000, v172
	v_rcp_f32_e32 v148, v148
	s_nop 0
	v_mov_b32_e32 v120, v119
	v_pk_fma_f32 v[118:119], v[120:121], v[148:149], v[128:129]
	v_cvt_pk_bf16_f32 v0, v132, v133
	v_cvt_pk_bf16_f32 v118, v118, v119
	v_and_b32_e32 v119, 0xffff0000, v118
	v_lshlrev_b32_e32 v118, 16, v118
	v_lshlrev_b32_e32 v121, 16, v175
	v_lshlrev_b32_e32 v120, 16, v174
	v_and_b32_e32 v129, 0xffff0000, v175
	v_and_b32_e32 v128, 0xffff0000, v174
	v_pk_add_f32 v[130:131], v[146:147], 1.0 op_sel_hi:[1,0]
	v_or_b32_sdwa v119, v119, v0 dst_sel:DWORD dst_unused:UNUSED_PAD src0_sel:DWORD src1_sel:WORD_1
	v_or_b32_sdwa v118, v118, v0 dst_sel:DWORD dst_unused:UNUSED_PAD src0_sel:DWORD src1_sel:WORD_0
	s_nop 0
	v_rcp_f32_e32 v131, v131
	s_nop 0
	s_nop 0
	v_rcp_f32_e32 v130, v130
	s_nop 0
	v_mov_b32_e32 v132, v114
	v_mov_b32_e32 v133, v116
	v_pk_fma_f32 v[120:121], v[132:133], v[130:131], v[120:121]
	v_rcp_f32_e32 v125, v125
	s_nop 0
	s_nop 0
	v_rcp_f32_e32 v124, v124
	s_nop 0
	v_mov_b32_e32 v116, v115
	v_pk_fma_f32 v[114:115], v[116:117], v[124:125], v[128:129]
	v_cvt_pk_bf16_f32 v0, v120, v121
	v_cvt_pk_bf16_f32 v114, v114, v115
	v_and_b32_e32 v115, 0xffff0000, v114
	v_lshlrev_b32_e32 v114, 16, v114
	v_add_u32_e32 v127, 0x16c00, v157
	v_or_b32_sdwa v121, v115, v0 dst_sel:DWORD dst_unused:UNUSED_PAD src0_sel:DWORD src1_sel:WORD_1
	v_or_b32_sdwa v120, v114, v0 dst_sel:DWORD dst_unused:UNUSED_PAD src0_sel:DWORD src1_sel:WORD_0
	v_add_u32_e32 v0, v127, v156
	v_add_u32_e32 v212, 0x44400, v210
	v_lshl_add_u64 v[168:169], v[212:213], 1, s[6:7]
	global_load_dwordx4 v[168:171], v[168:169], off
	v_add_u32_e32 v212, 0xc000, v211
	v_lshl_add_u64 v[172:173], v[212:213], 1, s[10:11]
	global_load_dwordx4 v[172:175], v[172:173], off
	global_store_dwordx4 v[122:123], v[118:121], off
	s_nop 1
	v_or_b32_e32 v118, 16, v159
	v_mul_lo_u32 v146, v118, s61
	v_add_u32_e32 v0, v0, v146
	s_waitcnt vmcnt(12)
	v_lshlrev_b32_e32 v122, 16, v176
	v_and_b32_e32 v123, 0xffff0000, v176
	v_lshlrev_b32_e32 v125, 16, v177
	v_and_b32_e32 v129, 0xffff0000, v177
	v_lshl_add_u64 v[114:115], v[0:1], 1, s[10:11]
	v_lshlrev_b32_e32 v124, 16, v178
	v_mul_f32_e32 v0, 0xbfb8aa3b, v122
	v_exp_f32_e32 v122, v0
	v_mul_f32_e32 v0, 0xbfb8aa3b, v124
	v_and_b32_e32 v116, 0xffff0000, v178
	v_exp_f32_e32 v124, v0
	v_mul_f32_e32 v0, 0xbfb8aa3b, v123
	v_exp_f32_e32 v128, v0
	v_mul_f32_e32 v0, 0xbfb8aa3b, v116
	v_exp_f32_e32 v116, v0
	v_mul_f32_e32 v0, 0xbfb8aa3b, v125
	v_exp_f32_e32 v123, v0
	v_lshlrev_b32_e32 v130, 16, v179
	v_mul_f32_e32 v0, 0xbfb8aa3b, v130
	v_and_b32_e32 v117, 0xffff0000, v179
	v_exp_f32_e32 v125, v0
	v_mul_f32_e32 v0, 0xbfb8aa3b, v129
	v_exp_f32_e32 v129, v0
	v_mul_f32_e32 v0, 0xbfb8aa3b, v117
	v_pk_add_f32 v[122:123], v[122:123], 1.0 op_sel_hi:[1,0]
	v_exp_f32_e32 v117, v0
	v_pk_add_f32 v[128:129], v[128:129], 1.0 op_sel_hi:[1,0]
	v_pk_add_f32 v[116:117], v[116:117], 1.0 op_sel_hi:[1,0]
	v_rcp_f32_e32 v123, v123
	s_nop 0
	s_waitcnt vmcnt(11)
	v_lshlrev_b32_e32 v131, 16, v183
	v_rcp_f32_e32 v122, v122
	s_nop 0
	v_mov_b32_e32 v132, v110
	v_mov_b32_e32 v133, v112
	v_lshlrev_b32_e32 v130, 16, v182
	v_pk_fma_f32 v[122:123], v[132:133], v[122:123], v[130:131]
	v_rcp_f32_e32 v129, v129
	s_nop 0
	v_and_b32_e32 v119, 0xffff0000, v183
	v_and_b32_e32 v118, 0xffff0000, v182
	v_rcp_f32_e32 v128, v128
	s_nop 0
	v_mov_b32_e32 v112, v111
	v_pk_fma_f32 v[110:111], v[112:113], v[128:129], v[118:119]
	v_cvt_pk_bf16_f32 v0, v122, v123
	v_cvt_pk_bf16_f32 v110, v110, v111
	v_and_b32_e32 v111, 0xffff0000, v110
	v_lshlrev_b32_e32 v110, 16, v110
	v_lshlrev_b32_e32 v113, 16, v185
	v_lshlrev_b32_e32 v112, 16, v184
	v_and_b32_e32 v119, 0xffff0000, v185
	v_and_b32_e32 v118, 0xffff0000, v184
	v_pk_add_f32 v[120:121], v[124:125], 1.0 op_sel_hi:[1,0]
	v_or_b32_sdwa v111, v111, v0 dst_sel:DWORD dst_unused:UNUSED_PAD src0_sel:DWORD src1_sel:WORD_1
	v_or_b32_sdwa v110, v110, v0 dst_sel:DWORD dst_unused:UNUSED_PAD src0_sel:DWORD src1_sel:WORD_0
	s_nop 0
	v_rcp_f32_e32 v121, v121
	s_nop 0
	s_nop 0
	v_rcp_f32_e32 v120, v120
	s_nop 0
	v_mov_b32_e32 v122, v106
	v_mov_b32_e32 v123, v108
	v_pk_fma_f32 v[112:113], v[122:123], v[120:121], v[112:113]
	v_rcp_f32_e32 v117, v117
	s_nop 0
	s_nop 0
	v_rcp_f32_e32 v116, v116
	s_nop 0
	v_mov_b32_e32 v108, v107
	v_pk_fma_f32 v[106:107], v[108:109], v[116:117], v[118:119]
	v_cvt_pk_bf16_f32 v0, v112, v113
	v_cvt_pk_bf16_f32 v106, v106, v107
	v_and_b32_e32 v107, 0xffff0000, v106
	v_lshlrev_b32_e32 v106, 16, v106
	v_or_b32_sdwa v113, v107, v0 dst_sel:DWORD dst_unused:UNUSED_PAD src0_sel:DWORD src1_sel:WORD_1
	v_or_b32_sdwa v112, v106, v0 dst_sel:DWORD dst_unused:UNUSED_PAD src0_sel:DWORD src1_sel:WORD_0
	v_add_u32_e32 v0, v127, v126
	v_add_u32_e32 v212, 0x44480, v210
	v_lshl_add_u64 v[176:177], v[212:213], 1, s[6:7]
	global_load_dwordx4 v[176:179], v[176:177], off
	v_add_u32_e32 v212, 0xc080, v211
	v_lshl_add_u64 v[182:183], v[212:213], 1, s[10:11]
	global_load_dwordx4 v[182:185], v[182:183], off
	global_store_dwordx4 v[114:115], v[110:113], off
	v_add_u32_e32 v0, v0, v146
	s_waitcnt vmcnt(13)
	v_lshlrev_b32_e32 v114, 16, v186
	v_and_b32_e32 v115, 0xffff0000, v186
	v_lshlrev_b32_e32 v117, 16, v187
	v_and_b32_e32 v119, 0xffff0000, v187
	v_lshl_add_u64 v[106:107], v[0:1], 1, s[10:11]
	v_lshlrev_b32_e32 v116, 16, v188
	v_mul_f32_e32 v0, 0xbfb8aa3b, v114
	v_exp_f32_e32 v114, v0
	v_mul_f32_e32 v0, 0xbfb8aa3b, v116
	v_and_b32_e32 v108, 0xffff0000, v188
	v_exp_f32_e32 v116, v0
	v_mul_f32_e32 v0, 0xbfb8aa3b, v115
	v_exp_f32_e32 v118, v0
	v_mul_f32_e32 v0, 0xbfb8aa3b, v108
	v_exp_f32_e32 v108, v0
	v_mul_f32_e32 v0, 0xbfb8aa3b, v117
	v_exp_f32_e32 v115, v0
	v_lshlrev_b32_e32 v120, 16, v189
	v_mul_f32_e32 v0, 0xbfb8aa3b, v120
	v_and_b32_e32 v109, 0xffff0000, v189
	v_exp_f32_e32 v117, v0
	v_mul_f32_e32 v0, 0xbfb8aa3b, v119
	v_exp_f32_e32 v119, v0
	v_mul_f32_e32 v0, 0xbfb8aa3b, v109
	v_pk_add_f32 v[114:115], v[114:115], 1.0 op_sel_hi:[1,0]
	v_exp_f32_e32 v109, v0
	v_pk_add_f32 v[118:119], v[118:119], 1.0 op_sel_hi:[1,0]
	v_pk_add_f32 v[108:109], v[108:109], 1.0 op_sel_hi:[1,0]
	v_rcp_f32_e32 v115, v115
	s_nop 0
	s_waitcnt vmcnt(12)
	v_lshlrev_b32_e32 v121, 16, v191
	v_rcp_f32_e32 v114, v114
	s_nop 0
	v_mov_b32_e32 v122, v102
	v_mov_b32_e32 v123, v104
	v_lshlrev_b32_e32 v120, 16, v190
	v_pk_fma_f32 v[114:115], v[122:123], v[114:115], v[120:121]
	v_rcp_f32_e32 v119, v119
	s_nop 0
	v_and_b32_e32 v111, 0xffff0000, v191
	v_and_b32_e32 v110, 0xffff0000, v190
	v_rcp_f32_e32 v118, v118
	s_nop 0
	v_mov_b32_e32 v104, v103
	v_pk_fma_f32 v[102:103], v[104:105], v[118:119], v[110:111]
	v_cvt_pk_bf16_f32 v0, v114, v115
	v_cvt_pk_bf16_f32 v102, v102, v103
	v_and_b32_e32 v103, 0xffff0000, v102
	v_lshlrev_b32_e32 v102, 16, v102
	v_lshlrev_b32_e32 v105, 16, v193
	v_lshlrev_b32_e32 v104, 16, v192
	v_and_b32_e32 v111, 0xffff0000, v193
	v_and_b32_e32 v110, 0xffff0000, v192
	v_pk_add_f32 v[112:113], v[116:117], 1.0 op_sel_hi:[1,0]
	v_or_b32_sdwa v103, v103, v0 dst_sel:DWORD dst_unused:UNUSED_PAD src0_sel:DWORD src1_sel:WORD_1
	v_or_b32_sdwa v102, v102, v0 dst_sel:DWORD dst_unused:UNUSED_PAD src0_sel:DWORD src1_sel:WORD_0
	s_nop 0
	v_rcp_f32_e32 v113, v113
	s_nop 0
	s_nop 0
	v_rcp_f32_e32 v112, v112
	s_nop 0
	v_mov_b32_e32 v114, v98
	v_mov_b32_e32 v115, v100
	v_pk_fma_f32 v[104:105], v[114:115], v[112:113], v[104:105]
	v_add_u32_e32 v116, 0x2d800, v157
	v_rcp_f32_e32 v109, v109
	s_nop 0
	s_nop 0
	v_rcp_f32_e32 v108, v108
	s_nop 0
	v_mov_b32_e32 v100, v99
	v_pk_fma_f32 v[98:99], v[100:101], v[108:109], v[110:111]
	v_cvt_pk_bf16_f32 v0, v104, v105
	v_cvt_pk_bf16_f32 v98, v98, v99
	v_and_b32_e32 v99, 0xffff0000, v98
	v_lshlrev_b32_e32 v98, 16, v98
	v_or_b32_sdwa v105, v99, v0 dst_sel:DWORD dst_unused:UNUSED_PAD src0_sel:DWORD src1_sel:WORD_1
	v_or_b32_sdwa v104, v98, v0 dst_sel:DWORD dst_unused:UNUSED_PAD src0_sel:DWORD src1_sel:WORD_0
	v_add_u32_e32 v0, v116, v156
	v_add_u32_e32 v212, 0xb6000, v210
	v_lshl_add_u64 v[186:187], v[212:213], 1, s[6:7]
	global_load_dwordx4 v[186:189], v[186:187], off
	v_add_u32_e32 v212, 0x20000, v211
	v_lshl_add_u64 v[190:191], v[212:213], 1, s[10:11]
	global_load_dwordx4 v[190:193], v[190:191], off
	global_store_dwordx4 v[106:107], v[102:105], off
	s_nop 1
	v_or_b32_e32 v102, 32, v159
	v_mul_lo_u32 v117, v102, s61
	v_add_u32_e32 v0, v0, v117
	s_waitcnt vmcnt(14)
	v_lshlrev_b32_e32 v106, 16, v194
	v_and_b32_e32 v107, 0xffff0000, v194
	v_lshlrev_b32_e32 v109, 16, v195
	v_and_b32_e32 v111, 0xffff0000, v195
	v_lshl_add_u64 v[98:99], v[0:1], 1, s[10:11]
	v_lshlrev_b32_e32 v108, 16, v196
	v_mul_f32_e32 v0, 0xbfb8aa3b, v106
	v_exp_f32_e32 v106, v0
	v_mul_f32_e32 v0, 0xbfb8aa3b, v108
	v_and_b32_e32 v100, 0xffff0000, v196
	v_exp_f32_e32 v108, v0
	v_mul_f32_e32 v0, 0xbfb8aa3b, v107
	v_exp_f32_e32 v110, v0
	v_mul_f32_e32 v0, 0xbfb8aa3b, v100
	v_exp_f32_e32 v100, v0
	v_mul_f32_e32 v0, 0xbfb8aa3b, v109
	v_exp_f32_e32 v107, v0
	v_lshlrev_b32_e32 v112, 16, v197
	v_mul_f32_e32 v0, 0xbfb8aa3b, v112
	v_and_b32_e32 v101, 0xffff0000, v197
	v_exp_f32_e32 v109, v0
	v_mul_f32_e32 v0, 0xbfb8aa3b, v111
	v_exp_f32_e32 v111, v0
	v_mul_f32_e32 v0, 0xbfb8aa3b, v101
	v_pk_add_f32 v[106:107], v[106:107], 1.0 op_sel_hi:[1,0]
	v_exp_f32_e32 v101, v0
	v_pk_add_f32 v[110:111], v[110:111], 1.0 op_sel_hi:[1,0]
	v_pk_add_f32 v[100:101], v[100:101], 1.0 op_sel_hi:[1,0]
	v_rcp_f32_e32 v107, v107
	s_nop 0
	s_waitcnt vmcnt(13)
	v_lshlrev_b32_e32 v113, 16, v199
	v_rcp_f32_e32 v106, v106
	s_nop 0
	v_mov_b32_e32 v114, v94
	v_mov_b32_e32 v115, v96
	v_lshlrev_b32_e32 v112, 16, v198
	v_pk_fma_f32 v[106:107], v[114:115], v[106:107], v[112:113]
	v_rcp_f32_e32 v111, v111
	s_nop 0
	v_and_b32_e32 v103, 0xffff0000, v199
	v_and_b32_e32 v102, 0xffff0000, v198
	v_rcp_f32_e32 v110, v110
	s_nop 0
	v_mov_b32_e32 v96, v95
	v_pk_fma_f32 v[94:95], v[96:97], v[110:111], v[102:103]
	v_cvt_pk_bf16_f32 v0, v106, v107
	v_cvt_pk_bf16_f32 v94, v94, v95
	v_and_b32_e32 v95, 0xffff0000, v94
	v_lshlrev_b32_e32 v94, 16, v94
	v_lshlrev_b32_e32 v97, 16, v201
	v_lshlrev_b32_e32 v96, 16, v200
	v_and_b32_e32 v103, 0xffff0000, v201
	v_and_b32_e32 v102, 0xffff0000, v200
	v_pk_add_f32 v[104:105], v[108:109], 1.0 op_sel_hi:[1,0]
	v_or_b32_sdwa v95, v95, v0 dst_sel:DWORD dst_unused:UNUSED_PAD src0_sel:DWORD src1_sel:WORD_1
	v_or_b32_sdwa v94, v94, v0 dst_sel:DWORD dst_unused:UNUSED_PAD src0_sel:DWORD src1_sel:WORD_0
	s_nop 0
	v_rcp_f32_e32 v105, v105
	s_nop 0
	s_nop 0
	v_rcp_f32_e32 v104, v104
	s_nop 0
	v_mov_b32_e32 v106, v90
	v_mov_b32_e32 v107, v92
	v_pk_fma_f32 v[96:97], v[106:107], v[104:105], v[96:97]
	v_rcp_f32_e32 v101, v101
	s_nop 0
	s_nop 0
	v_rcp_f32_e32 v100, v100
	s_nop 0
	v_mov_b32_e32 v92, v91
	v_pk_fma_f32 v[90:91], v[92:93], v[100:101], v[102:103]
	v_cvt_pk_bf16_f32 v0, v96, v97
	v_cvt_pk_bf16_f32 v90, v90, v91
	v_and_b32_e32 v91, 0xffff0000, v90
	v_lshlrev_b32_e32 v90, 16, v90
	v_or_b32_sdwa v97, v91, v0 dst_sel:DWORD dst_unused:UNUSED_PAD src0_sel:DWORD src1_sel:WORD_1
	v_or_b32_sdwa v96, v90, v0 dst_sel:DWORD dst_unused:UNUSED_PAD src0_sel:DWORD src1_sel:WORD_0
	v_add_u32_e32 v0, v116, v126
	v_add_u32_e32 v212, 0xb6080, v210
	v_lshl_add_u64 v[194:195], v[212:213], 1, s[6:7]
	global_load_dwordx4 v[194:197], v[194:195], off
	v_add_u32_e32 v212, 0x20080, v211
	v_lshl_add_u64 v[198:199], v[212:213], 1, s[10:11]
	global_load_dwordx4 v[198:201], v[198:199], off
	global_store_dwordx4 v[98:99], v[94:97], off
	v_add_u32_e32 v0, v0, v117
	s_waitcnt vmcnt(15)
	v_lshlrev_b32_e32 v98, 16, v202
	v_and_b32_e32 v99, 0xffff0000, v202
	v_lshlrev_b32_e32 v101, 16, v203
	v_and_b32_e32 v103, 0xffff0000, v203
	v_lshl_add_u64 v[90:91], v[0:1], 1, s[10:11]
	v_lshlrev_b32_e32 v100, 16, v204
	v_mul_f32_e32 v0, 0xbfb8aa3b, v98
	v_exp_f32_e32 v98, v0
	v_mul_f32_e32 v0, 0xbfb8aa3b, v100
	v_and_b32_e32 v92, 0xffff0000, v204
	v_exp_f32_e32 v100, v0
	v_mul_f32_e32 v0, 0xbfb8aa3b, v99
	v_exp_f32_e32 v102, v0
	v_mul_f32_e32 v0, 0xbfb8aa3b, v92
	v_exp_f32_e32 v92, v0
	v_mul_f32_e32 v0, 0xbfb8aa3b, v101
	v_exp_f32_e32 v99, v0
	v_lshlrev_b32_e32 v104, 16, v205
	v_mul_f32_e32 v0, 0xbfb8aa3b, v104
	v_and_b32_e32 v93, 0xffff0000, v205
	v_exp_f32_e32 v101, v0
	v_mul_f32_e32 v0, 0xbfb8aa3b, v103
	v_exp_f32_e32 v103, v0
	v_mul_f32_e32 v0, 0xbfb8aa3b, v93
	v_pk_add_f32 v[98:99], v[98:99], 1.0 op_sel_hi:[1,0]
	v_exp_f32_e32 v93, v0
	v_pk_add_f32 v[102:103], v[102:103], 1.0 op_sel_hi:[1,0]
	v_pk_add_f32 v[92:93], v[92:93], 1.0 op_sel_hi:[1,0]
	v_rcp_f32_e32 v99, v99
	s_nop 0
	s_waitcnt vmcnt(14)
	v_lshlrev_b32_e32 v105, 16, v207
	v_rcp_f32_e32 v98, v98
	s_nop 0
	v_mov_b32_e32 v106, v86
	v_mov_b32_e32 v107, v88
	v_lshlrev_b32_e32 v104, 16, v206
	v_pk_fma_f32 v[98:99], v[106:107], v[98:99], v[104:105]
	v_rcp_f32_e32 v103, v103
	s_nop 0
	v_and_b32_e32 v95, 0xffff0000, v207
	v_and_b32_e32 v94, 0xffff0000, v206
	v_rcp_f32_e32 v102, v102
	s_nop 0
	v_mov_b32_e32 v88, v87
	v_pk_fma_f32 v[86:87], v[88:89], v[102:103], v[94:95]
	v_cvt_pk_bf16_f32 v0, v98, v99
	v_cvt_pk_bf16_f32 v86, v86, v87
	v_and_b32_e32 v87, 0xffff0000, v86
	v_lshlrev_b32_e32 v86, 16, v86
	v_lshlrev_b32_e32 v89, 16, v209
	v_lshlrev_b32_e32 v88, 16, v208
	v_and_b32_e32 v95, 0xffff0000, v209
	v_and_b32_e32 v94, 0xffff0000, v208
	v_pk_add_f32 v[96:97], v[100:101], 1.0 op_sel_hi:[1,0]
	v_or_b32_sdwa v87, v87, v0 dst_sel:DWORD dst_unused:UNUSED_PAD src0_sel:DWORD src1_sel:WORD_1
	v_or_b32_sdwa v86, v86, v0 dst_sel:DWORD dst_unused:UNUSED_PAD src0_sel:DWORD src1_sel:WORD_0
	s_nop 0
	v_rcp_f32_e32 v97, v97
	s_nop 0
	s_nop 0
	v_rcp_f32_e32 v96, v96
	s_nop 0
	v_mov_b32_e32 v98, v82
	v_mov_b32_e32 v99, v84
	v_pk_fma_f32 v[88:89], v[98:99], v[96:97], v[88:89]
	v_add_u32_e32 v100, 0x44400, v157
	v_rcp_f32_e32 v93, v93
	s_nop 0
	s_nop 0
	v_rcp_f32_e32 v92, v92
	s_nop 0
	v_mov_b32_e32 v84, v83
	v_pk_fma_f32 v[82:83], v[84:85], v[92:93], v[94:95]
	v_cvt_pk_bf16_f32 v0, v88, v89
	v_cvt_pk_bf16_f32 v82, v82, v83
	v_and_b32_e32 v83, 0xffff0000, v82
	v_lshlrev_b32_e32 v82, 16, v82
	v_or_b32_sdwa v89, v83, v0 dst_sel:DWORD dst_unused:UNUSED_PAD src0_sel:DWORD src1_sel:WORD_1
	v_or_b32_sdwa v88, v82, v0 dst_sel:DWORD dst_unused:UNUSED_PAD src0_sel:DWORD src1_sel:WORD_0
	v_add_u32_e32 v0, v100, v156
	v_add_u32_e32 v212, 0xccc00, v210
	v_lshl_add_u64 v[202:203], v[212:213], 1, s[6:7]
	global_load_dwordx4 v[202:205], v[202:203], off
	v_add_u32_e32 v212, 0x24000, v211
	v_lshl_add_u64 v[206:207], v[212:213], 1, s[10:11]
	global_load_dwordx4 v[206:209], v[206:207], off
	global_store_dwordx4 v[90:91], v[86:89], off
	s_nop 1
	v_or_b32_e32 v86, 48, v159
	v_mul_lo_u32 v101, v86, s61
	v_add_u32_e32 v0, v0, v101
	s_waitcnt vmcnt(14)
	v_lshlrev_b32_e32 v90, 16, v168
	v_and_b32_e32 v91, 0xffff0000, v168
	v_lshlrev_b32_e32 v93, 16, v169
	v_and_b32_e32 v95, 0xffff0000, v169
	v_lshl_add_u64 v[82:83], v[0:1], 1, s[10:11]
	v_lshlrev_b32_e32 v92, 16, v170
	v_mul_f32_e32 v0, 0xbfb8aa3b, v90
	v_exp_f32_e32 v90, v0
	v_mul_f32_e32 v0, 0xbfb8aa3b, v92
	v_and_b32_e32 v84, 0xffff0000, v170
	v_exp_f32_e32 v92, v0
	v_mul_f32_e32 v0, 0xbfb8aa3b, v91
	v_exp_f32_e32 v94, v0
	v_mul_f32_e32 v0, 0xbfb8aa3b, v84
	v_exp_f32_e32 v84, v0
	v_mul_f32_e32 v0, 0xbfb8aa3b, v93
	v_exp_f32_e32 v91, v0
	v_lshlrev_b32_e32 v96, 16, v171
	v_mul_f32_e32 v0, 0xbfb8aa3b, v96
	v_and_b32_e32 v85, 0xffff0000, v171
	v_exp_f32_e32 v93, v0
	v_mul_f32_e32 v0, 0xbfb8aa3b, v95
	v_exp_f32_e32 v95, v0
	v_mul_f32_e32 v0, 0xbfb8aa3b, v85
	v_pk_add_f32 v[90:91], v[90:91], 1.0 op_sel_hi:[1,0]
	v_exp_f32_e32 v85, v0
	v_pk_add_f32 v[94:95], v[94:95], 1.0 op_sel_hi:[1,0]
	v_pk_add_f32 v[84:85], v[84:85], 1.0 op_sel_hi:[1,0]
	v_rcp_f32_e32 v91, v91
	s_nop 0
	s_waitcnt vmcnt(13)
	v_lshlrev_b32_e32 v97, 16, v173
	v_rcp_f32_e32 v90, v90
	s_nop 0
	v_mov_b32_e32 v98, v78
	v_mov_b32_e32 v99, v80
	v_lshlrev_b32_e32 v96, 16, v172
	v_pk_fma_f32 v[90:91], v[98:99], v[90:91], v[96:97]
	v_rcp_f32_e32 v95, v95
	s_nop 0
	v_and_b32_e32 v87, 0xffff0000, v173
	v_and_b32_e32 v86, 0xffff0000, v172
	v_rcp_f32_e32 v94, v94
	s_nop 0
	v_mov_b32_e32 v80, v79
	v_pk_fma_f32 v[78:79], v[80:81], v[94:95], v[86:87]
	v_cvt_pk_bf16_f32 v0, v90, v91
	v_cvt_pk_bf16_f32 v78, v78, v79
	v_and_b32_e32 v79, 0xffff0000, v78
	v_lshlrev_b32_e32 v78, 16, v78
	v_lshlrev_b32_e32 v81, 16, v175
	v_lshlrev_b32_e32 v80, 16, v174
	v_and_b32_e32 v87, 0xffff0000, v175
	v_and_b32_e32 v86, 0xffff0000, v174
	v_pk_add_f32 v[88:89], v[92:93], 1.0 op_sel_hi:[1,0]
	v_or_b32_sdwa v79, v79, v0 dst_sel:DWORD dst_unused:UNUSED_PAD src0_sel:DWORD src1_sel:WORD_1
	v_or_b32_sdwa v78, v78, v0 dst_sel:DWORD dst_unused:UNUSED_PAD src0_sel:DWORD src1_sel:WORD_0
	s_nop 0
	v_rcp_f32_e32 v89, v89
	s_nop 0
	s_nop 0
	v_rcp_f32_e32 v88, v88
	s_nop 0
	v_mov_b32_e32 v90, v74
	v_mov_b32_e32 v91, v76
	v_pk_fma_f32 v[80:81], v[90:91], v[88:89], v[80:81]
	v_rcp_f32_e32 v85, v85
	s_nop 0
	s_nop 0
	v_rcp_f32_e32 v84, v84
	s_nop 0
	v_mov_b32_e32 v76, v75
	v_pk_fma_f32 v[74:75], v[76:77], v[84:85], v[86:87]
	v_cvt_pk_bf16_f32 v0, v80, v81
	v_cvt_pk_bf16_f32 v74, v74, v75
	v_and_b32_e32 v75, 0xffff0000, v74
	v_lshlrev_b32_e32 v74, 16, v74
	v_or_b32_sdwa v81, v75, v0 dst_sel:DWORD dst_unused:UNUSED_PAD src0_sel:DWORD src1_sel:WORD_1
	v_or_b32_sdwa v80, v74, v0 dst_sel:DWORD dst_unused:UNUSED_PAD src0_sel:DWORD src1_sel:WORD_0
	v_add_u32_e32 v0, v100, v126
	v_add_u32_e32 v212, 0xccc80, v210
	v_lshl_add_u64 v[168:169], v[212:213], 1, s[6:7]
	global_load_dwordx4 v[168:171], v[168:169], off
	v_add_u32_e32 v212, 0x24080, v211
	v_lshl_add_u64 v[172:173], v[212:213], 1, s[10:11]
	global_load_dwordx4 v[172:175], v[172:173], off
	global_store_dwordx4 v[82:83], v[78:81], off
	v_add_u32_e32 v0, v0, v101
	s_waitcnt vmcnt(14)
	v_lshlrev_b32_e32 v82, 16, v176
	v_and_b32_e32 v83, 0xffff0000, v176
	v_lshlrev_b32_e32 v85, 16, v177
	v_and_b32_e32 v87, 0xffff0000, v177
	v_lshl_add_u64 v[74:75], v[0:1], 1, s[10:11]
	v_lshlrev_b32_e32 v84, 16, v178
	v_mul_f32_e32 v0, 0xbfb8aa3b, v82
	v_exp_f32_e32 v82, v0
	v_mul_f32_e32 v0, 0xbfb8aa3b, v84
	v_and_b32_e32 v76, 0xffff0000, v178
	v_exp_f32_e32 v84, v0
	v_mul_f32_e32 v0, 0xbfb8aa3b, v83
	v_exp_f32_e32 v86, v0
	v_mul_f32_e32 v0, 0xbfb8aa3b, v76
	v_exp_f32_e32 v76, v0
	v_mul_f32_e32 v0, 0xbfb8aa3b, v85
	v_exp_f32_e32 v83, v0
	v_lshlrev_b32_e32 v88, 16, v179
	v_mul_f32_e32 v0, 0xbfb8aa3b, v88
	v_and_b32_e32 v77, 0xffff0000, v179
	v_exp_f32_e32 v85, v0
	v_mul_f32_e32 v0, 0xbfb8aa3b, v87
	v_exp_f32_e32 v87, v0
	v_mul_f32_e32 v0, 0xbfb8aa3b, v77
	v_pk_add_f32 v[82:83], v[82:83], 1.0 op_sel_hi:[1,0]
	v_exp_f32_e32 v77, v0
	v_pk_add_f32 v[86:87], v[86:87], 1.0 op_sel_hi:[1,0]
	v_pk_add_f32 v[76:77], v[76:77], 1.0 op_sel_hi:[1,0]
	v_rcp_f32_e32 v83, v83
	s_nop 0
	s_waitcnt vmcnt(13)
	v_lshlrev_b32_e32 v89, 16, v183
	v_rcp_f32_e32 v82, v82
	s_nop 0
	v_mov_b32_e32 v90, v70
	v_mov_b32_e32 v91, v72
	v_lshlrev_b32_e32 v88, 16, v182
	v_pk_fma_f32 v[82:83], v[90:91], v[82:83], v[88:89]
	v_rcp_f32_e32 v87, v87
	s_nop 0
	v_and_b32_e32 v79, 0xffff0000, v183
	v_and_b32_e32 v78, 0xffff0000, v182
	v_rcp_f32_e32 v86, v86
	s_nop 0
	v_mov_b32_e32 v72, v71
	v_pk_fma_f32 v[70:71], v[72:73], v[86:87], v[78:79]
	v_cvt_pk_bf16_f32 v0, v82, v83
	v_cvt_pk_bf16_f32 v70, v70, v71
	v_and_b32_e32 v71, 0xffff0000, v70
	v_lshlrev_b32_e32 v70, 16, v70
	v_lshlrev_b32_e32 v73, 16, v185
	v_lshlrev_b32_e32 v72, 16, v184
	v_and_b32_e32 v79, 0xffff0000, v185
	v_and_b32_e32 v78, 0xffff0000, v184
	v_pk_add_f32 v[80:81], v[84:85], 1.0 op_sel_hi:[1,0]
	v_or_b32_sdwa v71, v71, v0 dst_sel:DWORD dst_unused:UNUSED_PAD src0_sel:DWORD src1_sel:WORD_1
	v_or_b32_sdwa v70, v70, v0 dst_sel:DWORD dst_unused:UNUSED_PAD src0_sel:DWORD src1_sel:WORD_0
	s_nop 0
	v_rcp_f32_e32 v81, v81
	s_nop 0
	s_nop 0
	v_rcp_f32_e32 v80, v80
	s_nop 0
	v_mov_b32_e32 v82, v66
	v_mov_b32_e32 v83, v68
	v_pk_fma_f32 v[72:73], v[82:83], v[80:81], v[72:73]
	v_add_u32_e32 v84, 0xb6000, v157
	v_rcp_f32_e32 v77, v77
	s_nop 0
	v_add_u32_e32 v85, 0xfff6a000, v158
	v_rcp_f32_e32 v76, v76
	s_nop 0
	v_mov_b32_e32 v68, v67
	v_pk_fma_f32 v[66:67], v[68:69], v[76:77], v[78:79]
	v_cvt_pk_bf16_f32 v0, v72, v73
	v_cvt_pk_bf16_f32 v66, v66, v67
	v_and_b32_e32 v67, 0xffff0000, v66
	v_lshlrev_b32_e32 v66, 16, v66
	v_or_b32_sdwa v73, v67, v0 dst_sel:DWORD dst_unused:UNUSED_PAD src0_sel:DWORD src1_sel:WORD_1
	v_or_b32_sdwa v72, v66, v0 dst_sel:DWORD dst_unused:UNUSED_PAD src0_sel:DWORD src1_sel:WORD_0
	v_add_u32_e32 v0, v84, v156
	v_add_u32_e32 v212, 0xe3800, v210
	v_lshl_add_u64 v[176:177], v[212:213], 1, s[6:7]
	global_load_dwordx4 v[176:179], v[176:177], off
	v_add_u32_e32 v212, 0x28000, v211
	v_lshl_add_u64 v[182:183], v[212:213], 1, s[10:11]
	global_load_dwordx4 v[182:185], v[182:183], off
	global_store_dwordx4 v[74:75], v[70:73], off
	v_add_u32_e32 v0, v0, v85
	s_waitcnt vmcnt(14)
	v_lshlrev_b32_e32 v74, 16, v186
	v_and_b32_e32 v75, 0xffff0000, v186
	v_lshlrev_b32_e32 v77, 16, v187
	v_and_b32_e32 v79, 0xffff0000, v187
	v_lshl_add_u64 v[66:67], v[0:1], 1, s[10:11]
	v_lshlrev_b32_e32 v76, 16, v188
	v_mul_f32_e32 v0, 0xbfb8aa3b, v74
	v_exp_f32_e32 v74, v0
	v_mul_f32_e32 v0, 0xbfb8aa3b, v76
	v_and_b32_e32 v68, 0xffff0000, v188
	v_exp_f32_e32 v76, v0
	v_mul_f32_e32 v0, 0xbfb8aa3b, v75
	v_exp_f32_e32 v78, v0
	v_mul_f32_e32 v0, 0xbfb8aa3b, v68
	v_exp_f32_e32 v68, v0
	v_mul_f32_e32 v0, 0xbfb8aa3b, v77
	v_exp_f32_e32 v75, v0
	v_lshlrev_b32_e32 v80, 16, v189
	v_mul_f32_e32 v0, 0xbfb8aa3b, v80
	v_and_b32_e32 v69, 0xffff0000, v189
	v_exp_f32_e32 v77, v0
	v_mul_f32_e32 v0, 0xbfb8aa3b, v79
	v_exp_f32_e32 v79, v0
	v_mul_f32_e32 v0, 0xbfb8aa3b, v69
	v_pk_add_f32 v[74:75], v[74:75], 1.0 op_sel_hi:[1,0]
	v_exp_f32_e32 v69, v0
	v_pk_add_f32 v[78:79], v[78:79], 1.0 op_sel_hi:[1,0]
	v_pk_add_f32 v[68:69], v[68:69], 1.0 op_sel_hi:[1,0]
	v_rcp_f32_e32 v75, v75
	s_nop 0
	s_waitcnt vmcnt(13)
	v_lshlrev_b32_e32 v81, 16, v191
	v_rcp_f32_e32 v74, v74
	s_nop 0
	v_mov_b32_e32 v82, v62
	v_mov_b32_e32 v83, v64
	v_lshlrev_b32_e32 v80, 16, v190
	v_pk_fma_f32 v[74:75], v[82:83], v[74:75], v[80:81]
	v_rcp_f32_e32 v79, v79
	s_nop 0
	v_and_b32_e32 v71, 0xffff0000, v191
	v_and_b32_e32 v70, 0xffff0000, v190
	v_rcp_f32_e32 v78, v78
	s_nop 0
	v_mov_b32_e32 v64, v63
	v_pk_fma_f32 v[62:63], v[64:65], v[78:79], v[70:71]
	v_cvt_pk_bf16_f32 v0, v74, v75
	v_cvt_pk_bf16_f32 v62, v62, v63
	v_and_b32_e32 v63, 0xffff0000, v62
	v_lshlrev_b32_e32 v62, 16, v62
	v_lshlrev_b32_e32 v65, 16, v193
	v_lshlrev_b32_e32 v64, 16, v192
	v_and_b32_e32 v71, 0xffff0000, v193
	v_and_b32_e32 v70, 0xffff0000, v192
	v_pk_add_f32 v[72:73], v[76:77], 1.0 op_sel_hi:[1,0]
	v_or_b32_sdwa v63, v63, v0 dst_sel:DWORD dst_unused:UNUSED_PAD src0_sel:DWORD src1_sel:WORD_1
	v_or_b32_sdwa v62, v62, v0 dst_sel:DWORD dst_unused:UNUSED_PAD src0_sel:DWORD src1_sel:WORD_0
	s_nop 0
	v_rcp_f32_e32 v73, v73
	s_nop 0
	s_nop 0
	v_rcp_f32_e32 v72, v72
	s_nop 0
	v_mov_b32_e32 v74, v58
	v_mov_b32_e32 v75, v60
	v_pk_fma_f32 v[64:65], v[74:75], v[72:73], v[64:65]
	v_rcp_f32_e32 v69, v69
	s_nop 0
	s_nop 0
	v_rcp_f32_e32 v68, v68
	s_nop 0
	v_mov_b32_e32 v60, v59
	v_pk_fma_f32 v[58:59], v[60:61], v[68:69], v[70:71]
	v_cvt_pk_bf16_f32 v0, v64, v65
	v_cvt_pk_bf16_f32 v58, v58, v59
	v_and_b32_e32 v59, 0xffff0000, v58
	v_lshlrev_b32_e32 v58, 16, v58
	v_or_b32_sdwa v65, v59, v0 dst_sel:DWORD dst_unused:UNUSED_PAD src0_sel:DWORD src1_sel:WORD_1
	v_or_b32_sdwa v64, v58, v0 dst_sel:DWORD dst_unused:UNUSED_PAD src0_sel:DWORD src1_sel:WORD_0
	v_add_u32_e32 v0, v84, v126
	v_add_u32_e32 v212, 0xe3880, v210
	v_lshl_add_u64 v[186:187], v[212:213], 1, s[6:7]
	global_load_dwordx4 v[186:189], v[186:187], off
	v_add_u32_e32 v212, 0x28080, v211
	v_lshl_add_u64 v[190:191], v[212:213], 1, s[10:11]
	global_load_dwordx4 v[190:193], v[190:191], off
	global_store_dwordx4 v[66:67], v[62:65], off
	v_add_u32_e32 v0, v0, v85
	s_waitcnt vmcnt(14)
	v_lshlrev_b32_e32 v66, 16, v194
	v_and_b32_e32 v67, 0xffff0000, v194
	v_lshlrev_b32_e32 v69, 16, v195
	v_and_b32_e32 v71, 0xffff0000, v195
	v_lshl_add_u64 v[58:59], v[0:1], 1, s[10:11]
	v_lshlrev_b32_e32 v68, 16, v196
	v_mul_f32_e32 v0, 0xbfb8aa3b, v66
	v_exp_f32_e32 v66, v0
	v_mul_f32_e32 v0, 0xbfb8aa3b, v68
	v_and_b32_e32 v60, 0xffff0000, v196
	v_exp_f32_e32 v68, v0
	v_mul_f32_e32 v0, 0xbfb8aa3b, v67
	v_exp_f32_e32 v70, v0
	v_mul_f32_e32 v0, 0xbfb8aa3b, v60
	v_exp_f32_e32 v60, v0
	v_mul_f32_e32 v0, 0xbfb8aa3b, v69
	v_exp_f32_e32 v67, v0
	v_lshlrev_b32_e32 v72, 16, v197
	v_mul_f32_e32 v0, 0xbfb8aa3b, v72
	v_and_b32_e32 v61, 0xffff0000, v197
	v_exp_f32_e32 v69, v0
	v_mul_f32_e32 v0, 0xbfb8aa3b, v71
	v_exp_f32_e32 v71, v0
	v_mul_f32_e32 v0, 0xbfb8aa3b, v61
	v_pk_add_f32 v[66:67], v[66:67], 1.0 op_sel_hi:[1,0]
	v_exp_f32_e32 v61, v0
	v_pk_add_f32 v[70:71], v[70:71], 1.0 op_sel_hi:[1,0]
	v_pk_add_f32 v[60:61], v[60:61], 1.0 op_sel_hi:[1,0]
	v_rcp_f32_e32 v67, v67
	s_nop 0
	s_waitcnt vmcnt(13)
	v_lshlrev_b32_e32 v73, 16, v199
	v_rcp_f32_e32 v66, v66
	s_nop 0
	v_mov_b32_e32 v74, v54
	v_mov_b32_e32 v75, v56
	v_lshlrev_b32_e32 v72, 16, v198
	v_pk_fma_f32 v[66:67], v[74:75], v[66:67], v[72:73]
	v_rcp_f32_e32 v71, v71
	s_nop 0
	v_and_b32_e32 v63, 0xffff0000, v199
	v_and_b32_e32 v62, 0xffff0000, v198
	v_rcp_f32_e32 v70, v70
	s_nop 0
	v_mov_b32_e32 v56, v55
	v_pk_fma_f32 v[54:55], v[56:57], v[70:71], v[62:63]
	v_cvt_pk_bf16_f32 v0, v66, v67
	v_cvt_pk_bf16_f32 v54, v54, v55
	v_and_b32_e32 v55, 0xffff0000, v54
	v_lshlrev_b32_e32 v54, 16, v54
	v_lshlrev_b32_e32 v57, 16, v201
	v_lshlrev_b32_e32 v56, 16, v200
	v_and_b32_e32 v63, 0xffff0000, v201
	v_and_b32_e32 v62, 0xffff0000, v200
	v_pk_add_f32 v[64:65], v[68:69], 1.0 op_sel_hi:[1,0]
	v_or_b32_sdwa v55, v55, v0 dst_sel:DWORD dst_unused:UNUSED_PAD src0_sel:DWORD src1_sel:WORD_1
	v_or_b32_sdwa v54, v54, v0 dst_sel:DWORD dst_unused:UNUSED_PAD src0_sel:DWORD src1_sel:WORD_0
	s_nop 0
	v_rcp_f32_e32 v65, v65
	s_nop 0
	s_nop 0
	v_rcp_f32_e32 v64, v64
	s_nop 0
	v_mov_b32_e32 v66, v50
	v_mov_b32_e32 v67, v52
	v_pk_fma_f32 v[56:57], v[66:67], v[64:65], v[56:57]
	v_add_u32_e32 v68, 0xccc00, v157
	v_rcp_f32_e32 v61, v61
	s_nop 0
	v_add_u32_e32 v69, 0xfff57400, v158
	v_rcp_f32_e32 v60, v60
	s_nop 0
	v_mov_b32_e32 v52, v51
	v_pk_fma_f32 v[50:51], v[52:53], v[60:61], v[62:63]
	v_cvt_pk_bf16_f32 v0, v56, v57
	v_cvt_pk_bf16_f32 v50, v50, v51
	v_and_b32_e32 v51, 0xffff0000, v50
	v_lshlrev_b32_e32 v50, 16, v50
	v_or_b32_sdwa v57, v51, v0 dst_sel:DWORD dst_unused:UNUSED_PAD src0_sel:DWORD src1_sel:WORD_1
	v_or_b32_sdwa v56, v50, v0 dst_sel:DWORD dst_unused:UNUSED_PAD src0_sel:DWORD src1_sel:WORD_0
	v_add_u32_e32 v0, v68, v156
	v_add_u32_e32 v212, 0xfa400, v210
	v_lshl_add_u64 v[194:195], v[212:213], 1, s[6:7]
	global_load_dwordx4 v[194:197], v[194:195], off
	v_add_u32_e32 v212, 0x2c000, v211
	v_lshl_add_u64 v[198:199], v[212:213], 1, s[10:11]
	global_load_dwordx4 v[198:201], v[198:199], off
	global_store_dwordx4 v[58:59], v[54:57], off
	v_add_u32_e32 v0, v0, v69
	s_waitcnt vmcnt(14)
	v_lshlrev_b32_e32 v58, 16, v202
	v_and_b32_e32 v59, 0xffff0000, v202
	v_lshlrev_b32_e32 v61, 16, v203
	v_and_b32_e32 v63, 0xffff0000, v203
	v_lshl_add_u64 v[50:51], v[0:1], 1, s[10:11]
	v_lshlrev_b32_e32 v60, 16, v204
	v_mul_f32_e32 v0, 0xbfb8aa3b, v58
	v_exp_f32_e32 v58, v0
	v_mul_f32_e32 v0, 0xbfb8aa3b, v60
	v_and_b32_e32 v52, 0xffff0000, v204
	v_exp_f32_e32 v60, v0
	v_mul_f32_e32 v0, 0xbfb8aa3b, v59
	v_exp_f32_e32 v62, v0
	v_mul_f32_e32 v0, 0xbfb8aa3b, v52
	v_exp_f32_e32 v52, v0
	v_mul_f32_e32 v0, 0xbfb8aa3b, v61
	v_exp_f32_e32 v59, v0
	v_lshlrev_b32_e32 v64, 16, v205
	v_mul_f32_e32 v0, 0xbfb8aa3b, v64
	v_and_b32_e32 v53, 0xffff0000, v205
	v_exp_f32_e32 v61, v0
	v_mul_f32_e32 v0, 0xbfb8aa3b, v63
	v_exp_f32_e32 v63, v0
	v_mul_f32_e32 v0, 0xbfb8aa3b, v53
	v_pk_add_f32 v[58:59], v[58:59], 1.0 op_sel_hi:[1,0]
	v_exp_f32_e32 v53, v0
	v_pk_add_f32 v[62:63], v[62:63], 1.0 op_sel_hi:[1,0]
	v_pk_add_f32 v[52:53], v[52:53], 1.0 op_sel_hi:[1,0]
	v_rcp_f32_e32 v59, v59
	s_nop 0
	s_waitcnt vmcnt(13)
	v_lshlrev_b32_e32 v65, 16, v207
	v_rcp_f32_e32 v58, v58
	s_nop 0
	v_mov_b32_e32 v66, v46
	v_mov_b32_e32 v67, v48
	v_lshlrev_b32_e32 v64, 16, v206
	v_pk_fma_f32 v[58:59], v[66:67], v[58:59], v[64:65]
	v_rcp_f32_e32 v63, v63
	s_nop 0
	v_and_b32_e32 v55, 0xffff0000, v207
	v_and_b32_e32 v54, 0xffff0000, v206
	v_rcp_f32_e32 v62, v62
	s_nop 0
	v_mov_b32_e32 v48, v47
	v_pk_fma_f32 v[46:47], v[48:49], v[62:63], v[54:55]
	v_cvt_pk_bf16_f32 v0, v58, v59
	v_cvt_pk_bf16_f32 v46, v46, v47
	v_and_b32_e32 v47, 0xffff0000, v46
	v_lshlrev_b32_e32 v46, 16, v46
	v_lshlrev_b32_e32 v49, 16, v209
	v_lshlrev_b32_e32 v48, 16, v208
	v_and_b32_e32 v55, 0xffff0000, v209
	v_and_b32_e32 v54, 0xffff0000, v208
	v_pk_add_f32 v[56:57], v[60:61], 1.0 op_sel_hi:[1,0]
	v_or_b32_sdwa v47, v47, v0 dst_sel:DWORD dst_unused:UNUSED_PAD src0_sel:DWORD src1_sel:WORD_1
	v_or_b32_sdwa v46, v46, v0 dst_sel:DWORD dst_unused:UNUSED_PAD src0_sel:DWORD src1_sel:WORD_0
	s_nop 0
	v_rcp_f32_e32 v57, v57
	s_nop 0
	s_nop 0
	v_rcp_f32_e32 v56, v56
	s_nop 0
	v_mov_b32_e32 v58, v42
	v_mov_b32_e32 v59, v44
	v_pk_fma_f32 v[48:49], v[58:59], v[56:57], v[48:49]
	v_rcp_f32_e32 v53, v53
	s_nop 0
	s_nop 0
	v_rcp_f32_e32 v52, v52
	s_nop 0
	v_mov_b32_e32 v44, v43
	v_pk_fma_f32 v[42:43], v[44:45], v[52:53], v[54:55]
	v_cvt_pk_bf16_f32 v0, v48, v49
	v_cvt_pk_bf16_f32 v42, v42, v43
	v_and_b32_e32 v43, 0xffff0000, v42
	v_lshlrev_b32_e32 v42, 16, v42
	v_or_b32_sdwa v49, v43, v0 dst_sel:DWORD dst_unused:UNUSED_PAD src0_sel:DWORD src1_sel:WORD_1
	v_or_b32_sdwa v48, v42, v0 dst_sel:DWORD dst_unused:UNUSED_PAD src0_sel:DWORD src1_sel:WORD_0
	v_add_u32_e32 v0, v68, v126
	v_add_u32_e32 v212, 0xfa480, v210
	v_lshl_add_u64 v[202:203], v[212:213], 1, s[6:7]
	global_load_dwordx4 v[202:205], v[202:203], off
	v_add_u32_e32 v212, 0x2c080, v211
	v_lshl_add_u64 v[206:207], v[212:213], 1, s[10:11]
	global_load_dwordx4 v[206:209], v[206:207], off
	global_store_dwordx4 v[50:51], v[46:49], off
	v_add_u32_e32 v0, v0, v69
	s_waitcnt vmcnt(14)
	v_lshlrev_b32_e32 v50, 16, v168
	v_and_b32_e32 v51, 0xffff0000, v168
	v_lshlrev_b32_e32 v53, 16, v169
	v_and_b32_e32 v55, 0xffff0000, v169
	v_lshl_add_u64 v[42:43], v[0:1], 1, s[10:11]
	v_lshlrev_b32_e32 v52, 16, v170
	v_mul_f32_e32 v0, 0xbfb8aa3b, v50
	v_exp_f32_e32 v50, v0
	v_mul_f32_e32 v0, 0xbfb8aa3b, v52
	v_and_b32_e32 v44, 0xffff0000, v170
	v_exp_f32_e32 v52, v0
	v_mul_f32_e32 v0, 0xbfb8aa3b, v51
	v_exp_f32_e32 v54, v0
	v_mul_f32_e32 v0, 0xbfb8aa3b, v44
	v_exp_f32_e32 v44, v0
	v_mul_f32_e32 v0, 0xbfb8aa3b, v53
	v_exp_f32_e32 v51, v0
	v_lshlrev_b32_e32 v56, 16, v171
	v_mul_f32_e32 v0, 0xbfb8aa3b, v56
	v_and_b32_e32 v45, 0xffff0000, v171
	v_exp_f32_e32 v53, v0
	v_mul_f32_e32 v0, 0xbfb8aa3b, v55
	v_exp_f32_e32 v55, v0
	v_mul_f32_e32 v0, 0xbfb8aa3b, v45
	v_pk_add_f32 v[50:51], v[50:51], 1.0 op_sel_hi:[1,0]
	v_exp_f32_e32 v45, v0
	v_pk_add_f32 v[54:55], v[54:55], 1.0 op_sel_hi:[1,0]
	v_pk_add_f32 v[44:45], v[44:45], 1.0 op_sel_hi:[1,0]
	v_rcp_f32_e32 v51, v51
	s_nop 0
	s_waitcnt vmcnt(13)
	v_lshlrev_b32_e32 v57, 16, v173
	v_rcp_f32_e32 v50, v50
	s_nop 0
	v_mov_b32_e32 v58, v38
	v_mov_b32_e32 v59, v40
	v_lshlrev_b32_e32 v56, 16, v172
	v_pk_fma_f32 v[50:51], v[58:59], v[50:51], v[56:57]
	v_rcp_f32_e32 v55, v55
	s_nop 0
	v_and_b32_e32 v47, 0xffff0000, v173
	v_and_b32_e32 v46, 0xffff0000, v172
	v_rcp_f32_e32 v54, v54
	s_nop 0
	v_mov_b32_e32 v40, v39
	v_pk_fma_f32 v[38:39], v[40:41], v[54:55], v[46:47]
	v_cvt_pk_bf16_f32 v0, v50, v51
	v_cvt_pk_bf16_f32 v38, v38, v39
	v_and_b32_e32 v39, 0xffff0000, v38
	v_lshlrev_b32_e32 v38, 16, v38
	v_lshlrev_b32_e32 v41, 16, v175
	v_lshlrev_b32_e32 v40, 16, v174
	v_and_b32_e32 v47, 0xffff0000, v175
	v_and_b32_e32 v46, 0xffff0000, v174
	v_pk_add_f32 v[48:49], v[52:53], 1.0 op_sel_hi:[1,0]
	v_or_b32_sdwa v39, v39, v0 dst_sel:DWORD dst_unused:UNUSED_PAD src0_sel:DWORD src1_sel:WORD_1
	v_or_b32_sdwa v38, v38, v0 dst_sel:DWORD dst_unused:UNUSED_PAD src0_sel:DWORD src1_sel:WORD_0
	s_nop 0
	v_rcp_f32_e32 v49, v49
	s_nop 0
	s_nop 0
	v_rcp_f32_e32 v48, v48
	s_nop 0
	v_mov_b32_e32 v50, v34
	v_mov_b32_e32 v51, v36
	v_pk_fma_f32 v[40:41], v[50:51], v[48:49], v[40:41]
	v_add_u32_e32 v52, 0xe3800, v157
	v_rcp_f32_e32 v45, v45
	s_nop 0
	v_add_u32_e32 v53, 0xfff44800, v158
	v_rcp_f32_e32 v44, v44
	s_nop 0
	v_mov_b32_e32 v36, v35
	v_pk_fma_f32 v[34:35], v[36:37], v[44:45], v[46:47]
	v_cvt_pk_bf16_f32 v0, v40, v41
	v_cvt_pk_bf16_f32 v34, v34, v35
	v_and_b32_e32 v35, 0xffff0000, v34
	v_lshlrev_b32_e32 v34, 16, v34
	v_or_b32_sdwa v41, v35, v0 dst_sel:DWORD dst_unused:UNUSED_PAD src0_sel:DWORD src1_sel:WORD_1
	v_or_b32_sdwa v40, v34, v0 dst_sel:DWORD dst_unused:UNUSED_PAD src0_sel:DWORD src1_sel:WORD_0
	v_add_u32_e32 v0, v52, v156
	global_store_dwordx4 v[42:43], v[38:41], off
	v_add_u32_e32 v0, v0, v53
	s_waitcnt vmcnt(12)
	v_lshlrev_b32_e32 v42, 16, v176
	v_and_b32_e32 v43, 0xffff0000, v176
	v_lshlrev_b32_e32 v45, 16, v177
	v_and_b32_e32 v47, 0xffff0000, v177
	v_lshl_add_u64 v[34:35], v[0:1], 1, s[10:11]
	v_lshlrev_b32_e32 v44, 16, v178
	v_mul_f32_e32 v0, 0xbfb8aa3b, v42
	v_exp_f32_e32 v42, v0
	v_mul_f32_e32 v0, 0xbfb8aa3b, v44
	v_and_b32_e32 v36, 0xffff0000, v178
	v_exp_f32_e32 v44, v0
	v_mul_f32_e32 v0, 0xbfb8aa3b, v43
	v_exp_f32_e32 v46, v0
	v_mul_f32_e32 v0, 0xbfb8aa3b, v36
	v_exp_f32_e32 v36, v0
	v_mul_f32_e32 v0, 0xbfb8aa3b, v45
	v_exp_f32_e32 v43, v0
	v_lshlrev_b32_e32 v48, 16, v179
	v_mul_f32_e32 v0, 0xbfb8aa3b, v48
	v_and_b32_e32 v37, 0xffff0000, v179
	v_exp_f32_e32 v45, v0
	v_mul_f32_e32 v0, 0xbfb8aa3b, v47
	v_exp_f32_e32 v47, v0
	v_mul_f32_e32 v0, 0xbfb8aa3b, v37
	v_pk_add_f32 v[42:43], v[42:43], 1.0 op_sel_hi:[1,0]
	v_exp_f32_e32 v37, v0
	v_pk_add_f32 v[46:47], v[46:47], 1.0 op_sel_hi:[1,0]
	v_pk_add_f32 v[36:37], v[36:37], 1.0 op_sel_hi:[1,0]
	v_rcp_f32_e32 v43, v43
	s_nop 0
	s_waitcnt vmcnt(11)
	v_lshlrev_b32_e32 v49, 16, v183
	v_rcp_f32_e32 v42, v42
	s_nop 0
	v_mov_b32_e32 v50, v30
	v_mov_b32_e32 v51, v32
	v_lshlrev_b32_e32 v48, 16, v182
	v_pk_fma_f32 v[42:43], v[50:51], v[42:43], v[48:49]
	v_rcp_f32_e32 v47, v47
	s_nop 0
	v_and_b32_e32 v39, 0xffff0000, v183
	v_and_b32_e32 v38, 0xffff0000, v182
	v_rcp_f32_e32 v46, v46
	s_nop 0
	v_mov_b32_e32 v32, v31
	v_pk_fma_f32 v[30:31], v[32:33], v[46:47], v[38:39]
	v_cvt_pk_bf16_f32 v0, v42, v43
	v_cvt_pk_bf16_f32 v30, v30, v31
	v_and_b32_e32 v31, 0xffff0000, v30
	v_lshlrev_b32_e32 v30, 16, v30
	v_lshlrev_b32_e32 v33, 16, v185
	v_lshlrev_b32_e32 v32, 16, v184
	v_and_b32_e32 v39, 0xffff0000, v185
	v_and_b32_e32 v38, 0xffff0000, v184
	v_pk_add_f32 v[40:41], v[44:45], 1.0 op_sel_hi:[1,0]
	v_or_b32_sdwa v31, v31, v0 dst_sel:DWORD dst_unused:UNUSED_PAD src0_sel:DWORD src1_sel:WORD_1
	v_or_b32_sdwa v30, v30, v0 dst_sel:DWORD dst_unused:UNUSED_PAD src0_sel:DWORD src1_sel:WORD_0
	s_nop 0
	v_rcp_f32_e32 v41, v41
	s_nop 0
	s_nop 0
	v_rcp_f32_e32 v40, v40
	s_nop 0
	v_mov_b32_e32 v42, v26
	v_mov_b32_e32 v43, v28
	v_pk_fma_f32 v[32:33], v[42:43], v[40:41], v[32:33]
	v_rcp_f32_e32 v37, v37
	s_nop 0
	s_nop 0
	v_rcp_f32_e32 v36, v36
	s_nop 0
	v_mov_b32_e32 v28, v27
	v_pk_fma_f32 v[26:27], v[28:29], v[36:37], v[38:39]
	v_cvt_pk_bf16_f32 v0, v32, v33
	v_cvt_pk_bf16_f32 v26, v26, v27
	v_and_b32_e32 v27, 0xffff0000, v26
	v_lshlrev_b32_e32 v26, 16, v26
	v_or_b32_sdwa v33, v27, v0 dst_sel:DWORD dst_unused:UNUSED_PAD src0_sel:DWORD src1_sel:WORD_1
	v_or_b32_sdwa v32, v26, v0 dst_sel:DWORD dst_unused:UNUSED_PAD src0_sel:DWORD src1_sel:WORD_0
	v_add_u32_e32 v0, v52, v126
	global_store_dwordx4 v[34:35], v[30:33], off
	v_add_u32_e32 v0, v0, v53
	s_waitcnt vmcnt(10)
	v_lshlrev_b32_e32 v34, 16, v186
	v_and_b32_e32 v35, 0xffff0000, v186
	v_lshlrev_b32_e32 v37, 16, v187
	v_and_b32_e32 v39, 0xffff0000, v187
	v_lshl_add_u64 v[26:27], v[0:1], 1, s[10:11]
	v_lshlrev_b32_e32 v36, 16, v188
	v_mul_f32_e32 v0, 0xbfb8aa3b, v34
	v_exp_f32_e32 v34, v0
	v_mul_f32_e32 v0, 0xbfb8aa3b, v36
	v_and_b32_e32 v28, 0xffff0000, v188
	v_exp_f32_e32 v36, v0
	v_mul_f32_e32 v0, 0xbfb8aa3b, v35
	v_exp_f32_e32 v38, v0
	v_mul_f32_e32 v0, 0xbfb8aa3b, v28
	v_exp_f32_e32 v28, v0
	v_mul_f32_e32 v0, 0xbfb8aa3b, v37
	v_exp_f32_e32 v35, v0
	v_lshlrev_b32_e32 v40, 16, v189
	v_mul_f32_e32 v0, 0xbfb8aa3b, v40
	v_and_b32_e32 v29, 0xffff0000, v189
	v_exp_f32_e32 v37, v0
	v_mul_f32_e32 v0, 0xbfb8aa3b, v39
	v_exp_f32_e32 v39, v0
	v_mul_f32_e32 v0, 0xbfb8aa3b, v29
	v_pk_add_f32 v[34:35], v[34:35], 1.0 op_sel_hi:[1,0]
	v_exp_f32_e32 v29, v0
	v_pk_add_f32 v[38:39], v[38:39], 1.0 op_sel_hi:[1,0]
	v_pk_add_f32 v[28:29], v[28:29], 1.0 op_sel_hi:[1,0]
	v_rcp_f32_e32 v35, v35
	s_nop 0
	s_waitcnt vmcnt(9)
	v_lshlrev_b32_e32 v41, 16, v191
	v_rcp_f32_e32 v34, v34
	s_nop 0
	v_mov_b32_e32 v42, v22
	v_mov_b32_e32 v43, v24
	v_lshlrev_b32_e32 v40, 16, v190
	v_pk_fma_f32 v[34:35], v[42:43], v[34:35], v[40:41]
	v_rcp_f32_e32 v39, v39
	s_nop 0
	v_and_b32_e32 v31, 0xffff0000, v191
	v_and_b32_e32 v30, 0xffff0000, v190
	v_rcp_f32_e32 v38, v38
	s_nop 0
	v_mov_b32_e32 v24, v23
	v_pk_fma_f32 v[22:23], v[24:25], v[38:39], v[30:31]
	v_cvt_pk_bf16_f32 v0, v34, v35
	v_cvt_pk_bf16_f32 v22, v22, v23
	v_and_b32_e32 v23, 0xffff0000, v22
	v_lshlrev_b32_e32 v22, 16, v22
	v_lshlrev_b32_e32 v25, 16, v193
	v_lshlrev_b32_e32 v24, 16, v192
	v_and_b32_e32 v31, 0xffff0000, v193
	v_and_b32_e32 v30, 0xffff0000, v192
	v_pk_add_f32 v[32:33], v[36:37], 1.0 op_sel_hi:[1,0]
	v_or_b32_sdwa v23, v23, v0 dst_sel:DWORD dst_unused:UNUSED_PAD src0_sel:DWORD src1_sel:WORD_1
	v_or_b32_sdwa v22, v22, v0 dst_sel:DWORD dst_unused:UNUSED_PAD src0_sel:DWORD src1_sel:WORD_0
	s_nop 0
	v_rcp_f32_e32 v33, v33
	s_nop 0
	s_nop 0
	v_rcp_f32_e32 v32, v32
	s_nop 0
	v_mov_b32_e32 v34, v18
	v_mov_b32_e32 v35, v20
	v_pk_fma_f32 v[24:25], v[34:35], v[32:33], v[24:25]
	v_add_u32_e32 v36, 0xfa400, v157
	v_rcp_f32_e32 v29, v29
	s_nop 0
	v_add_u32_e32 v37, 0xfff31c00, v158
	v_rcp_f32_e32 v28, v28
	s_nop 0
	v_mov_b32_e32 v20, v19
	v_pk_fma_f32 v[18:19], v[20:21], v[28:29], v[30:31]
	v_cvt_pk_bf16_f32 v0, v24, v25
	v_cvt_pk_bf16_f32 v18, v18, v19
	v_and_b32_e32 v19, 0xffff0000, v18
	v_lshlrev_b32_e32 v18, 16, v18
	v_or_b32_sdwa v25, v19, v0 dst_sel:DWORD dst_unused:UNUSED_PAD src0_sel:DWORD src1_sel:WORD_1
	v_or_b32_sdwa v24, v18, v0 dst_sel:DWORD dst_unused:UNUSED_PAD src0_sel:DWORD src1_sel:WORD_0
	v_add_u32_e32 v0, v36, v156
	global_store_dwordx4 v[26:27], v[22:25], off
	v_add_u32_e32 v0, v0, v37
	s_waitcnt vmcnt(8)
	v_lshlrev_b32_e32 v26, 16, v194
	v_and_b32_e32 v27, 0xffff0000, v194
	v_lshlrev_b32_e32 v29, 16, v195
	v_and_b32_e32 v31, 0xffff0000, v195
	v_lshl_add_u64 v[18:19], v[0:1], 1, s[10:11]
	v_lshlrev_b32_e32 v28, 16, v196
	v_mul_f32_e32 v0, 0xbfb8aa3b, v26
	v_exp_f32_e32 v26, v0
	v_mul_f32_e32 v0, 0xbfb8aa3b, v28
	v_and_b32_e32 v20, 0xffff0000, v196
	v_exp_f32_e32 v28, v0
	v_mul_f32_e32 v0, 0xbfb8aa3b, v27
	v_exp_f32_e32 v30, v0
	v_mul_f32_e32 v0, 0xbfb8aa3b, v20
	v_exp_f32_e32 v20, v0
	v_mul_f32_e32 v0, 0xbfb8aa3b, v29
	v_exp_f32_e32 v27, v0
	v_lshlrev_b32_e32 v32, 16, v197
	v_mul_f32_e32 v0, 0xbfb8aa3b, v32
	v_and_b32_e32 v21, 0xffff0000, v197
	v_exp_f32_e32 v29, v0
	v_mul_f32_e32 v0, 0xbfb8aa3b, v31
	v_exp_f32_e32 v31, v0
	v_mul_f32_e32 v0, 0xbfb8aa3b, v21
	v_pk_add_f32 v[26:27], v[26:27], 1.0 op_sel_hi:[1,0]
	v_exp_f32_e32 v21, v0
	v_pk_add_f32 v[30:31], v[30:31], 1.0 op_sel_hi:[1,0]
	v_pk_add_f32 v[20:21], v[20:21], 1.0 op_sel_hi:[1,0]
	v_rcp_f32_e32 v27, v27
	s_nop 0
	s_waitcnt vmcnt(7)
	v_lshlrev_b32_e32 v33, 16, v199
	v_rcp_f32_e32 v26, v26
	s_nop 0
	v_mov_b32_e32 v34, v14
	v_mov_b32_e32 v35, v16
	v_lshlrev_b32_e32 v32, 16, v198
	v_pk_fma_f32 v[26:27], v[34:35], v[26:27], v[32:33]
	v_rcp_f32_e32 v31, v31
	s_nop 0
	v_and_b32_e32 v23, 0xffff0000, v199
	v_and_b32_e32 v22, 0xffff0000, v198
	v_rcp_f32_e32 v30, v30
	s_nop 0
	v_mov_b32_e32 v16, v15
	v_pk_fma_f32 v[14:15], v[16:17], v[30:31], v[22:23]
	v_cvt_pk_bf16_f32 v0, v26, v27
	v_cvt_pk_bf16_f32 v14, v14, v15
	v_and_b32_e32 v15, 0xffff0000, v14
	v_lshlrev_b32_e32 v14, 16, v14
	v_lshlrev_b32_e32 v17, 16, v201
	v_lshlrev_b32_e32 v16, 16, v200
	v_and_b32_e32 v23, 0xffff0000, v201
	v_and_b32_e32 v22, 0xffff0000, v200
	v_pk_add_f32 v[24:25], v[28:29], 1.0 op_sel_hi:[1,0]
	v_or_b32_sdwa v15, v15, v0 dst_sel:DWORD dst_unused:UNUSED_PAD src0_sel:DWORD src1_sel:WORD_1
	v_or_b32_sdwa v14, v14, v0 dst_sel:DWORD dst_unused:UNUSED_PAD src0_sel:DWORD src1_sel:WORD_0
	s_nop 0
	v_rcp_f32_e32 v25, v25
	s_nop 0
	s_nop 0
	v_rcp_f32_e32 v24, v24
	s_nop 0
	v_mov_b32_e32 v26, v10
	v_mov_b32_e32 v27, v12
	v_pk_fma_f32 v[16:17], v[26:27], v[24:25], v[16:17]
	v_rcp_f32_e32 v21, v21
	s_nop 0
	s_nop 0
	v_rcp_f32_e32 v20, v20
	s_nop 0
	v_mov_b32_e32 v12, v11
	v_pk_fma_f32 v[10:11], v[12:13], v[20:21], v[22:23]
	v_cvt_pk_bf16_f32 v0, v16, v17
	v_cvt_pk_bf16_f32 v10, v10, v11
	v_and_b32_e32 v11, 0xffff0000, v10
	v_lshlrev_b32_e32 v10, 16, v10
	v_or_b32_sdwa v17, v11, v0 dst_sel:DWORD dst_unused:UNUSED_PAD src0_sel:DWORD src1_sel:WORD_1
	v_or_b32_sdwa v16, v10, v0 dst_sel:DWORD dst_unused:UNUSED_PAD src0_sel:DWORD src1_sel:WORD_0
	v_add_u32_e32 v0, v36, v126
	global_store_dwordx4 v[18:19], v[14:17], off
	v_add_u32_e32 v0, v0, v37
	s_waitcnt vmcnt(6)
	v_lshlrev_b32_e32 v18, 16, v202
	v_and_b32_e32 v19, 0xffff0000, v202
	v_lshlrev_b32_e32 v21, 16, v203
	v_and_b32_e32 v23, 0xffff0000, v203
	v_lshl_add_u64 v[10:11], v[0:1], 1, s[10:11]
	v_lshlrev_b32_e32 v20, 16, v204
	v_mul_f32_e32 v0, 0xbfb8aa3b, v18
	v_exp_f32_e32 v18, v0
	v_mul_f32_e32 v0, 0xbfb8aa3b, v20
	v_and_b32_e32 v12, 0xffff0000, v204
	v_exp_f32_e32 v20, v0
	v_mul_f32_e32 v0, 0xbfb8aa3b, v19
	v_exp_f32_e32 v22, v0
	v_mul_f32_e32 v0, 0xbfb8aa3b, v12
	v_exp_f32_e32 v12, v0
	v_mul_f32_e32 v0, 0xbfb8aa3b, v21
	v_exp_f32_e32 v19, v0
	v_lshlrev_b32_e32 v24, 16, v205
	v_mul_f32_e32 v0, 0xbfb8aa3b, v24
	v_and_b32_e32 v13, 0xffff0000, v205
	v_exp_f32_e32 v21, v0
	v_mul_f32_e32 v0, 0xbfb8aa3b, v23
	v_exp_f32_e32 v23, v0
	v_mul_f32_e32 v0, 0xbfb8aa3b, v13
	v_pk_add_f32 v[18:19], v[18:19], 1.0 op_sel_hi:[1,0]
	v_exp_f32_e32 v13, v0
	v_pk_add_f32 v[22:23], v[22:23], 1.0 op_sel_hi:[1,0]
	v_pk_add_f32 v[12:13], v[12:13], 1.0 op_sel_hi:[1,0]
	v_rcp_f32_e32 v19, v19
	s_nop 0
	s_waitcnt vmcnt(5)
	v_lshlrev_b32_e32 v25, 16, v207
	v_rcp_f32_e32 v18, v18
	s_nop 0
	v_mov_b32_e32 v26, v6
	v_mov_b32_e32 v27, v8
	v_lshlrev_b32_e32 v24, 16, v206
	v_pk_fma_f32 v[18:19], v[26:27], v[18:19], v[24:25]
	v_rcp_f32_e32 v23, v23
	s_nop 0
	v_and_b32_e32 v15, 0xffff0000, v207
	v_and_b32_e32 v14, 0xffff0000, v206
	v_rcp_f32_e32 v22, v22
	s_nop 0
	v_mov_b32_e32 v8, v7
	v_pk_fma_f32 v[6:7], v[8:9], v[22:23], v[14:15]
	v_cvt_pk_bf16_f32 v0, v18, v19
	v_cvt_pk_bf16_f32 v6, v6, v7
	v_and_b32_e32 v7, 0xffff0000, v6
	v_lshlrev_b32_e32 v6, 16, v6
	v_lshlrev_b32_e32 v9, 16, v209
	v_lshlrev_b32_e32 v8, 16, v208
	v_and_b32_e32 v15, 0xffff0000, v209
	v_and_b32_e32 v14, 0xffff0000, v208
	v_pk_add_f32 v[16:17], v[20:21], 1.0 op_sel_hi:[1,0]
	v_or_b32_sdwa v7, v7, v0 dst_sel:DWORD dst_unused:UNUSED_PAD src0_sel:DWORD src1_sel:WORD_1
	v_or_b32_sdwa v6, v6, v0 dst_sel:DWORD dst_unused:UNUSED_PAD src0_sel:DWORD src1_sel:WORD_0
	s_nop 0
	v_rcp_f32_e32 v17, v17
	s_nop 0
	s_nop 0
	v_rcp_f32_e32 v16, v16
	s_nop 0
	v_mov_b32_e32 v18, v2
	v_mov_b32_e32 v19, v4
	v_pk_fma_f32 v[8:9], v[18:19], v[16:17], v[8:9]
	v_rcp_f32_e32 v13, v13
	s_nop 0
	s_mov_b64 s[26:27], s[18:19]
	v_rcp_f32_e32 v12, v12
	s_nop 0
	v_mov_b32_e32 v4, v3
	v_pk_fma_f32 v[2:3], v[4:5], v[12:13], v[14:15]
	v_cvt_pk_bf16_f32 v0, v8, v9
	v_cvt_pk_bf16_f32 v2, v2, v3
	v_and_b32_e32 v3, 0xffff0000, v2
	v_lshlrev_b32_e32 v2, 16, v2
	v_or_b32_sdwa v9, v3, v0 dst_sel:DWORD dst_unused:UNUSED_PAD src0_sel:DWORD src1_sel:WORD_1
	v_or_b32_sdwa v8, v2, v0 dst_sel:DWORD dst_unused:UNUSED_PAD src0_sel:DWORD src1_sel:WORD_0
	s_and_b64 vcc, exec, s[12:13]
	global_store_dwordx4 v[10:11], v[6:9], off
	s_cbranch_vccz .LBB0_1369
	s_waitcnt vmcnt(0)
	v_readlane_b32 s76, v255, 8
	s_mov_b32 s92, 0x3b2aaaab
	s_cmp_gt_u32 s35, 3
	v_readlane_b32 s77, v255, 9
	s_mul_i32 s60, s33, 0x1800
	s_mul_hi_i32 s62, s64, 0x300
	s_mul_i32 s75, s33, 0x16c00
	s_mov_b32 s93, 0x3c800000
	s_cbranch_scc1 .LBB0_1376
	s_barrier

.LBB0_1428:
	v_add_u32_e32 v0, 0x10000, v139
	s_waitcnt vmcnt(0)
	ds_read_b128 v[142:145], v0
	ds_read_b128 v[146:149], v0 offset:1024
	ds_read_b128 v[150:153], v0 offset:2048
	ds_read_b128 v[154:157], v0 offset:3072
	s_add_u32 s28, s26, 0xfffc0080
	s_addc_u32 s29, s27, -1
	s_cmp_eq_u32 vcc_lo, 12
	s_cselect_b32 s31, s15, s29
	s_cselect_b32 s30, s89, s28
	s_cselect_b32 s29, s13, s97
	s_cselect_b32 s28, s90, s94
	v_lshl_add_u64 v[178:179], s[26:27], 0, v[134:135]
	s_add_i32 m0, s35, 0xc000
	ds_read_b128 v[158:161], v138
	ds_read_b128 v[162:165], v138 offset:1024
	ds_read_b128 v[166:169], v138 offset:2048
	ds_read_b128 v[170:173], v138 offset:3072
	ds_read_b128 v[174:177], v138 offset:4096
	ds_read_b128 v[182:185], v138 offset:5120
	ds_read_b128 v[186:189], v138 offset:6144
	ds_read_b128 v[190:193], v138 offset:7168
	global_load_lds_dwordx4 v[178:179], off
	v_lshl_add_u64 v[178:179], s[26:27], 0, v[136:137]
	s_add_i32 m0, s35, 0xe000
	s_nop 0
	global_load_lds_dwordx4 v[178:179], off
	s_waitcnt lgkmcnt(8)
	s_barrier
	s_waitcnt lgkmcnt(0)
	s_setprio 1
	s_waitcnt lgkmcnt(0)
	v_mfma_f32_16x16x32_bf16 v[126:129], v[142:145], v[158:161], v[126:129]
	v_mfma_f32_16x16x32_bf16 v[122:125], v[150:153], v[158:161], v[122:125]
	v_mfma_f32_16x16x32_bf16 v[110:113], v[142:145], v[166:169], v[110:113]
	v_mfma_f32_16x16x32_bf16 v[106:109], v[150:153], v[166:169], v[106:109]
	v_mfma_f32_16x16x32_bf16 v[94:97], v[142:145], v[174:177], v[94:97]
	v_mfma_f32_16x16x32_bf16 v[90:93], v[150:153], v[174:177], v[90:93]
	v_mfma_f32_16x16x32_bf16 v[78:81], v[142:145], v[186:189], v[78:81]
	v_mfma_f32_16x16x32_bf16 v[74:77], v[150:153], v[186:189], v[74:77]
	v_mfma_f32_16x16x32_bf16 v[126:129], v[146:149], v[162:165], v[126:129]
	v_mfma_f32_16x16x32_bf16 v[122:125], v[154:157], v[162:165], v[122:125]
	v_mfma_f32_16x16x32_bf16 v[110:113], v[146:149], v[170:173], v[110:113]
	v_mfma_f32_16x16x32_bf16 v[106:109], v[154:157], v[170:173], v[106:109]
	v_mfma_f32_16x16x32_bf16 v[94:97], v[146:149], v[182:185], v[94:97]
	v_mfma_f32_16x16x32_bf16 v[90:93], v[154:157], v[182:185], v[90:93]
	v_mfma_f32_16x16x32_bf16 v[78:81], v[146:149], v[190:193], v[78:81]
	v_mfma_f32_16x16x32_bf16 v[74:77], v[154:157], v[190:193], v[74:77]
	s_setprio 0
	s_barrier
	s_mov_b32 m0, s23
	v_add_u32_e32 v0, 0x14000, v139
	v_lshl_add_u64 v[178:179], s[28:29], 0, v[132:133]
	s_waitcnt vmcnt(0)
	ds_read_b128 v[194:197], v0
	ds_read_b128 v[198:201], v0 offset:1024
	ds_read_b128 v[202:205], v0 offset:2048
	ds_read_b128 v[206:209], v0 offset:3072
	global_load_lds_dwordx4 v[178:179], off
	v_lshl_add_u64 v[210:211], s[28:29], 0, v[130:131]
	s_mov_b32 m0, s25
	s_nop 0
	global_load_lds_dwordx4 v[210:211], off
	s_barrier
	s_waitcnt lgkmcnt(0)
	s_setprio 1
	s_waitcnt lgkmcnt(0)
	v_mfma_f32_16x16x32_bf16 v[118:121], v[194:197], v[158:161], v[118:121]
	v_mfma_f32_16x16x32_bf16 v[114:117], v[202:205], v[158:161], v[114:117]
	v_mfma_f32_16x16x32_bf16 v[102:105], v[194:197], v[166:169], v[102:105]
	v_mfma_f32_16x16x32_bf16 v[98:101], v[202:205], v[166:169], v[98:101]
	v_mfma_f32_16x16x32_bf16 v[86:89], v[194:197], v[174:177], v[86:89]
	v_mfma_f32_16x16x32_bf16 v[82:85], v[202:205], v[174:177], v[82:85]
	v_mfma_f32_16x16x32_bf16 v[70:73], v[194:197], v[186:189], v[70:73]
	v_mfma_f32_16x16x32_bf16 v[66:69], v[202:205], v[186:189], v[66:69]
	v_mfma_f32_16x16x32_bf16 v[118:121], v[198:201], v[162:165], v[118:121]
	v_mfma_f32_16x16x32_bf16 v[114:117], v[206:209], v[162:165], v[114:117]
	v_mfma_f32_16x16x32_bf16 v[102:105], v[198:201], v[170:173], v[102:105]
	v_mfma_f32_16x16x32_bf16 v[98:101], v[206:209], v[170:173], v[98:101]
	v_mfma_f32_16x16x32_bf16 v[86:89], v[198:201], v[182:185], v[86:89]
	v_mfma_f32_16x16x32_bf16 v[82:85], v[206:209], v[182:185], v[82:85]
	v_mfma_f32_16x16x32_bf16 v[70:73], v[198:201], v[190:193], v[70:73]
	v_mfma_f32_16x16x32_bf16 v[66:69], v[206:209], v[190:193], v[66:69]
	s_setprio 0
	s_mov_b32 m0, s35
	v_lshl_add_u64 v[212:213], s[30:31], 0, v[132:133]
	s_barrier
	s_waitcnt vmcnt(0)
	ds_read_b128 v[158:161], v138 offset:16384
	ds_read_b128 v[162:165], v138 offset:17408
	ds_read_b128 v[166:169], v138 offset:18432
	ds_read_b128 v[170:173], v138 offset:19456
	ds_read_b128 v[174:177], v138 offset:20480
	ds_read_b128 v[182:185], v138 offset:21504
	ds_read_b128 v[186:189], v138 offset:22528
	ds_read_b128 v[190:193], v138 offset:23552
	global_load_lds_dwordx4 v[212:213], off
	v_lshl_add_u64 v[214:215], s[30:31], 0, v[130:131]
	s_mov_b32 m0, s36
	s_nop 0
	global_load_lds_dwordx4 v[214:215], off
	s_barrier
	s_waitcnt lgkmcnt(0)
	s_setprio 1
	s_waitcnt lgkmcnt(0)
	v_mfma_f32_16x16x32_bf16 v[62:65], v[142:145], v[158:161], v[62:65]
	v_mfma_f32_16x16x32_bf16 v[58:61], v[150:153], v[158:161], v[58:61]
	v_mfma_f32_16x16x32_bf16 v[46:49], v[142:145], v[166:169], v[46:49]
	v_mfma_f32_16x16x32_bf16 v[42:45], v[150:153], v[166:169], v[42:45]
	v_mfma_f32_16x16x32_bf16 v[30:33], v[142:145], v[174:177], v[30:33]
	v_mfma_f32_16x16x32_bf16 v[26:29], v[150:153], v[174:177], v[26:29]
	v_mfma_f32_16x16x32_bf16 v[14:17], v[142:145], v[186:189], v[14:17]
	v_mfma_f32_16x16x32_bf16 v[10:13], v[150:153], v[186:189], v[10:13]
	v_mfma_f32_16x16x32_bf16 v[62:65], v[146:149], v[162:165], v[62:65]
	v_mfma_f32_16x16x32_bf16 v[58:61], v[154:157], v[162:165], v[58:61]
	v_mfma_f32_16x16x32_bf16 v[46:49], v[146:149], v[170:173], v[46:49]
	v_mfma_f32_16x16x32_bf16 v[42:45], v[154:157], v[170:173], v[42:45]
	v_mfma_f32_16x16x32_bf16 v[30:33], v[146:149], v[182:185], v[30:33]
	v_mfma_f32_16x16x32_bf16 v[26:29], v[154:157], v[182:185], v[26:29]
	v_mfma_f32_16x16x32_bf16 v[14:17], v[146:149], v[190:193], v[14:17]
	v_mfma_f32_16x16x32_bf16 v[10:13], v[154:157], v[190:193], v[10:13]
	s_setprio 0
	s_barrier
	s_add_u32 s76, s28, 0x40000
	s_addc_u32 s77, s29, 0
	s_mov_b32 m0, s37
	v_lshl_add_u64 v[142:143], s[76:77], 0, v[132:133]
	global_load_lds_dwordx4 v[142:143], off
	v_lshl_add_u64 v[142:143], s[76:77], 0, v[130:131]
	s_mov_b32 m0, s38
	s_nop 0
	global_load_lds_dwordx4 v[142:143], off
	s_waitcnt vmcnt(6)
	s_barrier
	s_setprio 1
	v_mfma_f32_16x16x32_bf16 v[54:57], v[194:197], v[158:161], v[54:57]
	v_mfma_f32_16x16x32_bf16 v[50:53], v[202:205], v[158:161], v[50:53]
	v_mfma_f32_16x16x32_bf16 v[38:41], v[194:197], v[166:169], v[38:41]
	v_mfma_f32_16x16x32_bf16 v[34:37], v[202:205], v[166:169], v[34:37]
	v_mfma_f32_16x16x32_bf16 v[22:25], v[194:197], v[174:177], v[22:25]
	v_mfma_f32_16x16x32_bf16 v[18:21], v[202:205], v[174:177], v[18:21]
	v_mfma_f32_16x16x32_bf16 v[6:9], v[194:197], v[186:189], v[6:9]
	v_mfma_f32_16x16x32_bf16 v[2:5], v[202:205], v[186:189], v[2:5]
	v_mfma_f32_16x16x32_bf16 v[54:57], v[198:201], v[162:165], v[54:57]
	v_mfma_f32_16x16x32_bf16 v[50:53], v[206:209], v[162:165], v[50:53]
	v_mfma_f32_16x16x32_bf16 v[38:41], v[198:201], v[170:173], v[38:41]
	v_mfma_f32_16x16x32_bf16 v[34:37], v[206:209], v[170:173], v[34:37]
	v_mfma_f32_16x16x32_bf16 v[22:25], v[198:201], v[182:185], v[22:25]
	v_mfma_f32_16x16x32_bf16 v[18:21], v[206:209], v[182:185], v[18:21]
	v_mfma_f32_16x16x32_bf16 v[6:9], v[198:201], v[190:193], v[6:9]
	v_mfma_f32_16x16x32_bf16 v[2:5], v[206:209], v[190:193], v[2:5]
	s_setprio 0
	v_add_u32_e32 v0, 0x18000, v139
	s_barrier
	s_waitcnt vmcnt(0)
	ds_read_b128 v[142:145], v0
	ds_read_b128 v[146:149], v0 offset:1024
	ds_read_b128 v[150:153], v0 offset:2048
	ds_read_b128 v[154:157], v0 offset:3072
	s_add_u32 s30, s30, 0x40000
	s_addc_u32 s31, s31, 0
	s_mov_b32 m0, s39
	v_lshl_add_u64 v[194:195], s[30:31], 0, v[132:133]
	ds_read_b128 v[158:161], v138 offset:32768
	ds_read_b128 v[162:165], v138 offset:33792
	ds_read_b128 v[166:169], v138 offset:34816
	ds_read_b128 v[170:173], v138 offset:35840
	ds_read_b128 v[174:177], v138 offset:36864
	ds_read_b128 v[182:185], v138 offset:37888
	ds_read_b128 v[186:189], v138 offset:38912
	ds_read_b128 v[190:193], v138 offset:39936
	global_load_lds_dwordx4 v[194:195], off
	v_lshl_add_u64 v[194:195], s[30:31], 0, v[130:131]
	s_mov_b32 m0, s60
	s_nop 0
	global_load_lds_dwordx4 v[194:195], off
	s_waitcnt lgkmcnt(8)
	s_barrier
	s_waitcnt lgkmcnt(0)
	s_setprio 1
	s_waitcnt lgkmcnt(0)
	v_mfma_f32_16x16x32_bf16 v[126:129], v[142:145], v[158:161], v[126:129]
	v_mfma_f32_16x16x32_bf16 v[122:125], v[150:153], v[158:161], v[122:125]
	v_mfma_f32_16x16x32_bf16 v[110:113], v[142:145], v[166:169], v[110:113]
	v_mfma_f32_16x16x32_bf16 v[106:109], v[150:153], v[166:169], v[106:109]
	v_mfma_f32_16x16x32_bf16 v[94:97], v[142:145], v[174:177], v[94:97]
	v_mfma_f32_16x16x32_bf16 v[90:93], v[150:153], v[174:177], v[90:93]
	v_mfma_f32_16x16x32_bf16 v[78:81], v[142:145], v[186:189], v[78:81]
	v_mfma_f32_16x16x32_bf16 v[74:77], v[150:153], v[186:189], v[74:77]
	v_mfma_f32_16x16x32_bf16 v[126:129], v[146:149], v[162:165], v[126:129]
	v_mfma_f32_16x16x32_bf16 v[122:125], v[154:157], v[162:165], v[122:125]
	v_mfma_f32_16x16x32_bf16 v[110:113], v[146:149], v[170:173], v[110:113]
	v_mfma_f32_16x16x32_bf16 v[106:109], v[154:157], v[170:173], v[106:109]
	v_mfma_f32_16x16x32_bf16 v[94:97], v[146:149], v[182:185], v[94:97]
	v_mfma_f32_16x16x32_bf16 v[90:93], v[154:157], v[182:185], v[90:93]
	v_mfma_f32_16x16x32_bf16 v[78:81], v[146:149], v[190:193], v[78:81]
	v_mfma_f32_16x16x32_bf16 v[74:77], v[154:157], v[190:193], v[74:77]
	s_setprio 0
	s_barrier
	s_mov_b32 m0, s68
	v_add_u32_e32 v0, 0x1c000, v139
	v_lshl_add_u64 v[178:179], v[178:179], 0, s[84:85]
	s_waitcnt vmcnt(0)
	ds_read_b128 v[194:197], v0
	ds_read_b128 v[198:201], v0 offset:1024
	ds_read_b128 v[202:205], v0 offset:2048
	ds_read_b128 v[206:209], v0 offset:3072
	global_load_lds_dwordx4 v[178:179], off
	v_lshl_add_u64 v[178:179], v[210:211], 0, s[84:85]
	s_mov_b32 m0, s69
	s_nop 0
	global_load_lds_dwordx4 v[178:179], off
	s_barrier
	s_waitcnt lgkmcnt(0)
	s_setprio 1
	s_waitcnt lgkmcnt(0)
	v_mfma_f32_16x16x32_bf16 v[118:121], v[194:197], v[158:161], v[118:121]
	v_mfma_f32_16x16x32_bf16 v[114:117], v[202:205], v[158:161], v[114:117]
	v_mfma_f32_16x16x32_bf16 v[102:105], v[194:197], v[166:169], v[102:105]
	v_mfma_f32_16x16x32_bf16 v[98:101], v[202:205], v[166:169], v[98:101]
	v_mfma_f32_16x16x32_bf16 v[86:89], v[194:197], v[174:177], v[86:89]
	v_mfma_f32_16x16x32_bf16 v[82:85], v[202:205], v[174:177], v[82:85]
	v_mfma_f32_16x16x32_bf16 v[70:73], v[194:197], v[186:189], v[70:73]
	v_mfma_f32_16x16x32_bf16 v[66:69], v[202:205], v[186:189], v[66:69]
	v_mfma_f32_16x16x32_bf16 v[118:121], v[198:201], v[162:165], v[118:121]
	v_mfma_f32_16x16x32_bf16 v[114:117], v[206:209], v[162:165], v[114:117]
	v_mfma_f32_16x16x32_bf16 v[102:105], v[198:201], v[170:173], v[102:105]
	v_mfma_f32_16x16x32_bf16 v[98:101], v[206:209], v[170:173], v[98:101]
	v_mfma_f32_16x16x32_bf16 v[86:89], v[198:201], v[182:185], v[86:89]
	v_mfma_f32_16x16x32_bf16 v[82:85], v[206:209], v[182:185], v[82:85]
	v_mfma_f32_16x16x32_bf16 v[70:73], v[198:201], v[190:193], v[70:73]
	v_mfma_f32_16x16x32_bf16 v[66:69], v[206:209], v[190:193], v[66:69]
	s_setprio 0
	s_mov_b32 m0, s75
	v_lshl_add_u64 v[178:179], v[212:213], 0, s[84:85]
	s_barrier
	s_waitcnt vmcnt(0)
	ds_read_b128 v[158:161], v138 offset:49152
	ds_read_b128 v[162:165], v138 offset:50176
	ds_read_b128 v[166:169], v138 offset:51200
	ds_read_b128 v[170:173], v138 offset:52224
	ds_read_b128 v[174:177], v138 offset:53248
	ds_read_b128 v[182:185], v138 offset:54272
	ds_read_b128 v[186:189], v138 offset:55296
	ds_read_b128 v[190:193], v138 offset:56320
	global_load_lds_dwordx4 v[178:179], off
	v_lshl_add_u64 v[178:179], v[214:215], 0, s[84:85]
	s_mov_b32 m0, s82
	s_nop 0
	global_load_lds_dwordx4 v[178:179], off
	s_barrier
	s_waitcnt lgkmcnt(0)
	s_setprio 1
	s_waitcnt lgkmcnt(0)
	v_mfma_f32_16x16x32_bf16 v[62:65], v[142:145], v[158:161], v[62:65]
	v_mfma_f32_16x16x32_bf16 v[58:61], v[150:153], v[158:161], v[58:61]
	v_mfma_f32_16x16x32_bf16 v[46:49], v[142:145], v[166:169], v[46:49]
	v_mfma_f32_16x16x32_bf16 v[42:45], v[150:153], v[166:169], v[42:45]
	v_mfma_f32_16x16x32_bf16 v[30:33], v[142:145], v[174:177], v[30:33]
	v_mfma_f32_16x16x32_bf16 v[26:29], v[150:153], v[174:177], v[26:29]
	v_mfma_f32_16x16x32_bf16 v[14:17], v[142:145], v[186:189], v[14:17]
	v_mfma_f32_16x16x32_bf16 v[10:13], v[150:153], v[186:189], v[10:13]
	v_mfma_f32_16x16x32_bf16 v[62:65], v[146:149], v[162:165], v[62:65]
	v_mfma_f32_16x16x32_bf16 v[58:61], v[154:157], v[162:165], v[58:61]
	v_mfma_f32_16x16x32_bf16 v[46:49], v[146:149], v[170:173], v[46:49]
	v_mfma_f32_16x16x32_bf16 v[42:45], v[154:157], v[170:173], v[42:45]
	v_mfma_f32_16x16x32_bf16 v[30:33], v[146:149], v[182:185], v[30:33]
	v_mfma_f32_16x16x32_bf16 v[26:29], v[154:157], v[182:185], v[26:29]
	v_mfma_f32_16x16x32_bf16 v[14:17], v[146:149], v[190:193], v[14:17]
	v_mfma_f32_16x16x32_bf16 v[10:13], v[154:157], v[190:193], v[10:13]
	s_setprio 0
	s_barrier
	s_add_u32 s28, s28, 0x40080
	s_addc_u32 s29, s29, 0
	s_mov_b32 m0, s92
	v_lshl_add_u64 v[142:143], s[28:29], 0, v[132:133]
	global_load_lds_dwordx4 v[142:143], off
	v_lshl_add_u64 v[142:143], s[28:29], 0, v[130:131]
	s_mov_b32 m0, s93
	s_nop 0
	global_load_lds_dwordx4 v[142:143], off
	s_waitcnt vmcnt(6)
	s_barrier
	s_setprio 1
	v_mfma_f32_16x16x32_bf16 v[54:57], v[194:197], v[158:161], v[54:57]
	v_mfma_f32_16x16x32_bf16 v[50:53], v[202:205], v[158:161], v[50:53]
	v_mfma_f32_16x16x32_bf16 v[38:41], v[194:197], v[166:169], v[38:41]
	v_mfma_f32_16x16x32_bf16 v[34:37], v[202:205], v[166:169], v[34:37]
	v_mfma_f32_16x16x32_bf16 v[22:25], v[194:197], v[174:177], v[22:25]
	v_mfma_f32_16x16x32_bf16 v[18:21], v[202:205], v[174:177], v[18:21]
	v_mfma_f32_16x16x32_bf16 v[6:9], v[194:197], v[186:189], v[6:9]
	v_mfma_f32_16x16x32_bf16 v[2:5], v[202:205], v[186:189], v[2:5]
	v_mfma_f32_16x16x32_bf16 v[54:57], v[198:201], v[162:165], v[54:57]
	v_mfma_f32_16x16x32_bf16 v[50:53], v[206:209], v[162:165], v[50:53]
	v_mfma_f32_16x16x32_bf16 v[38:41], v[198:201], v[170:173], v[38:41]
	v_mfma_f32_16x16x32_bf16 v[34:37], v[206:209], v[170:173], v[34:37]
	v_mfma_f32_16x16x32_bf16 v[22:25], v[198:201], v[182:185], v[22:25]
	v_mfma_f32_16x16x32_bf16 v[18:21], v[206:209], v[182:185], v[18:21]
	v_mfma_f32_16x16x32_bf16 v[6:9], v[198:201], v[190:193], v[6:9]
	v_mfma_f32_16x16x32_bf16 v[2:5], v[206:209], v[190:193], v[2:5]
	s_setprio 0
	s_add_i32 vcc_lo, vcc_lo, 2
	s_add_u32 s26, s26, 0x100
	s_addc_u32 s27, s27, 0
	s_add_u32 s94, s94, 0x100
	s_addc_u32 s97, s97, 0
	s_cmp_gt_u32 vcc_lo, 13
	s_barrier
	s_cbranch_scc0 .LBB0_1428
	s_lshl_b32 s13, s22, 8
	s_lshl_b32 s15, s24, 18
	s_add_i32 s15, s15, s13
	v_add_u32_e32 v0, s15, v140
	v_mov_b32_e32 v148, v0
	v_mov_b32_e32 v207, 0
	v_mov_b32_e32 v206, v148
	v_lshlrev_b64 v[150:151], 2, v[206:207]
	v_lshl_add_u64 v[150:151], s[8:9], 0, v[150:151]
	global_load_dwordx4 v[150:153], v[150:151], off
	v_add_u32_e32 v206, 0x10, v148
	v_lshlrev_b64 v[154:155], 2, v[206:207]
	v_lshl_add_u64 v[154:155], s[8:9], 0, v[154:155]
	global_load_dwordx4 v[154:157], v[154:155], off
	v_add_u32_e32 v206, 0x80, v148
	v_lshlrev_b64 v[158:159], 2, v[206:207]
	v_lshl_add_u64 v[158:159], s[8:9], 0, v[158:159]
	global_load_dwordx4 v[158:161], v[158:159], off
	v_add_u32_e32 v206, 0x90, v148
	v_lshlrev_b64 v[162:163], 2, v[206:207]
	v_lshl_add_u64 v[162:163], s[8:9], 0, v[162:163]
	global_load_dwordx4 v[162:165], v[162:163], off
	v_add_u32_e32 v206, 0x4000, v148
	v_lshlrev_b64 v[166:167], 2, v[206:207]
	v_lshl_add_u64 v[166:167], s[8:9], 0, v[166:167]
	global_load_dwordx4 v[166:169], v[166:167], off
	v_add_u32_e32 v206, 0x4010, v148
	v_lshlrev_b64 v[170:171], 2, v[206:207]
	v_lshl_add_u64 v[170:171], s[8:9], 0, v[170:171]
	global_load_dwordx4 v[170:173], v[170:171], off
	v_add_u32_e32 v206, 0x4080, v148
	v_lshlrev_b64 v[174:175], 2, v[206:207]
	v_lshl_add_u64 v[174:175], s[8:9], 0, v[174:175]
	global_load_dwordx4 v[174:177], v[174:175], off
	v_add_u32_e32 v206, 0x4090, v148
	v_lshlrev_b64 v[182:183], 2, v[206:207]
	v_lshl_add_u64 v[182:183], s[8:9], 0, v[182:183]
	global_load_dwordx4 v[182:185], v[182:183], off
	v_add_u32_e32 v206, 0x8000, v148
	v_lshlrev_b64 v[186:187], 2, v[206:207]
	v_lshl_add_u64 v[186:187], s[8:9], 0, v[186:187]
	global_load_dwordx4 v[186:189], v[186:187], off
	v_add_u32_e32 v206, 0x8010, v148
	v_lshlrev_b64 v[190:191], 2, v[206:207]
	v_lshl_add_u64 v[190:191], s[8:9], 0, v[190:191]
	global_load_dwordx4 v[190:193], v[190:191], off
	v_add_u32_e32 v206, 0x8080, v148
	v_lshlrev_b64 v[194:195], 2, v[206:207]
	v_lshl_add_u64 v[194:195], s[8:9], 0, v[194:195]
	global_load_dwordx4 v[194:197], v[194:195], off
	v_add_u32_e32 v206, 0x8090, v148
	v_lshlrev_b64 v[198:199], 2, v[206:207]
	v_lshl_add_u64 v[198:199], s[8:9], 0, v[198:199]
	global_load_dwordx4 v[198:201], v[198:199], off
	v_add_u32_e32 v206, 0xc000, v148
	v_lshlrev_b64 v[202:203], 2, v[206:207]
	v_lshl_add_u64 v[202:203], s[8:9], 0, v[202:203]
	global_load_dwordx4 v[202:205], v[202:203], off
	v_lshlrev_b64 v[146:147], 2, v[0:1]
	s_and_b64 vcc, exec, s[16:17]
	s_mov_b32 s22, s12
	s_mov_b32 s24, s14
	s_mov_b64 s[28:29], s[20:21]
	s_mov_b64 s[26:27], s[18:19]
	s_waitcnt vmcnt(12)
	v_pk_add_f32 v[128:129], v[128:129], v[152:153]
	v_pk_add_f32 v[126:127], v[126:127], v[150:151]
	v_lshl_add_u64 v[142:143], s[10:11], 0, v[146:147]
	v_add_u32_e32 v206, 0xc010, v148
	v_lshlrev_b64 v[150:151], 2, v[206:207]
	v_lshl_add_u64 v[150:151], s[8:9], 0, v[150:151]
	global_load_dwordx4 v[150:153], v[150:151], off
	global_store_dwordx4 v[142:143], v[126:129], off
	s_nop 1
	v_add_u32_e32 v126, 16, v0
	v_mov_b32_e32 v127, v1
	v_lshlrev_b64 v[142:143], 2, v[126:127]
	s_waitcnt vmcnt(13)
	v_pk_add_f32 v[124:125], v[124:125], v[156:157]
	v_pk_add_f32 v[122:123], v[122:123], v[154:155]
	v_lshl_add_u64 v[126:127], s[10:11], 0, v[142:143]
	v_add_u32_e32 v206, 0xc080, v148
	v_lshlrev_b64 v[154:155], 2, v[206:207]
	v_lshl_add_u64 v[154:155], s[8:9], 0, v[154:155]
	global_load_dwordx4 v[154:157], v[154:155], off
	global_store_dwordx4 v[126:127], v[122:125], off
	s_nop 1
	v_add_u32_e32 v122, 0x80, v0
	v_mov_b32_e32 v123, v1
	v_lshlrev_b64 v[126:127], 2, v[122:123]
	s_waitcnt vmcnt(14)
	v_pk_add_f32 v[120:121], v[120:121], v[160:161]
	v_pk_add_f32 v[118:119], v[118:119], v[158:159]
	v_lshl_add_u64 v[122:123], s[10:11], 0, v[126:127]
	v_add_u32_e32 v206, 0xc090, v148
	v_lshlrev_b64 v[158:159], 2, v[206:207]
	v_lshl_add_u64 v[158:159], s[8:9], 0, v[158:159]
	global_load_dwordx4 v[158:161], v[158:159], off
	global_store_dwordx4 v[122:123], v[118:121], off
	s_nop 1
	v_add_u32_e32 v118, 0x90, v0
	v_mov_b32_e32 v119, v1
	v_lshlrev_b64 v[122:123], 2, v[118:119]
	s_waitcnt vmcnt(15)
	v_pk_add_f32 v[116:117], v[116:117], v[164:165]
	v_pk_add_f32 v[114:115], v[114:115], v[162:163]
	v_lshl_add_u64 v[118:119], s[10:11], 0, v[122:123]
	v_add_u32_e32 v206, 0x20000, v148
	v_lshlrev_b64 v[162:163], 2, v[206:207]
	v_lshl_add_u64 v[162:163], s[8:9], 0, v[162:163]
	global_load_dwordx4 v[162:165], v[162:163], off
	global_store_dwordx4 v[118:119], v[114:117], off
	s_nop 1
	v_add_u32_e32 v114, 0x4000, v0
	v_mov_b32_e32 v115, v1
	v_lshlrev_b64 v[118:119], 2, v[114:115]
	s_waitcnt vmcnt(16)
	v_pk_add_f32 v[112:113], v[112:113], v[168:169]
	v_pk_add_f32 v[110:111], v[110:111], v[166:167]
	v_lshl_add_u64 v[114:115], s[10:11], 0, v[118:119]
	v_add_u32_e32 v206, 0x20010, v148
	v_lshlrev_b64 v[166:167], 2, v[206:207]
	v_lshl_add_u64 v[166:167], s[8:9], 0, v[166:167]
	global_load_dwordx4 v[166:169], v[166:167], off
	global_store_dwordx4 v[114:115], v[110:113], off
	s_nop 1
	v_add_u32_e32 v110, 0x4010, v0
	v_mov_b32_e32 v111, v1
	v_lshlrev_b64 v[114:115], 2, v[110:111]
	s_waitcnt vmcnt(17)
	v_pk_add_f32 v[108:109], v[108:109], v[172:173]
	v_pk_add_f32 v[106:107], v[106:107], v[170:171]
	v_lshl_add_u64 v[110:111], s[10:11], 0, v[114:115]
	v_add_u32_e32 v206, 0x20080, v148
	v_lshlrev_b64 v[170:171], 2, v[206:207]
	v_lshl_add_u64 v[170:171], s[8:9], 0, v[170:171]
	global_load_dwordx4 v[170:173], v[170:171], off
	global_store_dwordx4 v[110:111], v[106:109], off
	s_nop 1
	v_add_u32_e32 v106, 0x4080, v0
	v_mov_b32_e32 v107, v1
	v_lshlrev_b64 v[110:111], 2, v[106:107]
	s_waitcnt vmcnt(18)
	v_pk_add_f32 v[104:105], v[104:105], v[176:177]
	v_pk_add_f32 v[102:103], v[102:103], v[174:175]
	v_lshl_add_u64 v[106:107], s[10:11], 0, v[110:111]
	v_add_u32_e32 v206, 0x20090, v148
	v_lshlrev_b64 v[174:175], 2, v[206:207]
	v_lshl_add_u64 v[174:175], s[8:9], 0, v[174:175]
	global_load_dwordx4 v[174:177], v[174:175], off
	global_store_dwordx4 v[106:107], v[102:105], off
	s_nop 1
	v_add_u32_e32 v102, 0x4090, v0
	v_mov_b32_e32 v103, v1
	v_lshlrev_b64 v[106:107], 2, v[102:103]
	s_waitcnt vmcnt(19)
	v_pk_add_f32 v[100:101], v[100:101], v[184:185]
	v_pk_add_f32 v[98:99], v[98:99], v[182:183]
	v_lshl_add_u64 v[102:103], s[10:11], 0, v[106:107]
	v_add_u32_e32 v206, 0x24000, v148
	v_lshlrev_b64 v[182:183], 2, v[206:207]
	v_lshl_add_u64 v[182:183], s[8:9], 0, v[182:183]
	global_load_dwordx4 v[182:185], v[182:183], off
	global_store_dwordx4 v[102:103], v[98:101], off
	s_nop 1
	v_add_u32_e32 v98, 0x8000, v0
	v_mov_b32_e32 v99, v1
	v_lshlrev_b64 v[102:103], 2, v[98:99]
	s_waitcnt vmcnt(20)
	v_pk_add_f32 v[96:97], v[96:97], v[188:189]
	v_pk_add_f32 v[94:95], v[94:95], v[186:187]
	v_lshl_add_u64 v[98:99], s[10:11], 0, v[102:103]
	v_add_u32_e32 v206, 0x24010, v148
	v_lshlrev_b64 v[186:187], 2, v[206:207]
	v_lshl_add_u64 v[186:187], s[8:9], 0, v[186:187]
	global_load_dwordx4 v[186:189], v[186:187], off
	global_store_dwordx4 v[98:99], v[94:97], off
	s_nop 1
	v_add_u32_e32 v94, 0x8010, v0
	v_mov_b32_e32 v95, v1
	v_lshlrev_b64 v[98:99], 2, v[94:95]
	s_waitcnt vmcnt(21)
	v_pk_add_f32 v[92:93], v[92:93], v[192:193]
	v_pk_add_f32 v[90:91], v[90:91], v[190:191]
	v_lshl_add_u64 v[94:95], s[10:11], 0, v[98:99]
	v_add_u32_e32 v206, 0x24080, v148
	v_lshlrev_b64 v[190:191], 2, v[206:207]
	v_lshl_add_u64 v[190:191], s[8:9], 0, v[190:191]
	global_load_dwordx4 v[190:193], v[190:191], off
	global_store_dwordx4 v[94:95], v[90:93], off
	s_nop 1
	v_add_u32_e32 v90, 0x8080, v0
	v_mov_b32_e32 v91, v1
	v_lshlrev_b64 v[94:95], 2, v[90:91]
	s_waitcnt vmcnt(22)
	v_pk_add_f32 v[88:89], v[88:89], v[196:197]
	v_pk_add_f32 v[86:87], v[86:87], v[194:195]
	v_lshl_add_u64 v[90:91], s[10:11], 0, v[94:95]
	v_add_u32_e32 v206, 0x24090, v148
	v_lshlrev_b64 v[194:195], 2, v[206:207]
	v_lshl_add_u64 v[194:195], s[8:9], 0, v[194:195]
	global_load_dwordx4 v[194:197], v[194:195], off
	global_store_dwordx4 v[90:91], v[86:89], off
	s_nop 1
	v_add_u32_e32 v86, 0x8090, v0
	v_mov_b32_e32 v87, v1
	v_lshlrev_b64 v[90:91], 2, v[86:87]
	s_waitcnt vmcnt(23)
	v_pk_add_f32 v[84:85], v[84:85], v[200:201]
	v_pk_add_f32 v[82:83], v[82:83], v[198:199]
	v_lshl_add_u64 v[86:87], s[10:11], 0, v[90:91]
	v_add_u32_e32 v206, 0x28000, v148
	v_lshlrev_b64 v[198:199], 2, v[206:207]
	v_lshl_add_u64 v[198:199], s[8:9], 0, v[198:199]
	global_load_dwordx4 v[198:201], v[198:199], off
	global_store_dwordx4 v[86:87], v[82:85], off
	s_nop 1
	v_add_u32_e32 v82, 0xc000, v0
	v_mov_b32_e32 v83, v1
	v_lshlrev_b64 v[86:87], 2, v[82:83]
	s_waitcnt vmcnt(24)
	v_pk_add_f32 v[80:81], v[80:81], v[204:205]
	v_pk_add_f32 v[78:79], v[78:79], v[202:203]
	v_lshl_add_u64 v[82:83], s[10:11], 0, v[86:87]
	v_add_u32_e32 v206, 0x28010, v148
	v_lshlrev_b64 v[202:203], 2, v[206:207]
	v_lshl_add_u64 v[202:203], s[8:9], 0, v[202:203]
	global_load_dwordx4 v[202:205], v[202:203], off
	global_store_dwordx4 v[82:83], v[78:81], off
	s_nop 1
	v_add_u32_e32 v78, 0xc010, v0
	v_mov_b32_e32 v79, v1
	v_lshlrev_b64 v[82:83], 2, v[78:79]
	s_waitcnt vmcnt(25)
	v_pk_add_f32 v[76:77], v[76:77], v[152:153]
	v_pk_add_f32 v[74:75], v[74:75], v[150:151]
	v_lshl_add_u64 v[78:79], s[10:11], 0, v[82:83]
	v_add_u32_e32 v206, 0x28080, v148
	v_lshlrev_b64 v[150:151], 2, v[206:207]
	v_lshl_add_u64 v[150:151], s[8:9], 0, v[150:151]
	global_load_dwordx4 v[150:153], v[150:151], off
	global_store_dwordx4 v[78:79], v[74:77], off
	s_nop 1
	v_add_u32_e32 v74, 0xc080, v0
	v_mov_b32_e32 v75, v1
	v_lshlrev_b64 v[78:79], 2, v[74:75]
	s_waitcnt vmcnt(25)
	v_pk_add_f32 v[72:73], v[72:73], v[156:157]
	v_pk_add_f32 v[70:71], v[70:71], v[154:155]
	v_lshl_add_u64 v[74:75], s[10:11], 0, v[78:79]
	v_add_u32_e32 v206, 0x28090, v148
	v_lshlrev_b64 v[154:155], 2, v[206:207]
	v_lshl_add_u64 v[154:155], s[8:9], 0, v[154:155]
	global_load_dwordx4 v[154:157], v[154:155], off
	global_store_dwordx4 v[74:75], v[70:73], off
	s_nop 1
	v_add_u32_e32 v70, 0xc090, v0
	v_mov_b32_e32 v71, v1
	v_lshlrev_b64 v[74:75], 2, v[70:71]
	s_waitcnt vmcnt(25)
	v_pk_add_f32 v[68:69], v[68:69], v[160:161]
	v_pk_add_f32 v[66:67], v[66:67], v[158:159]
	v_lshl_add_u64 v[70:71], s[10:11], 0, v[74:75]
	v_add_u32_e32 v206, 0x2c000, v148
	v_lshlrev_b64 v[158:159], 2, v[206:207]
	v_lshl_add_u64 v[158:159], s[8:9], 0, v[158:159]
	global_load_dwordx4 v[158:161], v[158:159], off
	global_store_dwordx4 v[70:71], v[66:69], off
	s_nop 1
	v_add_u32_e32 v66, 0x20000, v0
	v_mov_b32_e32 v67, v1
	v_lshlrev_b64 v[70:71], 2, v[66:67]
	s_waitcnt vmcnt(25)
	v_pk_add_f32 v[64:65], v[64:65], v[164:165]
	v_pk_add_f32 v[62:63], v[62:63], v[162:163]
	v_lshl_add_u64 v[66:67], s[10:11], 0, v[70:71]
	v_add_u32_e32 v206, 0x2c010, v148
	v_lshlrev_b64 v[162:163], 2, v[206:207]
	v_lshl_add_u64 v[162:163], s[8:9], 0, v[162:163]
	global_load_dwordx4 v[162:165], v[162:163], off
	global_store_dwordx4 v[66:67], v[62:65], off
	s_nop 1
	v_add_u32_e32 v62, 0x20010, v0
	v_mov_b32_e32 v63, v1
	v_lshlrev_b64 v[66:67], 2, v[62:63]
	s_waitcnt vmcnt(25)
	v_pk_add_f32 v[60:61], v[60:61], v[168:169]
	v_pk_add_f32 v[58:59], v[58:59], v[166:167]
	v_lshl_add_u64 v[62:63], s[10:11], 0, v[66:67]
	v_add_u32_e32 v206, 0x2c080, v148
	v_lshlrev_b64 v[166:167], 2, v[206:207]
	v_lshl_add_u64 v[166:167], s[8:9], 0, v[166:167]
	global_load_dwordx4 v[166:169], v[166:167], off
	global_store_dwordx4 v[62:63], v[58:61], off
	s_nop 1
	v_add_u32_e32 v58, 0x20080, v0
	v_mov_b32_e32 v59, v1
	v_lshlrev_b64 v[62:63], 2, v[58:59]
	s_waitcnt vmcnt(25)
	v_pk_add_f32 v[56:57], v[56:57], v[172:173]
	v_pk_add_f32 v[54:55], v[54:55], v[170:171]
	v_lshl_add_u64 v[58:59], s[10:11], 0, v[62:63]
	v_add_u32_e32 v206, 0x2c090, v148
	v_lshlrev_b64 v[170:171], 2, v[206:207]
	v_lshl_add_u64 v[170:171], s[8:9], 0, v[170:171]
	global_load_dwordx4 v[170:173], v[170:171], off
	global_store_dwordx4 v[58:59], v[54:57], off
	s_nop 1
	v_add_u32_e32 v54, 0x20090, v0
	v_mov_b32_e32 v55, v1
	v_lshlrev_b64 v[58:59], 2, v[54:55]
	s_waitcnt vmcnt(25)
	v_pk_add_f32 v[52:53], v[52:53], v[176:177]
	v_pk_add_f32 v[50:51], v[50:51], v[174:175]
	v_lshl_add_u64 v[54:55], s[10:11], 0, v[58:59]
	global_store_dwordx4 v[54:55], v[50:53], off
	s_nop 1
	v_add_u32_e32 v50, 0x24000, v0
	v_mov_b32_e32 v51, v1
	v_lshlrev_b64 v[54:55], 2, v[50:51]
	s_waitcnt vmcnt(24)
	v_pk_add_f32 v[48:49], v[48:49], v[184:185]
	v_pk_add_f32 v[46:47], v[46:47], v[182:183]
	v_lshl_add_u64 v[50:51], s[10:11], 0, v[54:55]
	global_store_dwordx4 v[50:51], v[46:49], off
	s_nop 1
	v_add_u32_e32 v46, 0x24010, v0
	v_mov_b32_e32 v47, v1
	v_lshlrev_b64 v[50:51], 2, v[46:47]
	s_waitcnt vmcnt(23)
	v_pk_add_f32 v[44:45], v[44:45], v[188:189]
	v_pk_add_f32 v[42:43], v[42:43], v[186:187]
	v_lshl_add_u64 v[46:47], s[10:11], 0, v[50:51]
	global_store_dwordx4 v[46:47], v[42:45], off
	s_nop 1
	v_add_u32_e32 v42, 0x24080, v0
	v_mov_b32_e32 v43, v1
	v_lshlrev_b64 v[46:47], 2, v[42:43]
	s_waitcnt vmcnt(22)
	v_pk_add_f32 v[40:41], v[40:41], v[192:193]
	v_pk_add_f32 v[38:39], v[38:39], v[190:191]
	v_lshl_add_u64 v[42:43], s[10:11], 0, v[46:47]
	global_store_dwordx4 v[42:43], v[38:41], off
	s_nop 1
	v_add_u32_e32 v38, 0x24090, v0
	v_mov_b32_e32 v39, v1
	v_lshlrev_b64 v[42:43], 2, v[38:39]
	s_waitcnt vmcnt(21)
	v_pk_add_f32 v[36:37], v[36:37], v[196:197]
	v_pk_add_f32 v[34:35], v[34:35], v[194:195]
	v_lshl_add_u64 v[38:39], s[10:11], 0, v[42:43]
	global_store_dwordx4 v[38:39], v[34:37], off
	s_nop 1
	v_add_u32_e32 v34, 0x28000, v0
	v_mov_b32_e32 v35, v1
	v_lshlrev_b64 v[38:39], 2, v[34:35]
	s_waitcnt vmcnt(20)
	v_pk_add_f32 v[32:33], v[32:33], v[200:201]
	v_pk_add_f32 v[30:31], v[30:31], v[198:199]
	v_lshl_add_u64 v[34:35], s[10:11], 0, v[38:39]
	global_store_dwordx4 v[34:35], v[30:33], off
	s_nop 1
	v_add_u32_e32 v30, 0x28010, v0
	v_mov_b32_e32 v31, v1
	v_lshlrev_b64 v[34:35], 2, v[30:31]
	s_waitcnt vmcnt(19)
	v_pk_add_f32 v[28:29], v[28:29], v[204:205]
	v_pk_add_f32 v[26:27], v[26:27], v[202:203]
	v_lshl_add_u64 v[30:31], s[10:11], 0, v[34:35]
	global_store_dwordx4 v[30:31], v[26:29], off
	s_nop 1
	v_add_u32_e32 v26, 0x28080, v0
	v_mov_b32_e32 v27, v1
	v_lshlrev_b64 v[30:31], 2, v[26:27]
	s_waitcnt vmcnt(18)
	v_pk_add_f32 v[24:25], v[24:25], v[152:153]
	v_pk_add_f32 v[22:23], v[22:23], v[150:151]
	v_lshl_add_u64 v[26:27], s[10:11], 0, v[30:31]
	global_store_dwordx4 v[26:27], v[22:25], off
	s_nop 1
	v_add_u32_e32 v22, 0x28090, v0
	v_mov_b32_e32 v23, v1
	v_lshlrev_b64 v[26:27], 2, v[22:23]
	s_waitcnt vmcnt(17)
	v_pk_add_f32 v[20:21], v[20:21], v[156:157]
	v_pk_add_f32 v[18:19], v[18:19], v[154:155]
	v_lshl_add_u64 v[22:23], s[10:11], 0, v[26:27]
	global_store_dwordx4 v[22:23], v[18:21], off
	s_nop 1
	v_add_u32_e32 v18, 0x2c000, v0
	v_mov_b32_e32 v19, v1
	v_lshlrev_b64 v[22:23], 2, v[18:19]
	s_waitcnt vmcnt(16)
	v_pk_add_f32 v[16:17], v[16:17], v[160:161]
	v_pk_add_f32 v[14:15], v[14:15], v[158:159]
	v_lshl_add_u64 v[18:19], s[10:11], 0, v[22:23]
	global_store_dwordx4 v[18:19], v[14:17], off
	s_nop 1
	v_add_u32_e32 v14, 0x2c010, v0
	v_mov_b32_e32 v15, v1
	v_lshlrev_b64 v[18:19], 2, v[14:15]
	s_waitcnt vmcnt(15)
	v_pk_add_f32 v[12:13], v[12:13], v[164:165]
	v_pk_add_f32 v[10:11], v[10:11], v[162:163]
	v_lshl_add_u64 v[14:15], s[10:11], 0, v[18:19]
	global_store_dwordx4 v[14:15], v[10:13], off
	s_nop 1
	v_add_u32_e32 v10, 0x2c080, v0
	v_mov_b32_e32 v11, v1
	v_lshlrev_b64 v[14:15], 2, v[10:11]
	v_add_u32_e32 v0, 0x2c090, v0
	s_waitcnt vmcnt(14)
	v_pk_add_f32 v[8:9], v[8:9], v[168:169]
	v_pk_add_f32 v[6:7], v[6:7], v[166:167]
	v_lshl_add_u64 v[10:11], s[10:11], 0, v[14:15]
	global_store_dwordx4 v[10:11], v[6:9], off
	v_lshlrev_b64 v[10:11], 2, v[0:1]
	s_nop 0
	s_waitcnt vmcnt(13)
	v_pk_add_f32 v[4:5], v[4:5], v[172:173]
	v_pk_add_f32 v[2:3], v[2:3], v[170:171]
	v_lshl_add_u64 v[6:7], s[10:11], 0, v[10:11]
	global_store_dwordx4 v[6:7], v[2:5], off
	s_cbranch_vccz .LBB0_1425
	s_waitcnt vmcnt(0)
	v_readlane_b32 s76, v255, 8
	s_mov_b32 s92, 0x3b2aaaab
	s_cmp_gt_u32 s4, 3
	v_readlane_b32 s77, v255, 9
	s_mul_i32 s60, s33, 0x1800
	s_mul_hi_i32 s62, s64, 0x300
	s_mul_i32 s75, s33, 0x16c00
	s_mov_b32 s93, 0x3c800000
	s_cbranch_scc1 .LBB0_1432
	s_barrier

.LBB0_1441:
	v_add_u32_e32 v0, 0x10000, v139
	s_waitcnt vmcnt(0)
	ds_read_b128 v[142:145], v0
	ds_read_b128 v[146:149], v0 offset:1024
	ds_read_b128 v[150:153], v0 offset:2048
	ds_read_b128 v[154:157], v0 offset:3072
	s_add_u32 s26, s24, 0xfffc0080
	s_addc_u32 s27, s25, -1
	s_cmp_eq_u32 s97, 12
	s_cselect_b32 s29, s13, s27
	s_cselect_b32 s28, s89, s26
	s_cselect_b32 s27, s11, s96
	s_cselect_b32 s26, s90, s94
	v_lshl_add_u64 v[178:179], s[24:25], 0, v[134:135]
	s_add_i32 m0, s34, 0xc000
	ds_read_b128 v[158:161], v138
	ds_read_b128 v[162:165], v138 offset:1024
	ds_read_b128 v[166:169], v138 offset:2048
	ds_read_b128 v[170:173], v138 offset:3072
	ds_read_b128 v[174:177], v138 offset:4096
	ds_read_b128 v[182:185], v138 offset:5120
	ds_read_b128 v[186:189], v138 offset:6144
	ds_read_b128 v[190:193], v138 offset:7168
	global_load_lds_dwordx4 v[178:179], off
	v_lshl_add_u64 v[178:179], s[24:25], 0, v[136:137]
	s_add_i32 m0, s34, 0xe000
	s_nop 0
	global_load_lds_dwordx4 v[178:179], off
	s_waitcnt lgkmcnt(8)
	s_barrier
	s_waitcnt lgkmcnt(0)
	s_setprio 1
	s_waitcnt lgkmcnt(0)
	v_mfma_f32_16x16x32_bf16 v[126:129], v[142:145], v[158:161], v[126:129]
	v_mfma_f32_16x16x32_bf16 v[122:125], v[150:153], v[158:161], v[122:125]
	v_mfma_f32_16x16x32_bf16 v[110:113], v[142:145], v[166:169], v[110:113]
	v_mfma_f32_16x16x32_bf16 v[106:109], v[150:153], v[166:169], v[106:109]
	v_mfma_f32_16x16x32_bf16 v[94:97], v[142:145], v[174:177], v[94:97]
	v_mfma_f32_16x16x32_bf16 v[90:93], v[150:153], v[174:177], v[90:93]
	v_mfma_f32_16x16x32_bf16 v[78:81], v[142:145], v[186:189], v[78:81]
	v_mfma_f32_16x16x32_bf16 v[74:77], v[150:153], v[186:189], v[74:77]
	v_mfma_f32_16x16x32_bf16 v[126:129], v[146:149], v[162:165], v[126:129]
	v_mfma_f32_16x16x32_bf16 v[122:125], v[154:157], v[162:165], v[122:125]
	v_mfma_f32_16x16x32_bf16 v[110:113], v[146:149], v[170:173], v[110:113]
	v_mfma_f32_16x16x32_bf16 v[106:109], v[154:157], v[170:173], v[106:109]
	v_mfma_f32_16x16x32_bf16 v[94:97], v[146:149], v[182:185], v[94:97]
	v_mfma_f32_16x16x32_bf16 v[90:93], v[154:157], v[182:185], v[90:93]
	v_mfma_f32_16x16x32_bf16 v[78:81], v[146:149], v[190:193], v[78:81]
	v_mfma_f32_16x16x32_bf16 v[74:77], v[154:157], v[190:193], v[74:77]
	s_setprio 0
	s_barrier
	s_mov_b32 m0, s21
	v_add_u32_e32 v0, 0x14000, v139
	v_lshl_add_u64 v[178:179], s[26:27], 0, v[132:133]
	s_waitcnt vmcnt(0)
	ds_read_b128 v[194:197], v0
	ds_read_b128 v[198:201], v0 offset:1024
	ds_read_b128 v[202:205], v0 offset:2048
	ds_read_b128 v[206:209], v0 offset:3072
	global_load_lds_dwordx4 v[178:179], off
	v_lshl_add_u64 v[210:211], s[26:27], 0, v[130:131]
	s_mov_b32 m0, s23
	s_nop 0
	global_load_lds_dwordx4 v[210:211], off
	s_barrier
	s_waitcnt lgkmcnt(0)
	s_setprio 1
	s_waitcnt lgkmcnt(0)
	v_mfma_f32_16x16x32_bf16 v[118:121], v[194:197], v[158:161], v[118:121]
	v_mfma_f32_16x16x32_bf16 v[114:117], v[202:205], v[158:161], v[114:117]
	v_mfma_f32_16x16x32_bf16 v[102:105], v[194:197], v[166:169], v[102:105]
	v_mfma_f32_16x16x32_bf16 v[98:101], v[202:205], v[166:169], v[98:101]
	v_mfma_f32_16x16x32_bf16 v[86:89], v[194:197], v[174:177], v[86:89]
	v_mfma_f32_16x16x32_bf16 v[82:85], v[202:205], v[174:177], v[82:85]
	v_mfma_f32_16x16x32_bf16 v[70:73], v[194:197], v[186:189], v[70:73]
	v_mfma_f32_16x16x32_bf16 v[66:69], v[202:205], v[186:189], v[66:69]
	v_mfma_f32_16x16x32_bf16 v[118:121], v[198:201], v[162:165], v[118:121]
	v_mfma_f32_16x16x32_bf16 v[114:117], v[206:209], v[162:165], v[114:117]
	v_mfma_f32_16x16x32_bf16 v[102:105], v[198:201], v[170:173], v[102:105]
	v_mfma_f32_16x16x32_bf16 v[98:101], v[206:209], v[170:173], v[98:101]
	v_mfma_f32_16x16x32_bf16 v[86:89], v[198:201], v[182:185], v[86:89]
	v_mfma_f32_16x16x32_bf16 v[82:85], v[206:209], v[182:185], v[82:85]
	v_mfma_f32_16x16x32_bf16 v[70:73], v[198:201], v[190:193], v[70:73]
	v_mfma_f32_16x16x32_bf16 v[66:69], v[206:209], v[190:193], v[66:69]
	s_setprio 0
	s_mov_b32 m0, s34
	v_lshl_add_u64 v[212:213], s[28:29], 0, v[132:133]
	s_barrier
	s_waitcnt vmcnt(0)
	ds_read_b128 v[158:161], v138 offset:16384
	ds_read_b128 v[162:165], v138 offset:17408
	ds_read_b128 v[166:169], v138 offset:18432
	ds_read_b128 v[170:173], v138 offset:19456
	ds_read_b128 v[174:177], v138 offset:20480
	ds_read_b128 v[182:185], v138 offset:21504
	ds_read_b128 v[186:189], v138 offset:22528
	ds_read_b128 v[190:193], v138 offset:23552
	global_load_lds_dwordx4 v[212:213], off
	v_lshl_add_u64 v[214:215], s[28:29], 0, v[130:131]
	s_mov_b32 m0, s35
	s_nop 0
	global_load_lds_dwordx4 v[214:215], off
	s_barrier
	s_waitcnt lgkmcnt(0)
	s_setprio 1
	s_waitcnt lgkmcnt(0)
	v_mfma_f32_16x16x32_bf16 v[62:65], v[142:145], v[158:161], v[62:65]
	v_mfma_f32_16x16x32_bf16 v[58:61], v[150:153], v[158:161], v[58:61]
	v_mfma_f32_16x16x32_bf16 v[46:49], v[142:145], v[166:169], v[46:49]
	v_mfma_f32_16x16x32_bf16 v[42:45], v[150:153], v[166:169], v[42:45]
	v_mfma_f32_16x16x32_bf16 v[30:33], v[142:145], v[174:177], v[30:33]
	v_mfma_f32_16x16x32_bf16 v[26:29], v[150:153], v[174:177], v[26:29]
	v_mfma_f32_16x16x32_bf16 v[14:17], v[142:145], v[186:189], v[14:17]
	v_mfma_f32_16x16x32_bf16 v[10:13], v[150:153], v[186:189], v[10:13]
	v_mfma_f32_16x16x32_bf16 v[62:65], v[146:149], v[162:165], v[62:65]
	v_mfma_f32_16x16x32_bf16 v[58:61], v[154:157], v[162:165], v[58:61]
	v_mfma_f32_16x16x32_bf16 v[46:49], v[146:149], v[170:173], v[46:49]
	v_mfma_f32_16x16x32_bf16 v[42:45], v[154:157], v[170:173], v[42:45]
	v_mfma_f32_16x16x32_bf16 v[30:33], v[146:149], v[182:185], v[30:33]
	v_mfma_f32_16x16x32_bf16 v[26:29], v[154:157], v[182:185], v[26:29]
	v_mfma_f32_16x16x32_bf16 v[14:17], v[146:149], v[190:193], v[14:17]
	v_mfma_f32_16x16x32_bf16 v[10:13], v[154:157], v[190:193], v[10:13]
	s_setprio 0
	s_barrier
	s_add_u32 s76, s26, 0x40000
	s_addc_u32 s77, s27, 0
	s_mov_b32 m0, s36
	v_lshl_add_u64 v[142:143], s[76:77], 0, v[132:133]
	global_load_lds_dwordx4 v[142:143], off
	v_lshl_add_u64 v[142:143], s[76:77], 0, v[130:131]
	s_mov_b32 m0, s37
	s_nop 0
	global_load_lds_dwordx4 v[142:143], off
	s_waitcnt vmcnt(6)
	s_barrier
	s_setprio 1
	v_mfma_f32_16x16x32_bf16 v[54:57], v[194:197], v[158:161], v[54:57]
	v_mfma_f32_16x16x32_bf16 v[50:53], v[202:205], v[158:161], v[50:53]
	v_mfma_f32_16x16x32_bf16 v[38:41], v[194:197], v[166:169], v[38:41]
	v_mfma_f32_16x16x32_bf16 v[34:37], v[202:205], v[166:169], v[34:37]
	v_mfma_f32_16x16x32_bf16 v[22:25], v[194:197], v[174:177], v[22:25]
	v_mfma_f32_16x16x32_bf16 v[18:21], v[202:205], v[174:177], v[18:21]
	v_mfma_f32_16x16x32_bf16 v[6:9], v[194:197], v[186:189], v[6:9]
	v_mfma_f32_16x16x32_bf16 v[2:5], v[202:205], v[186:189], v[2:5]
	v_mfma_f32_16x16x32_bf16 v[54:57], v[198:201], v[162:165], v[54:57]
	v_mfma_f32_16x16x32_bf16 v[50:53], v[206:209], v[162:165], v[50:53]
	v_mfma_f32_16x16x32_bf16 v[38:41], v[198:201], v[170:173], v[38:41]
	v_mfma_f32_16x16x32_bf16 v[34:37], v[206:209], v[170:173], v[34:37]
	v_mfma_f32_16x16x32_bf16 v[22:25], v[198:201], v[182:185], v[22:25]
	v_mfma_f32_16x16x32_bf16 v[18:21], v[206:209], v[182:185], v[18:21]
	v_mfma_f32_16x16x32_bf16 v[6:9], v[198:201], v[190:193], v[6:9]
	v_mfma_f32_16x16x32_bf16 v[2:5], v[206:209], v[190:193], v[2:5]
	s_setprio 0
	v_add_u32_e32 v0, 0x18000, v139
	s_barrier
	s_waitcnt vmcnt(0)
	ds_read_b128 v[142:145], v0
	ds_read_b128 v[146:149], v0 offset:1024
	ds_read_b128 v[150:153], v0 offset:2048
	ds_read_b128 v[154:157], v0 offset:3072
	s_add_u32 s28, s28, 0x40000
	s_addc_u32 s29, s29, 0
	s_mov_b32 m0, s38
	v_lshl_add_u64 v[194:195], s[28:29], 0, v[132:133]
	ds_read_b128 v[158:161], v138 offset:32768
	ds_read_b128 v[162:165], v138 offset:33792
	ds_read_b128 v[166:169], v138 offset:34816
	ds_read_b128 v[170:173], v138 offset:35840
	ds_read_b128 v[174:177], v138 offset:36864
	ds_read_b128 v[182:185], v138 offset:37888
	ds_read_b128 v[186:189], v138 offset:38912
	ds_read_b128 v[190:193], v138 offset:39936
	global_load_lds_dwordx4 v[194:195], off
	v_lshl_add_u64 v[194:195], s[28:29], 0, v[130:131]
	s_mov_b32 m0, s39
	s_nop 0
	global_load_lds_dwordx4 v[194:195], off
	s_waitcnt lgkmcnt(8)
	s_barrier
	s_waitcnt lgkmcnt(0)
	s_setprio 1
	s_waitcnt lgkmcnt(0)
	v_mfma_f32_16x16x32_bf16 v[126:129], v[142:145], v[158:161], v[126:129]
	v_mfma_f32_16x16x32_bf16 v[122:125], v[150:153], v[158:161], v[122:125]
	v_mfma_f32_16x16x32_bf16 v[110:113], v[142:145], v[166:169], v[110:113]
	v_mfma_f32_16x16x32_bf16 v[106:109], v[150:153], v[166:169], v[106:109]
	v_mfma_f32_16x16x32_bf16 v[94:97], v[142:145], v[174:177], v[94:97]
	v_mfma_f32_16x16x32_bf16 v[90:93], v[150:153], v[174:177], v[90:93]
	v_mfma_f32_16x16x32_bf16 v[78:81], v[142:145], v[186:189], v[78:81]
	v_mfma_f32_16x16x32_bf16 v[74:77], v[150:153], v[186:189], v[74:77]
	v_mfma_f32_16x16x32_bf16 v[126:129], v[146:149], v[162:165], v[126:129]
	v_mfma_f32_16x16x32_bf16 v[122:125], v[154:157], v[162:165], v[122:125]
	v_mfma_f32_16x16x32_bf16 v[110:113], v[146:149], v[170:173], v[110:113]
	v_mfma_f32_16x16x32_bf16 v[106:109], v[154:157], v[170:173], v[106:109]
	v_mfma_f32_16x16x32_bf16 v[94:97], v[146:149], v[182:185], v[94:97]
	v_mfma_f32_16x16x32_bf16 v[90:93], v[154:157], v[182:185], v[90:93]
	v_mfma_f32_16x16x32_bf16 v[78:81], v[146:149], v[190:193], v[78:81]
	v_mfma_f32_16x16x32_bf16 v[74:77], v[154:157], v[190:193], v[74:77]
	s_setprio 0
	s_barrier
	s_mov_b32 m0, s60
	v_add_u32_e32 v0, 0x1c000, v139
	v_lshl_add_u64 v[178:179], v[178:179], 0, s[84:85]
	s_waitcnt vmcnt(0)
	ds_read_b128 v[194:197], v0
	ds_read_b128 v[198:201], v0 offset:1024
	ds_read_b128 v[202:205], v0 offset:2048
	ds_read_b128 v[206:209], v0 offset:3072
	global_load_lds_dwordx4 v[178:179], off
	v_lshl_add_u64 v[178:179], v[210:211], 0, s[84:85]
	s_mov_b32 m0, s68
	s_nop 0
	global_load_lds_dwordx4 v[178:179], off
	s_barrier
	s_waitcnt lgkmcnt(0)
	s_setprio 1
	s_waitcnt lgkmcnt(0)
	v_mfma_f32_16x16x32_bf16 v[118:121], v[194:197], v[158:161], v[118:121]
	v_mfma_f32_16x16x32_bf16 v[114:117], v[202:205], v[158:161], v[114:117]
	v_mfma_f32_16x16x32_bf16 v[102:105], v[194:197], v[166:169], v[102:105]
	v_mfma_f32_16x16x32_bf16 v[98:101], v[202:205], v[166:169], v[98:101]
	v_mfma_f32_16x16x32_bf16 v[86:89], v[194:197], v[174:177], v[86:89]
	v_mfma_f32_16x16x32_bf16 v[82:85], v[202:205], v[174:177], v[82:85]
	v_mfma_f32_16x16x32_bf16 v[70:73], v[194:197], v[186:189], v[70:73]
	v_mfma_f32_16x16x32_bf16 v[66:69], v[202:205], v[186:189], v[66:69]
	v_mfma_f32_16x16x32_bf16 v[118:121], v[198:201], v[162:165], v[118:121]
	v_mfma_f32_16x16x32_bf16 v[114:117], v[206:209], v[162:165], v[114:117]
	v_mfma_f32_16x16x32_bf16 v[102:105], v[198:201], v[170:173], v[102:105]
	v_mfma_f32_16x16x32_bf16 v[98:101], v[206:209], v[170:173], v[98:101]
	v_mfma_f32_16x16x32_bf16 v[86:89], v[198:201], v[182:185], v[86:89]
	v_mfma_f32_16x16x32_bf16 v[82:85], v[206:209], v[182:185], v[82:85]
	v_mfma_f32_16x16x32_bf16 v[70:73], v[198:201], v[190:193], v[70:73]
	v_mfma_f32_16x16x32_bf16 v[66:69], v[206:209], v[190:193], v[66:69]
	s_setprio 0
	s_mov_b32 m0, s69
	v_lshl_add_u64 v[178:179], v[212:213], 0, s[84:85]
	s_barrier
	s_waitcnt vmcnt(0)
	ds_read_b128 v[158:161], v138 offset:49152
	ds_read_b128 v[162:165], v138 offset:50176
	ds_read_b128 v[166:169], v138 offset:51200
	ds_read_b128 v[170:173], v138 offset:52224
	ds_read_b128 v[174:177], v138 offset:53248
	ds_read_b128 v[182:185], v138 offset:54272
	ds_read_b128 v[186:189], v138 offset:55296
	ds_read_b128 v[190:193], v138 offset:56320
	global_load_lds_dwordx4 v[178:179], off
	v_lshl_add_u64 v[178:179], v[214:215], 0, s[84:85]
	s_mov_b32 m0, s75
	s_nop 0
	global_load_lds_dwordx4 v[178:179], off
	s_barrier
	s_waitcnt lgkmcnt(0)
	s_setprio 1
	s_waitcnt lgkmcnt(0)
	v_mfma_f32_16x16x32_bf16 v[62:65], v[142:145], v[158:161], v[62:65]
	v_mfma_f32_16x16x32_bf16 v[58:61], v[150:153], v[158:161], v[58:61]
	v_mfma_f32_16x16x32_bf16 v[46:49], v[142:145], v[166:169], v[46:49]
	v_mfma_f32_16x16x32_bf16 v[42:45], v[150:153], v[166:169], v[42:45]
	v_mfma_f32_16x16x32_bf16 v[30:33], v[142:145], v[174:177], v[30:33]
	v_mfma_f32_16x16x32_bf16 v[26:29], v[150:153], v[174:177], v[26:29]
	v_mfma_f32_16x16x32_bf16 v[14:17], v[142:145], v[186:189], v[14:17]
	v_mfma_f32_16x16x32_bf16 v[10:13], v[150:153], v[186:189], v[10:13]
	v_mfma_f32_16x16x32_bf16 v[62:65], v[146:149], v[162:165], v[62:65]
	v_mfma_f32_16x16x32_bf16 v[58:61], v[154:157], v[162:165], v[58:61]
	v_mfma_f32_16x16x32_bf16 v[46:49], v[146:149], v[170:173], v[46:49]
	v_mfma_f32_16x16x32_bf16 v[42:45], v[154:157], v[170:173], v[42:45]
	v_mfma_f32_16x16x32_bf16 v[30:33], v[146:149], v[182:185], v[30:33]
	v_mfma_f32_16x16x32_bf16 v[26:29], v[154:157], v[182:185], v[26:29]
	v_mfma_f32_16x16x32_bf16 v[14:17], v[146:149], v[190:193], v[14:17]
	v_mfma_f32_16x16x32_bf16 v[10:13], v[154:157], v[190:193], v[10:13]
	s_setprio 0
	s_barrier
	s_add_u32 s26, s26, 0x40080
	s_addc_u32 s27, s27, 0
	s_mov_b32 m0, s82
	v_lshl_add_u64 v[142:143], s[26:27], 0, v[132:133]
	global_load_lds_dwordx4 v[142:143], off
	v_lshl_add_u64 v[142:143], s[26:27], 0, v[130:131]
	s_mov_b32 m0, s92
	s_nop 0
	global_load_lds_dwordx4 v[142:143], off
	s_waitcnt vmcnt(6)
	s_barrier
	s_setprio 1
	v_mfma_f32_16x16x32_bf16 v[54:57], v[194:197], v[158:161], v[54:57]
	v_mfma_f32_16x16x32_bf16 v[50:53], v[202:205], v[158:161], v[50:53]
	v_mfma_f32_16x16x32_bf16 v[38:41], v[194:197], v[166:169], v[38:41]
	v_mfma_f32_16x16x32_bf16 v[34:37], v[202:205], v[166:169], v[34:37]
	v_mfma_f32_16x16x32_bf16 v[22:25], v[194:197], v[174:177], v[22:25]
	v_mfma_f32_16x16x32_bf16 v[18:21], v[202:205], v[174:177], v[18:21]
	v_mfma_f32_16x16x32_bf16 v[6:9], v[194:197], v[186:189], v[6:9]
	v_mfma_f32_16x16x32_bf16 v[2:5], v[202:205], v[186:189], v[2:5]
	v_mfma_f32_16x16x32_bf16 v[54:57], v[198:201], v[162:165], v[54:57]
	v_mfma_f32_16x16x32_bf16 v[50:53], v[206:209], v[162:165], v[50:53]
	v_mfma_f32_16x16x32_bf16 v[38:41], v[198:201], v[170:173], v[38:41]
	v_mfma_f32_16x16x32_bf16 v[34:37], v[206:209], v[170:173], v[34:37]
	v_mfma_f32_16x16x32_bf16 v[22:25], v[198:201], v[182:185], v[22:25]
	v_mfma_f32_16x16x32_bf16 v[18:21], v[206:209], v[182:185], v[18:21]
	v_mfma_f32_16x16x32_bf16 v[6:9], v[198:201], v[190:193], v[6:9]
	v_mfma_f32_16x16x32_bf16 v[2:5], v[206:209], v[190:193], v[2:5]
	s_setprio 0
	s_add_i32 s97, s97, 2
	s_add_u32 s24, s24, 0x100
	s_addc_u32 s25, s25, 0
	s_add_u32 s94, s94, 0x100
	s_addc_u32 s96, s96, 0
	s_cmp_gt_u32 s97, 13
	s_barrier
	s_cbranch_scc0 .LBB0_1441
	s_lshl_b32 s11, s20, 8
	s_lshl_b32 s13, s22, 18
	s_add_i32 s13, s13, s11
	v_add_u32_e32 v0, s13, v140
	v_mov_b32_e32 v148, v0
	v_mov_b32_e32 v207, 0
	v_mov_b32_e32 v206, v148
	v_lshlrev_b64 v[150:151], 2, v[206:207]
	v_lshl_add_u64 v[150:151], s[6:7], 0, v[150:151]
	global_load_dwordx4 v[150:153], v[150:151], off
	v_add_u32_e32 v206, 0x10, v148
	v_lshlrev_b64 v[154:155], 2, v[206:207]
	v_lshl_add_u64 v[154:155], s[6:7], 0, v[154:155]
	global_load_dwordx4 v[154:157], v[154:155], off
	v_add_u32_e32 v206, 0x80, v148
	v_lshlrev_b64 v[158:159], 2, v[206:207]
	v_lshl_add_u64 v[158:159], s[6:7], 0, v[158:159]
	global_load_dwordx4 v[158:161], v[158:159], off
	v_add_u32_e32 v206, 0x90, v148
	v_lshlrev_b64 v[162:163], 2, v[206:207]
	v_lshl_add_u64 v[162:163], s[6:7], 0, v[162:163]
	global_load_dwordx4 v[162:165], v[162:163], off
	v_add_u32_e32 v206, 0x4000, v148
	v_lshlrev_b64 v[166:167], 2, v[206:207]
	v_lshl_add_u64 v[166:167], s[6:7], 0, v[166:167]
	global_load_dwordx4 v[166:169], v[166:167], off
	v_add_u32_e32 v206, 0x4010, v148
	v_lshlrev_b64 v[170:171], 2, v[206:207]
	v_lshl_add_u64 v[170:171], s[6:7], 0, v[170:171]
	global_load_dwordx4 v[170:173], v[170:171], off
	v_add_u32_e32 v206, 0x4080, v148
	v_lshlrev_b64 v[174:175], 2, v[206:207]
	v_lshl_add_u64 v[174:175], s[6:7], 0, v[174:175]
	global_load_dwordx4 v[174:177], v[174:175], off
	v_add_u32_e32 v206, 0x4090, v148
	v_lshlrev_b64 v[182:183], 2, v[206:207]
	v_lshl_add_u64 v[182:183], s[6:7], 0, v[182:183]
	global_load_dwordx4 v[182:185], v[182:183], off
	v_add_u32_e32 v206, 0x8000, v148
	v_lshlrev_b64 v[186:187], 2, v[206:207]
	v_lshl_add_u64 v[186:187], s[6:7], 0, v[186:187]
	global_load_dwordx4 v[186:189], v[186:187], off
	v_add_u32_e32 v206, 0x8010, v148
	v_lshlrev_b64 v[190:191], 2, v[206:207]
	v_lshl_add_u64 v[190:191], s[6:7], 0, v[190:191]
	global_load_dwordx4 v[190:193], v[190:191], off
	v_add_u32_e32 v206, 0x8080, v148
	v_lshlrev_b64 v[194:195], 2, v[206:207]
	v_lshl_add_u64 v[194:195], s[6:7], 0, v[194:195]
	global_load_dwordx4 v[194:197], v[194:195], off
	v_add_u32_e32 v206, 0x8090, v148
	v_lshlrev_b64 v[198:199], 2, v[206:207]
	v_lshl_add_u64 v[198:199], s[6:7], 0, v[198:199]
	global_load_dwordx4 v[198:201], v[198:199], off
	v_add_u32_e32 v206, 0xc000, v148
	v_lshlrev_b64 v[202:203], 2, v[206:207]
	v_lshl_add_u64 v[202:203], s[6:7], 0, v[202:203]
	global_load_dwordx4 v[202:205], v[202:203], off
	v_lshlrev_b64 v[146:147], 2, v[0:1]
	s_and_b64 vcc, exec, s[14:15]
	s_mov_b32 s20, s10
	s_mov_b32 s22, s12
	s_mov_b64 s[26:27], s[18:19]
	s_mov_b64 s[24:25], s[16:17]
	s_waitcnt vmcnt(12)
	v_pk_add_f32 v[128:129], v[128:129], v[152:153]
	v_pk_add_f32 v[126:127], v[126:127], v[150:151]
	v_lshl_add_u64 v[142:143], s[8:9], 0, v[146:147]
	v_add_u32_e32 v206, 0xc010, v148
	v_lshlrev_b64 v[150:151], 2, v[206:207]
	v_lshl_add_u64 v[150:151], s[6:7], 0, v[150:151]
	global_load_dwordx4 v[150:153], v[150:151], off
	global_store_dwordx4 v[142:143], v[126:129], off
	s_nop 1
	v_add_u32_e32 v126, 16, v0
	v_mov_b32_e32 v127, v1
	v_lshlrev_b64 v[142:143], 2, v[126:127]
	s_waitcnt vmcnt(13)
	v_pk_add_f32 v[124:125], v[124:125], v[156:157]
	v_pk_add_f32 v[122:123], v[122:123], v[154:155]
	v_lshl_add_u64 v[126:127], s[8:9], 0, v[142:143]
	v_add_u32_e32 v206, 0xc080, v148
	v_lshlrev_b64 v[154:155], 2, v[206:207]
	v_lshl_add_u64 v[154:155], s[6:7], 0, v[154:155]
	global_load_dwordx4 v[154:157], v[154:155], off
	global_store_dwordx4 v[126:127], v[122:125], off
	s_nop 1
	v_add_u32_e32 v122, 0x80, v0
	v_mov_b32_e32 v123, v1
	v_lshlrev_b64 v[126:127], 2, v[122:123]
	s_waitcnt vmcnt(14)
	v_pk_add_f32 v[120:121], v[120:121], v[160:161]
	v_pk_add_f32 v[118:119], v[118:119], v[158:159]
	v_lshl_add_u64 v[122:123], s[8:9], 0, v[126:127]
	v_add_u32_e32 v206, 0xc090, v148
	v_lshlrev_b64 v[158:159], 2, v[206:207]
	v_lshl_add_u64 v[158:159], s[6:7], 0, v[158:159]
	global_load_dwordx4 v[158:161], v[158:159], off
	global_store_dwordx4 v[122:123], v[118:121], off
	s_nop 1
	v_add_u32_e32 v118, 0x90, v0
	v_mov_b32_e32 v119, v1
	v_lshlrev_b64 v[122:123], 2, v[118:119]
	s_waitcnt vmcnt(15)
	v_pk_add_f32 v[116:117], v[116:117], v[164:165]
	v_pk_add_f32 v[114:115], v[114:115], v[162:163]
	v_lshl_add_u64 v[118:119], s[8:9], 0, v[122:123]
	v_add_u32_e32 v206, 0x20000, v148
	v_lshlrev_b64 v[162:163], 2, v[206:207]
	v_lshl_add_u64 v[162:163], s[6:7], 0, v[162:163]
	global_load_dwordx4 v[162:165], v[162:163], off
	global_store_dwordx4 v[118:119], v[114:117], off
	s_nop 1
	v_add_u32_e32 v114, 0x4000, v0
	v_mov_b32_e32 v115, v1
	v_lshlrev_b64 v[118:119], 2, v[114:115]
	s_waitcnt vmcnt(16)
	v_pk_add_f32 v[112:113], v[112:113], v[168:169]
	v_pk_add_f32 v[110:111], v[110:111], v[166:167]
	v_lshl_add_u64 v[114:115], s[8:9], 0, v[118:119]
	v_add_u32_e32 v206, 0x20010, v148
	v_lshlrev_b64 v[166:167], 2, v[206:207]
	v_lshl_add_u64 v[166:167], s[6:7], 0, v[166:167]
	global_load_dwordx4 v[166:169], v[166:167], off
	global_store_dwordx4 v[114:115], v[110:113], off
	s_nop 1
	v_add_u32_e32 v110, 0x4010, v0
	v_mov_b32_e32 v111, v1
	v_lshlrev_b64 v[114:115], 2, v[110:111]
	s_waitcnt vmcnt(17)
	v_pk_add_f32 v[108:109], v[108:109], v[172:173]
	v_pk_add_f32 v[106:107], v[106:107], v[170:171]
	v_lshl_add_u64 v[110:111], s[8:9], 0, v[114:115]
	v_add_u32_e32 v206, 0x20080, v148
	v_lshlrev_b64 v[170:171], 2, v[206:207]
	v_lshl_add_u64 v[170:171], s[6:7], 0, v[170:171]
	global_load_dwordx4 v[170:173], v[170:171], off
	global_store_dwordx4 v[110:111], v[106:109], off
	s_nop 1
	v_add_u32_e32 v106, 0x4080, v0
	v_mov_b32_e32 v107, v1
	v_lshlrev_b64 v[110:111], 2, v[106:107]
	s_waitcnt vmcnt(18)
	v_pk_add_f32 v[104:105], v[104:105], v[176:177]
	v_pk_add_f32 v[102:103], v[102:103], v[174:175]
	v_lshl_add_u64 v[106:107], s[8:9], 0, v[110:111]
	v_add_u32_e32 v206, 0x20090, v148
	v_lshlrev_b64 v[174:175], 2, v[206:207]
	v_lshl_add_u64 v[174:175], s[6:7], 0, v[174:175]
	global_load_dwordx4 v[174:177], v[174:175], off
	global_store_dwordx4 v[106:107], v[102:105], off
	s_nop 1
	v_add_u32_e32 v102, 0x4090, v0
	v_mov_b32_e32 v103, v1
	v_lshlrev_b64 v[106:107], 2, v[102:103]
	s_waitcnt vmcnt(19)
	v_pk_add_f32 v[100:101], v[100:101], v[184:185]
	v_pk_add_f32 v[98:99], v[98:99], v[182:183]
	v_lshl_add_u64 v[102:103], s[8:9], 0, v[106:107]
	v_add_u32_e32 v206, 0x24000, v148
	v_lshlrev_b64 v[182:183], 2, v[206:207]
	v_lshl_add_u64 v[182:183], s[6:7], 0, v[182:183]
	global_load_dwordx4 v[182:185], v[182:183], off
	global_store_dwordx4 v[102:103], v[98:101], off
	s_nop 1
	v_add_u32_e32 v98, 0x8000, v0
	v_mov_b32_e32 v99, v1
	v_lshlrev_b64 v[102:103], 2, v[98:99]
	s_waitcnt vmcnt(20)
	v_pk_add_f32 v[96:97], v[96:97], v[188:189]
	v_pk_add_f32 v[94:95], v[94:95], v[186:187]
	v_lshl_add_u64 v[98:99], s[8:9], 0, v[102:103]
	v_add_u32_e32 v206, 0x24010, v148
	v_lshlrev_b64 v[186:187], 2, v[206:207]
	v_lshl_add_u64 v[186:187], s[6:7], 0, v[186:187]
	global_load_dwordx4 v[186:189], v[186:187], off
	global_store_dwordx4 v[98:99], v[94:97], off
	s_nop 1
	v_add_u32_e32 v94, 0x8010, v0
	v_mov_b32_e32 v95, v1
	v_lshlrev_b64 v[98:99], 2, v[94:95]
	s_waitcnt vmcnt(21)
	v_pk_add_f32 v[92:93], v[92:93], v[192:193]
	v_pk_add_f32 v[90:91], v[90:91], v[190:191]
	v_lshl_add_u64 v[94:95], s[8:9], 0, v[98:99]
	v_add_u32_e32 v206, 0x24080, v148
	v_lshlrev_b64 v[190:191], 2, v[206:207]
	v_lshl_add_u64 v[190:191], s[6:7], 0, v[190:191]
	global_load_dwordx4 v[190:193], v[190:191], off
	global_store_dwordx4 v[94:95], v[90:93], off
	s_nop 1
	v_add_u32_e32 v90, 0x8080, v0
	v_mov_b32_e32 v91, v1
	v_lshlrev_b64 v[94:95], 2, v[90:91]
	s_waitcnt vmcnt(22)
	v_pk_add_f32 v[88:89], v[88:89], v[196:197]
	v_pk_add_f32 v[86:87], v[86:87], v[194:195]
	v_lshl_add_u64 v[90:91], s[8:9], 0, v[94:95]
	v_add_u32_e32 v206, 0x24090, v148
	v_lshlrev_b64 v[194:195], 2, v[206:207]
	v_lshl_add_u64 v[194:195], s[6:7], 0, v[194:195]
	global_load_dwordx4 v[194:197], v[194:195], off
	global_store_dwordx4 v[90:91], v[86:89], off
	s_nop 1
	v_add_u32_e32 v86, 0x8090, v0
	v_mov_b32_e32 v87, v1
	v_lshlrev_b64 v[90:91], 2, v[86:87]
	s_waitcnt vmcnt(23)
	v_pk_add_f32 v[84:85], v[84:85], v[200:201]
	v_pk_add_f32 v[82:83], v[82:83], v[198:199]
	v_lshl_add_u64 v[86:87], s[8:9], 0, v[90:91]
	v_add_u32_e32 v206, 0x28000, v148
	v_lshlrev_b64 v[198:199], 2, v[206:207]
	v_lshl_add_u64 v[198:199], s[6:7], 0, v[198:199]
	global_load_dwordx4 v[198:201], v[198:199], off
	global_store_dwordx4 v[86:87], v[82:85], off
	s_nop 1
	v_add_u32_e32 v82, 0xc000, v0
	v_mov_b32_e32 v83, v1
	v_lshlrev_b64 v[86:87], 2, v[82:83]
	s_waitcnt vmcnt(24)
	v_pk_add_f32 v[80:81], v[80:81], v[204:205]
	v_pk_add_f32 v[78:79], v[78:79], v[202:203]
	v_lshl_add_u64 v[82:83], s[8:9], 0, v[86:87]
	v_add_u32_e32 v206, 0x28010, v148
	v_lshlrev_b64 v[202:203], 2, v[206:207]
	v_lshl_add_u64 v[202:203], s[6:7], 0, v[202:203]
	global_load_dwordx4 v[202:205], v[202:203], off
	global_store_dwordx4 v[82:83], v[78:81], off
	s_nop 1
	v_add_u32_e32 v78, 0xc010, v0
	v_mov_b32_e32 v79, v1
	v_lshlrev_b64 v[82:83], 2, v[78:79]
	s_waitcnt vmcnt(25)
	v_pk_add_f32 v[76:77], v[76:77], v[152:153]
	v_pk_add_f32 v[74:75], v[74:75], v[150:151]
	v_lshl_add_u64 v[78:79], s[8:9], 0, v[82:83]
	v_add_u32_e32 v206, 0x28080, v148
	v_lshlrev_b64 v[150:151], 2, v[206:207]
	v_lshl_add_u64 v[150:151], s[6:7], 0, v[150:151]
	global_load_dwordx4 v[150:153], v[150:151], off
	global_store_dwordx4 v[78:79], v[74:77], off
	s_nop 1
	v_add_u32_e32 v74, 0xc080, v0
	v_mov_b32_e32 v75, v1
	v_lshlrev_b64 v[78:79], 2, v[74:75]
	s_waitcnt vmcnt(25)
	v_pk_add_f32 v[72:73], v[72:73], v[156:157]
	v_pk_add_f32 v[70:71], v[70:71], v[154:155]
	v_lshl_add_u64 v[74:75], s[8:9], 0, v[78:79]
	v_add_u32_e32 v206, 0x28090, v148
	v_lshlrev_b64 v[154:155], 2, v[206:207]
	v_lshl_add_u64 v[154:155], s[6:7], 0, v[154:155]
	global_load_dwordx4 v[154:157], v[154:155], off
	global_store_dwordx4 v[74:75], v[70:73], off
	s_nop 1
	v_add_u32_e32 v70, 0xc090, v0
	v_mov_b32_e32 v71, v1
	v_lshlrev_b64 v[74:75], 2, v[70:71]
	s_waitcnt vmcnt(25)
	v_pk_add_f32 v[68:69], v[68:69], v[160:161]
	v_pk_add_f32 v[66:67], v[66:67], v[158:159]
	v_lshl_add_u64 v[70:71], s[8:9], 0, v[74:75]
	v_add_u32_e32 v206, 0x2c000, v148
	v_lshlrev_b64 v[158:159], 2, v[206:207]
	v_lshl_add_u64 v[158:159], s[6:7], 0, v[158:159]
	global_load_dwordx4 v[158:161], v[158:159], off
	global_store_dwordx4 v[70:71], v[66:69], off
	s_nop 1
	v_add_u32_e32 v66, 0x20000, v0
	v_mov_b32_e32 v67, v1
	v_lshlrev_b64 v[70:71], 2, v[66:67]
	s_waitcnt vmcnt(25)
	v_pk_add_f32 v[64:65], v[64:65], v[164:165]
	v_pk_add_f32 v[62:63], v[62:63], v[162:163]
	v_lshl_add_u64 v[66:67], s[8:9], 0, v[70:71]
	v_add_u32_e32 v206, 0x2c010, v148
	v_lshlrev_b64 v[162:163], 2, v[206:207]
	v_lshl_add_u64 v[162:163], s[6:7], 0, v[162:163]
	global_load_dwordx4 v[162:165], v[162:163], off
	global_store_dwordx4 v[66:67], v[62:65], off
	s_nop 1
	v_add_u32_e32 v62, 0x20010, v0
	v_mov_b32_e32 v63, v1
	v_lshlrev_b64 v[66:67], 2, v[62:63]
	s_waitcnt vmcnt(25)
	v_pk_add_f32 v[60:61], v[60:61], v[168:169]
	v_pk_add_f32 v[58:59], v[58:59], v[166:167]
	v_lshl_add_u64 v[62:63], s[8:9], 0, v[66:67]
	v_add_u32_e32 v206, 0x2c080, v148
	v_lshlrev_b64 v[166:167], 2, v[206:207]
	v_lshl_add_u64 v[166:167], s[6:7], 0, v[166:167]
	global_load_dwordx4 v[166:169], v[166:167], off
	global_store_dwordx4 v[62:63], v[58:61], off
	s_nop 1
	v_add_u32_e32 v58, 0x20080, v0
	v_mov_b32_e32 v59, v1
	v_lshlrev_b64 v[62:63], 2, v[58:59]
	s_waitcnt vmcnt(25)
	v_pk_add_f32 v[56:57], v[56:57], v[172:173]
	v_pk_add_f32 v[54:55], v[54:55], v[170:171]
	v_lshl_add_u64 v[58:59], s[8:9], 0, v[62:63]
	v_add_u32_e32 v206, 0x2c090, v148
	v_lshlrev_b64 v[170:171], 2, v[206:207]
	v_lshl_add_u64 v[170:171], s[6:7], 0, v[170:171]
	global_load_dwordx4 v[170:173], v[170:171], off
	global_store_dwordx4 v[58:59], v[54:57], off
	s_nop 1
	v_add_u32_e32 v54, 0x20090, v0
	v_mov_b32_e32 v55, v1
	v_lshlrev_b64 v[58:59], 2, v[54:55]
	s_waitcnt vmcnt(25)
	v_pk_add_f32 v[52:53], v[52:53], v[176:177]
	v_pk_add_f32 v[50:51], v[50:51], v[174:175]
	v_lshl_add_u64 v[54:55], s[8:9], 0, v[58:59]
	global_store_dwordx4 v[54:55], v[50:53], off
	s_nop 1
	v_add_u32_e32 v50, 0x24000, v0
	v_mov_b32_e32 v51, v1
	v_lshlrev_b64 v[54:55], 2, v[50:51]
	s_waitcnt vmcnt(24)
	v_pk_add_f32 v[48:49], v[48:49], v[184:185]
	v_pk_add_f32 v[46:47], v[46:47], v[182:183]
	v_lshl_add_u64 v[50:51], s[8:9], 0, v[54:55]
	global_store_dwordx4 v[50:51], v[46:49], off
	s_nop 1
	v_add_u32_e32 v46, 0x24010, v0
	v_mov_b32_e32 v47, v1
	v_lshlrev_b64 v[50:51], 2, v[46:47]
	s_waitcnt vmcnt(23)
	v_pk_add_f32 v[44:45], v[44:45], v[188:189]
	v_pk_add_f32 v[42:43], v[42:43], v[186:187]
	v_lshl_add_u64 v[46:47], s[8:9], 0, v[50:51]
	global_store_dwordx4 v[46:47], v[42:45], off
	s_nop 1
	v_add_u32_e32 v42, 0x24080, v0
	v_mov_b32_e32 v43, v1
	v_lshlrev_b64 v[46:47], 2, v[42:43]
	s_waitcnt vmcnt(22)
	v_pk_add_f32 v[40:41], v[40:41], v[192:193]
	v_pk_add_f32 v[38:39], v[38:39], v[190:191]
	v_lshl_add_u64 v[42:43], s[8:9], 0, v[46:47]
	global_store_dwordx4 v[42:43], v[38:41], off
	s_nop 1
	v_add_u32_e32 v38, 0x24090, v0
	v_mov_b32_e32 v39, v1
	v_lshlrev_b64 v[42:43], 2, v[38:39]
	s_waitcnt vmcnt(21)
	v_pk_add_f32 v[36:37], v[36:37], v[196:197]
	v_pk_add_f32 v[34:35], v[34:35], v[194:195]
	v_lshl_add_u64 v[38:39], s[8:9], 0, v[42:43]
	global_store_dwordx4 v[38:39], v[34:37], off
	s_nop 1
	v_add_u32_e32 v34, 0x28000, v0
	v_mov_b32_e32 v35, v1
	v_lshlrev_b64 v[38:39], 2, v[34:35]
	s_waitcnt vmcnt(20)
	v_pk_add_f32 v[32:33], v[32:33], v[200:201]
	v_pk_add_f32 v[30:31], v[30:31], v[198:199]
	v_lshl_add_u64 v[34:35], s[8:9], 0, v[38:39]
	global_store_dwordx4 v[34:35], v[30:33], off
	s_nop 1
	v_add_u32_e32 v30, 0x28010, v0
	v_mov_b32_e32 v31, v1
	v_lshlrev_b64 v[34:35], 2, v[30:31]
	s_waitcnt vmcnt(19)
	v_pk_add_f32 v[28:29], v[28:29], v[204:205]
	v_pk_add_f32 v[26:27], v[26:27], v[202:203]
	v_lshl_add_u64 v[30:31], s[8:9], 0, v[34:35]
	global_store_dwordx4 v[30:31], v[26:29], off
	s_nop 1
	v_add_u32_e32 v26, 0x28080, v0
	v_mov_b32_e32 v27, v1
	v_lshlrev_b64 v[30:31], 2, v[26:27]
	s_waitcnt vmcnt(18)
	v_pk_add_f32 v[24:25], v[24:25], v[152:153]
	v_pk_add_f32 v[22:23], v[22:23], v[150:151]
	v_lshl_add_u64 v[26:27], s[8:9], 0, v[30:31]
	global_store_dwordx4 v[26:27], v[22:25], off
	s_nop 1
	v_add_u32_e32 v22, 0x28090, v0
	v_mov_b32_e32 v23, v1
	v_lshlrev_b64 v[26:27], 2, v[22:23]
	s_waitcnt vmcnt(17)
	v_pk_add_f32 v[20:21], v[20:21], v[156:157]
	v_pk_add_f32 v[18:19], v[18:19], v[154:155]
	v_lshl_add_u64 v[22:23], s[8:9], 0, v[26:27]
	global_store_dwordx4 v[22:23], v[18:21], off
	s_nop 1
	v_add_u32_e32 v18, 0x2c000, v0
	v_mov_b32_e32 v19, v1
	v_lshlrev_b64 v[22:23], 2, v[18:19]
	s_waitcnt vmcnt(16)
	v_pk_add_f32 v[16:17], v[16:17], v[160:161]
	v_pk_add_f32 v[14:15], v[14:15], v[158:159]
	v_lshl_add_u64 v[18:19], s[8:9], 0, v[22:23]
	global_store_dwordx4 v[18:19], v[14:17], off
	s_nop 1
	v_add_u32_e32 v14, 0x2c010, v0
	v_mov_b32_e32 v15, v1
	v_lshlrev_b64 v[18:19], 2, v[14:15]
	s_waitcnt vmcnt(15)
	v_pk_add_f32 v[12:13], v[12:13], v[164:165]
	v_pk_add_f32 v[10:11], v[10:11], v[162:163]
	v_lshl_add_u64 v[14:15], s[8:9], 0, v[18:19]
	global_store_dwordx4 v[14:15], v[10:13], off
	s_nop 1
	v_add_u32_e32 v10, 0x2c080, v0
	v_mov_b32_e32 v11, v1
	v_lshlrev_b64 v[14:15], 2, v[10:11]
	v_add_u32_e32 v0, 0x2c090, v0
	s_waitcnt vmcnt(14)
	v_pk_add_f32 v[8:9], v[8:9], v[168:169]
	v_pk_add_f32 v[6:7], v[6:7], v[166:167]
	v_lshl_add_u64 v[10:11], s[8:9], 0, v[14:15]
	global_store_dwordx4 v[10:11], v[6:9], off
	v_lshlrev_b64 v[10:11], 2, v[0:1]
	s_nop 0
	s_waitcnt vmcnt(13)
	v_pk_add_f32 v[4:5], v[4:5], v[172:173]
	v_pk_add_f32 v[2:3], v[2:3], v[170:171]
	v_lshl_add_u64 v[6:7], s[8:9], 0, v[10:11]
	global_store_dwordx4 v[6:7], v[2:5], off
	s_cbranch_vccz .LBB0_1438
	s_waitcnt vmcnt(0)
	v_readlane_b32 s76, v255, 8
	s_mov_b32 s92, 0x3b2aaaab
	s_cmp_gt_u32 s3, 3
	v_readlane_b32 s77, v255, 9
	s_mul_i32 s60, s33, 0x1800
	s_mul_hi_i32 s62, s64, 0x300
	s_mul_i32 s75, s33, 0x16c00
	s_mov_b32 s93, 0x3c800000
	s_cbranch_scc1 .LBB0_1445
	s_barrier
